# K-loop DMA waits relaxed: vmcnt(8) at the end of both load segments (each stage pair gets ~4 segments to land) instead of one vmcnt(6)
# baseline (speedup 1.0000x reference)
;     __device__ __forceinline__ void prefetch(const Unit& u, int ui) const { if (rs) rs_prefetch(rs, u.pm, ui); }
;     __device__ __forceinline__ void prefetch(const Unit& u, int ui) const { rs_prefetch(rs, u.pm, ui); }
; #define PG8_STAGE(bufoff, gbase, voff) do { _Pragma("unroll") for (int _i = 0; _i < 2; ++_i) \
;         __builtin_amdgcn_global_load_lds((const unsigned*)((const char*)(gbase) + (voff)[_i]), (LAS unsigned*)(lds + (bufoff) + ldsw + _i * 8192), 16, 0, 0); } while (0)
; #define PG8_LDA(dst, b, h) do { _Pragma("unroll") for (int m = 0; m < 4; ++m) _Pragma("unroll") for (int k = 0; k < 2; ++k) dst[m][k] = *(const LAS bf16x8*)(lds + PG8_SA(b, h) + aoff + m * 2048 + k * 1024); } while (0)
; #define PG8_LDB(dst, b, h) do { _Pragma("unroll") for (int n = 0; n < 2; ++n) _Pragma("unroll") for (int k = 0; k < 2; ++k) dst[n][k] = *(const LAS bf16x8*)(lds + PG8_SB(b, h) + boff + n * 2048 + k * 1024); } while (0)
; template <class Epi, class Sched>
; __device__ __forceinline__ void gemm_phase(LAS unsigned char* lds, const Gemm g, const Sched& S, const Epi& E) {
;     ...
;     for (;;) {
;         E.prefetch(cur, ui);
;         const bool has_next = S.next(ui + 1, nxt);
;         const char* nA = has_next ? (const char*)g.A + (size_t)nxt.pm * tstepA : cA; const char* nB = has_next ? (const char*)g.Bt + (size_t)nxt.pn * tstepB : cB;
;         for (int t = 0; t < nt; t += 2) {
;             const bool last = (t == nt - 2);
;             const char* a1 = cA + (size_t)(t + 1) * kstep;
;             const char* a2 = last ? nA : cA + (size_t)(t + 2) * kstep; const char* b2 = last ? nB : cB + (size_t)(t + 2) * kstep;
;             const char* a3 = a2 + kstep; const char* b3 = b2 + kstep;
;             if (last && has_next) S.a_ready(nxt);
;             PG8_LDB(B0, 0, 0); PG8_SCHED; PG8_LDA(At, 0, 0); PG8_STAGE(PG8_SA(1, 1), a1 + hstepA, voffA);
;             PG8_WAIT_L(8); PG8_BAR; PG8_WAIT_L(0); PG8_MMA(0, 0, At, B0); PG8_BAR; PG8_SCHED;
;             PG8_LDB(B1, 0, 1); PG8_STAGE(PG8_SB(0, 0), b2, voffB);
;             PG8_BAR; PG8_WAIT_L(0); PG8_MMA(0, 1, At, B1); PG8_BAR;
;             PG8_LDA(At, 0, 1); PG8_STAGE(PG8_SA(0, 0), a2, voffA);
;             PG8_BAR; PG8_WAIT_L(0); PG8_MMA(1, 0, At, B0); PG8_BAR; PG8_SCHED;
;             PG8_STAGE(PG8_SB(0, 1), b2 + hstepB, voffB);
;             PG8_WAIT_V(6); PG8_BAR; PG8_MMA(1, 1, At, B1); PG8_BAR;
.LBB0_351:
	v_mov_b64_e32 v[4:5], 0xd80
	s_ashr_i32 s15, s14, 31
	v_cmp_lt_i64_e32 vcc, s[4:5], v[4:5]
	s_lshl_b64 s[4:5], s[14:15], 20
	s_add_u32 s18, s88, s4
	s_addc_u32 s19, s89, s5
	s_and_b64 s[4:5], vcc, exec
	s_cselect_b32 s15, s19, s7
	s_cselect_b32 s51, s18, s6
	s_ashr_i32 s1, s0, 31
	s_lshl_b64 s[4:5], s[0:1], 20
	s_add_u32 s4, s28, s4
	s_addc_u32 s5, s29, s5
	s_and_b64 s[24:25], vcc, exec
	s_cselect_b32 s1, s5, s21
	s_cselect_b32 s52, s4, s20
	s_add_u32 s6, s6, 0x80080
	s_addc_u32 s7, s7, 0
	s_add_u32 s53, s20, 0x100
	s_addc_u32 s54, s21, 0
	s_mov_b32 s55, -2
	s_waitcnt lgkmcnt(0)
	s_setprio 0
	s_add_u32 s20, s6, 0xfff80080
	s_addc_u32 s21, s7, -1
	s_add_i32 s56, 0, 0x10000
	v_add_u32_e32 v2, s56, v1
	ds_read_b128 v[144:147], v2
	ds_read_b128 v[150:153], v2 offset:1024
	ds_read_b128 v[154:157], v2 offset:2048
	ds_read_b128 v[158:161], v2 offset:3072
	s_cmp_eq_u32 s55, 28
	s_cselect_b32 s25, s15, s21
	s_cselect_b32 s24, s51, s20
	s_cselect_b32 s21, s1, s54
	s_cselect_b32 s20, s52, s53
	ds_read_b128 v[162:165], v149
	ds_read_b128 v[166:169], v149 offset:1024
	ds_read_b128 v[170:173], v149 offset:2048
	ds_read_b128 v[174:177], v149 offset:3072
	ds_read_b128 v[178:181], v149 offset:4096
	ds_read_b128 v[182:185], v149 offset:5120
	ds_read_b128 v[186:189], v149 offset:6144
	ds_read_b128 v[190:193], v149 offset:7168
	s_add_i32 s58, 0, 0x14000
	v_add_u32_e32 v2, s58, v1
	ds_read_b128 v[194:197], v2
	ds_read_b128 v[198:201], v2 offset:1024
	ds_read_b128 v[202:205], v2 offset:2048
	ds_read_b128 v[206:209], v2 offset:3072
	s_add_i32 m0, s31, 0xc000
	s_nop 0
	global_load_lds_dwordx4 v140, s[6:7]
	s_add_i32 m0, s31, 0xe000
	s_nop 0
	global_load_lds_dwordx4 v142, s[6:7]
	s_waitcnt lgkmcnt(0)
	s_waitcnt vmcnt(8)
	s_setprio 1
	s_barrier
	v_mfma_f32_16x16x32_bf16 v[128:131], v[144:147], v[162:165], 0
	v_mfma_f32_16x16x32_bf16 v[124:127], v[154:157], v[162:165], 0
	v_mfma_f32_16x16x32_bf16 v[112:115], v[144:147], v[170:173], 0
	v_mfma_f32_16x16x32_bf16 v[108:111], v[154:157], v[170:173], 0
	v_mfma_f32_16x16x32_bf16 v[96:99], v[144:147], v[178:181], 0
	v_mfma_f32_16x16x32_bf16 v[92:95], v[154:157], v[178:181], 0
	v_mfma_f32_16x16x32_bf16 v[80:83], v[144:147], v[186:189], 0
	v_mfma_f32_16x16x32_bf16 v[76:79], v[154:157], v[186:189], 0
	v_mfma_f32_16x16x32_bf16 v[128:131], v[150:153], v[166:169], v[128:131]
	v_mfma_f32_16x16x32_bf16 v[124:127], v[158:161], v[166:169], v[124:127]
	v_mfma_f32_16x16x32_bf16 v[112:115], v[150:153], v[174:177], v[112:115]
	v_mfma_f32_16x16x32_bf16 v[108:111], v[158:161], v[174:177], v[108:111]
	v_mfma_f32_16x16x32_bf16 v[96:99], v[150:153], v[182:185], v[96:99]
	v_mfma_f32_16x16x32_bf16 v[92:95], v[158:161], v[182:185], v[92:95]
	v_mfma_f32_16x16x32_bf16 v[80:83], v[150:153], v[190:193], v[80:83]
	v_mfma_f32_16x16x32_bf16 v[76:79], v[158:161], v[190:193], v[76:79]
	v_mfma_f32_16x16x32_bf16 v[120:123], v[194:197], v[162:165], 0
	v_mfma_f32_16x16x32_bf16 v[116:119], v[202:205], v[162:165], 0
	v_mfma_f32_16x16x32_bf16 v[104:107], v[194:197], v[170:173], 0
	v_mfma_f32_16x16x32_bf16 v[100:103], v[202:205], v[170:173], 0
	v_mfma_f32_16x16x32_bf16 v[88:91], v[194:197], v[178:181], 0
	v_mfma_f32_16x16x32_bf16 v[84:87], v[202:205], v[178:181], 0
	v_mfma_f32_16x16x32_bf16 v[72:75], v[194:197], v[186:189], 0
	v_mfma_f32_16x16x32_bf16 v[68:71], v[202:205], v[186:189], 0
	v_mfma_f32_16x16x32_bf16 v[120:123], v[198:201], v[166:169], v[120:123]
	v_mfma_f32_16x16x32_bf16 v[116:119], v[206:209], v[166:169], v[116:119]
	v_mfma_f32_16x16x32_bf16 v[104:107], v[198:201], v[174:177], v[104:107]
	v_mfma_f32_16x16x32_bf16 v[100:103], v[206:209], v[174:177], v[100:103]
	v_mfma_f32_16x16x32_bf16 v[88:91], v[198:201], v[182:185], v[88:91]
	v_mfma_f32_16x16x32_bf16 v[84:87], v[206:209], v[182:185], v[84:87]
	v_mfma_f32_16x16x32_bf16 v[72:75], v[198:201], v[190:193], v[72:75]
	v_mfma_f32_16x16x32_bf16 v[68:71], v[206:209], v[190:193], v[68:71]
	s_barrier
	s_setprio 0
	ds_read_b128 v[162:165], v149 offset:16384
	ds_read_b128 v[166:169], v149 offset:17408
	ds_read_b128 v[170:173], v149 offset:18432
	ds_read_b128 v[174:177], v149 offset:19456
	ds_read_b128 v[178:181], v149 offset:20480
	ds_read_b128 v[182:185], v149 offset:21504
	ds_read_b128 v[186:189], v149 offset:22528
	ds_read_b128 v[190:193], v149 offset:23552
	s_add_i32 s56, s56, s30
	v_lshl_add_u64 v[210:211], s[20:21], 0, v[136:137]
	s_mov_b32 m0, s56
	s_nop 0
	global_load_lds_dwordx4 v[210:211], off
	v_lshl_add_u64 v[212:213], s[20:21], 0, v[132:133]
	s_add_i32 m0, s56, 0x2000
	s_nop 0
	global_load_lds_dwordx4 v[212:213], off
	s_mov_b32 m0, s31
	v_lshl_add_u64 v[216:217], s[24:25], 0, v[138:139]
	global_load_lds_dwordx4 v[216:217], off
	v_lshl_add_u64 v[218:219], s[24:25], 0, v[134:135]
	s_mov_b32 m0, s35
	s_nop 0
	global_load_lds_dwordx4 v[218:219], off
	s_add_u32 s56, s20, 0x80000
	s_addc_u32 s57, s21, 0
	s_add_i32 s58, s58, s30
	s_mov_b32 m0, s58
	s_nop 0
	global_load_lds_dwordx4 v136, s[56:57]
	s_add_i32 m0, s58, 0x2000
	s_nop 0
	global_load_lds_dwordx4 v132, s[56:57]
	s_waitcnt lgkmcnt(0)
	s_waitcnt vmcnt(8)
	s_setprio 1
	s_barrier
; #define PG8_STAGE(bufoff, gbase, voff) do { _Pragma("unroll") for (int _i = 0; _i < 2; ++_i) \
;         __builtin_amdgcn_global_load_lds((const unsigned*)((const char*)(gbase) + (voff)[_i]), (LAS unsigned*)(lds + (bufoff) + ldsw + _i * 8192), 16, 0, 0); } while (0)
; #define PG8_LDA(dst, b, h) do { _Pragma("unroll") for (int m = 0; m < 4; ++m) _Pragma("unroll") for (int k = 0; k < 2; ++k) dst[m][k] = *(const LAS bf16x8*)(lds + PG8_SA(b, h) + aoff + m * 2048 + k * 1024); } while (0)
; #define PG8_LDB(dst, b, h) do { _Pragma("unroll") for (int n = 0; n < 2; ++n) _Pragma("unroll") for (int k = 0; k < 2; ++k) dst[n][k] = *(const LAS bf16x8*)(lds + PG8_SB(b, h) + boff + n * 2048 + k * 1024); } while (0)
; #define PG8_MMA(ai, bj, At, Bt) do { __builtin_amdgcn_s_setprio(1); _Pragma("unroll") for (int m = 0; m < 4; ++m) _Pragma("unroll") for (int n = 0; n < 2; ++n) _Pragma("unroll") for (int k = 0; k < 2; ++k) \
;         acc[ai][bj][m][n] = __builtin_amdgcn_mfma_f32_16x16x32_bf16(Bt[n][k], At[m][k], acc[ai][bj][m][n], 0, 0, 0); __builtin_amdgcn_s_setprio(0); } while (0)
; #define PG8_WAIT_V(n) asm volatile("s_waitcnt vmcnt(" #n ")" ::: "memory")
; #define PG8_WAIT_L(n) asm volatile("s_waitcnt lgkmcnt(" #n ")" ::: "memory")
; #define PG8_BAR __builtin_amdgcn_s_barrier()
; #define PG8_SCHED __builtin_amdgcn_sched_barrier(0)
; template <class Epi, class Sched>
; __device__ __forceinline__ void gemm_phase(LAS unsigned char* lds, const Gemm g, const Sched& S, const Epi& E) {
;     ...
;             PG8_WAIT_V(6); PG8_BAR; PG8_MMA(1, 1, At, B1); PG8_BAR;
;             PG8_LDB(B0, 1, 0); PG8_SCHED; PG8_LDA(At, 1, 0); PG8_STAGE(PG8_SA(0, 1), a2 + hstepA, voffA);
;             PG8_WAIT_L(8); PG8_BAR; PG8_WAIT_L(0); PG8_MMA(0, 0, At, B0); PG8_BAR; PG8_SCHED;
;             PG8_LDB(B1, 1, 1); PG8_STAGE(PG8_SB(1, 0), b3, voffB);
;             PG8_BAR; PG8_WAIT_L(0); PG8_MMA(0, 1, At, B1); PG8_BAR;
;             PG8_LDA(At, 1, 1); PG8_STAGE(PG8_SA(1, 0), a3, voffA);
;             PG8_BAR; PG8_WAIT_L(0); PG8_MMA(1, 0, At, B0); PG8_BAR; PG8_SCHED;
	v_mfma_f32_16x16x32_bf16 v[64:67], v[144:147], v[162:165], 0
	v_mfma_f32_16x16x32_bf16 v[60:63], v[154:157], v[162:165], 0
	v_mfma_f32_16x16x32_bf16 v[48:51], v[144:147], v[170:173], 0
	v_mfma_f32_16x16x32_bf16 v[44:47], v[154:157], v[170:173], 0
	v_mfma_f32_16x16x32_bf16 v[32:35], v[144:147], v[178:181], 0
	v_mfma_f32_16x16x32_bf16 v[28:31], v[154:157], v[178:181], 0
	v_mfma_f32_16x16x32_bf16 v[16:19], v[144:147], v[186:189], 0
	v_mfma_f32_16x16x32_bf16 v[12:15], v[154:157], v[186:189], 0
	v_mfma_f32_16x16x32_bf16 v[64:67], v[150:153], v[166:169], v[64:67]
	v_mfma_f32_16x16x32_bf16 v[60:63], v[158:161], v[166:169], v[60:63]
	v_mfma_f32_16x16x32_bf16 v[48:51], v[150:153], v[174:177], v[48:51]
	v_mfma_f32_16x16x32_bf16 v[44:47], v[158:161], v[174:177], v[44:47]
	v_mfma_f32_16x16x32_bf16 v[32:35], v[150:153], v[182:185], v[32:35]
	v_mfma_f32_16x16x32_bf16 v[28:31], v[158:161], v[182:185], v[28:31]
	v_mfma_f32_16x16x32_bf16 v[16:19], v[150:153], v[190:193], v[16:19]
	v_mfma_f32_16x16x32_bf16 v[12:15], v[158:161], v[190:193], v[12:15]
	v_mfma_f32_16x16x32_bf16 v[56:59], v[194:197], v[162:165], 0
	v_mfma_f32_16x16x32_bf16 v[52:55], v[202:205], v[162:165], 0
	v_mfma_f32_16x16x32_bf16 v[40:43], v[194:197], v[170:173], 0
	v_mfma_f32_16x16x32_bf16 v[36:39], v[202:205], v[170:173], 0
	v_mfma_f32_16x16x32_bf16 v[24:27], v[194:197], v[178:181], 0
	v_mfma_f32_16x16x32_bf16 v[20:23], v[202:205], v[178:181], 0
	v_mfma_f32_16x16x32_bf16 v[8:11], v[194:197], v[186:189], 0
	v_mfma_f32_16x16x32_bf16 v[4:7], v[202:205], v[186:189], 0
	v_mfma_f32_16x16x32_bf16 v[56:59], v[198:201], v[166:169], v[56:59]
	v_mfma_f32_16x16x32_bf16 v[52:55], v[206:209], v[166:169], v[52:55]
	v_mfma_f32_16x16x32_bf16 v[40:43], v[198:201], v[174:177], v[40:43]
	v_mfma_f32_16x16x32_bf16 v[36:39], v[206:209], v[174:177], v[36:39]
	v_mfma_f32_16x16x32_bf16 v[24:27], v[198:201], v[182:185], v[24:27]
	v_mfma_f32_16x16x32_bf16 v[20:23], v[206:209], v[182:185], v[20:23]
	v_mfma_f32_16x16x32_bf16 v[8:11], v[198:201], v[190:193], v[8:11]
	v_mfma_f32_16x16x32_bf16 v[4:7], v[206:209], v[190:193], v[4:7]
	s_barrier
	s_setprio 0
	s_add_i32 s56, 0, 0x18000
	v_add_u32_e32 v2, s56, v1
	ds_read_b128 v[144:147], v2
	ds_read_b128 v[150:153], v2 offset:1024
	ds_read_b128 v[154:157], v2 offset:2048
	ds_read_b128 v[158:161], v2 offset:3072
	s_add_u32 s24, s24, 0x80000
	s_addc_u32 s25, s25, 0
	ds_read_b128 v[162:165], v149 offset:32768
	ds_read_b128 v[166:169], v149 offset:33792
	ds_read_b128 v[170:173], v149 offset:34816
	ds_read_b128 v[174:177], v149 offset:35840
	ds_read_b128 v[178:181], v149 offset:36864
	ds_read_b128 v[182:185], v149 offset:37888
	ds_read_b128 v[186:189], v149 offset:38912
	ds_read_b128 v[190:193], v149 offset:39936
	s_mov_b32 m0, s36
	s_nop 0
	global_load_lds_dwordx4 v138, s[24:25]
	s_mov_b32 m0, s37
	s_nop 0
	global_load_lds_dwordx4 v134, s[24:25]
	s_add_i32 s24, 0, 0x1c000
	v_add_u32_e32 v2, s24, v1
	ds_read_b128 v[194:197], v2
	ds_read_b128 v[198:201], v2 offset:1024
	ds_read_b128 v[202:205], v2 offset:2048
	ds_read_b128 v[206:209], v2 offset:3072
	s_waitcnt lgkmcnt(0)
	s_waitcnt vmcnt(8)
	s_setprio 1
	s_barrier
	v_mfma_f32_16x16x32_bf16 v[128:131], v[144:147], v[162:165], v[128:131]
	v_mfma_f32_16x16x32_bf16 v[124:127], v[154:157], v[162:165], v[124:127]
	v_mfma_f32_16x16x32_bf16 v[112:115], v[144:147], v[170:173], v[112:115]
	v_mfma_f32_16x16x32_bf16 v[108:111], v[154:157], v[170:173], v[108:111]
	v_mfma_f32_16x16x32_bf16 v[96:99], v[144:147], v[178:181], v[96:99]
	v_mfma_f32_16x16x32_bf16 v[92:95], v[154:157], v[178:181], v[92:95]
	v_mfma_f32_16x16x32_bf16 v[80:83], v[144:147], v[186:189], v[80:83]
	v_mfma_f32_16x16x32_bf16 v[76:79], v[154:157], v[186:189], v[76:79]
	v_mfma_f32_16x16x32_bf16 v[128:131], v[150:153], v[166:169], v[128:131]
	v_mfma_f32_16x16x32_bf16 v[124:127], v[158:161], v[166:169], v[124:127]
	v_mfma_f32_16x16x32_bf16 v[112:115], v[150:153], v[174:177], v[112:115]
	v_mfma_f32_16x16x32_bf16 v[108:111], v[158:161], v[174:177], v[108:111]
	v_mfma_f32_16x16x32_bf16 v[96:99], v[150:153], v[182:185], v[96:99]
	v_mfma_f32_16x16x32_bf16 v[92:95], v[158:161], v[182:185], v[92:95]
	v_mfma_f32_16x16x32_bf16 v[80:83], v[150:153], v[190:193], v[80:83]
	v_mfma_f32_16x16x32_bf16 v[76:79], v[158:161], v[190:193], v[76:79]
	v_mfma_f32_16x16x32_bf16 v[120:123], v[194:197], v[162:165], v[120:123]
	v_mfma_f32_16x16x32_bf16 v[116:119], v[202:205], v[162:165], v[116:119]
	v_mfma_f32_16x16x32_bf16 v[104:107], v[194:197], v[170:173], v[104:107]
	v_mfma_f32_16x16x32_bf16 v[100:103], v[202:205], v[170:173], v[100:103]
	v_mfma_f32_16x16x32_bf16 v[88:91], v[194:197], v[178:181], v[88:91]
	v_mfma_f32_16x16x32_bf16 v[84:87], v[202:205], v[178:181], v[84:87]
	v_mfma_f32_16x16x32_bf16 v[72:75], v[194:197], v[186:189], v[72:75]
	v_mfma_f32_16x16x32_bf16 v[68:71], v[202:205], v[186:189], v[68:71]
	v_mfma_f32_16x16x32_bf16 v[120:123], v[198:201], v[166:169], v[120:123]
	v_mfma_f32_16x16x32_bf16 v[116:119], v[206:209], v[166:169], v[116:119]
	v_mfma_f32_16x16x32_bf16 v[104:107], v[198:201], v[174:177], v[104:107]
	v_mfma_f32_16x16x32_bf16 v[100:103], v[206:209], v[174:177], v[100:103]
	v_mfma_f32_16x16x32_bf16 v[88:91], v[198:201], v[182:185], v[88:91]
	v_mfma_f32_16x16x32_bf16 v[84:87], v[206:209], v[182:185], v[84:87]
	v_mfma_f32_16x16x32_bf16 v[72:75], v[198:201], v[190:193], v[72:75]
	v_mfma_f32_16x16x32_bf16 v[68:71], v[206:209], v[190:193], v[68:71]
	s_barrier
; #define PG8_STAGE(bufoff, gbase, voff) do { _Pragma("unroll") for (int _i = 0; _i < 2; ++_i) \
;         __builtin_amdgcn_global_load_lds((const unsigned*)((const char*)(gbase) + (voff)[_i]), (LAS unsigned*)(lds + (bufoff) + ldsw + _i * 8192), 16, 0, 0); } while (0)
; #define PG8_LDA(dst, b, h) do { _Pragma("unroll") for (int m = 0; m < 4; ++m) _Pragma("unroll") for (int k = 0; k < 2; ++k) dst[m][k] = *(const LAS bf16x8*)(lds + PG8_SA(b, h) + aoff + m * 2048 + k * 1024); } while (0)
; #define PG8_LDB(dst, b, h) do { _Pragma("unroll") for (int n = 0; n < 2; ++n) _Pragma("unroll") for (int k = 0; k < 2; ++k) dst[n][k] = *(const LAS bf16x8*)(lds + PG8_SB(b, h) + boff + n * 2048 + k * 1024); } while (0)
; #define PG8_MMA(ai, bj, At, Bt) do { __builtin_amdgcn_s_setprio(1); _Pragma("unroll") for (int m = 0; m < 4; ++m) _Pragma("unroll") for (int n = 0; n < 2; ++n) _Pragma("unroll") for (int k = 0; k < 2; ++k) \
;         acc[ai][bj][m][n] = __builtin_amdgcn_mfma_f32_16x16x32_bf16(Bt[n][k], At[m][k], acc[ai][bj][m][n], 0, 0, 0); __builtin_amdgcn_s_setprio(0); } while (0)
; #define PG8_WAIT_V(n) asm volatile("s_waitcnt vmcnt(" #n ")" ::: "memory")
; #define PG8_WAIT_L(n) asm volatile("s_waitcnt lgkmcnt(" #n ")" ::: "memory")
; #define PG8_BAR __builtin_amdgcn_s_barrier()
; #define PG8_SCHED __builtin_amdgcn_sched_barrier(0)
; template <class Epi, class Sched>
; __device__ __forceinline__ void gemm_phase(LAS unsigned char* lds, const Gemm g, const Sched& S, const Epi& E) {
;     ...
;         for (int t = 0; t < nt; t += 2) {
;             const bool last = (t == nt - 2);
;             const char* a1 = cA + (size_t)(t + 1) * kstep;
;             const char* a2 = last ? nA : cA + (size_t)(t + 2) * kstep; const char* b2 = last ? nB : cB + (size_t)(t + 2) * kstep;
;             const char* a3 = a2 + kstep; const char* b3 = b2 + kstep;
;             if (last && has_next) S.a_ready(nxt);
;             PG8_LDB(B0, 0, 0); PG8_SCHED; PG8_LDA(At, 0, 0); PG8_STAGE(PG8_SA(1, 1), a1 + hstepA, voffA);
;             PG8_WAIT_L(8); PG8_BAR; PG8_WAIT_L(0); PG8_MMA(0, 0, At, B0); PG8_BAR; PG8_SCHED;
;     ...
;             PG8_LDA(At, 1, 1); PG8_STAGE(PG8_SA(1, 0), a3, voffA);
;             PG8_BAR; PG8_WAIT_L(0); PG8_MMA(1, 0, At, B0); PG8_BAR; PG8_SCHED;
;             PG8_STAGE(PG8_SB(1, 1), b3 + hstepB, voffB);
;             PG8_WAIT_V(6); PG8_BAR; PG8_MMA(1, 1, At, B1); PG8_BAR;
	s_setprio 0
	ds_read_b128 v[162:165], v149 offset:49152
	ds_read_b128 v[166:169], v149 offset:50176
	ds_read_b128 v[170:173], v149 offset:51200
	ds_read_b128 v[174:177], v149 offset:52224
	ds_read_b128 v[178:181], v149 offset:53248
	ds_read_b128 v[182:185], v149 offset:54272
	ds_read_b128 v[186:189], v149 offset:55296
	ds_read_b128 v[190:193], v149 offset:56320
	s_add_i32 s25, s56, s30
	v_lshl_add_u64 v[210:211], v[210:211], 0, s[8:9]
	s_mov_b32 m0, s25
	s_nop 0
	global_load_lds_dwordx4 v[210:211], off
	v_lshl_add_u64 v[210:211], v[212:213], 0, s[8:9]
	s_add_i32 m0, s25, 0x2000
	s_nop 0
	global_load_lds_dwordx4 v[210:211], off
	s_mov_b32 m0, s40
	v_lshl_add_u64 v[210:211], v[216:217], 0, s[8:9]
	global_load_lds_dwordx4 v[210:211], off
	v_lshl_add_u64 v[210:211], v[218:219], 0, s[8:9]
	s_mov_b32 m0, s41
	s_nop 0
	global_load_lds_dwordx4 v[210:211], off
	s_add_u32 s20, s20, 0x80080
	s_addc_u32 s21, s21, 0
	s_add_i32 s24, s24, s30
	s_mov_b32 m0, s24
	s_nop 0
	global_load_lds_dwordx4 v136, s[20:21]
	s_add_i32 m0, s24, 0x2000
	s_nop 0
	global_load_lds_dwordx4 v132, s[20:21]
	s_add_i32 s55, s55, 2
	s_add_u32 s6, s6, 0x100
	s_addc_u32 s7, s7, 0
	s_add_u32 s53, s53, 0x100
	s_addc_u32 s54, s54, 0
	s_cmp_gt_u32 s55, 29
	s_waitcnt lgkmcnt(0)
	s_waitcnt vmcnt(8)
	s_setprio 1
	s_barrier
	v_mfma_f32_16x16x32_bf16 v[64:67], v[144:147], v[162:165], v[64:67]
	v_mfma_f32_16x16x32_bf16 v[60:63], v[154:157], v[162:165], v[60:63]
	v_mfma_f32_16x16x32_bf16 v[48:51], v[144:147], v[170:173], v[48:51]
	v_mfma_f32_16x16x32_bf16 v[44:47], v[154:157], v[170:173], v[44:47]
	v_mfma_f32_16x16x32_bf16 v[32:35], v[144:147], v[178:181], v[32:35]
	v_mfma_f32_16x16x32_bf16 v[28:31], v[154:157], v[178:181], v[28:31]
	v_mfma_f32_16x16x32_bf16 v[16:19], v[144:147], v[186:189], v[16:19]
	v_mfma_f32_16x16x32_bf16 v[12:15], v[154:157], v[186:189], v[12:15]
	v_mfma_f32_16x16x32_bf16 v[64:67], v[150:153], v[166:169], v[64:67]
	v_mfma_f32_16x16x32_bf16 v[60:63], v[158:161], v[166:169], v[60:63]
	v_mfma_f32_16x16x32_bf16 v[48:51], v[150:153], v[174:177], v[48:51]
	v_mfma_f32_16x16x32_bf16 v[44:47], v[158:161], v[174:177], v[44:47]
	v_mfma_f32_16x16x32_bf16 v[32:35], v[150:153], v[182:185], v[32:35]
	v_mfma_f32_16x16x32_bf16 v[28:31], v[158:161], v[182:185], v[28:31]
	v_mfma_f32_16x16x32_bf16 v[16:19], v[150:153], v[190:193], v[16:19]
	v_mfma_f32_16x16x32_bf16 v[12:15], v[158:161], v[190:193], v[12:15]
	v_mfma_f32_16x16x32_bf16 v[56:59], v[194:197], v[162:165], v[56:59]
	v_mfma_f32_16x16x32_bf16 v[52:55], v[202:205], v[162:165], v[52:55]
	v_mfma_f32_16x16x32_bf16 v[40:43], v[194:197], v[170:173], v[40:43]
	v_mfma_f32_16x16x32_bf16 v[36:39], v[202:205], v[170:173], v[36:39]
	v_mfma_f32_16x16x32_bf16 v[24:27], v[194:197], v[178:181], v[24:27]
	v_mfma_f32_16x16x32_bf16 v[20:23], v[202:205], v[178:181], v[20:23]
	v_mfma_f32_16x16x32_bf16 v[8:11], v[194:197], v[186:189], v[8:11]
	v_mfma_f32_16x16x32_bf16 v[4:7], v[202:205], v[186:189], v[4:7]
	v_mfma_f32_16x16x32_bf16 v[56:59], v[198:201], v[166:169], v[56:59]
	v_mfma_f32_16x16x32_bf16 v[52:55], v[206:209], v[166:169], v[52:55]
	v_mfma_f32_16x16x32_bf16 v[40:43], v[198:201], v[174:177], v[40:43]
	v_mfma_f32_16x16x32_bf16 v[36:39], v[206:209], v[174:177], v[36:39]
	v_mfma_f32_16x16x32_bf16 v[24:27], v[198:201], v[182:185], v[24:27]
	v_mfma_f32_16x16x32_bf16 v[20:23], v[206:209], v[182:185], v[20:23]
	v_mfma_f32_16x16x32_bf16 v[8:11], v[198:201], v[190:193], v[8:11]
	v_mfma_f32_16x16x32_bf16 v[4:7], v[206:209], v[190:193], v[4:7]
	s_barrier
	s_setprio 0
.LBB0_352:
	s_setprio 0
	s_add_u32 s20, s6, 0xfff80080
	s_addc_u32 s21, s7, -1
	s_add_i32 s56, 0, 0x10000
	v_add_u32_e32 v2, s56, v1
	ds_read_b128 v[144:147], v2
	ds_read_b128 v[150:153], v2 offset:1024
	ds_read_b128 v[154:157], v2 offset:2048
	ds_read_b128 v[158:161], v2 offset:3072
	s_cmp_eq_u32 s55, 28
	s_cselect_b32 s25, s15, s21
	s_cselect_b32 s24, s51, s20
	s_cselect_b32 s21, s1, s54
	s_cselect_b32 s20, s52, s53
	ds_read_b128 v[162:165], v149
	ds_read_b128 v[166:169], v149 offset:1024
	ds_read_b128 v[170:173], v149 offset:2048
	ds_read_b128 v[174:177], v149 offset:3072
	ds_read_b128 v[178:181], v149 offset:4096
	ds_read_b128 v[182:185], v149 offset:5120
	ds_read_b128 v[186:189], v149 offset:6144
	ds_read_b128 v[190:193], v149 offset:7168
	s_add_i32 s58, 0, 0x14000
	v_add_u32_e32 v2, s58, v1
	ds_read_b128 v[194:197], v2
	ds_read_b128 v[198:201], v2 offset:1024
	ds_read_b128 v[202:205], v2 offset:2048
	ds_read_b128 v[206:209], v2 offset:3072
	s_add_i32 m0, s31, 0xc000
	s_nop 0
	global_load_lds_dwordx4 v140, s[6:7]
	s_add_i32 m0, s31, 0xe000
	s_nop 0
	global_load_lds_dwordx4 v142, s[6:7]
	s_waitcnt lgkmcnt(0)
	s_waitcnt vmcnt(8)
	s_setprio 1
	s_barrier
; #define PG8_STAGE(bufoff, gbase, voff) do { _Pragma("unroll") for (int _i = 0; _i < 2; ++_i) \
;         __builtin_amdgcn_global_load_lds((const unsigned*)((const char*)(gbase) + (voff)[_i]), (LAS unsigned*)(lds + (bufoff) + ldsw + _i * 8192), 16, 0, 0); } while (0)
; #define PG8_LDA(dst, b, h) do { _Pragma("unroll") for (int m = 0; m < 4; ++m) _Pragma("unroll") for (int k = 0; k < 2; ++k) dst[m][k] = *(const LAS bf16x8*)(lds + PG8_SA(b, h) + aoff + m * 2048 + k * 1024); } while (0)
; #define PG8_LDB(dst, b, h) do { _Pragma("unroll") for (int n = 0; n < 2; ++n) _Pragma("unroll") for (int k = 0; k < 2; ++k) dst[n][k] = *(const LAS bf16x8*)(lds + PG8_SB(b, h) + boff + n * 2048 + k * 1024); } while (0)
; #define PG8_MMA(ai, bj, At, Bt) do { __builtin_amdgcn_s_setprio(1); _Pragma("unroll") for (int m = 0; m < 4; ++m) _Pragma("unroll") for (int n = 0; n < 2; ++n) _Pragma("unroll") for (int k = 0; k < 2; ++k) \
;         acc[ai][bj][m][n] = __builtin_amdgcn_mfma_f32_16x16x32_bf16(Bt[n][k], At[m][k], acc[ai][bj][m][n], 0, 0, 0); __builtin_amdgcn_s_setprio(0); } while (0)
; #define PG8_WAIT_V(n) asm volatile("s_waitcnt vmcnt(" #n ")" ::: "memory")
; #define PG8_WAIT_L(n) asm volatile("s_waitcnt lgkmcnt(" #n ")" ::: "memory")
; #define PG8_BAR __builtin_amdgcn_s_barrier()
; #define PG8_SCHED __builtin_amdgcn_sched_barrier(0)
; template <class Epi, class Sched>
; __device__ __forceinline__ void gemm_phase(LAS unsigned char* lds, const Gemm g, const Sched& S, const Epi& E) {
;     ...
;             PG8_WAIT_L(8); PG8_BAR; PG8_WAIT_L(0); PG8_MMA(0, 0, At, B0); PG8_BAR; PG8_SCHED;
;             PG8_LDB(B1, 0, 1); PG8_STAGE(PG8_SB(0, 0), b2, voffB);
;             PG8_BAR; PG8_WAIT_L(0); PG8_MMA(0, 1, At, B1); PG8_BAR;
;             PG8_LDA(At, 0, 1); PG8_STAGE(PG8_SA(0, 0), a2, voffA);
;             PG8_BAR; PG8_WAIT_L(0); PG8_MMA(1, 0, At, B0); PG8_BAR; PG8_SCHED;
;             PG8_STAGE(PG8_SB(0, 1), b2 + hstepB, voffB);
;             PG8_WAIT_V(6); PG8_BAR; PG8_MMA(1, 1, At, B1); PG8_BAR;
;             PG8_LDB(B0, 1, 0); PG8_SCHED; PG8_LDA(At, 1, 0); PG8_STAGE(PG8_SA(0, 1), a2 + hstepA, voffA);
;             PG8_WAIT_L(8); PG8_BAR; PG8_WAIT_L(0); PG8_MMA(0, 0, At, B0); PG8_BAR; PG8_SCHED;
	v_mfma_f32_16x16x32_bf16 v[128:131], v[144:147], v[162:165], v[128:131]
	v_mfma_f32_16x16x32_bf16 v[124:127], v[154:157], v[162:165], v[124:127]
	v_mfma_f32_16x16x32_bf16 v[112:115], v[144:147], v[170:173], v[112:115]
	v_mfma_f32_16x16x32_bf16 v[108:111], v[154:157], v[170:173], v[108:111]
	v_mfma_f32_16x16x32_bf16 v[96:99], v[144:147], v[178:181], v[96:99]
	v_mfma_f32_16x16x32_bf16 v[92:95], v[154:157], v[178:181], v[92:95]
	v_mfma_f32_16x16x32_bf16 v[80:83], v[144:147], v[186:189], v[80:83]
	v_mfma_f32_16x16x32_bf16 v[76:79], v[154:157], v[186:189], v[76:79]
	v_mfma_f32_16x16x32_bf16 v[128:131], v[150:153], v[166:169], v[128:131]
	v_mfma_f32_16x16x32_bf16 v[124:127], v[158:161], v[166:169], v[124:127]
	v_mfma_f32_16x16x32_bf16 v[112:115], v[150:153], v[174:177], v[112:115]
	v_mfma_f32_16x16x32_bf16 v[108:111], v[158:161], v[174:177], v[108:111]
	v_mfma_f32_16x16x32_bf16 v[96:99], v[150:153], v[182:185], v[96:99]
	v_mfma_f32_16x16x32_bf16 v[92:95], v[158:161], v[182:185], v[92:95]
	v_mfma_f32_16x16x32_bf16 v[80:83], v[150:153], v[190:193], v[80:83]
	v_mfma_f32_16x16x32_bf16 v[76:79], v[158:161], v[190:193], v[76:79]
	v_mfma_f32_16x16x32_bf16 v[120:123], v[194:197], v[162:165], v[120:123]
	v_mfma_f32_16x16x32_bf16 v[116:119], v[202:205], v[162:165], v[116:119]
	v_mfma_f32_16x16x32_bf16 v[104:107], v[194:197], v[170:173], v[104:107]
	v_mfma_f32_16x16x32_bf16 v[100:103], v[202:205], v[170:173], v[100:103]
	v_mfma_f32_16x16x32_bf16 v[88:91], v[194:197], v[178:181], v[88:91]
	v_mfma_f32_16x16x32_bf16 v[84:87], v[202:205], v[178:181], v[84:87]
	v_mfma_f32_16x16x32_bf16 v[72:75], v[194:197], v[186:189], v[72:75]
	v_mfma_f32_16x16x32_bf16 v[68:71], v[202:205], v[186:189], v[68:71]
	v_mfma_f32_16x16x32_bf16 v[120:123], v[198:201], v[166:169], v[120:123]
	v_mfma_f32_16x16x32_bf16 v[116:119], v[206:209], v[166:169], v[116:119]
	v_mfma_f32_16x16x32_bf16 v[104:107], v[198:201], v[174:177], v[104:107]
	v_mfma_f32_16x16x32_bf16 v[100:103], v[206:209], v[174:177], v[100:103]
	v_mfma_f32_16x16x32_bf16 v[88:91], v[198:201], v[182:185], v[88:91]
	v_mfma_f32_16x16x32_bf16 v[84:87], v[206:209], v[182:185], v[84:87]
	v_mfma_f32_16x16x32_bf16 v[72:75], v[198:201], v[190:193], v[72:75]
	v_mfma_f32_16x16x32_bf16 v[68:71], v[206:209], v[190:193], v[68:71]
	s_barrier
	s_setprio 0
	ds_read_b128 v[162:165], v149 offset:16384
	ds_read_b128 v[166:169], v149 offset:17408
	ds_read_b128 v[170:173], v149 offset:18432
	ds_read_b128 v[174:177], v149 offset:19456
	ds_read_b128 v[178:181], v149 offset:20480
	ds_read_b128 v[182:185], v149 offset:21504
	ds_read_b128 v[186:189], v149 offset:22528
	ds_read_b128 v[190:193], v149 offset:23552
	s_add_i32 s56, s56, s30
	v_lshl_add_u64 v[210:211], s[20:21], 0, v[136:137]
	s_mov_b32 m0, s56
	s_nop 0
	global_load_lds_dwordx4 v[210:211], off
	v_lshl_add_u64 v[212:213], s[20:21], 0, v[132:133]
	s_add_i32 m0, s56, 0x2000
	s_nop 0
	global_load_lds_dwordx4 v[212:213], off
	s_mov_b32 m0, s31
	v_lshl_add_u64 v[216:217], s[24:25], 0, v[138:139]
	global_load_lds_dwordx4 v[216:217], off
	v_lshl_add_u64 v[218:219], s[24:25], 0, v[134:135]
	s_mov_b32 m0, s35
	s_nop 0
	global_load_lds_dwordx4 v[218:219], off
	s_add_u32 s56, s20, 0x80000
	s_addc_u32 s57, s21, 0
	s_add_i32 s58, s58, s30
	s_mov_b32 m0, s58
	s_nop 0
	global_load_lds_dwordx4 v136, s[56:57]
	s_add_i32 m0, s58, 0x2000
	s_nop 0
	global_load_lds_dwordx4 v132, s[56:57]
	s_waitcnt lgkmcnt(0)
	s_waitcnt vmcnt(8)
	s_setprio 1
	s_barrier
	v_mfma_f32_16x16x32_bf16 v[64:67], v[144:147], v[162:165], v[64:67]
	v_mfma_f32_16x16x32_bf16 v[60:63], v[154:157], v[162:165], v[60:63]
	v_mfma_f32_16x16x32_bf16 v[48:51], v[144:147], v[170:173], v[48:51]
	v_mfma_f32_16x16x32_bf16 v[44:47], v[154:157], v[170:173], v[44:47]
	v_mfma_f32_16x16x32_bf16 v[32:35], v[144:147], v[178:181], v[32:35]
	v_mfma_f32_16x16x32_bf16 v[28:31], v[154:157], v[178:181], v[28:31]
	v_mfma_f32_16x16x32_bf16 v[16:19], v[144:147], v[186:189], v[16:19]
	v_mfma_f32_16x16x32_bf16 v[12:15], v[154:157], v[186:189], v[12:15]
	v_mfma_f32_16x16x32_bf16 v[64:67], v[150:153], v[166:169], v[64:67]
	v_mfma_f32_16x16x32_bf16 v[60:63], v[158:161], v[166:169], v[60:63]
	v_mfma_f32_16x16x32_bf16 v[48:51], v[150:153], v[174:177], v[48:51]
	v_mfma_f32_16x16x32_bf16 v[44:47], v[158:161], v[174:177], v[44:47]
	v_mfma_f32_16x16x32_bf16 v[32:35], v[150:153], v[182:185], v[32:35]
	v_mfma_f32_16x16x32_bf16 v[28:31], v[158:161], v[182:185], v[28:31]
	v_mfma_f32_16x16x32_bf16 v[16:19], v[150:153], v[190:193], v[16:19]
	v_mfma_f32_16x16x32_bf16 v[12:15], v[158:161], v[190:193], v[12:15]
	v_mfma_f32_16x16x32_bf16 v[56:59], v[194:197], v[162:165], v[56:59]
	v_mfma_f32_16x16x32_bf16 v[52:55], v[202:205], v[162:165], v[52:55]
	v_mfma_f32_16x16x32_bf16 v[40:43], v[194:197], v[170:173], v[40:43]
	v_mfma_f32_16x16x32_bf16 v[36:39], v[202:205], v[170:173], v[36:39]
	v_mfma_f32_16x16x32_bf16 v[24:27], v[194:197], v[178:181], v[24:27]
	v_mfma_f32_16x16x32_bf16 v[20:23], v[202:205], v[178:181], v[20:23]
	v_mfma_f32_16x16x32_bf16 v[8:11], v[194:197], v[186:189], v[8:11]
	v_mfma_f32_16x16x32_bf16 v[4:7], v[202:205], v[186:189], v[4:7]
	v_mfma_f32_16x16x32_bf16 v[56:59], v[198:201], v[166:169], v[56:59]
	v_mfma_f32_16x16x32_bf16 v[52:55], v[206:209], v[166:169], v[52:55]
	v_mfma_f32_16x16x32_bf16 v[40:43], v[198:201], v[174:177], v[40:43]
	v_mfma_f32_16x16x32_bf16 v[36:39], v[206:209], v[174:177], v[36:39]
	v_mfma_f32_16x16x32_bf16 v[24:27], v[198:201], v[182:185], v[24:27]
	v_mfma_f32_16x16x32_bf16 v[20:23], v[206:209], v[182:185], v[20:23]
	v_mfma_f32_16x16x32_bf16 v[8:11], v[198:201], v[190:193], v[8:11]
	v_mfma_f32_16x16x32_bf16 v[4:7], v[206:209], v[190:193], v[4:7]
	s_barrier
; #define PG8_STAGE(bufoff, gbase, voff) do { _Pragma("unroll") for (int _i = 0; _i < 2; ++_i) \
;         __builtin_amdgcn_global_load_lds((const unsigned*)((const char*)(gbase) + (voff)[_i]), (LAS unsigned*)(lds + (bufoff) + ldsw + _i * 8192), 16, 0, 0); } while (0)
; #define PG8_LDA(dst, b, h) do { _Pragma("unroll") for (int m = 0; m < 4; ++m) _Pragma("unroll") for (int k = 0; k < 2; ++k) dst[m][k] = *(const LAS bf16x8*)(lds + PG8_SA(b, h) + aoff + m * 2048 + k * 1024); } while (0)
; #define PG8_LDB(dst, b, h) do { _Pragma("unroll") for (int n = 0; n < 2; ++n) _Pragma("unroll") for (int k = 0; k < 2; ++k) dst[n][k] = *(const LAS bf16x8*)(lds + PG8_SB(b, h) + boff + n * 2048 + k * 1024); } while (0)
; #define PG8_MMA(ai, bj, At, Bt) do { __builtin_amdgcn_s_setprio(1); _Pragma("unroll") for (int m = 0; m < 4; ++m) _Pragma("unroll") for (int n = 0; n < 2; ++n) _Pragma("unroll") for (int k = 0; k < 2; ++k) \
;         acc[ai][bj][m][n] = __builtin_amdgcn_mfma_f32_16x16x32_bf16(Bt[n][k], At[m][k], acc[ai][bj][m][n], 0, 0, 0); __builtin_amdgcn_s_setprio(0); } while (0)
; #define PG8_WAIT_V(n) asm volatile("s_waitcnt vmcnt(" #n ")" ::: "memory")
; #define PG8_WAIT_L(n) asm volatile("s_waitcnt lgkmcnt(" #n ")" ::: "memory")
; #define PG8_BAR __builtin_amdgcn_s_barrier()
; #define PG8_SCHED __builtin_amdgcn_sched_barrier(0)
; template <class Epi, class Sched>
; __device__ __forceinline__ void gemm_phase(LAS unsigned char* lds, const Gemm g, const Sched& S, const Epi& E) {
;     ...
;             PG8_LDB(B0, 1, 0); PG8_SCHED; PG8_LDA(At, 1, 0); PG8_STAGE(PG8_SA(0, 1), a2 + hstepA, voffA);
;             PG8_WAIT_L(8); PG8_BAR; PG8_WAIT_L(0); PG8_MMA(0, 0, At, B0); PG8_BAR; PG8_SCHED;
;             PG8_LDB(B1, 1, 1); PG8_STAGE(PG8_SB(1, 0), b3, voffB);
;             PG8_BAR; PG8_WAIT_L(0); PG8_MMA(0, 1, At, B1); PG8_BAR;
;             PG8_LDA(At, 1, 1); PG8_STAGE(PG8_SA(1, 0), a3, voffA);
;             PG8_BAR; PG8_WAIT_L(0); PG8_MMA(1, 0, At, B0); PG8_BAR; PG8_SCHED;
;             PG8_STAGE(PG8_SB(1, 1), b3 + hstepB, voffB);
;             PG8_WAIT_V(6); PG8_BAR; PG8_MMA(1, 1, At, B1); PG8_BAR;
	s_setprio 0
	s_add_i32 s56, 0, 0x18000
	v_add_u32_e32 v2, s56, v1
	ds_read_b128 v[144:147], v2
	ds_read_b128 v[150:153], v2 offset:1024
	ds_read_b128 v[154:157], v2 offset:2048
	ds_read_b128 v[158:161], v2 offset:3072
	s_add_u32 s24, s24, 0x80000
	s_addc_u32 s25, s25, 0
	ds_read_b128 v[162:165], v149 offset:32768
	ds_read_b128 v[166:169], v149 offset:33792
	ds_read_b128 v[170:173], v149 offset:34816
	ds_read_b128 v[174:177], v149 offset:35840
	ds_read_b128 v[178:181], v149 offset:36864
	ds_read_b128 v[182:185], v149 offset:37888
	ds_read_b128 v[186:189], v149 offset:38912
	ds_read_b128 v[190:193], v149 offset:39936
	s_mov_b32 m0, s36
	s_nop 0
	global_load_lds_dwordx4 v138, s[24:25]
	s_mov_b32 m0, s37
	s_nop 0
	global_load_lds_dwordx4 v134, s[24:25]
	s_add_i32 s24, 0, 0x1c000
	v_add_u32_e32 v2, s24, v1
	ds_read_b128 v[194:197], v2
	ds_read_b128 v[198:201], v2 offset:1024
	ds_read_b128 v[202:205], v2 offset:2048
	ds_read_b128 v[206:209], v2 offset:3072
	s_waitcnt lgkmcnt(0)
	s_waitcnt vmcnt(8)
	s_setprio 1
	s_barrier
	v_mfma_f32_16x16x32_bf16 v[128:131], v[144:147], v[162:165], v[128:131]
	v_mfma_f32_16x16x32_bf16 v[124:127], v[154:157], v[162:165], v[124:127]
	v_mfma_f32_16x16x32_bf16 v[112:115], v[144:147], v[170:173], v[112:115]
	v_mfma_f32_16x16x32_bf16 v[108:111], v[154:157], v[170:173], v[108:111]
	v_mfma_f32_16x16x32_bf16 v[96:99], v[144:147], v[178:181], v[96:99]
	v_mfma_f32_16x16x32_bf16 v[92:95], v[154:157], v[178:181], v[92:95]
	v_mfma_f32_16x16x32_bf16 v[80:83], v[144:147], v[186:189], v[80:83]
	v_mfma_f32_16x16x32_bf16 v[76:79], v[154:157], v[186:189], v[76:79]
	v_mfma_f32_16x16x32_bf16 v[128:131], v[150:153], v[166:169], v[128:131]
	v_mfma_f32_16x16x32_bf16 v[124:127], v[158:161], v[166:169], v[124:127]
	v_mfma_f32_16x16x32_bf16 v[112:115], v[150:153], v[174:177], v[112:115]
	v_mfma_f32_16x16x32_bf16 v[108:111], v[158:161], v[174:177], v[108:111]
	v_mfma_f32_16x16x32_bf16 v[96:99], v[150:153], v[182:185], v[96:99]
	v_mfma_f32_16x16x32_bf16 v[92:95], v[158:161], v[182:185], v[92:95]
	v_mfma_f32_16x16x32_bf16 v[80:83], v[150:153], v[190:193], v[80:83]
	v_mfma_f32_16x16x32_bf16 v[76:79], v[158:161], v[190:193], v[76:79]
	v_mfma_f32_16x16x32_bf16 v[120:123], v[194:197], v[162:165], v[120:123]
	v_mfma_f32_16x16x32_bf16 v[116:119], v[202:205], v[162:165], v[116:119]
	v_mfma_f32_16x16x32_bf16 v[104:107], v[194:197], v[170:173], v[104:107]
	v_mfma_f32_16x16x32_bf16 v[100:103], v[202:205], v[170:173], v[100:103]
	v_mfma_f32_16x16x32_bf16 v[88:91], v[194:197], v[178:181], v[88:91]
	v_mfma_f32_16x16x32_bf16 v[84:87], v[202:205], v[178:181], v[84:87]
	v_mfma_f32_16x16x32_bf16 v[72:75], v[194:197], v[186:189], v[72:75]
	v_mfma_f32_16x16x32_bf16 v[68:71], v[202:205], v[186:189], v[68:71]
	v_mfma_f32_16x16x32_bf16 v[120:123], v[198:201], v[166:169], v[120:123]
	v_mfma_f32_16x16x32_bf16 v[116:119], v[206:209], v[166:169], v[116:119]
	v_mfma_f32_16x16x32_bf16 v[104:107], v[198:201], v[174:177], v[104:107]
	v_mfma_f32_16x16x32_bf16 v[100:103], v[206:209], v[174:177], v[100:103]
	v_mfma_f32_16x16x32_bf16 v[88:91], v[198:201], v[182:185], v[88:91]
	v_mfma_f32_16x16x32_bf16 v[84:87], v[206:209], v[182:185], v[84:87]
	v_mfma_f32_16x16x32_bf16 v[72:75], v[198:201], v[190:193], v[72:75]
	v_mfma_f32_16x16x32_bf16 v[68:71], v[206:209], v[190:193], v[68:71]
	s_barrier
	s_setprio 0
	ds_read_b128 v[162:165], v149 offset:49152
	ds_read_b128 v[166:169], v149 offset:50176
	ds_read_b128 v[170:173], v149 offset:51200
	ds_read_b128 v[174:177], v149 offset:52224
	ds_read_b128 v[178:181], v149 offset:53248
	ds_read_b128 v[182:185], v149 offset:54272
	ds_read_b128 v[186:189], v149 offset:55296
	ds_read_b128 v[190:193], v149 offset:56320
	s_add_i32 s25, s56, s30
	v_lshl_add_u64 v[210:211], v[210:211], 0, s[8:9]
	s_mov_b32 m0, s25
	s_nop 0
	global_load_lds_dwordx4 v[210:211], off
	v_lshl_add_u64 v[210:211], v[212:213], 0, s[8:9]
	s_add_i32 m0, s25, 0x2000
	s_nop 0
	global_load_lds_dwordx4 v[210:211], off
	s_mov_b32 m0, s40
	v_lshl_add_u64 v[210:211], v[216:217], 0, s[8:9]
	global_load_lds_dwordx4 v[210:211], off
	v_lshl_add_u64 v[210:211], v[218:219], 0, s[8:9]
	s_mov_b32 m0, s41
	s_nop 0
	global_load_lds_dwordx4 v[210:211], off
	s_add_u32 s20, s20, 0x80080
	s_addc_u32 s21, s21, 0
	s_add_i32 s24, s24, s30
	s_mov_b32 m0, s24
	s_nop 0
	global_load_lds_dwordx4 v136, s[20:21]
	s_add_i32 m0, s24, 0x2000
	s_nop 0
	global_load_lds_dwordx4 v132, s[20:21]
	s_add_i32 s55, s55, 2
	s_add_u32 s6, s6, 0x100
	s_addc_u32 s7, s7, 0
	s_add_u32 s53, s53, 0x100
	s_addc_u32 s54, s54, 0
	s_cmp_gt_u32 s55, 29
	s_waitcnt lgkmcnt(0)
	s_waitcnt vmcnt(8)
	s_setprio 1
	s_barrier
; __device__ __forceinline__ unsigned cvt_pk_bf16(float lo, float hi) { const f32x2 v = {lo, hi}; const bf16v2_ r = __builtin_convertvector(v, bf16v2_); return __builtin_bit_cast(unsigned, r); }
; __device__ __forceinline__ int opaque_tid() { int t = threadIdx.x; asm volatile("" : "+v"(t)); return t; }
; #define PG8_WAIT_V(n) asm volatile("s_waitcnt vmcnt(" #n ")" ::: "memory")
; #define PG8_WAIT_L(n) asm volatile("s_waitcnt lgkmcnt(" #n ")" ::: "memory")
; template <class Epi, class Sched>
; __device__ __forceinline__ void gemm_phase(LAS unsigned char* lds, const Gemm g, const Sched& S, const Epi& E) {
;     ...
;             PG8_WAIT_V(6); PG8_BAR; PG8_MMA(1, 1, At, B1); PG8_BAR;
;             PG8_LDB(B0, 1, 0); PG8_SCHED; PG8_LDA(At, 1, 0); PG8_STAGE(PG8_SA(0, 1), a2 + hstepA, voffA);
;             PG8_WAIT_L(8); PG8_BAR; PG8_WAIT_L(0); PG8_MMA(0, 0, At, B0); PG8_BAR; PG8_SCHED;
;             PG8_LDB(B1, 1, 1); PG8_STAGE(PG8_SB(1, 0), b3, voffB);
;             PG8_BAR; PG8_WAIT_L(0); PG8_MMA(0, 1, At, B1); PG8_BAR;
;             PG8_LDA(At, 1, 1); PG8_STAGE(PG8_SA(1, 0), a3, voffA);
;             PG8_BAR; PG8_WAIT_L(0); PG8_MMA(1, 0, At, B0); PG8_BAR; PG8_SCHED;
;             PG8_STAGE(PG8_SB(1, 1), b3 + hstepB, voffB);
;             PG8_WAIT_V(6); PG8_BAR; PG8_MMA(1, 1, At, B1); PG8_BAR;
;     __device__ __forceinline__ void operator()(const f32x4 (&acc)[2][2][4][2], const Unit& u, int wr, int wc, int ui, int) const {
;         const int ol_ = opaque_tid() & 63, fr = ol_ & 15, fq = ol_ >> 4;
;         const int row0 = u.pm * BM + wr * 64 + fr, col0 = u.pn * BM + wc * 32 + 8 * fq;
;         const bool cmp = (u.pn == 8 || u.pn == 9);
;         bf16_t* cb = (u.pn == 8) ? kcmp : vcmp;
;         float r_[2][4];
;         rs_read(r_, ui, wr, fr);
; #pragma unroll
;         for (int ai = 0; ai < 2; ++ai)
; #pragma unroll
;             for (int m = 0; m < 4; ++m) { const int row = row0 + ai * HALF + m * 16; const float r = r_[ai][m];
; #pragma unroll
;                 for (int bj = 0; bj < 2; ++bj) { const f32x4 v0 = acc[ai][bj][m][0] * r, v1 = acc[ai][bj][m][1] * r;
;                     u32x4 w; w.x = cvt_pk_bf16(v0[0], v0[1]); w.y = cvt_pk_bf16(v0[2], v0[3]); w.z = cvt_pk_bf16(v1[0], v1[1]); w.w = cvt_pk_bf16(v1[2], v1[3]);
;                     bf16_t* p = cmp ? cb + ((size_t)((row / T) * 2 + bj) * T + (row % T)) * 128 + wc * 32 + 8 * fq
	v_mfma_f32_16x16x32_bf16 v[64:67], v[144:147], v[162:165], v[64:67]
	v_mfma_f32_16x16x32_bf16 v[60:63], v[154:157], v[162:165], v[60:63]
	v_mfma_f32_16x16x32_bf16 v[48:51], v[144:147], v[170:173], v[48:51]
	v_mfma_f32_16x16x32_bf16 v[44:47], v[154:157], v[170:173], v[44:47]
	v_mfma_f32_16x16x32_bf16 v[32:35], v[144:147], v[178:181], v[32:35]
	v_mfma_f32_16x16x32_bf16 v[28:31], v[154:157], v[178:181], v[28:31]
	v_mfma_f32_16x16x32_bf16 v[16:19], v[144:147], v[186:189], v[16:19]
	v_mfma_f32_16x16x32_bf16 v[12:15], v[154:157], v[186:189], v[12:15]
	v_mfma_f32_16x16x32_bf16 v[64:67], v[150:153], v[166:169], v[64:67]
	v_mfma_f32_16x16x32_bf16 v[60:63], v[158:161], v[166:169], v[60:63]
	v_mfma_f32_16x16x32_bf16 v[48:51], v[150:153], v[174:177], v[48:51]
	v_mfma_f32_16x16x32_bf16 v[44:47], v[158:161], v[174:177], v[44:47]
	v_mfma_f32_16x16x32_bf16 v[32:35], v[150:153], v[182:185], v[32:35]
	v_mfma_f32_16x16x32_bf16 v[28:31], v[158:161], v[182:185], v[28:31]
	v_mfma_f32_16x16x32_bf16 v[16:19], v[150:153], v[190:193], v[16:19]
	v_mfma_f32_16x16x32_bf16 v[12:15], v[158:161], v[190:193], v[12:15]
	v_mfma_f32_16x16x32_bf16 v[56:59], v[194:197], v[162:165], v[56:59]
	v_mfma_f32_16x16x32_bf16 v[52:55], v[202:205], v[162:165], v[52:55]
	v_mfma_f32_16x16x32_bf16 v[40:43], v[194:197], v[170:173], v[40:43]
	v_mfma_f32_16x16x32_bf16 v[36:39], v[202:205], v[170:173], v[36:39]
	v_mfma_f32_16x16x32_bf16 v[24:27], v[194:197], v[178:181], v[24:27]
	v_mfma_f32_16x16x32_bf16 v[20:23], v[202:205], v[178:181], v[20:23]
	v_mfma_f32_16x16x32_bf16 v[8:11], v[194:197], v[186:189], v[8:11]
	v_mfma_f32_16x16x32_bf16 v[4:7], v[202:205], v[186:189], v[4:7]
	v_mfma_f32_16x16x32_bf16 v[56:59], v[198:201], v[166:169], v[56:59]
	v_mfma_f32_16x16x32_bf16 v[52:55], v[206:209], v[166:169], v[52:55]
	v_mfma_f32_16x16x32_bf16 v[40:43], v[198:201], v[174:177], v[40:43]
	v_mfma_f32_16x16x32_bf16 v[36:39], v[206:209], v[174:177], v[36:39]
	v_mfma_f32_16x16x32_bf16 v[24:27], v[198:201], v[182:185], v[24:27]
	v_mfma_f32_16x16x32_bf16 v[20:23], v[206:209], v[182:185], v[20:23]
	v_mfma_f32_16x16x32_bf16 v[8:11], v[198:201], v[190:193], v[8:11]
	v_mfma_f32_16x16x32_bf16 v[4:7], v[206:209], v[190:193], v[4:7]
	s_barrier
	s_cbranch_scc0 .LBB0_352
	s_setprio 0
	s_lshl_b32 s1, s50, 8
	s_lshl_b32 s6, s44, 8
	s_add_i32 s1, s1, s38
	s_or_b32 s6, s6, s39
	s_cmp_eq_u32 s44, 8
	s_mov_b32 s7, 0x3bcb0000
	s_cselect_b32 s15, s7, 0x3ccb4000
	s_lshl_b32 s7, s45, 10
	v_mov_b32_e32 v2, v0
	s_and_b32 s7, s7, 0x400
	s_add_i32 s7, s46, s7
	v_and_b32_e32 v144, 15, v2
	v_or_b32_e32 v148, s1, v144
	v_lshl_add_u32 v144, v144, 2, s7
	v_lshrrev_b32_e32 v2, 1, v2
	ds_read2_b32 v[164:165], v144 offset1:16
	ds_read2_b32 v[160:161], v144 offset0:32 offset1:48
	ds_read2_b32 v[156:157], v144 offset0:128 offset1:144
	ds_read2_b32 v[152:153], v144 offset0:160 offset1:176
	v_and_b32_e32 v2, 24, v2
	v_or_b32_e32 v146, s6, v2
	s_and_b32 s6, s44, -2
	s_cmp_lg_u32 s6, 8
	s_cselect_b64 s[6:7], -1, 0
	s_add_u32 s24, s47, s15
	s_waitcnt lgkmcnt(0)
	v_mov_b32_e32 v162, v165
	v_mov_b32_e32 v158, v161
	v_mov_b32_e32 v154, v157
	v_mov_b32_e32 v144, v153
	v_ashrrev_i32_e32 v147, 31, v146
	s_addc_u32 s25, s48, 0
	s_mov_b64 s[20:21], -1
	s_and_b64 vcc, exec, s[6:7]
	s_cbranch_vccz .LBB0_355
	v_mov_b64_e32 v[150:151], s[92:93]
	s_movk_i32 s15, 0x3600
	v_mad_i64_i32 v[150:151], s[20:21], v148, s15, v[150:151]
	v_lshl_add_u64 v[170:171], v[146:147], 1, v[150:151]
	s_mov_b64 s[20:21], 0

; #define PG8_STAGE(bufoff, gbase, voff) do { _Pragma("unroll") for (int _i = 0; _i < 2; ++_i) \
;         __builtin_amdgcn_global_load_lds((const unsigned*)((const char*)(gbase) + (voff)[_i]), (LAS unsigned*)(lds + (bufoff) + ldsw + _i * 8192), 16, 0, 0); } while (0)
; #define PG8_LDA(dst, b, h) do { _Pragma("unroll") for (int m = 0; m < 4; ++m) _Pragma("unroll") for (int k = 0; k < 2; ++k) dst[m][k] = *(const LAS bf16x8*)(lds + PG8_SA(b, h) + aoff + m * 2048 + k * 1024); } while (0)
; #define PG8_LDB(dst, b, h) do { _Pragma("unroll") for (int n = 0; n < 2; ++n) _Pragma("unroll") for (int k = 0; k < 2; ++k) dst[n][k] = *(const LAS bf16x8*)(lds + PG8_SB(b, h) + boff + n * 2048 + k * 1024); } while (0)
; #define PG8_WAIT_V(n) asm volatile("s_waitcnt vmcnt(" #n ")" ::: "memory")
; #define PG8_WAIT_L(n) asm volatile("s_waitcnt lgkmcnt(" #n ")" ::: "memory")
; #define PG8_BAR __builtin_amdgcn_s_barrier()
; #define PG8_SCHED __builtin_amdgcn_sched_barrier(0)
; template <class Epi, class Sched>
; __device__ __forceinline__ void gemm_phase(LAS unsigned char* lds, const Gemm g, const Sched& S, const Epi& E) {
;     ...
;         const bool has_next = S.next(ui + 1, nxt);
;         const char* nA = has_next ? (const char*)g.A + (size_t)nxt.pm * tstepA : cA; const char* nB = has_next ? (const char*)g.Bt + (size_t)nxt.pn * tstepB : cB;
;         for (int t = 0; t < nt; t += 2) {
;             const bool last = (t == nt - 2);
;             const char* a1 = cA + (size_t)(t + 1) * kstep;
;             const char* a2 = last ? nA : cA + (size_t)(t + 2) * kstep; const char* b2 = last ? nB : cB + (size_t)(t + 2) * kstep;
;             const char* a3 = a2 + kstep; const char* b3 = b2 + kstep;
;             if (last && has_next) S.a_ready(nxt);
;             PG8_LDB(B0, 0, 0); PG8_SCHED; PG8_LDA(At, 0, 0); PG8_STAGE(PG8_SA(1, 1), a1 + hstepA, voffA);
;             PG8_WAIT_L(8); PG8_BAR; PG8_WAIT_L(0); PG8_MMA(0, 0, At, B0); PG8_BAR; PG8_SCHED;
;             PG8_LDB(B1, 0, 1); PG8_STAGE(PG8_SB(0, 0), b2, voffB);
;             PG8_BAR; PG8_WAIT_L(0); PG8_MMA(0, 1, At, B1); PG8_BAR;
;             PG8_LDA(At, 0, 1); PG8_STAGE(PG8_SA(0, 0), a2, voffA);
;             PG8_BAR; PG8_WAIT_L(0); PG8_MMA(1, 0, At, B0); PG8_BAR; PG8_SCHED;
;             PG8_STAGE(PG8_SB(0, 1), b2 + hstepB, voffB);
;             PG8_WAIT_V(6); PG8_BAR; PG8_MMA(1, 1, At, B1); PG8_BAR;
.LBB0_490:
	s_ashr_i32 s53, s52, 31
	s_lshl_b64 s[18:19], s[52:53], 20
	s_add_u32 s54, s25, s18
	v_cmp_lt_i64_e64 s[14:15], s[14:15], 16
	s_addc_u32 s55, s28, s19
	s_and_b64 s[18:19], s[14:15], exec
	s_cselect_b32 s18, s55, s5
	s_cselect_b32 s19, s54, s4
	s_ashr_i32 s51, s50, 31
	s_lshl_b64 s[56:57], s[50:51], 21
	s_add_u32 s56, s44, s56
	s_addc_u32 s57, s45, s57
	s_and_b64 s[14:15], s[14:15], exec
	s_cselect_b32 s51, s57, s7
	s_cselect_b32 s53, s56, s6
	s_add_u32 s4, s4, 0x80080
	s_addc_u32 s5, s5, 0
	s_add_u32 s65, s6, 0x100
	s_addc_u32 s66, s7, 0
	s_mov_b32 s67, -2
	s_waitcnt lgkmcnt(0)
	s_setprio 0
	s_add_u32 s6, s4, 0xfff80080
	s_addc_u32 s7, s5, -1
	s_add_i32 s68, 0, 0x10000
	v_add_u32_e32 v154, s68, v1
	ds_read_b128 v[142:145], v154
	ds_read_b128 v[146:149], v154 offset:1024
	ds_read_b128 v[150:153], v154 offset:2048
	ds_read_b128 v[158:161], v154 offset:3072
	s_cmp_eq_u32 s67, 60
	s_cselect_b32 s15, s18, s7
	s_cselect_b32 s14, s19, s6
	s_cselect_b32 s7, s51, s66
	s_cselect_b32 s6, s53, s65
	ds_read_b128 v[162:165], v156
	ds_read_b128 v[166:169], v156 offset:1024
	ds_read_b128 v[170:173], v156 offset:2048
	ds_read_b128 v[174:177], v156 offset:3072
	ds_read_b128 v[178:181], v156 offset:4096
	ds_read_b128 v[182:185], v156 offset:5120
	ds_read_b128 v[186:189], v156 offset:6144
	ds_read_b128 v[190:193], v156 offset:7168
	s_add_i32 s70, 0, 0x14000
	v_add_u32_e32 v154, s70, v1
	ds_read_b128 v[194:197], v154
	ds_read_b128 v[198:201], v154 offset:1024
	ds_read_b128 v[202:205], v154 offset:2048
	ds_read_b128 v[206:209], v154 offset:3072
	s_add_i32 m0, s30, 0xc000
	s_nop 0
	global_load_lds_dwordx4 v138, s[4:5]
	s_add_i32 m0, s30, 0xe000
	s_nop 0
	global_load_lds_dwordx4 v140, s[4:5]
	s_waitcnt lgkmcnt(0)
	s_waitcnt vmcnt(8)
	s_setprio 1
	s_barrier
	v_mfma_f32_16x16x32_bf16 v[128:131], v[142:145], v[162:165], 0
	v_mfma_f32_16x16x32_bf16 v[124:127], v[150:153], v[162:165], 0
	v_mfma_f32_16x16x32_bf16 v[120:123], v[142:145], v[170:173], 0
	v_mfma_f32_16x16x32_bf16 v[116:119], v[150:153], v[170:173], 0
	v_mfma_f32_16x16x32_bf16 v[112:115], v[142:145], v[178:181], 0
	v_mfma_f32_16x16x32_bf16 v[108:111], v[150:153], v[178:181], 0
	v_mfma_f32_16x16x32_bf16 v[104:107], v[142:145], v[186:189], 0
	v_mfma_f32_16x16x32_bf16 v[100:103], v[150:153], v[186:189], 0
	v_mfma_f32_16x16x32_bf16 v[128:131], v[146:149], v[166:169], v[128:131]
	v_mfma_f32_16x16x32_bf16 v[124:127], v[158:161], v[166:169], v[124:127]
	v_mfma_f32_16x16x32_bf16 v[120:123], v[146:149], v[174:177], v[120:123]
	v_mfma_f32_16x16x32_bf16 v[116:119], v[158:161], v[174:177], v[116:119]
	v_mfma_f32_16x16x32_bf16 v[112:115], v[146:149], v[182:185], v[112:115]
	v_mfma_f32_16x16x32_bf16 v[108:111], v[158:161], v[182:185], v[108:111]
	v_mfma_f32_16x16x32_bf16 v[104:107], v[146:149], v[190:193], v[104:107]
	v_mfma_f32_16x16x32_bf16 v[100:103], v[158:161], v[190:193], v[100:103]
	v_mfma_f32_16x16x32_bf16 v[64:67], v[194:197], v[162:165], 0
	v_mfma_f32_16x16x32_bf16 v[60:63], v[202:205], v[162:165], 0
	v_mfma_f32_16x16x32_bf16 v[56:59], v[194:197], v[170:173], 0
	v_mfma_f32_16x16x32_bf16 v[52:55], v[202:205], v[170:173], 0
	v_mfma_f32_16x16x32_bf16 v[48:51], v[194:197], v[178:181], 0
	v_mfma_f32_16x16x32_bf16 v[44:47], v[202:205], v[178:181], 0
	v_mfma_f32_16x16x32_bf16 v[40:43], v[194:197], v[186:189], 0
	v_mfma_f32_16x16x32_bf16 v[36:39], v[202:205], v[186:189], 0
	v_mfma_f32_16x16x32_bf16 v[64:67], v[198:201], v[166:169], v[64:67]
	v_mfma_f32_16x16x32_bf16 v[60:63], v[206:209], v[166:169], v[60:63]
	v_mfma_f32_16x16x32_bf16 v[56:59], v[198:201], v[174:177], v[56:59]
	v_mfma_f32_16x16x32_bf16 v[52:55], v[206:209], v[174:177], v[52:55]
	v_mfma_f32_16x16x32_bf16 v[48:51], v[198:201], v[182:185], v[48:51]
	v_mfma_f32_16x16x32_bf16 v[44:47], v[206:209], v[182:185], v[44:47]
	v_mfma_f32_16x16x32_bf16 v[40:43], v[198:201], v[190:193], v[40:43]
	v_mfma_f32_16x16x32_bf16 v[36:39], v[206:209], v[190:193], v[36:39]
	s_barrier
	s_setprio 0
	ds_read_b128 v[162:165], v156 offset:16384
	ds_read_b128 v[166:169], v156 offset:17408
	ds_read_b128 v[170:173], v156 offset:18432
	ds_read_b128 v[174:177], v156 offset:19456
	ds_read_b128 v[178:181], v156 offset:20480
	ds_read_b128 v[182:185], v156 offset:21504
	ds_read_b128 v[186:189], v156 offset:22528
	ds_read_b128 v[190:193], v156 offset:23552
	s_add_i32 s68, s68, s29
	v_lshl_add_u64 v[154:155], s[6:7], 0, v[2:3]
	s_mov_b32 m0, s68
	v_lshl_add_u64 v[210:211], s[6:7], 0, v[136:137]
	global_load_lds_dwordx4 v[154:155], off
	s_add_i32 m0, s68, 0x2000
	s_nop 0
	global_load_lds_dwordx4 v[210:211], off
	s_mov_b32 m0, s30
	v_lshl_add_u64 v[212:213], s[14:15], 0, v[132:133]
	global_load_lds_dwordx4 v[212:213], off
	v_lshl_add_u64 v[216:217], s[14:15], 0, v[134:135]
	s_mov_b32 m0, s31
	s_nop 0
	global_load_lds_dwordx4 v[216:217], off
	s_add_u32 s68, s6, 0x100000
	s_addc_u32 s69, s7, 0
	s_add_i32 s70, s70, s29
	s_mov_b32 m0, s70
	s_nop 0
	global_load_lds_dwordx4 v2, s[68:69]
	s_add_i32 m0, s70, 0x2000
	s_nop 0
	global_load_lds_dwordx4 v136, s[68:69]
	s_waitcnt lgkmcnt(0)
	s_waitcnt vmcnt(8)
	s_setprio 1
	s_barrier
; #define PG8_STAGE(bufoff, gbase, voff) do { _Pragma("unroll") for (int _i = 0; _i < 2; ++_i) \
;         __builtin_amdgcn_global_load_lds((const unsigned*)((const char*)(gbase) + (voff)[_i]), (LAS unsigned*)(lds + (bufoff) + ldsw + _i * 8192), 16, 0, 0); } while (0)
; #define PG8_LDA(dst, b, h) do { _Pragma("unroll") for (int m = 0; m < 4; ++m) _Pragma("unroll") for (int k = 0; k < 2; ++k) dst[m][k] = *(const LAS bf16x8*)(lds + PG8_SA(b, h) + aoff + m * 2048 + k * 1024); } while (0)
; #define PG8_LDB(dst, b, h) do { _Pragma("unroll") for (int n = 0; n < 2; ++n) _Pragma("unroll") for (int k = 0; k < 2; ++k) dst[n][k] = *(const LAS bf16x8*)(lds + PG8_SB(b, h) + boff + n * 2048 + k * 1024); } while (0)
; #define PG8_MMA(ai, bj, At, Bt) do { __builtin_amdgcn_s_setprio(1); _Pragma("unroll") for (int m = 0; m < 4; ++m) _Pragma("unroll") for (int n = 0; n < 2; ++n) _Pragma("unroll") for (int k = 0; k < 2; ++k) \
;         acc[ai][bj][m][n] = __builtin_amdgcn_mfma_f32_16x16x32_bf16(Bt[n][k], At[m][k], acc[ai][bj][m][n], 0, 0, 0); __builtin_amdgcn_s_setprio(0); } while (0)
; #define PG8_WAIT_V(n) asm volatile("s_waitcnt vmcnt(" #n ")" ::: "memory")
; #define PG8_WAIT_L(n) asm volatile("s_waitcnt lgkmcnt(" #n ")" ::: "memory")
; #define PG8_BAR __builtin_amdgcn_s_barrier()
; #define PG8_SCHED __builtin_amdgcn_sched_barrier(0)
; template <class Epi, class Sched>
; __device__ __forceinline__ void gemm_phase(LAS unsigned char* lds, const Gemm g, const Sched& S, const Epi& E) {
;     ...
;             PG8_WAIT_V(6); PG8_BAR; PG8_MMA(1, 1, At, B1); PG8_BAR;
;             PG8_LDB(B0, 1, 0); PG8_SCHED; PG8_LDA(At, 1, 0); PG8_STAGE(PG8_SA(0, 1), a2 + hstepA, voffA);
;             PG8_WAIT_L(8); PG8_BAR; PG8_WAIT_L(0); PG8_MMA(0, 0, At, B0); PG8_BAR; PG8_SCHED;
;             PG8_LDB(B1, 1, 1); PG8_STAGE(PG8_SB(1, 0), b3, voffB);
;             PG8_BAR; PG8_WAIT_L(0); PG8_MMA(0, 1, At, B1); PG8_BAR;
;             PG8_LDA(At, 1, 1); PG8_STAGE(PG8_SA(1, 0), a3, voffA);
;             PG8_BAR; PG8_WAIT_L(0); PG8_MMA(1, 0, At, B0); PG8_BAR; PG8_SCHED;
	v_mfma_f32_16x16x32_bf16 v[96:99], v[142:145], v[162:165], 0
	v_mfma_f32_16x16x32_bf16 v[92:95], v[150:153], v[162:165], 0
	v_mfma_f32_16x16x32_bf16 v[88:91], v[142:145], v[170:173], 0
	v_mfma_f32_16x16x32_bf16 v[84:87], v[150:153], v[170:173], 0
	v_mfma_f32_16x16x32_bf16 v[80:83], v[142:145], v[178:181], 0
	v_mfma_f32_16x16x32_bf16 v[76:79], v[150:153], v[178:181], 0
	v_mfma_f32_16x16x32_bf16 v[72:75], v[142:145], v[186:189], 0
	v_mfma_f32_16x16x32_bf16 v[68:71], v[150:153], v[186:189], 0
	v_mfma_f32_16x16x32_bf16 v[96:99], v[146:149], v[166:169], v[96:99]
	v_mfma_f32_16x16x32_bf16 v[92:95], v[158:161], v[166:169], v[92:95]
	v_mfma_f32_16x16x32_bf16 v[88:91], v[146:149], v[174:177], v[88:91]
	v_mfma_f32_16x16x32_bf16 v[84:87], v[158:161], v[174:177], v[84:87]
	v_mfma_f32_16x16x32_bf16 v[80:83], v[146:149], v[182:185], v[80:83]
	v_mfma_f32_16x16x32_bf16 v[76:79], v[158:161], v[182:185], v[76:79]
	v_mfma_f32_16x16x32_bf16 v[72:75], v[146:149], v[190:193], v[72:75]
	v_mfma_f32_16x16x32_bf16 v[68:71], v[158:161], v[190:193], v[68:71]
	v_mfma_f32_16x16x32_bf16 v[32:35], v[194:197], v[162:165], 0
	v_mfma_f32_16x16x32_bf16 v[28:31], v[202:205], v[162:165], 0
	v_mfma_f32_16x16x32_bf16 v[24:27], v[194:197], v[170:173], 0
	v_mfma_f32_16x16x32_bf16 v[20:23], v[202:205], v[170:173], 0
	v_mfma_f32_16x16x32_bf16 v[16:19], v[194:197], v[178:181], 0
	v_mfma_f32_16x16x32_bf16 v[12:15], v[202:205], v[178:181], 0
	v_mfma_f32_16x16x32_bf16 v[8:11], v[194:197], v[186:189], 0
	v_mfma_f32_16x16x32_bf16 v[4:7], v[202:205], v[186:189], 0
	v_mfma_f32_16x16x32_bf16 v[32:35], v[198:201], v[166:169], v[32:35]
	v_mfma_f32_16x16x32_bf16 v[28:31], v[206:209], v[166:169], v[28:31]
	v_mfma_f32_16x16x32_bf16 v[24:27], v[198:201], v[174:177], v[24:27]
	v_mfma_f32_16x16x32_bf16 v[20:23], v[206:209], v[174:177], v[20:23]
	v_mfma_f32_16x16x32_bf16 v[16:19], v[198:201], v[182:185], v[16:19]
	v_mfma_f32_16x16x32_bf16 v[12:15], v[206:209], v[182:185], v[12:15]
	v_mfma_f32_16x16x32_bf16 v[8:11], v[198:201], v[190:193], v[8:11]
	v_mfma_f32_16x16x32_bf16 v[4:7], v[206:209], v[190:193], v[4:7]
	s_barrier
	s_setprio 0
	s_add_i32 s68, 0, 0x18000
	v_add_u32_e32 v157, s68, v1
	ds_read_b128 v[142:145], v157
	ds_read_b128 v[146:149], v157 offset:1024
	ds_read_b128 v[150:153], v157 offset:2048
	ds_read_b128 v[158:161], v157 offset:3072
	s_add_u32 s14, s14, 0x80000
	s_addc_u32 s15, s15, 0
	ds_read_b128 v[162:165], v156 offset:32768
	ds_read_b128 v[166:169], v156 offset:33792
	ds_read_b128 v[170:173], v156 offset:34816
	ds_read_b128 v[174:177], v156 offset:35840
	ds_read_b128 v[178:181], v156 offset:36864
	ds_read_b128 v[182:185], v156 offset:37888
	ds_read_b128 v[186:189], v156 offset:38912
	ds_read_b128 v[190:193], v156 offset:39936
	s_mov_b32 m0, s38
	s_nop 0
	global_load_lds_dwordx4 v132, s[14:15]
	s_mov_b32 m0, s39
	s_nop 0
	global_load_lds_dwordx4 v134, s[14:15]
	s_add_i32 s14, 0, 0x1c000
	v_add_u32_e32 v157, s14, v1
	ds_read_b128 v[194:197], v157
	ds_read_b128 v[198:201], v157 offset:1024
	ds_read_b128 v[202:205], v157 offset:2048
	ds_read_b128 v[206:209], v157 offset:3072
	s_waitcnt lgkmcnt(0)
	s_waitcnt vmcnt(8)
	s_setprio 1
	s_barrier
	v_mfma_f32_16x16x32_bf16 v[128:131], v[142:145], v[162:165], v[128:131]
	v_mfma_f32_16x16x32_bf16 v[124:127], v[150:153], v[162:165], v[124:127]
	v_mfma_f32_16x16x32_bf16 v[120:123], v[142:145], v[170:173], v[120:123]
	v_mfma_f32_16x16x32_bf16 v[116:119], v[150:153], v[170:173], v[116:119]
	v_mfma_f32_16x16x32_bf16 v[112:115], v[142:145], v[178:181], v[112:115]
	v_mfma_f32_16x16x32_bf16 v[108:111], v[150:153], v[178:181], v[108:111]
	v_mfma_f32_16x16x32_bf16 v[104:107], v[142:145], v[186:189], v[104:107]
	v_mfma_f32_16x16x32_bf16 v[100:103], v[150:153], v[186:189], v[100:103]
	v_mfma_f32_16x16x32_bf16 v[128:131], v[146:149], v[166:169], v[128:131]
	v_mfma_f32_16x16x32_bf16 v[124:127], v[158:161], v[166:169], v[124:127]
	v_mfma_f32_16x16x32_bf16 v[120:123], v[146:149], v[174:177], v[120:123]
	v_mfma_f32_16x16x32_bf16 v[116:119], v[158:161], v[174:177], v[116:119]
	v_mfma_f32_16x16x32_bf16 v[112:115], v[146:149], v[182:185], v[112:115]
	v_mfma_f32_16x16x32_bf16 v[108:111], v[158:161], v[182:185], v[108:111]
	v_mfma_f32_16x16x32_bf16 v[104:107], v[146:149], v[190:193], v[104:107]
	v_mfma_f32_16x16x32_bf16 v[100:103], v[158:161], v[190:193], v[100:103]
	v_mfma_f32_16x16x32_bf16 v[64:67], v[194:197], v[162:165], v[64:67]
	v_mfma_f32_16x16x32_bf16 v[60:63], v[202:205], v[162:165], v[60:63]
	v_mfma_f32_16x16x32_bf16 v[56:59], v[194:197], v[170:173], v[56:59]
	v_mfma_f32_16x16x32_bf16 v[52:55], v[202:205], v[170:173], v[52:55]
	v_mfma_f32_16x16x32_bf16 v[48:51], v[194:197], v[178:181], v[48:51]
	v_mfma_f32_16x16x32_bf16 v[44:47], v[202:205], v[178:181], v[44:47]
	v_mfma_f32_16x16x32_bf16 v[40:43], v[194:197], v[186:189], v[40:43]
	v_mfma_f32_16x16x32_bf16 v[36:39], v[202:205], v[186:189], v[36:39]
	v_mfma_f32_16x16x32_bf16 v[64:67], v[198:201], v[166:169], v[64:67]
	v_mfma_f32_16x16x32_bf16 v[60:63], v[206:209], v[166:169], v[60:63]
	v_mfma_f32_16x16x32_bf16 v[56:59], v[198:201], v[174:177], v[56:59]
	v_mfma_f32_16x16x32_bf16 v[52:55], v[206:209], v[174:177], v[52:55]
	v_mfma_f32_16x16x32_bf16 v[48:51], v[198:201], v[182:185], v[48:51]
	v_mfma_f32_16x16x32_bf16 v[44:47], v[206:209], v[182:185], v[44:47]
	v_mfma_f32_16x16x32_bf16 v[40:43], v[198:201], v[190:193], v[40:43]
	v_mfma_f32_16x16x32_bf16 v[36:39], v[206:209], v[190:193], v[36:39]
	s_barrier
; #define PG8_STAGE(bufoff, gbase, voff) do { _Pragma("unroll") for (int _i = 0; _i < 2; ++_i) \
;         __builtin_amdgcn_global_load_lds((const unsigned*)((const char*)(gbase) + (voff)[_i]), (LAS unsigned*)(lds + (bufoff) + ldsw + _i * 8192), 16, 0, 0); } while (0)
; #define PG8_LDA(dst, b, h) do { _Pragma("unroll") for (int m = 0; m < 4; ++m) _Pragma("unroll") for (int k = 0; k < 2; ++k) dst[m][k] = *(const LAS bf16x8*)(lds + PG8_SA(b, h) + aoff + m * 2048 + k * 1024); } while (0)
; #define PG8_LDB(dst, b, h) do { _Pragma("unroll") for (int n = 0; n < 2; ++n) _Pragma("unroll") for (int k = 0; k < 2; ++k) dst[n][k] = *(const LAS bf16x8*)(lds + PG8_SB(b, h) + boff + n * 2048 + k * 1024); } while (0)
; #define PG8_MMA(ai, bj, At, Bt) do { __builtin_amdgcn_s_setprio(1); _Pragma("unroll") for (int m = 0; m < 4; ++m) _Pragma("unroll") for (int n = 0; n < 2; ++n) _Pragma("unroll") for (int k = 0; k < 2; ++k) \
;         acc[ai][bj][m][n] = __builtin_amdgcn_mfma_f32_16x16x32_bf16(Bt[n][k], At[m][k], acc[ai][bj][m][n], 0, 0, 0); __builtin_amdgcn_s_setprio(0); } while (0)
; #define PG8_WAIT_V(n) asm volatile("s_waitcnt vmcnt(" #n ")" ::: "memory")
; #define PG8_WAIT_L(n) asm volatile("s_waitcnt lgkmcnt(" #n ")" ::: "memory")
; #define PG8_BAR __builtin_amdgcn_s_barrier()
; #define PG8_SCHED __builtin_amdgcn_sched_barrier(0)
; template <class Epi, class Sched>
; __device__ __forceinline__ void gemm_phase(LAS unsigned char* lds, const Gemm g, const Sched& S, const Epi& E) {
;     ...
;             PG8_LDB(B0, 0, 0); PG8_SCHED; PG8_LDA(At, 0, 0); PG8_STAGE(PG8_SA(1, 1), a1 + hstepA, voffA);
;             PG8_WAIT_L(8); PG8_BAR; PG8_WAIT_L(0); PG8_MMA(0, 0, At, B0); PG8_BAR; PG8_SCHED;
;     ...
;             PG8_LDA(At, 1, 1); PG8_STAGE(PG8_SA(1, 0), a3, voffA);
;             PG8_BAR; PG8_WAIT_L(0); PG8_MMA(1, 0, At, B0); PG8_BAR; PG8_SCHED;
;             PG8_STAGE(PG8_SB(1, 1), b3 + hstepB, voffB);
;             PG8_WAIT_V(6); PG8_BAR; PG8_MMA(1, 1, At, B1); PG8_BAR;
	s_setprio 0
	ds_read_b128 v[162:165], v156 offset:49152
	ds_read_b128 v[166:169], v156 offset:50176
	ds_read_b128 v[170:173], v156 offset:51200
	ds_read_b128 v[174:177], v156 offset:52224
	ds_read_b128 v[178:181], v156 offset:53248
	ds_read_b128 v[182:185], v156 offset:54272
	ds_read_b128 v[186:189], v156 offset:55296
	ds_read_b128 v[190:193], v156 offset:56320
	s_add_i32 s15, s68, s29
	v_lshl_add_u64 v[154:155], v[154:155], 0, s[8:9]
	s_mov_b32 m0, s15
	s_nop 0
	global_load_lds_dwordx4 v[154:155], off
	v_lshl_add_u64 v[154:155], v[210:211], 0, s[8:9]
	s_add_i32 m0, s15, 0x2000
	s_nop 0
	global_load_lds_dwordx4 v[154:155], off
	s_mov_b32 m0, s62
	v_lshl_add_u64 v[154:155], v[212:213], 0, s[8:9]
	global_load_lds_dwordx4 v[154:155], off
	v_lshl_add_u64 v[154:155], v[216:217], 0, s[8:9]
	s_mov_b32 m0, s63
	s_nop 0
	global_load_lds_dwordx4 v[154:155], off
	s_add_u32 s6, s6, 0x100080
	s_addc_u32 s7, s7, 0
	s_add_i32 s14, s14, s29
	s_mov_b32 m0, s14
	s_nop 0
	global_load_lds_dwordx4 v2, s[6:7]
	s_add_i32 m0, s14, 0x2000
	s_nop 0
	global_load_lds_dwordx4 v136, s[6:7]
	s_add_i32 s67, s67, 2
	s_add_u32 s4, s4, 0x100
	s_addc_u32 s5, s5, 0
	s_add_u32 s65, s65, 0x100
	s_addc_u32 s66, s66, 0
	s_cmp_gt_u32 s67, 61
	s_waitcnt lgkmcnt(0)
	s_waitcnt vmcnt(8)
	s_setprio 1
	s_barrier
	v_mfma_f32_16x16x32_bf16 v[96:99], v[142:145], v[162:165], v[96:99]
	v_mfma_f32_16x16x32_bf16 v[92:95], v[150:153], v[162:165], v[92:95]
	v_mfma_f32_16x16x32_bf16 v[88:91], v[142:145], v[170:173], v[88:91]
	v_mfma_f32_16x16x32_bf16 v[84:87], v[150:153], v[170:173], v[84:87]
	v_mfma_f32_16x16x32_bf16 v[80:83], v[142:145], v[178:181], v[80:83]
	v_mfma_f32_16x16x32_bf16 v[76:79], v[150:153], v[178:181], v[76:79]
	v_mfma_f32_16x16x32_bf16 v[72:75], v[142:145], v[186:189], v[72:75]
	v_mfma_f32_16x16x32_bf16 v[68:71], v[150:153], v[186:189], v[68:71]
	v_mfma_f32_16x16x32_bf16 v[96:99], v[146:149], v[166:169], v[96:99]
	v_mfma_f32_16x16x32_bf16 v[92:95], v[158:161], v[166:169], v[92:95]
	v_mfma_f32_16x16x32_bf16 v[88:91], v[146:149], v[174:177], v[88:91]
	v_mfma_f32_16x16x32_bf16 v[84:87], v[158:161], v[174:177], v[84:87]
	v_mfma_f32_16x16x32_bf16 v[80:83], v[146:149], v[182:185], v[80:83]
	v_mfma_f32_16x16x32_bf16 v[76:79], v[158:161], v[182:185], v[76:79]
	v_mfma_f32_16x16x32_bf16 v[72:75], v[146:149], v[190:193], v[72:75]
	v_mfma_f32_16x16x32_bf16 v[68:71], v[158:161], v[190:193], v[68:71]
	v_mfma_f32_16x16x32_bf16 v[32:35], v[194:197], v[162:165], v[32:35]
	v_mfma_f32_16x16x32_bf16 v[28:31], v[202:205], v[162:165], v[28:31]
	v_mfma_f32_16x16x32_bf16 v[24:27], v[194:197], v[170:173], v[24:27]
	v_mfma_f32_16x16x32_bf16 v[20:23], v[202:205], v[170:173], v[20:23]
	v_mfma_f32_16x16x32_bf16 v[16:19], v[194:197], v[178:181], v[16:19]
	v_mfma_f32_16x16x32_bf16 v[12:15], v[202:205], v[178:181], v[12:15]
	v_mfma_f32_16x16x32_bf16 v[8:11], v[194:197], v[186:189], v[8:11]
	v_mfma_f32_16x16x32_bf16 v[4:7], v[202:205], v[186:189], v[4:7]
	v_mfma_f32_16x16x32_bf16 v[32:35], v[198:201], v[166:169], v[32:35]
	v_mfma_f32_16x16x32_bf16 v[28:31], v[206:209], v[166:169], v[28:31]
	v_mfma_f32_16x16x32_bf16 v[24:27], v[198:201], v[174:177], v[24:27]
	v_mfma_f32_16x16x32_bf16 v[20:23], v[206:209], v[174:177], v[20:23]
	v_mfma_f32_16x16x32_bf16 v[16:19], v[198:201], v[182:185], v[16:19]
	v_mfma_f32_16x16x32_bf16 v[12:15], v[206:209], v[182:185], v[12:15]
	v_mfma_f32_16x16x32_bf16 v[8:11], v[198:201], v[190:193], v[8:11]
	v_mfma_f32_16x16x32_bf16 v[4:7], v[206:209], v[190:193], v[4:7]
	s_barrier
	s_setprio 0
.LBB0_491:
	s_setprio 0
	s_add_u32 s6, s4, 0xfff80080
	s_addc_u32 s7, s5, -1
	s_add_i32 s68, 0, 0x10000
	v_add_u32_e32 v154, s68, v1
	ds_read_b128 v[142:145], v154
	ds_read_b128 v[146:149], v154 offset:1024
	ds_read_b128 v[150:153], v154 offset:2048
	ds_read_b128 v[158:161], v154 offset:3072
	s_cmp_eq_u32 s67, 60
	s_cselect_b32 s15, s18, s7
	s_cselect_b32 s14, s19, s6
	s_cselect_b32 s7, s51, s66
	s_cselect_b32 s6, s53, s65
	ds_read_b128 v[162:165], v156
	ds_read_b128 v[166:169], v156 offset:1024
	ds_read_b128 v[170:173], v156 offset:2048
	ds_read_b128 v[174:177], v156 offset:3072
	ds_read_b128 v[178:181], v156 offset:4096
	ds_read_b128 v[182:185], v156 offset:5120
	ds_read_b128 v[186:189], v156 offset:6144
	ds_read_b128 v[190:193], v156 offset:7168
	s_add_i32 s70, 0, 0x14000
	v_add_u32_e32 v154, s70, v1
	ds_read_b128 v[194:197], v154
	ds_read_b128 v[198:201], v154 offset:1024
	ds_read_b128 v[202:205], v154 offset:2048
	ds_read_b128 v[206:209], v154 offset:3072
	s_add_i32 m0, s30, 0xc000
	s_nop 0
	global_load_lds_dwordx4 v138, s[4:5]
	s_add_i32 m0, s30, 0xe000
	s_nop 0
	global_load_lds_dwordx4 v140, s[4:5]
	s_waitcnt lgkmcnt(0)
	s_waitcnt vmcnt(8)
	s_setprio 1
	s_barrier
; #define PG8_STAGE(bufoff, gbase, voff) do { _Pragma("unroll") for (int _i = 0; _i < 2; ++_i) \
;         __builtin_amdgcn_global_load_lds((const unsigned*)((const char*)(gbase) + (voff)[_i]), (LAS unsigned*)(lds + (bufoff) + ldsw + _i * 8192), 16, 0, 0); } while (0)
; #define PG8_LDA(dst, b, h) do { _Pragma("unroll") for (int m = 0; m < 4; ++m) _Pragma("unroll") for (int k = 0; k < 2; ++k) dst[m][k] = *(const LAS bf16x8*)(lds + PG8_SA(b, h) + aoff + m * 2048 + k * 1024); } while (0)
; #define PG8_LDB(dst, b, h) do { _Pragma("unroll") for (int n = 0; n < 2; ++n) _Pragma("unroll") for (int k = 0; k < 2; ++k) dst[n][k] = *(const LAS bf16x8*)(lds + PG8_SB(b, h) + boff + n * 2048 + k * 1024); } while (0)
; #define PG8_MMA(ai, bj, At, Bt) do { __builtin_amdgcn_s_setprio(1); _Pragma("unroll") for (int m = 0; m < 4; ++m) _Pragma("unroll") for (int n = 0; n < 2; ++n) _Pragma("unroll") for (int k = 0; k < 2; ++k) \
;         acc[ai][bj][m][n] = __builtin_amdgcn_mfma_f32_16x16x32_bf16(Bt[n][k], At[m][k], acc[ai][bj][m][n], 0, 0, 0); __builtin_amdgcn_s_setprio(0); } while (0)
; #define PG8_WAIT_V(n) asm volatile("s_waitcnt vmcnt(" #n ")" ::: "memory")
; #define PG8_WAIT_L(n) asm volatile("s_waitcnt lgkmcnt(" #n ")" ::: "memory")
; #define PG8_BAR __builtin_amdgcn_s_barrier()
; #define PG8_SCHED __builtin_amdgcn_sched_barrier(0)
; template <class Epi, class Sched>
; __device__ __forceinline__ void gemm_phase(LAS unsigned char* lds, const Gemm g, const Sched& S, const Epi& E) {
;     ...
;             PG8_WAIT_L(8); PG8_BAR; PG8_WAIT_L(0); PG8_MMA(0, 0, At, B0); PG8_BAR; PG8_SCHED;
;             PG8_LDB(B1, 0, 1); PG8_STAGE(PG8_SB(0, 0), b2, voffB);
;             PG8_BAR; PG8_WAIT_L(0); PG8_MMA(0, 1, At, B1); PG8_BAR;
;             PG8_LDA(At, 0, 1); PG8_STAGE(PG8_SA(0, 0), a2, voffA);
;             PG8_BAR; PG8_WAIT_L(0); PG8_MMA(1, 0, At, B0); PG8_BAR; PG8_SCHED;
;             PG8_STAGE(PG8_SB(0, 1), b2 + hstepB, voffB);
;             PG8_WAIT_V(6); PG8_BAR; PG8_MMA(1, 1, At, B1); PG8_BAR;
	v_mfma_f32_16x16x32_bf16 v[128:131], v[142:145], v[162:165], v[128:131]
	v_mfma_f32_16x16x32_bf16 v[124:127], v[150:153], v[162:165], v[124:127]
	v_mfma_f32_16x16x32_bf16 v[120:123], v[142:145], v[170:173], v[120:123]
	v_mfma_f32_16x16x32_bf16 v[116:119], v[150:153], v[170:173], v[116:119]
	v_mfma_f32_16x16x32_bf16 v[112:115], v[142:145], v[178:181], v[112:115]
	v_mfma_f32_16x16x32_bf16 v[108:111], v[150:153], v[178:181], v[108:111]
	v_mfma_f32_16x16x32_bf16 v[104:107], v[142:145], v[186:189], v[104:107]
	v_mfma_f32_16x16x32_bf16 v[100:103], v[150:153], v[186:189], v[100:103]
	v_mfma_f32_16x16x32_bf16 v[128:131], v[146:149], v[166:169], v[128:131]
	v_mfma_f32_16x16x32_bf16 v[124:127], v[158:161], v[166:169], v[124:127]
	v_mfma_f32_16x16x32_bf16 v[120:123], v[146:149], v[174:177], v[120:123]
	v_mfma_f32_16x16x32_bf16 v[116:119], v[158:161], v[174:177], v[116:119]
	v_mfma_f32_16x16x32_bf16 v[112:115], v[146:149], v[182:185], v[112:115]
	v_mfma_f32_16x16x32_bf16 v[108:111], v[158:161], v[182:185], v[108:111]
	v_mfma_f32_16x16x32_bf16 v[104:107], v[146:149], v[190:193], v[104:107]
	v_mfma_f32_16x16x32_bf16 v[100:103], v[158:161], v[190:193], v[100:103]
	v_mfma_f32_16x16x32_bf16 v[64:67], v[194:197], v[162:165], v[64:67]
	v_mfma_f32_16x16x32_bf16 v[60:63], v[202:205], v[162:165], v[60:63]
	v_mfma_f32_16x16x32_bf16 v[56:59], v[194:197], v[170:173], v[56:59]
	v_mfma_f32_16x16x32_bf16 v[52:55], v[202:205], v[170:173], v[52:55]
	v_mfma_f32_16x16x32_bf16 v[48:51], v[194:197], v[178:181], v[48:51]
	v_mfma_f32_16x16x32_bf16 v[44:47], v[202:205], v[178:181], v[44:47]
	v_mfma_f32_16x16x32_bf16 v[40:43], v[194:197], v[186:189], v[40:43]
	v_mfma_f32_16x16x32_bf16 v[36:39], v[202:205], v[186:189], v[36:39]
	v_mfma_f32_16x16x32_bf16 v[64:67], v[198:201], v[166:169], v[64:67]
	v_mfma_f32_16x16x32_bf16 v[60:63], v[206:209], v[166:169], v[60:63]
	v_mfma_f32_16x16x32_bf16 v[56:59], v[198:201], v[174:177], v[56:59]
	v_mfma_f32_16x16x32_bf16 v[52:55], v[206:209], v[174:177], v[52:55]
	v_mfma_f32_16x16x32_bf16 v[48:51], v[198:201], v[182:185], v[48:51]
	v_mfma_f32_16x16x32_bf16 v[44:47], v[206:209], v[182:185], v[44:47]
	v_mfma_f32_16x16x32_bf16 v[40:43], v[198:201], v[190:193], v[40:43]
	v_mfma_f32_16x16x32_bf16 v[36:39], v[206:209], v[190:193], v[36:39]
	s_barrier
	s_setprio 0
	ds_read_b128 v[162:165], v156 offset:16384
	ds_read_b128 v[166:169], v156 offset:17408
	ds_read_b128 v[170:173], v156 offset:18432
	ds_read_b128 v[174:177], v156 offset:19456
	ds_read_b128 v[178:181], v156 offset:20480
	ds_read_b128 v[182:185], v156 offset:21504
	ds_read_b128 v[186:189], v156 offset:22528
	ds_read_b128 v[190:193], v156 offset:23552
	s_add_i32 s68, s68, s29
	v_lshl_add_u64 v[154:155], s[6:7], 0, v[2:3]
	s_mov_b32 m0, s68
	v_lshl_add_u64 v[210:211], s[6:7], 0, v[136:137]
	global_load_lds_dwordx4 v[154:155], off
	s_add_i32 m0, s68, 0x2000
	s_nop 0
	global_load_lds_dwordx4 v[210:211], off
	s_mov_b32 m0, s30
	v_lshl_add_u64 v[212:213], s[14:15], 0, v[132:133]
	global_load_lds_dwordx4 v[212:213], off
	v_lshl_add_u64 v[216:217], s[14:15], 0, v[134:135]
	s_mov_b32 m0, s31
	s_nop 0
	global_load_lds_dwordx4 v[216:217], off
	s_add_u32 s68, s6, 0x100000
	s_addc_u32 s69, s7, 0
	s_add_i32 s70, s70, s29
	s_mov_b32 m0, s70
	s_nop 0
	global_load_lds_dwordx4 v2, s[68:69]
	s_add_i32 m0, s70, 0x2000
	s_nop 0
	global_load_lds_dwordx4 v136, s[68:69]
	s_waitcnt lgkmcnt(0)
	s_waitcnt vmcnt(8)
	s_setprio 1
	s_barrier
	v_mfma_f32_16x16x32_bf16 v[96:99], v[142:145], v[162:165], v[96:99]
	v_mfma_f32_16x16x32_bf16 v[92:95], v[150:153], v[162:165], v[92:95]
	v_mfma_f32_16x16x32_bf16 v[88:91], v[142:145], v[170:173], v[88:91]
	v_mfma_f32_16x16x32_bf16 v[84:87], v[150:153], v[170:173], v[84:87]
	v_mfma_f32_16x16x32_bf16 v[80:83], v[142:145], v[178:181], v[80:83]
	v_mfma_f32_16x16x32_bf16 v[76:79], v[150:153], v[178:181], v[76:79]
	v_mfma_f32_16x16x32_bf16 v[72:75], v[142:145], v[186:189], v[72:75]
	v_mfma_f32_16x16x32_bf16 v[68:71], v[150:153], v[186:189], v[68:71]
	v_mfma_f32_16x16x32_bf16 v[96:99], v[146:149], v[166:169], v[96:99]
	v_mfma_f32_16x16x32_bf16 v[92:95], v[158:161], v[166:169], v[92:95]
	v_mfma_f32_16x16x32_bf16 v[88:91], v[146:149], v[174:177], v[88:91]
	v_mfma_f32_16x16x32_bf16 v[84:87], v[158:161], v[174:177], v[84:87]
	v_mfma_f32_16x16x32_bf16 v[80:83], v[146:149], v[182:185], v[80:83]
	v_mfma_f32_16x16x32_bf16 v[76:79], v[158:161], v[182:185], v[76:79]
	v_mfma_f32_16x16x32_bf16 v[72:75], v[146:149], v[190:193], v[72:75]
	v_mfma_f32_16x16x32_bf16 v[68:71], v[158:161], v[190:193], v[68:71]
	v_mfma_f32_16x16x32_bf16 v[32:35], v[194:197], v[162:165], v[32:35]
	v_mfma_f32_16x16x32_bf16 v[28:31], v[202:205], v[162:165], v[28:31]
	v_mfma_f32_16x16x32_bf16 v[24:27], v[194:197], v[170:173], v[24:27]
	v_mfma_f32_16x16x32_bf16 v[20:23], v[202:205], v[170:173], v[20:23]
	v_mfma_f32_16x16x32_bf16 v[16:19], v[194:197], v[178:181], v[16:19]
	v_mfma_f32_16x16x32_bf16 v[12:15], v[202:205], v[178:181], v[12:15]
	v_mfma_f32_16x16x32_bf16 v[8:11], v[194:197], v[186:189], v[8:11]
	v_mfma_f32_16x16x32_bf16 v[4:7], v[202:205], v[186:189], v[4:7]
	v_mfma_f32_16x16x32_bf16 v[32:35], v[198:201], v[166:169], v[32:35]
	v_mfma_f32_16x16x32_bf16 v[28:31], v[206:209], v[166:169], v[28:31]
	v_mfma_f32_16x16x32_bf16 v[24:27], v[198:201], v[174:177], v[24:27]
	v_mfma_f32_16x16x32_bf16 v[20:23], v[206:209], v[174:177], v[20:23]
	v_mfma_f32_16x16x32_bf16 v[16:19], v[198:201], v[182:185], v[16:19]
	v_mfma_f32_16x16x32_bf16 v[12:15], v[206:209], v[182:185], v[12:15]
	v_mfma_f32_16x16x32_bf16 v[8:11], v[198:201], v[190:193], v[8:11]
	v_mfma_f32_16x16x32_bf16 v[4:7], v[206:209], v[190:193], v[4:7]
	s_barrier
; #define PG8_STAGE(bufoff, gbase, voff) do { _Pragma("unroll") for (int _i = 0; _i < 2; ++_i) \
;         __builtin_amdgcn_global_load_lds((const unsigned*)((const char*)(gbase) + (voff)[_i]), (LAS unsigned*)(lds + (bufoff) + ldsw + _i * 8192), 16, 0, 0); } while (0)
; #define PG8_LDA(dst, b, h) do { _Pragma("unroll") for (int m = 0; m < 4; ++m) _Pragma("unroll") for (int k = 0; k < 2; ++k) dst[m][k] = *(const LAS bf16x8*)(lds + PG8_SA(b, h) + aoff + m * 2048 + k * 1024); } while (0)
; #define PG8_LDB(dst, b, h) do { _Pragma("unroll") for (int n = 0; n < 2; ++n) _Pragma("unroll") for (int k = 0; k < 2; ++k) dst[n][k] = *(const LAS bf16x8*)(lds + PG8_SB(b, h) + boff + n * 2048 + k * 1024); } while (0)
; #define PG8_MMA(ai, bj, At, Bt) do { __builtin_amdgcn_s_setprio(1); _Pragma("unroll") for (int m = 0; m < 4; ++m) _Pragma("unroll") for (int n = 0; n < 2; ++n) _Pragma("unroll") for (int k = 0; k < 2; ++k) \
;         acc[ai][bj][m][n] = __builtin_amdgcn_mfma_f32_16x16x32_bf16(Bt[n][k], At[m][k], acc[ai][bj][m][n], 0, 0, 0); __builtin_amdgcn_s_setprio(0); } while (0)
; #define PG8_WAIT_L(n) asm volatile("s_waitcnt lgkmcnt(" #n ")" ::: "memory")
; #define PG8_BAR __builtin_amdgcn_s_barrier()
; #define PG8_SCHED __builtin_amdgcn_sched_barrier(0)
; template <class Epi, class Sched>
; __device__ __forceinline__ void gemm_phase(LAS unsigned char* lds, const Gemm g, const Sched& S, const Epi& E) {
;     ...
;             PG8_LDB(B0, 1, 0); PG8_SCHED; PG8_LDA(At, 1, 0); PG8_STAGE(PG8_SA(0, 1), a2 + hstepA, voffA);
;             PG8_WAIT_L(8); PG8_BAR; PG8_WAIT_L(0); PG8_MMA(0, 0, At, B0); PG8_BAR; PG8_SCHED;
;             PG8_LDB(B1, 1, 1); PG8_STAGE(PG8_SB(1, 0), b3, voffB);
;             PG8_BAR; PG8_WAIT_L(0); PG8_MMA(0, 1, At, B1); PG8_BAR;
	s_setprio 0
	s_add_i32 s68, 0, 0x18000
	v_add_u32_e32 v157, s68, v1
	ds_read_b128 v[142:145], v157
	ds_read_b128 v[146:149], v157 offset:1024
	ds_read_b128 v[150:153], v157 offset:2048
	ds_read_b128 v[158:161], v157 offset:3072
	s_add_u32 s14, s14, 0x80000
	s_addc_u32 s15, s15, 0
	ds_read_b128 v[162:165], v156 offset:32768
	ds_read_b128 v[166:169], v156 offset:33792
	ds_read_b128 v[170:173], v156 offset:34816
	ds_read_b128 v[174:177], v156 offset:35840
	ds_read_b128 v[178:181], v156 offset:36864
	ds_read_b128 v[182:185], v156 offset:37888
	ds_read_b128 v[186:189], v156 offset:38912
	ds_read_b128 v[190:193], v156 offset:39936
	s_mov_b32 m0, s38
	s_nop 0
	global_load_lds_dwordx4 v132, s[14:15]
	s_mov_b32 m0, s39
	s_nop 0
	global_load_lds_dwordx4 v134, s[14:15]
	s_add_i32 s14, 0, 0x1c000
	v_add_u32_e32 v157, s14, v1
	ds_read_b128 v[194:197], v157
	ds_read_b128 v[198:201], v157 offset:1024
	ds_read_b128 v[202:205], v157 offset:2048
	ds_read_b128 v[206:209], v157 offset:3072
	s_waitcnt lgkmcnt(0)
	s_waitcnt vmcnt(8)
	s_setprio 1
	s_barrier
	v_mfma_f32_16x16x32_bf16 v[128:131], v[142:145], v[162:165], v[128:131]
	v_mfma_f32_16x16x32_bf16 v[124:127], v[150:153], v[162:165], v[124:127]
	v_mfma_f32_16x16x32_bf16 v[120:123], v[142:145], v[170:173], v[120:123]
	v_mfma_f32_16x16x32_bf16 v[116:119], v[150:153], v[170:173], v[116:119]
	v_mfma_f32_16x16x32_bf16 v[112:115], v[142:145], v[178:181], v[112:115]
	v_mfma_f32_16x16x32_bf16 v[108:111], v[150:153], v[178:181], v[108:111]
	v_mfma_f32_16x16x32_bf16 v[104:107], v[142:145], v[186:189], v[104:107]
	v_mfma_f32_16x16x32_bf16 v[100:103], v[150:153], v[186:189], v[100:103]
	v_mfma_f32_16x16x32_bf16 v[128:131], v[146:149], v[166:169], v[128:131]
	v_mfma_f32_16x16x32_bf16 v[124:127], v[158:161], v[166:169], v[124:127]
	v_mfma_f32_16x16x32_bf16 v[120:123], v[146:149], v[174:177], v[120:123]
	v_mfma_f32_16x16x32_bf16 v[116:119], v[158:161], v[174:177], v[116:119]
	v_mfma_f32_16x16x32_bf16 v[112:115], v[146:149], v[182:185], v[112:115]
	v_mfma_f32_16x16x32_bf16 v[108:111], v[158:161], v[182:185], v[108:111]
	v_mfma_f32_16x16x32_bf16 v[104:107], v[146:149], v[190:193], v[104:107]
	v_mfma_f32_16x16x32_bf16 v[100:103], v[158:161], v[190:193], v[100:103]
	v_mfma_f32_16x16x32_bf16 v[64:67], v[194:197], v[162:165], v[64:67]
	v_mfma_f32_16x16x32_bf16 v[60:63], v[202:205], v[162:165], v[60:63]
	v_mfma_f32_16x16x32_bf16 v[56:59], v[194:197], v[170:173], v[56:59]
	v_mfma_f32_16x16x32_bf16 v[52:55], v[202:205], v[170:173], v[52:55]
	v_mfma_f32_16x16x32_bf16 v[48:51], v[194:197], v[178:181], v[48:51]
	v_mfma_f32_16x16x32_bf16 v[44:47], v[202:205], v[178:181], v[44:47]
	v_mfma_f32_16x16x32_bf16 v[40:43], v[194:197], v[186:189], v[40:43]
	v_mfma_f32_16x16x32_bf16 v[36:39], v[202:205], v[186:189], v[36:39]
	v_mfma_f32_16x16x32_bf16 v[64:67], v[198:201], v[166:169], v[64:67]
	v_mfma_f32_16x16x32_bf16 v[60:63], v[206:209], v[166:169], v[60:63]
	v_mfma_f32_16x16x32_bf16 v[56:59], v[198:201], v[174:177], v[56:59]
	v_mfma_f32_16x16x32_bf16 v[52:55], v[206:209], v[174:177], v[52:55]
	v_mfma_f32_16x16x32_bf16 v[48:51], v[198:201], v[182:185], v[48:51]
	v_mfma_f32_16x16x32_bf16 v[44:47], v[206:209], v[182:185], v[44:47]
	v_mfma_f32_16x16x32_bf16 v[40:43], v[198:201], v[190:193], v[40:43]
	v_mfma_f32_16x16x32_bf16 v[36:39], v[206:209], v[190:193], v[36:39]
	s_barrier
; __device__ __forceinline__ int opaque_tid() { int t = threadIdx.x; asm volatile("" : "+v"(t)); return t; }
; #define PG8_STAGE(bufoff, gbase, voff) do { _Pragma("unroll") for (int _i = 0; _i < 2; ++_i) \
;         __builtin_amdgcn_global_load_lds((const unsigned*)((const char*)(gbase) + (voff)[_i]), (LAS unsigned*)(lds + (bufoff) + ldsw + _i * 8192), 16, 0, 0); } while (0)
; #define PG8_LDA(dst, b, h) do { _Pragma("unroll") for (int m = 0; m < 4; ++m) _Pragma("unroll") for (int k = 0; k < 2; ++k) dst[m][k] = *(const LAS bf16x8*)(lds + PG8_SA(b, h) + aoff + m * 2048 + k * 1024); } while (0)
; #define PG8_MMA(ai, bj, At, Bt) do { __builtin_amdgcn_s_setprio(1); _Pragma("unroll") for (int m = 0; m < 4; ++m) _Pragma("unroll") for (int n = 0; n < 2; ++n) _Pragma("unroll") for (int k = 0; k < 2; ++k) \
;         acc[ai][bj][m][n] = __builtin_amdgcn_mfma_f32_16x16x32_bf16(Bt[n][k], At[m][k], acc[ai][bj][m][n], 0, 0, 0); __builtin_amdgcn_s_setprio(0); } while (0)
; #define PG8_WAIT_V(n) asm volatile("s_waitcnt vmcnt(" #n ")" ::: "memory")
; #define PG8_WAIT_L(n) asm volatile("s_waitcnt lgkmcnt(" #n ")" ::: "memory")
; #define PG8_BAR __builtin_amdgcn_s_barrier()
; #define PG8_SCHED __builtin_amdgcn_sched_barrier(0)
; template <class Epi, class Sched>
; __device__ __forceinline__ void gemm_phase(LAS unsigned char* lds, const Gemm g, const Sched& S, const Epi& E) {
;     ...
;             PG8_LDA(At, 1, 1); PG8_STAGE(PG8_SA(1, 0), a3, voffA);
;             PG8_BAR; PG8_WAIT_L(0); PG8_MMA(1, 0, At, B0); PG8_BAR; PG8_SCHED;
;             PG8_STAGE(PG8_SB(1, 1), b3 + hstepB, voffB);
;             PG8_WAIT_V(6); PG8_BAR; PG8_MMA(1, 1, At, B1); PG8_BAR;
;     __device__ __forceinline__ void operator()(const f32x4 (&acc)[2][2][4][2], const Unit& u, int wr, int wc, int, int) const {
;         const int ol_ = opaque_tid() & 63, fr = ol_ & 15, fq = ol_ >> 4;
;         const int row0 = u.pm * BM + wr * 64 + fr, col0 = u.pn * BM + wc * 32 + 8 * fq;
; #pragma unroll
;         for (int bj = 0; bj < 2; ++bj) { f32x4 b0 = (f32x4){0.f, 0.f, 0.f, 0.f}, b1 = b0;
; #pragma unroll 8
;             for (int pp = 0; pp < 32; ++pp) { b0 += *(const f32x4*)(bias + pp * 256 + col0 + bj * HALF); b1 += *(const f32x4*)(bias + pp * 256 + col0 + bj * HALF + 4); }
	s_setprio 0
	ds_read_b128 v[162:165], v156 offset:49152
	ds_read_b128 v[166:169], v156 offset:50176
	ds_read_b128 v[170:173], v156 offset:51200
	ds_read_b128 v[174:177], v156 offset:52224
	ds_read_b128 v[178:181], v156 offset:53248
	ds_read_b128 v[182:185], v156 offset:54272
	ds_read_b128 v[186:189], v156 offset:55296
	ds_read_b128 v[190:193], v156 offset:56320
	s_add_i32 s15, s68, s29
	v_lshl_add_u64 v[154:155], v[154:155], 0, s[8:9]
	s_mov_b32 m0, s15
	s_nop 0
	global_load_lds_dwordx4 v[154:155], off
	v_lshl_add_u64 v[154:155], v[210:211], 0, s[8:9]
	s_add_i32 m0, s15, 0x2000
	s_nop 0
	global_load_lds_dwordx4 v[154:155], off
	s_mov_b32 m0, s62
	v_lshl_add_u64 v[154:155], v[212:213], 0, s[8:9]
	global_load_lds_dwordx4 v[154:155], off
	v_lshl_add_u64 v[154:155], v[216:217], 0, s[8:9]
	s_mov_b32 m0, s63
	s_nop 0
	global_load_lds_dwordx4 v[154:155], off
	s_add_u32 s6, s6, 0x100080
	s_addc_u32 s7, s7, 0
	s_add_i32 s14, s14, s29
	s_mov_b32 m0, s14
	s_nop 0
	global_load_lds_dwordx4 v2, s[6:7]
	s_add_i32 m0, s14, 0x2000
	s_nop 0
	global_load_lds_dwordx4 v136, s[6:7]
	s_add_i32 s67, s67, 2
	s_add_u32 s4, s4, 0x100
	s_addc_u32 s5, s5, 0
	s_add_u32 s65, s65, 0x100
	s_addc_u32 s66, s66, 0
	s_cmp_gt_u32 s67, 61
	s_waitcnt lgkmcnt(0)
	s_waitcnt vmcnt(8)
	s_setprio 1
	s_barrier
	v_mfma_f32_16x16x32_bf16 v[96:99], v[142:145], v[162:165], v[96:99]
	v_mfma_f32_16x16x32_bf16 v[92:95], v[150:153], v[162:165], v[92:95]
	v_mfma_f32_16x16x32_bf16 v[88:91], v[142:145], v[170:173], v[88:91]
	v_mfma_f32_16x16x32_bf16 v[84:87], v[150:153], v[170:173], v[84:87]
	v_mfma_f32_16x16x32_bf16 v[80:83], v[142:145], v[178:181], v[80:83]
	v_mfma_f32_16x16x32_bf16 v[76:79], v[150:153], v[178:181], v[76:79]
	v_mfma_f32_16x16x32_bf16 v[72:75], v[142:145], v[186:189], v[72:75]
	v_mfma_f32_16x16x32_bf16 v[68:71], v[150:153], v[186:189], v[68:71]
	v_mfma_f32_16x16x32_bf16 v[96:99], v[146:149], v[166:169], v[96:99]
	v_mfma_f32_16x16x32_bf16 v[92:95], v[158:161], v[166:169], v[92:95]
	v_mfma_f32_16x16x32_bf16 v[88:91], v[146:149], v[174:177], v[88:91]
	v_mfma_f32_16x16x32_bf16 v[84:87], v[158:161], v[174:177], v[84:87]
	v_mfma_f32_16x16x32_bf16 v[80:83], v[146:149], v[182:185], v[80:83]
	v_mfma_f32_16x16x32_bf16 v[76:79], v[158:161], v[182:185], v[76:79]
	v_mfma_f32_16x16x32_bf16 v[72:75], v[146:149], v[190:193], v[72:75]
	v_mfma_f32_16x16x32_bf16 v[68:71], v[158:161], v[190:193], v[68:71]
	v_mfma_f32_16x16x32_bf16 v[32:35], v[194:197], v[162:165], v[32:35]
	v_mfma_f32_16x16x32_bf16 v[28:31], v[202:205], v[162:165], v[28:31]
	v_mfma_f32_16x16x32_bf16 v[24:27], v[194:197], v[170:173], v[24:27]
	v_mfma_f32_16x16x32_bf16 v[20:23], v[202:205], v[170:173], v[20:23]
	v_mfma_f32_16x16x32_bf16 v[16:19], v[194:197], v[178:181], v[16:19]
	v_mfma_f32_16x16x32_bf16 v[12:15], v[202:205], v[178:181], v[12:15]
	v_mfma_f32_16x16x32_bf16 v[8:11], v[194:197], v[186:189], v[8:11]
	v_mfma_f32_16x16x32_bf16 v[4:7], v[202:205], v[186:189], v[4:7]
	v_mfma_f32_16x16x32_bf16 v[32:35], v[198:201], v[166:169], v[32:35]
	v_mfma_f32_16x16x32_bf16 v[28:31], v[206:209], v[166:169], v[28:31]
	v_mfma_f32_16x16x32_bf16 v[24:27], v[198:201], v[174:177], v[24:27]
	v_mfma_f32_16x16x32_bf16 v[20:23], v[206:209], v[174:177], v[20:23]
	v_mfma_f32_16x16x32_bf16 v[16:19], v[198:201], v[182:185], v[16:19]
	v_mfma_f32_16x16x32_bf16 v[12:15], v[206:209], v[182:185], v[12:15]
	v_mfma_f32_16x16x32_bf16 v[8:11], v[198:201], v[190:193], v[8:11]
	v_mfma_f32_16x16x32_bf16 v[4:7], v[206:209], v[190:193], v[4:7]
	s_barrier
	s_cbranch_scc0 .LBB0_491
	s_setprio 0
	v_mov_b32_e32 v157, v0
	s_lshl_b32 s1, s1, 8
	v_lshrrev_b32_e32 v142, 1, v157
	v_and_or_b32 v142, v142, 24, s1
	v_or_b32_e32 v154, s61, v142
	v_ashrrev_i32_e32 v155, 31, v154
	v_mov_b32_e32 v144, 0
	v_lshl_add_u64 v[142:143], v[154:155], 2, s[46:47]
	s_mov_b64 s[4:5], 0
	v_mov_b32_e32 v145, v144
	v_mov_b32_e32 v146, v144
	v_mov_b32_e32 v147, v144
	v_mov_b32_e32 v148, v144
	v_mov_b32_e32 v149, v144
	v_mov_b32_e32 v150, v144
	v_mov_b32_e32 v151, v144

; #define PG8_STAGE(bufoff, gbase, voff) do { _Pragma("unroll") for (int _i = 0; _i < 2; ++_i) \
;         __builtin_amdgcn_global_load_lds((const unsigned*)((const char*)(gbase) + (voff)[_i]), (LAS unsigned*)(lds + (bufoff) + ldsw + _i * 8192), 16, 0, 0); } while (0)
; #define PG8_LDA(dst, b, h) do { _Pragma("unroll") for (int m = 0; m < 4; ++m) _Pragma("unroll") for (int k = 0; k < 2; ++k) dst[m][k] = *(const LAS bf16x8*)(lds + PG8_SA(b, h) + aoff + m * 2048 + k * 1024); } while (0)
; #define PG8_LDB(dst, b, h) do { _Pragma("unroll") for (int n = 0; n < 2; ++n) _Pragma("unroll") for (int k = 0; k < 2; ++k) dst[n][k] = *(const LAS bf16x8*)(lds + PG8_SB(b, h) + boff + n * 2048 + k * 1024); } while (0)
; #define PG8_WAIT_V(n) asm volatile("s_waitcnt vmcnt(" #n ")" ::: "memory")
; #define PG8_WAIT_L(n) asm volatile("s_waitcnt lgkmcnt(" #n ")" ::: "memory")
; #define PG8_BAR __builtin_amdgcn_s_barrier()
; #define PG8_SCHED __builtin_amdgcn_sched_barrier(0)
; template <class Epi, class Sched>
; __device__ __forceinline__ void gemm_phase(LAS unsigned char* lds, const Gemm g, const Sched& S, const Epi& E) {
;     ...
;         const bool has_next = S.next(ui + 1, nxt);
;         const char* nA = has_next ? (const char*)g.A + (size_t)nxt.pm * tstepA : cA; const char* nB = has_next ? (const char*)g.Bt + (size_t)nxt.pn * tstepB : cB;
;         for (int t = 0; t < nt; t += 2) {
;             const bool last = (t == nt - 2);
;             const char* a1 = cA + (size_t)(t + 1) * kstep;
;             const char* a2 = last ? nA : cA + (size_t)(t + 2) * kstep; const char* b2 = last ? nB : cB + (size_t)(t + 2) * kstep;
;             const char* a3 = a2 + kstep; const char* b3 = b2 + kstep;
;             if (last && has_next) S.a_ready(nxt);
;             PG8_LDB(B0, 0, 0); PG8_SCHED; PG8_LDA(At, 0, 0); PG8_STAGE(PG8_SA(1, 1), a1 + hstepA, voffA);
;             PG8_WAIT_L(8); PG8_BAR; PG8_WAIT_L(0); PG8_MMA(0, 0, At, B0); PG8_BAR; PG8_SCHED;
;             PG8_LDB(B1, 0, 1); PG8_STAGE(PG8_SB(0, 0), b2, voffB);
;             PG8_BAR; PG8_WAIT_L(0); PG8_MMA(0, 1, At, B1); PG8_BAR;
;             PG8_LDA(At, 0, 1); PG8_STAGE(PG8_SA(0, 0), a2, voffA);
;             PG8_BAR; PG8_WAIT_L(0); PG8_MMA(1, 0, At, B0); PG8_BAR; PG8_SCHED;
;             PG8_STAGE(PG8_SB(0, 1), b2 + hstepB, voffB);
;             PG8_WAIT_V(6); PG8_BAR; PG8_MMA(1, 1, At, B1); PG8_BAR;
.LBB0_965:
	v_mov_b64_e32 v[4:5], 0x400
	s_ashr_i32 s15, s14, 31
	v_cmp_lt_i64_e32 vcc, s[4:5], v[4:5]
	s_lshl_b64 s[4:5], s[14:15], 20
	v_readlane_b32 s48, v252, 0
	v_readlane_b32 s49, v252, 1
	s_add_u32 s4, s48, s4
	s_addc_u32 s5, s49, s5
	s_and_b64 s[18:19], vcc, exec
	s_cselect_b32 s15, s5, s7
	s_cselect_b32 s47, s4, s6
	s_ashr_i32 s1, s0, 31
	s_lshl_b64 s[18:19], s[0:1], 20
	s_add_u32 s18, s28, s18
	s_addc_u32 s19, s29, s19
	s_and_b64 s[24:25], vcc, exec
	s_cselect_b32 s1, s19, s21
	s_cselect_b32 s48, s18, s20
	s_add_u32 s6, s6, 0x80080
	s_addc_u32 s7, s7, 0
	v_readlane_b32 s50, v252, 2
	v_readlane_b32 s51, v252, 3
	s_add_u32 s49, s20, 0x100
	s_addc_u32 s50, s21, 0
	s_mov_b32 s51, -2
	s_waitcnt lgkmcnt(0)
	s_setprio 0
	s_add_u32 s20, s6, 0xfff80080
	s_addc_u32 s21, s7, -1
	s_add_i32 s52, 0, 0x10000
	v_add_u32_e32 v144, s52, v1
	ds_read_b128 v[132:135], v144
	ds_read_b128 v[136:139], v144 offset:1024
	ds_read_b128 v[140:143], v144 offset:2048
	ds_read_b128 v[144:147], v144 offset:3072
	s_cmp_eq_u32 s51, 28
	s_cselect_b32 s25, s15, s21
	s_cselect_b32 s24, s47, s20
	s_cselect_b32 s21, s1, s50
	s_cselect_b32 s20, s48, s49
	ds_read_b128 v[148:151], v224
	ds_read_b128 v[152:155], v224 offset:1024
	ds_read_b128 v[156:159], v224 offset:2048
	ds_read_b128 v[160:163], v224 offset:3072
	ds_read_b128 v[164:167], v224 offset:4096
	ds_read_b128 v[168:171], v224 offset:5120
	ds_read_b128 v[172:175], v224 offset:6144
	ds_read_b128 v[176:179], v224 offset:7168
	s_add_i32 s54, 0, 0x14000
	v_add_u32_e32 v202, s54, v1
	ds_read_b128 v[180:183], v202
	ds_read_b128 v[184:187], v202 offset:1024
	ds_read_b128 v[188:191], v202 offset:2048
	ds_read_b128 v[202:205], v202 offset:3072
	s_add_i32 m0, s31, 0xc000
	s_nop 0
	global_load_lds_dwordx4 v198, s[6:7]
	s_add_i32 m0, s31, 0xe000
	s_nop 0
	global_load_lds_dwordx4 v200, s[6:7]
	s_waitcnt lgkmcnt(0)
	s_waitcnt vmcnt(8)
	s_setprio 1
	s_barrier
	v_mfma_f32_16x16x32_bf16 v[128:131], v[132:135], v[148:151], 0
	v_mfma_f32_16x16x32_bf16 v[124:127], v[140:143], v[148:151], 0
	v_mfma_f32_16x16x32_bf16 v[112:115], v[132:135], v[156:159], 0
	v_mfma_f32_16x16x32_bf16 v[108:111], v[140:143], v[156:159], 0
	v_mfma_f32_16x16x32_bf16 v[100:103], v[132:135], v[164:167], 0
	v_mfma_f32_16x16x32_bf16 v[92:95], v[140:143], v[164:167], 0
	v_mfma_f32_16x16x32_bf16 v[84:87], v[132:135], v[172:175], 0
	v_mfma_f32_16x16x32_bf16 v[76:79], v[140:143], v[172:175], 0
	v_mfma_f32_16x16x32_bf16 v[128:131], v[136:139], v[152:155], v[128:131]
	v_mfma_f32_16x16x32_bf16 v[124:127], v[144:147], v[152:155], v[124:127]
	v_mfma_f32_16x16x32_bf16 v[112:115], v[136:139], v[160:163], v[112:115]
	v_mfma_f32_16x16x32_bf16 v[108:111], v[144:147], v[160:163], v[108:111]
	v_mfma_f32_16x16x32_bf16 v[100:103], v[136:139], v[168:171], v[100:103]
	v_mfma_f32_16x16x32_bf16 v[92:95], v[144:147], v[168:171], v[92:95]
	v_mfma_f32_16x16x32_bf16 v[84:87], v[136:139], v[176:179], v[84:87]
	v_mfma_f32_16x16x32_bf16 v[76:79], v[144:147], v[176:179], v[76:79]
	v_mfma_f32_16x16x32_bf16 v[120:123], v[180:183], v[148:151], 0
	v_mfma_f32_16x16x32_bf16 v[116:119], v[188:191], v[148:151], 0
	v_mfma_f32_16x16x32_bf16 v[104:107], v[180:183], v[156:159], 0
	v_mfma_f32_16x16x32_bf16 v[96:99], v[188:191], v[156:159], 0
	v_mfma_f32_16x16x32_bf16 v[88:91], v[180:183], v[164:167], 0
	v_mfma_f32_16x16x32_bf16 v[80:83], v[188:191], v[164:167], 0
	v_mfma_f32_16x16x32_bf16 v[72:75], v[180:183], v[172:175], 0
	v_mfma_f32_16x16x32_bf16 v[68:71], v[188:191], v[172:175], 0
	v_mfma_f32_16x16x32_bf16 v[120:123], v[184:187], v[152:155], v[120:123]
	v_mfma_f32_16x16x32_bf16 v[116:119], v[202:205], v[152:155], v[116:119]
	v_mfma_f32_16x16x32_bf16 v[104:107], v[184:187], v[160:163], v[104:107]
	v_mfma_f32_16x16x32_bf16 v[96:99], v[202:205], v[160:163], v[96:99]
	v_mfma_f32_16x16x32_bf16 v[88:91], v[184:187], v[168:171], v[88:91]
	v_mfma_f32_16x16x32_bf16 v[80:83], v[202:205], v[168:171], v[80:83]
	v_mfma_f32_16x16x32_bf16 v[72:75], v[184:187], v[176:179], v[72:75]
	v_mfma_f32_16x16x32_bf16 v[68:71], v[202:205], v[176:179], v[68:71]
	s_barrier
	s_setprio 0
	ds_read_b128 v[148:151], v224 offset:16384
	ds_read_b128 v[152:155], v224 offset:17408
	ds_read_b128 v[156:159], v224 offset:18432
	ds_read_b128 v[160:163], v224 offset:19456
	ds_read_b128 v[164:167], v224 offset:20480
	ds_read_b128 v[168:171], v224 offset:21504
	ds_read_b128 v[172:175], v224 offset:22528
	ds_read_b128 v[176:179], v224 offset:23552
	s_add_i32 s52, s52, s30
	v_lshl_add_u64 v[206:207], s[20:21], 0, v[2:3]
	s_mov_b32 m0, s52
	s_nop 0
	global_load_lds_dwordx4 v[206:207], off
	v_lshl_add_u64 v[208:209], s[20:21], 0, v[192:193]
	s_add_i32 m0, s52, 0x2000
	s_nop 0
	global_load_lds_dwordx4 v[208:209], off
	s_mov_b32 m0, s31
	v_lshl_add_u64 v[210:211], s[24:25], 0, v[196:197]
	global_load_lds_dwordx4 v[210:211], off
	v_lshl_add_u64 v[212:213], s[24:25], 0, v[194:195]
	s_mov_b32 m0, s35
	s_nop 0
	global_load_lds_dwordx4 v[212:213], off
	s_add_u32 s52, s20, 0x80000
	s_addc_u32 s53, s21, 0
	s_add_i32 s54, s54, s30
	s_mov_b32 m0, s54
	s_nop 0
	global_load_lds_dwordx4 v2, s[52:53]
	s_add_i32 m0, s54, 0x2000
	s_nop 0
	global_load_lds_dwordx4 v192, s[52:53]
	s_waitcnt lgkmcnt(0)
	s_waitcnt vmcnt(8)
	s_setprio 1
	s_barrier
; #define PG8_STAGE(bufoff, gbase, voff) do { _Pragma("unroll") for (int _i = 0; _i < 2; ++_i) \
;         __builtin_amdgcn_global_load_lds((const unsigned*)((const char*)(gbase) + (voff)[_i]), (LAS unsigned*)(lds + (bufoff) + ldsw + _i * 8192), 16, 0, 0); } while (0)
; #define PG8_LDA(dst, b, h) do { _Pragma("unroll") for (int m = 0; m < 4; ++m) _Pragma("unroll") for (int k = 0; k < 2; ++k) dst[m][k] = *(const LAS bf16x8*)(lds + PG8_SA(b, h) + aoff + m * 2048 + k * 1024); } while (0)
; #define PG8_LDB(dst, b, h) do { _Pragma("unroll") for (int n = 0; n < 2; ++n) _Pragma("unroll") for (int k = 0; k < 2; ++k) dst[n][k] = *(const LAS bf16x8*)(lds + PG8_SB(b, h) + boff + n * 2048 + k * 1024); } while (0)
; #define PG8_MMA(ai, bj, At, Bt) do { __builtin_amdgcn_s_setprio(1); _Pragma("unroll") for (int m = 0; m < 4; ++m) _Pragma("unroll") for (int n = 0; n < 2; ++n) _Pragma("unroll") for (int k = 0; k < 2; ++k) \
;         acc[ai][bj][m][n] = __builtin_amdgcn_mfma_f32_16x16x32_bf16(Bt[n][k], At[m][k], acc[ai][bj][m][n], 0, 0, 0); __builtin_amdgcn_s_setprio(0); } while (0)
; #define PG8_WAIT_V(n) asm volatile("s_waitcnt vmcnt(" #n ")" ::: "memory")
; #define PG8_WAIT_L(n) asm volatile("s_waitcnt lgkmcnt(" #n ")" ::: "memory")
; #define PG8_BAR __builtin_amdgcn_s_barrier()
; #define PG8_SCHED __builtin_amdgcn_sched_barrier(0)
; template <class Epi, class Sched>
; __device__ __forceinline__ void gemm_phase(LAS unsigned char* lds, const Gemm g, const Sched& S, const Epi& E) {
;     ...
;             PG8_WAIT_V(6); PG8_BAR; PG8_MMA(1, 1, At, B1); PG8_BAR;
;             PG8_LDB(B0, 1, 0); PG8_SCHED; PG8_LDA(At, 1, 0); PG8_STAGE(PG8_SA(0, 1), a2 + hstepA, voffA);
;             PG8_WAIT_L(8); PG8_BAR; PG8_WAIT_L(0); PG8_MMA(0, 0, At, B0); PG8_BAR; PG8_SCHED;
;             PG8_LDB(B1, 1, 1); PG8_STAGE(PG8_SB(1, 0), b3, voffB);
;             PG8_BAR; PG8_WAIT_L(0); PG8_MMA(0, 1, At, B1); PG8_BAR;
;             PG8_LDA(At, 1, 1); PG8_STAGE(PG8_SA(1, 0), a3, voffA);
;             PG8_BAR; PG8_WAIT_L(0); PG8_MMA(1, 0, At, B0); PG8_BAR; PG8_SCHED;
	v_mfma_f32_16x16x32_bf16 v[64:67], v[132:135], v[148:151], 0
	v_mfma_f32_16x16x32_bf16 v[60:63], v[140:143], v[148:151], 0
	v_mfma_f32_16x16x32_bf16 v[52:55], v[132:135], v[156:159], 0
	v_mfma_f32_16x16x32_bf16 v[44:47], v[140:143], v[156:159], 0
	v_mfma_f32_16x16x32_bf16 v[36:39], v[132:135], v[164:167], 0
	v_mfma_f32_16x16x32_bf16 v[28:31], v[140:143], v[164:167], 0
	v_mfma_f32_16x16x32_bf16 v[20:23], v[132:135], v[172:175], 0
	v_mfma_f32_16x16x32_bf16 v[12:15], v[140:143], v[172:175], 0
	v_mfma_f32_16x16x32_bf16 v[64:67], v[136:139], v[152:155], v[64:67]
	v_mfma_f32_16x16x32_bf16 v[60:63], v[144:147], v[152:155], v[60:63]
	v_mfma_f32_16x16x32_bf16 v[52:55], v[136:139], v[160:163], v[52:55]
	v_mfma_f32_16x16x32_bf16 v[44:47], v[144:147], v[160:163], v[44:47]
	v_mfma_f32_16x16x32_bf16 v[36:39], v[136:139], v[168:171], v[36:39]
	v_mfma_f32_16x16x32_bf16 v[28:31], v[144:147], v[168:171], v[28:31]
	v_mfma_f32_16x16x32_bf16 v[20:23], v[136:139], v[176:179], v[20:23]
	v_mfma_f32_16x16x32_bf16 v[12:15], v[144:147], v[176:179], v[12:15]
	v_mfma_f32_16x16x32_bf16 v[56:59], v[180:183], v[148:151], 0
	v_mfma_f32_16x16x32_bf16 v[48:51], v[188:191], v[148:151], 0
	v_mfma_f32_16x16x32_bf16 v[40:43], v[180:183], v[156:159], 0
	v_mfma_f32_16x16x32_bf16 v[32:35], v[188:191], v[156:159], 0
	v_mfma_f32_16x16x32_bf16 v[24:27], v[180:183], v[164:167], 0
	v_mfma_f32_16x16x32_bf16 v[16:19], v[188:191], v[164:167], 0
	v_mfma_f32_16x16x32_bf16 v[8:11], v[180:183], v[172:175], 0
	v_mfma_f32_16x16x32_bf16 v[4:7], v[188:191], v[172:175], 0
	v_mfma_f32_16x16x32_bf16 v[56:59], v[184:187], v[152:155], v[56:59]
	v_mfma_f32_16x16x32_bf16 v[48:51], v[202:205], v[152:155], v[48:51]
	v_mfma_f32_16x16x32_bf16 v[40:43], v[184:187], v[160:163], v[40:43]
	v_mfma_f32_16x16x32_bf16 v[32:35], v[202:205], v[160:163], v[32:35]
	v_mfma_f32_16x16x32_bf16 v[24:27], v[184:187], v[168:171], v[24:27]
	v_mfma_f32_16x16x32_bf16 v[16:19], v[202:205], v[168:171], v[16:19]
	v_mfma_f32_16x16x32_bf16 v[8:11], v[184:187], v[176:179], v[8:11]
	v_mfma_f32_16x16x32_bf16 v[4:7], v[202:205], v[176:179], v[4:7]
	s_barrier
	s_setprio 0
	s_add_i32 s52, 0, 0x18000
	v_add_u32_e32 v144, s52, v1
	ds_read_b128 v[132:135], v144
	ds_read_b128 v[136:139], v144 offset:1024
	ds_read_b128 v[140:143], v144 offset:2048
	ds_read_b128 v[144:147], v144 offset:3072
	s_add_u32 s24, s24, 0x80000
	s_addc_u32 s25, s25, 0
	ds_read_b128 v[148:151], v224 offset:32768
	ds_read_b128 v[152:155], v224 offset:33792
	ds_read_b128 v[156:159], v224 offset:34816
	ds_read_b128 v[160:163], v224 offset:35840
	ds_read_b128 v[164:167], v224 offset:36864
	ds_read_b128 v[168:171], v224 offset:37888
	ds_read_b128 v[172:175], v224 offset:38912
	ds_read_b128 v[176:179], v224 offset:39936
	s_mov_b32 m0, s36
	s_nop 0
	global_load_lds_dwordx4 v196, s[24:25]
	s_mov_b32 m0, s37
	s_nop 0
	global_load_lds_dwordx4 v194, s[24:25]
	s_add_i32 s24, 0, 0x1c000
	v_add_u32_e32 v202, s24, v1
	ds_read_b128 v[180:183], v202
	ds_read_b128 v[184:187], v202 offset:1024
	ds_read_b128 v[188:191], v202 offset:2048
	ds_read_b128 v[202:205], v202 offset:3072
	s_waitcnt lgkmcnt(0)
	s_waitcnt vmcnt(8)
	s_setprio 1
	s_barrier
	v_mfma_f32_16x16x32_bf16 v[128:131], v[132:135], v[148:151], v[128:131]
	v_mfma_f32_16x16x32_bf16 v[124:127], v[140:143], v[148:151], v[124:127]
	v_mfma_f32_16x16x32_bf16 v[112:115], v[132:135], v[156:159], v[112:115]
	v_mfma_f32_16x16x32_bf16 v[108:111], v[140:143], v[156:159], v[108:111]
	v_mfma_f32_16x16x32_bf16 v[100:103], v[132:135], v[164:167], v[100:103]
	v_mfma_f32_16x16x32_bf16 v[92:95], v[140:143], v[164:167], v[92:95]
	v_mfma_f32_16x16x32_bf16 v[84:87], v[132:135], v[172:175], v[84:87]
	v_mfma_f32_16x16x32_bf16 v[76:79], v[140:143], v[172:175], v[76:79]
	v_mfma_f32_16x16x32_bf16 v[128:131], v[136:139], v[152:155], v[128:131]
	v_mfma_f32_16x16x32_bf16 v[124:127], v[144:147], v[152:155], v[124:127]
	v_mfma_f32_16x16x32_bf16 v[112:115], v[136:139], v[160:163], v[112:115]
	v_mfma_f32_16x16x32_bf16 v[108:111], v[144:147], v[160:163], v[108:111]
	v_mfma_f32_16x16x32_bf16 v[100:103], v[136:139], v[168:171], v[100:103]
	v_mfma_f32_16x16x32_bf16 v[92:95], v[144:147], v[168:171], v[92:95]
	v_mfma_f32_16x16x32_bf16 v[84:87], v[136:139], v[176:179], v[84:87]
	v_mfma_f32_16x16x32_bf16 v[76:79], v[144:147], v[176:179], v[76:79]
	v_mfma_f32_16x16x32_bf16 v[120:123], v[180:183], v[148:151], v[120:123]
	v_mfma_f32_16x16x32_bf16 v[116:119], v[188:191], v[148:151], v[116:119]
	v_mfma_f32_16x16x32_bf16 v[104:107], v[180:183], v[156:159], v[104:107]
	v_mfma_f32_16x16x32_bf16 v[96:99], v[188:191], v[156:159], v[96:99]
	v_mfma_f32_16x16x32_bf16 v[88:91], v[180:183], v[164:167], v[88:91]
	v_mfma_f32_16x16x32_bf16 v[80:83], v[188:191], v[164:167], v[80:83]
	v_mfma_f32_16x16x32_bf16 v[72:75], v[180:183], v[172:175], v[72:75]
	v_mfma_f32_16x16x32_bf16 v[68:71], v[188:191], v[172:175], v[68:71]
	v_mfma_f32_16x16x32_bf16 v[120:123], v[184:187], v[152:155], v[120:123]
	v_mfma_f32_16x16x32_bf16 v[116:119], v[202:205], v[152:155], v[116:119]
	v_mfma_f32_16x16x32_bf16 v[104:107], v[184:187], v[160:163], v[104:107]
	v_mfma_f32_16x16x32_bf16 v[96:99], v[202:205], v[160:163], v[96:99]
	v_mfma_f32_16x16x32_bf16 v[88:91], v[184:187], v[168:171], v[88:91]
	v_mfma_f32_16x16x32_bf16 v[80:83], v[202:205], v[168:171], v[80:83]
	v_mfma_f32_16x16x32_bf16 v[72:75], v[184:187], v[176:179], v[72:75]
	v_mfma_f32_16x16x32_bf16 v[68:71], v[202:205], v[176:179], v[68:71]
	s_barrier
; #define PG8_STAGE(bufoff, gbase, voff) do { _Pragma("unroll") for (int _i = 0; _i < 2; ++_i) \
;         __builtin_amdgcn_global_load_lds((const unsigned*)((const char*)(gbase) + (voff)[_i]), (LAS unsigned*)(lds + (bufoff) + ldsw + _i * 8192), 16, 0, 0); } while (0)
; #define PG8_LDA(dst, b, h) do { _Pragma("unroll") for (int m = 0; m < 4; ++m) _Pragma("unroll") for (int k = 0; k < 2; ++k) dst[m][k] = *(const LAS bf16x8*)(lds + PG8_SA(b, h) + aoff + m * 2048 + k * 1024); } while (0)
; #define PG8_LDB(dst, b, h) do { _Pragma("unroll") for (int n = 0; n < 2; ++n) _Pragma("unroll") for (int k = 0; k < 2; ++k) dst[n][k] = *(const LAS bf16x8*)(lds + PG8_SB(b, h) + boff + n * 2048 + k * 1024); } while (0)
; #define PG8_MMA(ai, bj, At, Bt) do { __builtin_amdgcn_s_setprio(1); _Pragma("unroll") for (int m = 0; m < 4; ++m) _Pragma("unroll") for (int n = 0; n < 2; ++n) _Pragma("unroll") for (int k = 0; k < 2; ++k) \
;         acc[ai][bj][m][n] = __builtin_amdgcn_mfma_f32_16x16x32_bf16(Bt[n][k], At[m][k], acc[ai][bj][m][n], 0, 0, 0); __builtin_amdgcn_s_setprio(0); } while (0)
; #define PG8_WAIT_V(n) asm volatile("s_waitcnt vmcnt(" #n ")" ::: "memory")
; #define PG8_WAIT_L(n) asm volatile("s_waitcnt lgkmcnt(" #n ")" ::: "memory")
; #define PG8_BAR __builtin_amdgcn_s_barrier()
; #define PG8_SCHED __builtin_amdgcn_sched_barrier(0)
; template <class Epi, class Sched>
; __device__ __forceinline__ void gemm_phase(LAS unsigned char* lds, const Gemm g, const Sched& S, const Epi& E) {
;     ...
;             PG8_LDB(B0, 0, 0); PG8_SCHED; PG8_LDA(At, 0, 0); PG8_STAGE(PG8_SA(1, 1), a1 + hstepA, voffA);
;             PG8_WAIT_L(8); PG8_BAR; PG8_WAIT_L(0); PG8_MMA(0, 0, At, B0); PG8_BAR; PG8_SCHED;
;     ...
;             PG8_LDA(At, 1, 1); PG8_STAGE(PG8_SA(1, 0), a3, voffA);
;             PG8_BAR; PG8_WAIT_L(0); PG8_MMA(1, 0, At, B0); PG8_BAR; PG8_SCHED;
;             PG8_STAGE(PG8_SB(1, 1), b3 + hstepB, voffB);
;             PG8_WAIT_V(6); PG8_BAR; PG8_MMA(1, 1, At, B1); PG8_BAR;
	s_setprio 0
	ds_read_b128 v[148:151], v224 offset:49152
	ds_read_b128 v[152:155], v224 offset:50176
	ds_read_b128 v[156:159], v224 offset:51200
	ds_read_b128 v[160:163], v224 offset:52224
	ds_read_b128 v[164:167], v224 offset:53248
	ds_read_b128 v[168:171], v224 offset:54272
	ds_read_b128 v[172:175], v224 offset:55296
	ds_read_b128 v[176:179], v224 offset:56320
	s_add_i32 s25, s52, s30
	v_lshl_add_u64 v[206:207], v[206:207], 0, s[8:9]
	s_mov_b32 m0, s25
	s_nop 0
	global_load_lds_dwordx4 v[206:207], off
	v_lshl_add_u64 v[206:207], v[208:209], 0, s[8:9]
	s_add_i32 m0, s25, 0x2000
	s_nop 0
	global_load_lds_dwordx4 v[206:207], off
	s_mov_b32 m0, s40
	v_lshl_add_u64 v[206:207], v[210:211], 0, s[8:9]
	global_load_lds_dwordx4 v[206:207], off
	v_lshl_add_u64 v[206:207], v[212:213], 0, s[8:9]
	s_mov_b32 m0, s41
	s_nop 0
	global_load_lds_dwordx4 v[206:207], off
	s_add_u32 s20, s20, 0x80080
	s_addc_u32 s21, s21, 0
	s_add_i32 s24, s24, s30
	s_mov_b32 m0, s24
	s_nop 0
	global_load_lds_dwordx4 v2, s[20:21]
	s_add_i32 m0, s24, 0x2000
	s_nop 0
	global_load_lds_dwordx4 v192, s[20:21]
	s_add_i32 s51, s51, 2
	s_add_u32 s6, s6, 0x100
	s_addc_u32 s7, s7, 0
	s_add_u32 s49, s49, 0x100
	s_addc_u32 s50, s50, 0
	s_cmp_gt_u32 s51, 29
	s_waitcnt lgkmcnt(0)
	s_waitcnt vmcnt(8)
	s_setprio 1
	s_barrier
	v_mfma_f32_16x16x32_bf16 v[64:67], v[132:135], v[148:151], v[64:67]
	v_mfma_f32_16x16x32_bf16 v[60:63], v[140:143], v[148:151], v[60:63]
	v_mfma_f32_16x16x32_bf16 v[52:55], v[132:135], v[156:159], v[52:55]
	v_mfma_f32_16x16x32_bf16 v[44:47], v[140:143], v[156:159], v[44:47]
	v_mfma_f32_16x16x32_bf16 v[36:39], v[132:135], v[164:167], v[36:39]
	v_mfma_f32_16x16x32_bf16 v[28:31], v[140:143], v[164:167], v[28:31]
	v_mfma_f32_16x16x32_bf16 v[20:23], v[132:135], v[172:175], v[20:23]
	v_mfma_f32_16x16x32_bf16 v[12:15], v[140:143], v[172:175], v[12:15]
	v_mfma_f32_16x16x32_bf16 v[64:67], v[136:139], v[152:155], v[64:67]
	v_mfma_f32_16x16x32_bf16 v[60:63], v[144:147], v[152:155], v[60:63]
	v_mfma_f32_16x16x32_bf16 v[52:55], v[136:139], v[160:163], v[52:55]
	v_mfma_f32_16x16x32_bf16 v[44:47], v[144:147], v[160:163], v[44:47]
	v_mfma_f32_16x16x32_bf16 v[36:39], v[136:139], v[168:171], v[36:39]
	v_mfma_f32_16x16x32_bf16 v[28:31], v[144:147], v[168:171], v[28:31]
	v_mfma_f32_16x16x32_bf16 v[20:23], v[136:139], v[176:179], v[20:23]
	v_mfma_f32_16x16x32_bf16 v[12:15], v[144:147], v[176:179], v[12:15]
	v_mfma_f32_16x16x32_bf16 v[56:59], v[180:183], v[148:151], v[56:59]
	v_mfma_f32_16x16x32_bf16 v[48:51], v[188:191], v[148:151], v[48:51]
	v_mfma_f32_16x16x32_bf16 v[40:43], v[180:183], v[156:159], v[40:43]
	v_mfma_f32_16x16x32_bf16 v[32:35], v[188:191], v[156:159], v[32:35]
	v_mfma_f32_16x16x32_bf16 v[24:27], v[180:183], v[164:167], v[24:27]
	v_mfma_f32_16x16x32_bf16 v[16:19], v[188:191], v[164:167], v[16:19]
	v_mfma_f32_16x16x32_bf16 v[8:11], v[180:183], v[172:175], v[8:11]
	v_mfma_f32_16x16x32_bf16 v[4:7], v[188:191], v[172:175], v[4:7]
	v_mfma_f32_16x16x32_bf16 v[56:59], v[184:187], v[152:155], v[56:59]
	v_mfma_f32_16x16x32_bf16 v[48:51], v[202:205], v[152:155], v[48:51]
	v_mfma_f32_16x16x32_bf16 v[40:43], v[184:187], v[160:163], v[40:43]
	v_mfma_f32_16x16x32_bf16 v[32:35], v[202:205], v[160:163], v[32:35]
	v_mfma_f32_16x16x32_bf16 v[24:27], v[184:187], v[168:171], v[24:27]
	v_mfma_f32_16x16x32_bf16 v[16:19], v[202:205], v[168:171], v[16:19]
	v_mfma_f32_16x16x32_bf16 v[8:11], v[184:187], v[176:179], v[8:11]
	v_mfma_f32_16x16x32_bf16 v[4:7], v[202:205], v[176:179], v[4:7]
	s_barrier
	s_setprio 0
.LBB0_966:
	s_setprio 0
	s_add_u32 s20, s6, 0xfff80080
	s_addc_u32 s21, s7, -1
	s_add_i32 s52, 0, 0x10000
	v_add_u32_e32 v144, s52, v1
	ds_read_b128 v[132:135], v144
	ds_read_b128 v[136:139], v144 offset:1024
	ds_read_b128 v[140:143], v144 offset:2048
	ds_read_b128 v[144:147], v144 offset:3072
	s_cmp_eq_u32 s51, 28
	s_cselect_b32 s25, s15, s21
	s_cselect_b32 s24, s47, s20
	s_cselect_b32 s21, s1, s50
	s_cselect_b32 s20, s48, s49
	ds_read_b128 v[148:151], v224
	ds_read_b128 v[152:155], v224 offset:1024
	ds_read_b128 v[156:159], v224 offset:2048
	ds_read_b128 v[160:163], v224 offset:3072
	ds_read_b128 v[164:167], v224 offset:4096
	ds_read_b128 v[168:171], v224 offset:5120
	ds_read_b128 v[172:175], v224 offset:6144
	ds_read_b128 v[176:179], v224 offset:7168
	s_add_i32 s54, 0, 0x14000
	v_add_u32_e32 v202, s54, v1
	ds_read_b128 v[180:183], v202
	ds_read_b128 v[184:187], v202 offset:1024
	ds_read_b128 v[188:191], v202 offset:2048
	ds_read_b128 v[202:205], v202 offset:3072
	s_add_i32 m0, s31, 0xc000
	s_nop 0
	global_load_lds_dwordx4 v198, s[6:7]
	s_add_i32 m0, s31, 0xe000
	s_nop 0
	global_load_lds_dwordx4 v200, s[6:7]
	s_waitcnt lgkmcnt(0)
	s_waitcnt vmcnt(8)
	s_setprio 1
	s_barrier
; #define PG8_STAGE(bufoff, gbase, voff) do { _Pragma("unroll") for (int _i = 0; _i < 2; ++_i) \
;         __builtin_amdgcn_global_load_lds((const unsigned*)((const char*)(gbase) + (voff)[_i]), (LAS unsigned*)(lds + (bufoff) + ldsw + _i * 8192), 16, 0, 0); } while (0)
; #define PG8_LDA(dst, b, h) do { _Pragma("unroll") for (int m = 0; m < 4; ++m) _Pragma("unroll") for (int k = 0; k < 2; ++k) dst[m][k] = *(const LAS bf16x8*)(lds + PG8_SA(b, h) + aoff + m * 2048 + k * 1024); } while (0)
; #define PG8_LDB(dst, b, h) do { _Pragma("unroll") for (int n = 0; n < 2; ++n) _Pragma("unroll") for (int k = 0; k < 2; ++k) dst[n][k] = *(const LAS bf16x8*)(lds + PG8_SB(b, h) + boff + n * 2048 + k * 1024); } while (0)
; #define PG8_MMA(ai, bj, At, Bt) do { __builtin_amdgcn_s_setprio(1); _Pragma("unroll") for (int m = 0; m < 4; ++m) _Pragma("unroll") for (int n = 0; n < 2; ++n) _Pragma("unroll") for (int k = 0; k < 2; ++k) \
;         acc[ai][bj][m][n] = __builtin_amdgcn_mfma_f32_16x16x32_bf16(Bt[n][k], At[m][k], acc[ai][bj][m][n], 0, 0, 0); __builtin_amdgcn_s_setprio(0); } while (0)
; #define PG8_WAIT_V(n) asm volatile("s_waitcnt vmcnt(" #n ")" ::: "memory")
; #define PG8_WAIT_L(n) asm volatile("s_waitcnt lgkmcnt(" #n ")" ::: "memory")
; #define PG8_BAR __builtin_amdgcn_s_barrier()
; #define PG8_SCHED __builtin_amdgcn_sched_barrier(0)
; template <class Epi, class Sched>
; __device__ __forceinline__ void gemm_phase(LAS unsigned char* lds, const Gemm g, const Sched& S, const Epi& E) {
;     ...
;             PG8_WAIT_L(8); PG8_BAR; PG8_WAIT_L(0); PG8_MMA(0, 0, At, B0); PG8_BAR; PG8_SCHED;
;             PG8_LDB(B1, 0, 1); PG8_STAGE(PG8_SB(0, 0), b2, voffB);
;             PG8_BAR; PG8_WAIT_L(0); PG8_MMA(0, 1, At, B1); PG8_BAR;
;             PG8_LDA(At, 0, 1); PG8_STAGE(PG8_SA(0, 0), a2, voffA);
;             PG8_BAR; PG8_WAIT_L(0); PG8_MMA(1, 0, At, B0); PG8_BAR; PG8_SCHED;
;             PG8_STAGE(PG8_SB(0, 1), b2 + hstepB, voffB);
;             PG8_WAIT_V(6); PG8_BAR; PG8_MMA(1, 1, At, B1); PG8_BAR;
	v_mfma_f32_16x16x32_bf16 v[128:131], v[132:135], v[148:151], v[128:131]
	v_mfma_f32_16x16x32_bf16 v[124:127], v[140:143], v[148:151], v[124:127]
	v_mfma_f32_16x16x32_bf16 v[112:115], v[132:135], v[156:159], v[112:115]
	v_mfma_f32_16x16x32_bf16 v[108:111], v[140:143], v[156:159], v[108:111]
	v_mfma_f32_16x16x32_bf16 v[100:103], v[132:135], v[164:167], v[100:103]
	v_mfma_f32_16x16x32_bf16 v[92:95], v[140:143], v[164:167], v[92:95]
	v_mfma_f32_16x16x32_bf16 v[84:87], v[132:135], v[172:175], v[84:87]
	v_mfma_f32_16x16x32_bf16 v[76:79], v[140:143], v[172:175], v[76:79]
	v_mfma_f32_16x16x32_bf16 v[128:131], v[136:139], v[152:155], v[128:131]
	v_mfma_f32_16x16x32_bf16 v[124:127], v[144:147], v[152:155], v[124:127]
	v_mfma_f32_16x16x32_bf16 v[112:115], v[136:139], v[160:163], v[112:115]
	v_mfma_f32_16x16x32_bf16 v[108:111], v[144:147], v[160:163], v[108:111]
	v_mfma_f32_16x16x32_bf16 v[100:103], v[136:139], v[168:171], v[100:103]
	v_mfma_f32_16x16x32_bf16 v[92:95], v[144:147], v[168:171], v[92:95]
	v_mfma_f32_16x16x32_bf16 v[84:87], v[136:139], v[176:179], v[84:87]
	v_mfma_f32_16x16x32_bf16 v[76:79], v[144:147], v[176:179], v[76:79]
	v_mfma_f32_16x16x32_bf16 v[120:123], v[180:183], v[148:151], v[120:123]
	v_mfma_f32_16x16x32_bf16 v[116:119], v[188:191], v[148:151], v[116:119]
	v_mfma_f32_16x16x32_bf16 v[104:107], v[180:183], v[156:159], v[104:107]
	v_mfma_f32_16x16x32_bf16 v[96:99], v[188:191], v[156:159], v[96:99]
	v_mfma_f32_16x16x32_bf16 v[88:91], v[180:183], v[164:167], v[88:91]
	v_mfma_f32_16x16x32_bf16 v[80:83], v[188:191], v[164:167], v[80:83]
	v_mfma_f32_16x16x32_bf16 v[72:75], v[180:183], v[172:175], v[72:75]
	v_mfma_f32_16x16x32_bf16 v[68:71], v[188:191], v[172:175], v[68:71]
	v_mfma_f32_16x16x32_bf16 v[120:123], v[184:187], v[152:155], v[120:123]
	v_mfma_f32_16x16x32_bf16 v[116:119], v[202:205], v[152:155], v[116:119]
	v_mfma_f32_16x16x32_bf16 v[104:107], v[184:187], v[160:163], v[104:107]
	v_mfma_f32_16x16x32_bf16 v[96:99], v[202:205], v[160:163], v[96:99]
	v_mfma_f32_16x16x32_bf16 v[88:91], v[184:187], v[168:171], v[88:91]
	v_mfma_f32_16x16x32_bf16 v[80:83], v[202:205], v[168:171], v[80:83]
	v_mfma_f32_16x16x32_bf16 v[72:75], v[184:187], v[176:179], v[72:75]
	v_mfma_f32_16x16x32_bf16 v[68:71], v[202:205], v[176:179], v[68:71]
	s_barrier
	s_setprio 0
	ds_read_b128 v[148:151], v224 offset:16384
	ds_read_b128 v[152:155], v224 offset:17408
	ds_read_b128 v[156:159], v224 offset:18432
	ds_read_b128 v[160:163], v224 offset:19456
	ds_read_b128 v[164:167], v224 offset:20480
	ds_read_b128 v[168:171], v224 offset:21504
	ds_read_b128 v[172:175], v224 offset:22528
	ds_read_b128 v[176:179], v224 offset:23552
	s_add_i32 s52, s52, s30
	v_lshl_add_u64 v[206:207], s[20:21], 0, v[2:3]
	s_mov_b32 m0, s52
	s_nop 0
	global_load_lds_dwordx4 v[206:207], off
	v_lshl_add_u64 v[208:209], s[20:21], 0, v[192:193]
	s_add_i32 m0, s52, 0x2000
	s_nop 0
	global_load_lds_dwordx4 v[208:209], off
	s_mov_b32 m0, s31
	v_lshl_add_u64 v[210:211], s[24:25], 0, v[196:197]
	global_load_lds_dwordx4 v[210:211], off
	v_lshl_add_u64 v[212:213], s[24:25], 0, v[194:195]
	s_mov_b32 m0, s35
	s_nop 0
	global_load_lds_dwordx4 v[212:213], off
	s_add_u32 s52, s20, 0x80000
	s_addc_u32 s53, s21, 0
	s_add_i32 s54, s54, s30
	s_mov_b32 m0, s54
	s_nop 0
	global_load_lds_dwordx4 v2, s[52:53]
	s_add_i32 m0, s54, 0x2000
	s_nop 0
	global_load_lds_dwordx4 v192, s[52:53]
	s_waitcnt lgkmcnt(0)
	s_waitcnt vmcnt(8)
	s_setprio 1
	s_barrier
	v_mfma_f32_16x16x32_bf16 v[64:67], v[132:135], v[148:151], v[64:67]
	v_mfma_f32_16x16x32_bf16 v[60:63], v[140:143], v[148:151], v[60:63]
	v_mfma_f32_16x16x32_bf16 v[52:55], v[132:135], v[156:159], v[52:55]
	v_mfma_f32_16x16x32_bf16 v[44:47], v[140:143], v[156:159], v[44:47]
	v_mfma_f32_16x16x32_bf16 v[36:39], v[132:135], v[164:167], v[36:39]
	v_mfma_f32_16x16x32_bf16 v[28:31], v[140:143], v[164:167], v[28:31]
	v_mfma_f32_16x16x32_bf16 v[20:23], v[132:135], v[172:175], v[20:23]
	v_mfma_f32_16x16x32_bf16 v[12:15], v[140:143], v[172:175], v[12:15]
	v_mfma_f32_16x16x32_bf16 v[64:67], v[136:139], v[152:155], v[64:67]
	v_mfma_f32_16x16x32_bf16 v[60:63], v[144:147], v[152:155], v[60:63]
	v_mfma_f32_16x16x32_bf16 v[52:55], v[136:139], v[160:163], v[52:55]
	v_mfma_f32_16x16x32_bf16 v[44:47], v[144:147], v[160:163], v[44:47]
	v_mfma_f32_16x16x32_bf16 v[36:39], v[136:139], v[168:171], v[36:39]
	v_mfma_f32_16x16x32_bf16 v[28:31], v[144:147], v[168:171], v[28:31]
	v_mfma_f32_16x16x32_bf16 v[20:23], v[136:139], v[176:179], v[20:23]
	v_mfma_f32_16x16x32_bf16 v[12:15], v[144:147], v[176:179], v[12:15]
	v_mfma_f32_16x16x32_bf16 v[56:59], v[180:183], v[148:151], v[56:59]
	v_mfma_f32_16x16x32_bf16 v[48:51], v[188:191], v[148:151], v[48:51]
	v_mfma_f32_16x16x32_bf16 v[40:43], v[180:183], v[156:159], v[40:43]
	v_mfma_f32_16x16x32_bf16 v[32:35], v[188:191], v[156:159], v[32:35]
	v_mfma_f32_16x16x32_bf16 v[24:27], v[180:183], v[164:167], v[24:27]
	v_mfma_f32_16x16x32_bf16 v[16:19], v[188:191], v[164:167], v[16:19]
	v_mfma_f32_16x16x32_bf16 v[8:11], v[180:183], v[172:175], v[8:11]
	v_mfma_f32_16x16x32_bf16 v[4:7], v[188:191], v[172:175], v[4:7]
	v_mfma_f32_16x16x32_bf16 v[56:59], v[184:187], v[152:155], v[56:59]
	v_mfma_f32_16x16x32_bf16 v[48:51], v[202:205], v[152:155], v[48:51]
	v_mfma_f32_16x16x32_bf16 v[40:43], v[184:187], v[160:163], v[40:43]
	v_mfma_f32_16x16x32_bf16 v[32:35], v[202:205], v[160:163], v[32:35]
	v_mfma_f32_16x16x32_bf16 v[24:27], v[184:187], v[168:171], v[24:27]
	v_mfma_f32_16x16x32_bf16 v[16:19], v[202:205], v[168:171], v[16:19]
	v_mfma_f32_16x16x32_bf16 v[8:11], v[184:187], v[176:179], v[8:11]
	v_mfma_f32_16x16x32_bf16 v[4:7], v[202:205], v[176:179], v[4:7]
	s_barrier
; #define PG8_STAGE(bufoff, gbase, voff) do { _Pragma("unroll") for (int _i = 0; _i < 2; ++_i) \
;         __builtin_amdgcn_global_load_lds((const unsigned*)((const char*)(gbase) + (voff)[_i]), (LAS unsigned*)(lds + (bufoff) + ldsw + _i * 8192), 16, 0, 0); } while (0)
; #define PG8_LDA(dst, b, h) do { _Pragma("unroll") for (int m = 0; m < 4; ++m) _Pragma("unroll") for (int k = 0; k < 2; ++k) dst[m][k] = *(const LAS bf16x8*)(lds + PG8_SA(b, h) + aoff + m * 2048 + k * 1024); } while (0)
; #define PG8_LDB(dst, b, h) do { _Pragma("unroll") for (int n = 0; n < 2; ++n) _Pragma("unroll") for (int k = 0; k < 2; ++k) dst[n][k] = *(const LAS bf16x8*)(lds + PG8_SB(b, h) + boff + n * 2048 + k * 1024); } while (0)
; #define PG8_MMA(ai, bj, At, Bt) do { __builtin_amdgcn_s_setprio(1); _Pragma("unroll") for (int m = 0; m < 4; ++m) _Pragma("unroll") for (int n = 0; n < 2; ++n) _Pragma("unroll") for (int k = 0; k < 2; ++k) \
;         acc[ai][bj][m][n] = __builtin_amdgcn_mfma_f32_16x16x32_bf16(Bt[n][k], At[m][k], acc[ai][bj][m][n], 0, 0, 0); __builtin_amdgcn_s_setprio(0); } while (0)
; #define PG8_WAIT_L(n) asm volatile("s_waitcnt lgkmcnt(" #n ")" ::: "memory")
; #define PG8_BAR __builtin_amdgcn_s_barrier()
; #define PG8_SCHED __builtin_amdgcn_sched_barrier(0)
; template <class Epi, class Sched>
; __device__ __forceinline__ void gemm_phase(LAS unsigned char* lds, const Gemm g, const Sched& S, const Epi& E) {
;     ...
;             PG8_LDB(B0, 1, 0); PG8_SCHED; PG8_LDA(At, 1, 0); PG8_STAGE(PG8_SA(0, 1), a2 + hstepA, voffA);
;             PG8_WAIT_L(8); PG8_BAR; PG8_WAIT_L(0); PG8_MMA(0, 0, At, B0); PG8_BAR; PG8_SCHED;
;             PG8_LDB(B1, 1, 1); PG8_STAGE(PG8_SB(1, 0), b3, voffB);
;             PG8_BAR; PG8_WAIT_L(0); PG8_MMA(0, 1, At, B1); PG8_BAR;
;             PG8_LDA(At, 1, 1); PG8_STAGE(PG8_SA(1, 0), a3, voffA);
;             PG8_BAR; PG8_WAIT_L(0); PG8_MMA(1, 0, At, B0); PG8_BAR; PG8_SCHED;
;             PG8_STAGE(PG8_SB(1, 1), b3 + hstepB, voffB);
	s_setprio 0
	s_add_i32 s52, 0, 0x18000
	v_add_u32_e32 v144, s52, v1
	ds_read_b128 v[132:135], v144
	ds_read_b128 v[136:139], v144 offset:1024
	ds_read_b128 v[140:143], v144 offset:2048
	ds_read_b128 v[144:147], v144 offset:3072
	s_add_u32 s24, s24, 0x80000
	s_addc_u32 s25, s25, 0
	ds_read_b128 v[148:151], v224 offset:32768
	ds_read_b128 v[152:155], v224 offset:33792
	ds_read_b128 v[156:159], v224 offset:34816
	ds_read_b128 v[160:163], v224 offset:35840
	ds_read_b128 v[164:167], v224 offset:36864
	ds_read_b128 v[168:171], v224 offset:37888
	ds_read_b128 v[172:175], v224 offset:38912
	ds_read_b128 v[176:179], v224 offset:39936
	s_mov_b32 m0, s36
	s_nop 0
	global_load_lds_dwordx4 v196, s[24:25]
	s_mov_b32 m0, s37
	s_nop 0
	global_load_lds_dwordx4 v194, s[24:25]
	s_add_i32 s24, 0, 0x1c000
	v_add_u32_e32 v202, s24, v1
	ds_read_b128 v[180:183], v202
	ds_read_b128 v[184:187], v202 offset:1024
	ds_read_b128 v[188:191], v202 offset:2048
	ds_read_b128 v[202:205], v202 offset:3072
	s_waitcnt lgkmcnt(0)
	s_waitcnt vmcnt(8)
	s_setprio 1
	s_barrier
	v_mfma_f32_16x16x32_bf16 v[128:131], v[132:135], v[148:151], v[128:131]
	v_mfma_f32_16x16x32_bf16 v[124:127], v[140:143], v[148:151], v[124:127]
	v_mfma_f32_16x16x32_bf16 v[112:115], v[132:135], v[156:159], v[112:115]
	v_mfma_f32_16x16x32_bf16 v[108:111], v[140:143], v[156:159], v[108:111]
	v_mfma_f32_16x16x32_bf16 v[100:103], v[132:135], v[164:167], v[100:103]
	v_mfma_f32_16x16x32_bf16 v[92:95], v[140:143], v[164:167], v[92:95]
	v_mfma_f32_16x16x32_bf16 v[84:87], v[132:135], v[172:175], v[84:87]
	v_mfma_f32_16x16x32_bf16 v[76:79], v[140:143], v[172:175], v[76:79]
	v_mfma_f32_16x16x32_bf16 v[128:131], v[136:139], v[152:155], v[128:131]
	v_mfma_f32_16x16x32_bf16 v[124:127], v[144:147], v[152:155], v[124:127]
	v_mfma_f32_16x16x32_bf16 v[112:115], v[136:139], v[160:163], v[112:115]
	v_mfma_f32_16x16x32_bf16 v[108:111], v[144:147], v[160:163], v[108:111]
	v_mfma_f32_16x16x32_bf16 v[100:103], v[136:139], v[168:171], v[100:103]
	v_mfma_f32_16x16x32_bf16 v[92:95], v[144:147], v[168:171], v[92:95]
	v_mfma_f32_16x16x32_bf16 v[84:87], v[136:139], v[176:179], v[84:87]
	v_mfma_f32_16x16x32_bf16 v[76:79], v[144:147], v[176:179], v[76:79]
	v_mfma_f32_16x16x32_bf16 v[120:123], v[180:183], v[148:151], v[120:123]
	v_mfma_f32_16x16x32_bf16 v[116:119], v[188:191], v[148:151], v[116:119]
	v_mfma_f32_16x16x32_bf16 v[104:107], v[180:183], v[156:159], v[104:107]
	v_mfma_f32_16x16x32_bf16 v[96:99], v[188:191], v[156:159], v[96:99]
	v_mfma_f32_16x16x32_bf16 v[88:91], v[180:183], v[164:167], v[88:91]
	v_mfma_f32_16x16x32_bf16 v[80:83], v[188:191], v[164:167], v[80:83]
	v_mfma_f32_16x16x32_bf16 v[72:75], v[180:183], v[172:175], v[72:75]
	v_mfma_f32_16x16x32_bf16 v[68:71], v[188:191], v[172:175], v[68:71]
	v_mfma_f32_16x16x32_bf16 v[120:123], v[184:187], v[152:155], v[120:123]
	v_mfma_f32_16x16x32_bf16 v[116:119], v[202:205], v[152:155], v[116:119]
	v_mfma_f32_16x16x32_bf16 v[104:107], v[184:187], v[160:163], v[104:107]
	v_mfma_f32_16x16x32_bf16 v[96:99], v[202:205], v[160:163], v[96:99]
	v_mfma_f32_16x16x32_bf16 v[88:91], v[184:187], v[168:171], v[88:91]
	v_mfma_f32_16x16x32_bf16 v[80:83], v[202:205], v[168:171], v[80:83]
	v_mfma_f32_16x16x32_bf16 v[72:75], v[184:187], v[176:179], v[72:75]
	v_mfma_f32_16x16x32_bf16 v[68:71], v[202:205], v[176:179], v[68:71]
	s_barrier
	s_setprio 0
	ds_read_b128 v[148:151], v224 offset:49152
	ds_read_b128 v[152:155], v224 offset:50176
	ds_read_b128 v[156:159], v224 offset:51200
	ds_read_b128 v[160:163], v224 offset:52224
	ds_read_b128 v[164:167], v224 offset:53248
	ds_read_b128 v[168:171], v224 offset:54272
	ds_read_b128 v[172:175], v224 offset:55296
	ds_read_b128 v[176:179], v224 offset:56320
	s_add_i32 s25, s52, s30
	v_lshl_add_u64 v[206:207], v[206:207], 0, s[8:9]
	s_mov_b32 m0, s25
	s_nop 0
	global_load_lds_dwordx4 v[206:207], off
	v_lshl_add_u64 v[206:207], v[208:209], 0, s[8:9]
	s_add_i32 m0, s25, 0x2000
	s_nop 0
	global_load_lds_dwordx4 v[206:207], off
	s_mov_b32 m0, s40
	v_lshl_add_u64 v[206:207], v[210:211], 0, s[8:9]
	global_load_lds_dwordx4 v[206:207], off
	v_lshl_add_u64 v[206:207], v[212:213], 0, s[8:9]
	s_mov_b32 m0, s41
	s_nop 0
	global_load_lds_dwordx4 v[206:207], off
	s_add_u32 s20, s20, 0x80080
	s_addc_u32 s21, s21, 0
	s_add_i32 s24, s24, s30
	s_mov_b32 m0, s24
	s_nop 0
	global_load_lds_dwordx4 v2, s[20:21]
	s_add_i32 m0, s24, 0x2000
	s_nop 0
	global_load_lds_dwordx4 v192, s[20:21]
	s_add_i32 s51, s51, 2
	s_add_u32 s6, s6, 0x100
	s_addc_u32 s7, s7, 0
	s_add_u32 s49, s49, 0x100
	s_addc_u32 s50, s50, 0
	s_cmp_gt_u32 s51, 29
	s_waitcnt lgkmcnt(0)
	s_waitcnt vmcnt(8)
	s_setprio 1
	s_barrier
; __device__ __forceinline__ unsigned cvt_pk_bf16(float lo, float hi) { const f32x2 v = {lo, hi}; const bf16v2_ r = __builtin_convertvector(v, bf16v2_); return __builtin_bit_cast(unsigned, r); }
; __device__ __forceinline__ float bflo(unsigned w) { return __uint_as_float(w << 16); }
; __device__ __forceinline__ float bfhi(unsigned w) { return __uint_as_float(w & 0xffff0000u); }
; #define PG8_MMA(ai, bj, At, Bt) do { __builtin_amdgcn_s_setprio(1); _Pragma("unroll") for (int m = 0; m < 4; ++m) _Pragma("unroll") for (int n = 0; n < 2; ++n) _Pragma("unroll") for (int k = 0; k < 2; ++k) \
;         acc[ai][bj][m][n] = __builtin_amdgcn_mfma_f32_16x16x32_bf16(Bt[n][k], At[m][k], acc[ai][bj][m][n], 0, 0, 0); __builtin_amdgcn_s_setprio(0); } while (0)
; #define PG8_WAIT_V(n) asm volatile("s_waitcnt vmcnt(" #n ")" ::: "memory")
; #define PG8_BAR __builtin_amdgcn_s_barrier()
;     __device__ __forceinline__ void operator()(const f32x4 (&acc)[2][2][4][2], const Unit& u, int wr, int wc, int, int) const {
;     ...
;                 for (int bj = 0; bj < 2; ++bj) cin[ai][m][bj] = *(const u32x4*)(C + (size_t)(row0 + ai * HALF + m * 16) * ldc + col0 + bj * HALF);
; #pragma unroll
;         for (int ai = 0; ai < 2; ++ai)
; #pragma unroll
;             for (int m = 0; m < 4; ++m)
; #pragma unroll
;                 for (int bj = 0; bj < 2; ++bj) { const u32x4 c = cin[ai][m][bj]; const f32x4 v0 = acc[ai][bj][m][0], v1 = acc[ai][bj][m][1];
;                     u32x4 w; w.x = cvt_pk_bf16(bflo(c.x) + v0[0], bfhi(c.x) + v0[1]); w.y = cvt_pk_bf16(bflo(c.y) + v0[2], bfhi(c.y) + v0[3]);
;                     w.z = cvt_pk_bf16(bflo(c.z) + v1[0], bfhi(c.z) + v1[1]); w.w = cvt_pk_bf16(bflo(c.w) + v1[2], bfhi(c.w) + v1[3]);
;                     *(u32x4*)(C + (size_t)(row0 + ai * HALF + m * 16) * ldc + col0 + bj * HALF) = w; }
; template <class Epi, class Sched>
; __device__ __forceinline__ void gemm_phase(LAS unsigned char* lds, const Gemm g, const Sched& S, const Epi& E) {
;     ...
;             PG8_WAIT_V(6); PG8_BAR; PG8_MMA(1, 1, At, B1); PG8_BAR;
	v_mfma_f32_16x16x32_bf16 v[64:67], v[132:135], v[148:151], v[64:67]
	v_mfma_f32_16x16x32_bf16 v[60:63], v[140:143], v[148:151], v[60:63]
	v_mfma_f32_16x16x32_bf16 v[52:55], v[132:135], v[156:159], v[52:55]
	v_mfma_f32_16x16x32_bf16 v[44:47], v[140:143], v[156:159], v[44:47]
	v_mfma_f32_16x16x32_bf16 v[36:39], v[132:135], v[164:167], v[36:39]
	v_mfma_f32_16x16x32_bf16 v[28:31], v[140:143], v[164:167], v[28:31]
	v_mfma_f32_16x16x32_bf16 v[20:23], v[132:135], v[172:175], v[20:23]
	v_mfma_f32_16x16x32_bf16 v[12:15], v[140:143], v[172:175], v[12:15]
	v_mfma_f32_16x16x32_bf16 v[64:67], v[136:139], v[152:155], v[64:67]
	v_mfma_f32_16x16x32_bf16 v[60:63], v[144:147], v[152:155], v[60:63]
	v_mfma_f32_16x16x32_bf16 v[52:55], v[136:139], v[160:163], v[52:55]
	v_mfma_f32_16x16x32_bf16 v[44:47], v[144:147], v[160:163], v[44:47]
	v_mfma_f32_16x16x32_bf16 v[36:39], v[136:139], v[168:171], v[36:39]
	v_mfma_f32_16x16x32_bf16 v[28:31], v[144:147], v[168:171], v[28:31]
	v_mfma_f32_16x16x32_bf16 v[20:23], v[136:139], v[176:179], v[20:23]
	v_mfma_f32_16x16x32_bf16 v[12:15], v[144:147], v[176:179], v[12:15]
	v_mfma_f32_16x16x32_bf16 v[56:59], v[180:183], v[148:151], v[56:59]
	v_mfma_f32_16x16x32_bf16 v[48:51], v[188:191], v[148:151], v[48:51]
	v_mfma_f32_16x16x32_bf16 v[40:43], v[180:183], v[156:159], v[40:43]
	v_mfma_f32_16x16x32_bf16 v[32:35], v[188:191], v[156:159], v[32:35]
	v_mfma_f32_16x16x32_bf16 v[24:27], v[180:183], v[164:167], v[24:27]
	v_mfma_f32_16x16x32_bf16 v[16:19], v[188:191], v[164:167], v[16:19]
	v_mfma_f32_16x16x32_bf16 v[8:11], v[180:183], v[172:175], v[8:11]
	v_mfma_f32_16x16x32_bf16 v[4:7], v[188:191], v[172:175], v[4:7]
	v_mfma_f32_16x16x32_bf16 v[56:59], v[184:187], v[152:155], v[56:59]
	v_mfma_f32_16x16x32_bf16 v[48:51], v[202:205], v[152:155], v[48:51]
	v_mfma_f32_16x16x32_bf16 v[40:43], v[184:187], v[160:163], v[40:43]
	v_mfma_f32_16x16x32_bf16 v[32:35], v[202:205], v[160:163], v[32:35]
	v_mfma_f32_16x16x32_bf16 v[24:27], v[184:187], v[168:171], v[24:27]
	v_mfma_f32_16x16x32_bf16 v[16:19], v[202:205], v[168:171], v[16:19]
	v_mfma_f32_16x16x32_bf16 v[8:11], v[184:187], v[176:179], v[8:11]
	v_mfma_f32_16x16x32_bf16 v[4:7], v[202:205], v[176:179], v[4:7]
	s_barrier
	s_cbranch_scc0 .LBB0_966
	s_setprio 0
	v_mov_b32_e32 v133, v0
	s_lshl_b32 s1, s46, 8
	s_add_i32 s1, s1, s38
	v_and_or_b32 v132, v133, 15, s1
	s_lshl_b32 s1, s45, 8
	v_lshrrev_b32_e32 v133, 1, v133
	v_and_or_b32 v133, v133, 24, s1
	v_or_b32_e32 v134, s39, v133
	v_ashrrev_i32_e32 v135, 31, v134
	v_lshlrev_b64 v[202:203], 1, v[134:135]
	v_ashrrev_i32_e32 v133, 31, v132
	v_lshl_add_u64 v[134:135], s[88:89], 0, v[202:203]
	v_lshlrev_b64 v[226:227], 12, v[132:133]
	v_lshl_add_u64 v[136:137], v[134:135], 0, v[226:227]
	global_load_dwordx4 v[216:219], v[136:137], off
	global_load_dwordx4 v[188:191], v[136:137], off offset:256
	v_or_b32_e32 v136, 16, v132
	v_ashrrev_i32_e32 v137, 31, v136
	v_lshlrev_b64 v[222:223], 12, v[136:137]
	v_lshl_add_u64 v[136:137], v[134:135], 0, v[222:223]
	global_load_dwordx4 v[184:187], v[136:137], off
	global_load_dwordx4 v[180:183], v[136:137], off offset:256
	v_or_b32_e32 v136, 32, v132
	v_ashrrev_i32_e32 v137, 31, v136
	v_lshlrev_b64 v[220:221], 12, v[136:137]
	v_lshl_add_u64 v[136:137], v[134:135], 0, v[220:221]
	global_load_dwordx4 v[176:179], v[136:137], off
	global_load_dwordx4 v[168:171], v[136:137], off offset:256
	v_or_b32_e32 v132, 48, v132
	v_ashrrev_i32_e32 v133, 31, v132
	v_lshlrev_b64 v[212:213], 12, v[132:133]
	v_lshl_add_u64 v[132:133], v[134:135], 0, v[212:213]
	global_load_dwordx4 v[172:175], v[132:133], off
	global_load_dwordx4 v[164:167], v[132:133], off offset:256
	s_mov_b64 s[6:7], 0x80000
	v_lshl_add_u64 v[210:211], v[226:227], 0, s[6:7]
	v_lshl_add_u64 v[132:133], v[134:135], 0, v[210:211]
	global_load_dwordx4 v[160:163], v[132:133], off
	global_load_dwordx4 v[156:159], v[132:133], off offset:256
	s_mov_b64 s[6:7], 0x90000
	v_lshl_add_u64 v[208:209], v[226:227], 0, s[6:7]
	v_lshl_add_u64 v[132:133], v[134:135], 0, v[208:209]
	global_load_dwordx4 v[152:155], v[132:133], off
	global_load_dwordx4 v[148:151], v[132:133], off offset:256
	s_mov_b64 s[6:7], 0xa0000
	v_lshl_add_u64 v[206:207], v[226:227], 0, s[6:7]
	v_lshl_add_u64 v[132:133], v[134:135], 0, v[206:207]
	global_load_dwordx4 v[144:147], v[132:133], off
	global_load_dwordx4 v[140:143], v[132:133], off offset:256
	s_mov_b64 s[6:7], 0xb0000
	v_lshl_add_u64 v[204:205], v[226:227], 0, s[6:7]
	v_lshl_add_u64 v[132:133], v[134:135], 0, v[204:205]
	global_load_dwordx4 v[136:139], v[132:133], off
	s_nop 0
	global_load_dwordx4 v[132:135], v[132:133], off offset:256
	s_and_b64 vcc, exec, s[42:43]
	s_mov_b32 s45, s0
	s_mov_b32 s46, s14
	s_mov_b64 s[20:21], s[18:19]
	s_mov_b64 s[6:7], s[4:5]
	s_waitcnt vmcnt(15)
	v_lshlrev_b32_e32 v228, 16, v216
	v_and_b32_e32 v229, 0xffff0000, v216
	v_lshlrev_b32_e32 v216, 16, v217
	v_and_b32_e32 v217, 0xffff0000, v217
	v_pk_add_f32 v[128:129], v[128:129], v[228:229]
	v_pk_add_f32 v[130:131], v[130:131], v[216:217]
	v_cvt_pk_bf16_f32 v128, v128, v129
	v_cvt_pk_bf16_f32 v129, v130, v131
	v_lshlrev_b32_e32 v130, 16, v218
	v_and_b32_e32 v131, 0xffff0000, v218
	v_pk_add_f32 v[124:125], v[124:125], v[130:131]
	s_nop 0
	v_cvt_pk_bf16_f32 v130, v124, v125
	v_lshlrev_b32_e32 v124, 16, v219
	v_and_b32_e32 v125, 0xffff0000, v219
	v_pk_add_f32 v[124:125], v[126:127], v[124:125]
	s_waitcnt vmcnt(14)
; __device__ __forceinline__ unsigned cvt_pk_bf16(float lo, float hi) { const f32x2 v = {lo, hi}; const bf16v2_ r = __builtin_convertvector(v, bf16v2_); return __builtin_bit_cast(unsigned, r); }
; __device__ __forceinline__ float bflo(unsigned w) { return __uint_as_float(w << 16); }
; __device__ __forceinline__ float bfhi(unsigned w) { return __uint_as_float(w & 0xffff0000u); }
;     __device__ __forceinline__ void operator()(const f32x4 (&acc)[2][2][4][2], const Unit& u, int wr, int wc, int, int) const {
;     ...
;         for (int ai = 0; ai < 2; ++ai)
; #pragma unroll
;             for (int m = 0; m < 4; ++m)
; #pragma unroll
;                 for (int bj = 0; bj < 2; ++bj) { const u32x4 c = cin[ai][m][bj]; const f32x4 v0 = acc[ai][bj][m][0], v1 = acc[ai][bj][m][1];
;                     u32x4 w; w.x = cvt_pk_bf16(bflo(c.x) + v0[0], bfhi(c.x) + v0[1]); w.y = cvt_pk_bf16(bflo(c.y) + v0[2], bfhi(c.y) + v0[3]);
;                     w.z = cvt_pk_bf16(bflo(c.z) + v1[0], bfhi(c.z) + v1[1]); w.w = cvt_pk_bf16(bflo(c.w) + v1[2], bfhi(c.w) + v1[3]);
;                     *(u32x4*)(C + (size_t)(row0 + ai * HALF + m * 16) * ldc + col0 + bj * HALF) = w; }
	v_lshlrev_b32_e32 v126, 16, v188
	v_and_b32_e32 v127, 0xffff0000, v188
	v_pk_add_f32 v[120:121], v[120:121], v[126:127]
	v_lshlrev_b32_e32 v126, 16, v189
	v_and_b32_e32 v127, 0xffff0000, v189
	v_pk_add_f32 v[122:123], v[122:123], v[126:127]
	v_cvt_pk_bf16_f32 v120, v120, v121
	v_cvt_pk_bf16_f32 v121, v122, v123
	v_lshlrev_b32_e32 v122, 16, v190
	v_and_b32_e32 v123, 0xffff0000, v190
	v_pk_add_f32 v[116:117], v[116:117], v[122:123]
	v_cvt_pk_bf16_f32 v131, v124, v125
	v_cvt_pk_bf16_f32 v122, v116, v117
	v_lshlrev_b32_e32 v116, 16, v191
	v_and_b32_e32 v117, 0xffff0000, v191
	v_pk_add_f32 v[116:117], v[118:119], v[116:117]
	v_lshl_add_u64 v[124:125], s[88:89], 0, v[226:227]
	v_cvt_pk_bf16_f32 v123, v116, v117
	s_waitcnt vmcnt(13)
	v_lshlrev_b32_e32 v116, 16, v184
	v_and_b32_e32 v117, 0xffff0000, v184
	v_pk_add_f32 v[112:113], v[112:113], v[116:117]
	v_lshlrev_b32_e32 v116, 16, v185
	v_and_b32_e32 v117, 0xffff0000, v185
	v_pk_add_f32 v[114:115], v[114:115], v[116:117]
	v_cvt_pk_bf16_f32 v112, v112, v113
	v_cvt_pk_bf16_f32 v113, v114, v115
	v_lshlrev_b32_e32 v114, 16, v186
	v_and_b32_e32 v115, 0xffff0000, v186
	v_pk_add_f32 v[108:109], v[108:109], v[114:115]
	v_lshl_add_u64 v[124:125], v[124:125], 0, v[202:203]
	v_cvt_pk_bf16_f32 v114, v108, v109
	v_lshlrev_b32_e32 v108, 16, v187
	v_and_b32_e32 v109, 0xffff0000, v187
	v_pk_add_f32 v[108:109], v[110:111], v[108:109]
	s_waitcnt vmcnt(12)
	v_lshlrev_b32_e32 v110, 16, v180
	v_and_b32_e32 v111, 0xffff0000, v180
	v_pk_add_f32 v[104:105], v[104:105], v[110:111]
	v_lshlrev_b32_e32 v110, 16, v181
	v_and_b32_e32 v111, 0xffff0000, v181
	v_pk_add_f32 v[106:107], v[106:107], v[110:111]
	v_cvt_pk_bf16_f32 v104, v104, v105
	v_cvt_pk_bf16_f32 v105, v106, v107
	v_lshlrev_b32_e32 v106, 16, v182
	v_and_b32_e32 v107, 0xffff0000, v182
	v_pk_add_f32 v[96:97], v[96:97], v[106:107]
	v_cvt_pk_bf16_f32 v115, v108, v109
	v_cvt_pk_bf16_f32 v106, v96, v97
	v_lshlrev_b32_e32 v96, 16, v183
	v_and_b32_e32 v97, 0xffff0000, v183
	v_pk_add_f32 v[96:97], v[98:99], v[96:97]
	s_waitcnt vmcnt(11)
	v_lshlrev_b32_e32 v98, 16, v177
	v_cvt_pk_bf16_f32 v107, v96, v97
	v_lshlrev_b32_e32 v96, 16, v176
	v_and_b32_e32 v97, 0xffff0000, v176
	v_and_b32_e32 v99, 0xffff0000, v177
	v_pk_add_f32 v[96:97], v[100:101], v[96:97]
	v_pk_add_f32 v[98:99], v[102:103], v[98:99]
	v_cvt_pk_bf16_f32 v96, v96, v97
	v_cvt_pk_bf16_f32 v97, v98, v99
	v_lshlrev_b32_e32 v98, 16, v178
	v_and_b32_e32 v99, 0xffff0000, v178
	v_pk_add_f32 v[92:93], v[92:93], v[98:99]
	v_lshl_add_u64 v[108:109], s[88:89], 0, v[222:223]
	v_cvt_pk_bf16_f32 v98, v92, v93
	v_lshlrev_b32_e32 v92, 16, v179
	v_and_b32_e32 v93, 0xffff0000, v179
	v_pk_add_f32 v[92:93], v[94:95], v[92:93]
	s_waitcnt vmcnt(10)
	v_lshlrev_b32_e32 v94, 16, v168
	v_and_b32_e32 v95, 0xffff0000, v168
	v_pk_add_f32 v[88:89], v[88:89], v[94:95]
	v_lshlrev_b32_e32 v94, 16, v169
	v_and_b32_e32 v95, 0xffff0000, v169
	v_pk_add_f32 v[90:91], v[90:91], v[94:95]
	v_cvt_pk_bf16_f32 v88, v88, v89
	v_cvt_pk_bf16_f32 v89, v90, v91
	v_lshlrev_b32_e32 v90, 16, v170
	v_and_b32_e32 v91, 0xffff0000, v170
	v_pk_add_f32 v[80:81], v[80:81], v[90:91]
	v_cvt_pk_bf16_f32 v99, v92, v93
	v_cvt_pk_bf16_f32 v90, v80, v81
	v_lshlrev_b32_e32 v80, 16, v171
	v_and_b32_e32 v81, 0xffff0000, v171
	v_pk_add_f32 v[80:81], v[82:83], v[80:81]
	s_waitcnt vmcnt(9)
	v_lshlrev_b32_e32 v82, 16, v173
	v_cvt_pk_bf16_f32 v91, v80, v81
	v_lshlrev_b32_e32 v80, 16, v172
	v_and_b32_e32 v81, 0xffff0000, v172
	v_and_b32_e32 v83, 0xffff0000, v173
	v_pk_add_f32 v[80:81], v[84:85], v[80:81]
	v_pk_add_f32 v[82:83], v[86:87], v[82:83]
	v_cvt_pk_bf16_f32 v80, v80, v81
	v_cvt_pk_bf16_f32 v81, v82, v83
	v_lshlrev_b32_e32 v82, 16, v174
	v_and_b32_e32 v83, 0xffff0000, v174
	v_pk_add_f32 v[76:77], v[76:77], v[82:83]
	v_lshl_add_u64 v[92:93], s[88:89], 0, v[220:221]
	v_cvt_pk_bf16_f32 v82, v76, v77
	v_lshlrev_b32_e32 v76, 16, v175
	v_and_b32_e32 v77, 0xffff0000, v175
	v_pk_add_f32 v[76:77], v[78:79], v[76:77]
	s_waitcnt vmcnt(8)
	v_lshlrev_b32_e32 v78, 16, v164
	v_and_b32_e32 v79, 0xffff0000, v164
	v_pk_add_f32 v[72:73], v[72:73], v[78:79]
	v_lshlrev_b32_e32 v78, 16, v165
	v_and_b32_e32 v79, 0xffff0000, v165
	v_pk_add_f32 v[74:75], v[74:75], v[78:79]
	v_cvt_pk_bf16_f32 v72, v72, v73
	v_cvt_pk_bf16_f32 v73, v74, v75
	v_lshlrev_b32_e32 v74, 16, v166
	v_and_b32_e32 v75, 0xffff0000, v166
	v_pk_add_f32 v[68:69], v[68:69], v[74:75]
	v_cvt_pk_bf16_f32 v83, v76, v77
	v_cvt_pk_bf16_f32 v74, v68, v69
	v_lshlrev_b32_e32 v68, 16, v167
	v_and_b32_e32 v69, 0xffff0000, v167
	v_pk_add_f32 v[68:69], v[70:71], v[68:69]
	v_lshl_add_u64 v[76:77], s[88:89], 0, v[212:213]
	v_cvt_pk_bf16_f32 v75, v68, v69
	s_waitcnt vmcnt(7)
	v_lshlrev_b32_e32 v68, 16, v160
	v_and_b32_e32 v69, 0xffff0000, v160
	v_pk_add_f32 v[64:65], v[64:65], v[68:69]
	v_lshlrev_b32_e32 v68, 16, v161
	v_and_b32_e32 v69, 0xffff0000, v161
	v_pk_add_f32 v[66:67], v[66:67], v[68:69]
	v_cvt_pk_bf16_f32 v64, v64, v65
	v_cvt_pk_bf16_f32 v65, v66, v67
	v_lshlrev_b32_e32 v66, 16, v162
	v_and_b32_e32 v67, 0xffff0000, v162
	v_pk_add_f32 v[60:61], v[60:61], v[66:67]
	v_lshl_add_u64 v[108:109], v[108:109], 0, v[202:203]
	v_cvt_pk_bf16_f32 v66, v60, v61
	v_lshlrev_b32_e32 v60, 16, v163
	v_and_b32_e32 v61, 0xffff0000, v163
	v_pk_add_f32 v[60:61], v[62:63], v[60:61]
	s_waitcnt vmcnt(6)
; __device__ __forceinline__ unsigned cvt_pk_bf16(float lo, float hi) { const f32x2 v = {lo, hi}; const bf16v2_ r = __builtin_convertvector(v, bf16v2_); return __builtin_bit_cast(unsigned, r); }
; __device__ __forceinline__ float bflo(unsigned w) { return __uint_as_float(w << 16); }
; __device__ __forceinline__ float bfhi(unsigned w) { return __uint_as_float(w & 0xffff0000u); }
; #define PG8_WAIT_V(n) asm volatile("s_waitcnt vmcnt(" #n ")" ::: "memory")
; #define PG8_BAR __builtin_amdgcn_s_barrier()
;     __device__ __forceinline__ void operator()(const f32x4 (&acc)[2][2][4][2], const Unit& u, int wr, int wc, int, int) const {
;     ...
;         for (int ai = 0; ai < 2; ++ai)
; #pragma unroll
;             for (int m = 0; m < 4; ++m)
; #pragma unroll
;                 for (int bj = 0; bj < 2; ++bj) { const u32x4 c = cin[ai][m][bj]; const f32x4 v0 = acc[ai][bj][m][0], v1 = acc[ai][bj][m][1];
;                     u32x4 w; w.x = cvt_pk_bf16(bflo(c.x) + v0[0], bfhi(c.x) + v0[1]); w.y = cvt_pk_bf16(bflo(c.y) + v0[2], bfhi(c.y) + v0[3]);
;                     w.z = cvt_pk_bf16(bflo(c.z) + v1[0], bfhi(c.z) + v1[1]); w.w = cvt_pk_bf16(bflo(c.w) + v1[2], bfhi(c.w) + v1[3]);
;                     *(u32x4*)(C + (size_t)(row0 + ai * HALF + m * 16) * ldc + col0 + bj * HALF) = w; }
; template <class Epi, class Sched>
; __device__ __forceinline__ void gemm_phase(LAS unsigned char* lds, const Gemm g, const Sched& S, const Epi& E) {
;     ...
;     PG8_WAIT_V(0);
;     if (wr == 0) PG8_BAR;
;     PG8_BAR;
	v_lshlrev_b32_e32 v62, 16, v156
	v_and_b32_e32 v63, 0xffff0000, v156
	v_pk_add_f32 v[56:57], v[56:57], v[62:63]
	v_lshlrev_b32_e32 v62, 16, v157
	v_and_b32_e32 v63, 0xffff0000, v157
	v_pk_add_f32 v[58:59], v[58:59], v[62:63]
	v_cvt_pk_bf16_f32 v56, v56, v57
	v_cvt_pk_bf16_f32 v57, v58, v59
	v_lshlrev_b32_e32 v58, 16, v158
	v_and_b32_e32 v59, 0xffff0000, v158
	v_pk_add_f32 v[48:49], v[48:49], v[58:59]
	v_cvt_pk_bf16_f32 v67, v60, v61
	v_cvt_pk_bf16_f32 v58, v48, v49
	v_lshlrev_b32_e32 v48, 16, v159
	v_and_b32_e32 v49, 0xffff0000, v159
	v_pk_add_f32 v[48:49], v[50:51], v[48:49]
	s_waitcnt vmcnt(5)
	v_lshlrev_b32_e32 v50, 16, v153
	v_cvt_pk_bf16_f32 v59, v48, v49
	v_lshlrev_b32_e32 v48, 16, v152
	v_and_b32_e32 v49, 0xffff0000, v152
	v_and_b32_e32 v51, 0xffff0000, v153
	v_pk_add_f32 v[48:49], v[52:53], v[48:49]
	v_pk_add_f32 v[50:51], v[54:55], v[50:51]
	v_cvt_pk_bf16_f32 v48, v48, v49
	v_cvt_pk_bf16_f32 v49, v50, v51
	v_lshlrev_b32_e32 v50, 16, v154
	v_and_b32_e32 v51, 0xffff0000, v154
	v_pk_add_f32 v[44:45], v[44:45], v[50:51]
	v_lshl_add_u64 v[60:61], s[88:89], 0, v[210:211]
	v_cvt_pk_bf16_f32 v50, v44, v45
	v_lshlrev_b32_e32 v44, 16, v155
	v_and_b32_e32 v45, 0xffff0000, v155
	v_pk_add_f32 v[44:45], v[46:47], v[44:45]
	s_waitcnt vmcnt(4)
	v_lshlrev_b32_e32 v46, 16, v148
	v_and_b32_e32 v47, 0xffff0000, v148
	v_pk_add_f32 v[40:41], v[40:41], v[46:47]
	v_lshlrev_b32_e32 v46, 16, v149
	v_and_b32_e32 v47, 0xffff0000, v149
	v_pk_add_f32 v[42:43], v[42:43], v[46:47]
	v_cvt_pk_bf16_f32 v40, v40, v41
	v_cvt_pk_bf16_f32 v41, v42, v43
	v_lshlrev_b32_e32 v42, 16, v150
	v_and_b32_e32 v43, 0xffff0000, v150
	v_pk_add_f32 v[32:33], v[32:33], v[42:43]
	v_cvt_pk_bf16_f32 v51, v44, v45
	v_cvt_pk_bf16_f32 v42, v32, v33
	v_lshlrev_b32_e32 v32, 16, v151
	v_and_b32_e32 v33, 0xffff0000, v151
	v_pk_add_f32 v[32:33], v[34:35], v[32:33]
	s_waitcnt vmcnt(3)
	v_lshlrev_b32_e32 v34, 16, v145
	v_cvt_pk_bf16_f32 v43, v32, v33
	v_lshlrev_b32_e32 v32, 16, v144
	v_and_b32_e32 v33, 0xffff0000, v144
	v_and_b32_e32 v35, 0xffff0000, v145
	v_pk_add_f32 v[32:33], v[36:37], v[32:33]
	v_pk_add_f32 v[34:35], v[38:39], v[34:35]
	v_cvt_pk_bf16_f32 v32, v32, v33
	v_cvt_pk_bf16_f32 v33, v34, v35
	v_lshlrev_b32_e32 v34, 16, v146
	v_and_b32_e32 v35, 0xffff0000, v146
	v_pk_add_f32 v[28:29], v[28:29], v[34:35]
	v_lshl_add_u64 v[44:45], s[88:89], 0, v[208:209]
	v_cvt_pk_bf16_f32 v34, v28, v29
	v_lshlrev_b32_e32 v28, 16, v147
	v_and_b32_e32 v29, 0xffff0000, v147
	v_pk_add_f32 v[28:29], v[30:31], v[28:29]
	s_waitcnt vmcnt(2)
	v_lshlrev_b32_e32 v30, 16, v140
	v_and_b32_e32 v31, 0xffff0000, v140
	v_pk_add_f32 v[24:25], v[24:25], v[30:31]
	v_lshlrev_b32_e32 v30, 16, v141
	v_and_b32_e32 v31, 0xffff0000, v141
	v_pk_add_f32 v[26:27], v[26:27], v[30:31]
	v_cvt_pk_bf16_f32 v24, v24, v25
	v_cvt_pk_bf16_f32 v25, v26, v27
	v_lshlrev_b32_e32 v26, 16, v142
	v_and_b32_e32 v27, 0xffff0000, v142
	v_pk_add_f32 v[16:17], v[16:17], v[26:27]
	v_cvt_pk_bf16_f32 v35, v28, v29
	v_cvt_pk_bf16_f32 v26, v16, v17
	v_lshlrev_b32_e32 v16, 16, v143
	v_and_b32_e32 v17, 0xffff0000, v143
	v_pk_add_f32 v[16:17], v[18:19], v[16:17]
	s_waitcnt vmcnt(1)
	v_lshlrev_b32_e32 v18, 16, v137
	v_cvt_pk_bf16_f32 v27, v16, v17
	v_lshlrev_b32_e32 v16, 16, v136
	v_and_b32_e32 v17, 0xffff0000, v136
	v_and_b32_e32 v19, 0xffff0000, v137
	v_pk_add_f32 v[16:17], v[20:21], v[16:17]
	v_pk_add_f32 v[18:19], v[22:23], v[18:19]
	v_cvt_pk_bf16_f32 v16, v16, v17
	v_cvt_pk_bf16_f32 v17, v18, v19
	v_lshlrev_b32_e32 v18, 16, v138
	v_and_b32_e32 v19, 0xffff0000, v138
	v_pk_add_f32 v[12:13], v[12:13], v[18:19]
	v_lshl_add_u64 v[28:29], s[88:89], 0, v[206:207]
	v_cvt_pk_bf16_f32 v18, v12, v13
	v_lshlrev_b32_e32 v12, 16, v139
	v_and_b32_e32 v13, 0xffff0000, v139
	v_pk_add_f32 v[12:13], v[14:15], v[12:13]
	s_waitcnt vmcnt(0)
	v_lshlrev_b32_e32 v14, 16, v132
	v_and_b32_e32 v15, 0xffff0000, v132
	v_pk_add_f32 v[8:9], v[8:9], v[14:15]
	v_lshlrev_b32_e32 v14, 16, v133
	v_and_b32_e32 v15, 0xffff0000, v133
	v_pk_add_f32 v[10:11], v[10:11], v[14:15]
	v_cvt_pk_bf16_f32 v8, v8, v9
	v_cvt_pk_bf16_f32 v9, v10, v11
	v_lshlrev_b32_e32 v10, 16, v134
	v_and_b32_e32 v11, 0xffff0000, v134
	v_pk_add_f32 v[4:5], v[4:5], v[10:11]
	v_cvt_pk_bf16_f32 v19, v12, v13
	v_cvt_pk_bf16_f32 v10, v4, v5
	v_lshlrev_b32_e32 v4, 16, v135
	v_and_b32_e32 v5, 0xffff0000, v135
	v_lshl_add_u64 v[12:13], s[88:89], 0, v[204:205]
	v_pk_add_f32 v[4:5], v[6:7], v[4:5]
	v_lshl_add_u64 v[92:93], v[92:93], 0, v[202:203]
	v_lshl_add_u64 v[76:77], v[76:77], 0, v[202:203]
	v_lshl_add_u64 v[60:61], v[60:61], 0, v[202:203]
	v_lshl_add_u64 v[44:45], v[44:45], 0, v[202:203]
	v_lshl_add_u64 v[28:29], v[28:29], 0, v[202:203]
	v_lshl_add_u64 v[12:13], v[12:13], 0, v[202:203]
	v_cvt_pk_bf16_f32 v11, v4, v5
	global_store_dwordx4 v[124:125], v[128:131], off
	global_store_dwordx4 v[124:125], v[120:123], off offset:256
	global_store_dwordx4 v[108:109], v[112:115], off
	global_store_dwordx4 v[108:109], v[104:107], off offset:256
	global_store_dwordx4 v[92:93], v[96:99], off
	global_store_dwordx4 v[92:93], v[88:91], off offset:256
	global_store_dwordx4 v[76:77], v[80:83], off
	global_store_dwordx4 v[76:77], v[72:75], off offset:256
	global_store_dwordx4 v[60:61], v[64:67], off
	global_store_dwordx4 v[60:61], v[56:59], off offset:256
	global_store_dwordx4 v[44:45], v[48:51], off
	global_store_dwordx4 v[44:45], v[40:43], off offset:256
	global_store_dwordx4 v[28:29], v[32:35], off
	global_store_dwordx4 v[28:29], v[24:27], off offset:256
	global_store_dwordx4 v[12:13], v[16:19], off
	global_store_dwordx4 v[12:13], v[8:11], off offset:256
	s_cbranch_vccz .LBB0_959
	s_waitcnt vmcnt(0)
	s_cmpk_gt_u32 s2, 0xff
	s_cbranch_scc1 .LBB0_970
	s_barrier

; #define PG8_STAGE(bufoff, gbase, voff) do { _Pragma("unroll") for (int _i = 0; _i < 2; ++_i) \
;         __builtin_amdgcn_global_load_lds((const unsigned*)((const char*)(gbase) + (voff)[_i]), (LAS unsigned*)(lds + (bufoff) + ldsw + _i * 8192), 16, 0, 0); } while (0)
; #define PG8_LDA(dst, b, h) do { _Pragma("unroll") for (int m = 0; m < 4; ++m) _Pragma("unroll") for (int k = 0; k < 2; ++k) dst[m][k] = *(const LAS bf16x8*)(lds + PG8_SA(b, h) + aoff + m * 2048 + k * 1024); } while (0)
; #define PG8_LDB(dst, b, h) do { _Pragma("unroll") for (int n = 0; n < 2; ++n) _Pragma("unroll") for (int k = 0; k < 2; ++k) dst[n][k] = *(const LAS bf16x8*)(lds + PG8_SB(b, h) + boff + n * 2048 + k * 1024); } while (0)
; #define PG8_WAIT_V(n) asm volatile("s_waitcnt vmcnt(" #n ")" ::: "memory")
; #define PG8_WAIT_L(n) asm volatile("s_waitcnt lgkmcnt(" #n ")" ::: "memory")
; #define PG8_BAR __builtin_amdgcn_s_barrier()
; #define PG8_SCHED __builtin_amdgcn_sched_barrier(0)
; template <class Epi, class Sched>
; __device__ __forceinline__ void gemm_phase(LAS unsigned char* lds, const Gemm g, const Sched& S, const Epi& E) {
;     ...
;         const bool has_next = S.next(ui + 1, nxt);
;         const char* nA = has_next ? (const char*)g.A + (size_t)nxt.pm * tstepA : cA; const char* nB = has_next ? (const char*)g.Bt + (size_t)nxt.pn * tstepB : cB;
;         for (int t = 0; t < nt; t += 2) {
;             const bool last = (t == nt - 2);
;             const char* a1 = cA + (size_t)(t + 1) * kstep;
;             const char* a2 = last ? nA : cA + (size_t)(t + 2) * kstep; const char* b2 = last ? nB : cB + (size_t)(t + 2) * kstep;
;             const char* a3 = a2 + kstep; const char* b3 = b2 + kstep;
;             if (last && has_next) S.a_ready(nxt);
;             PG8_LDB(B0, 0, 0); PG8_SCHED; PG8_LDA(At, 0, 0); PG8_STAGE(PG8_SA(1, 1), a1 + hstepA, voffA);
;             PG8_WAIT_L(8); PG8_BAR; PG8_WAIT_L(0); PG8_MMA(0, 0, At, B0); PG8_BAR; PG8_SCHED;
;             PG8_LDB(B1, 0, 1); PG8_STAGE(PG8_SB(0, 0), b2, voffB);
;             PG8_BAR; PG8_WAIT_L(0); PG8_MMA(0, 1, At, B1); PG8_BAR;
;             PG8_LDA(At, 0, 1); PG8_STAGE(PG8_SA(0, 0), a2, voffA);
;             PG8_BAR; PG8_WAIT_L(0); PG8_MMA(1, 0, At, B0); PG8_BAR; PG8_SCHED;
;             PG8_STAGE(PG8_SB(0, 1), b2 + hstepB, voffB);
;             PG8_WAIT_V(6); PG8_BAR; PG8_MMA(1, 1, At, B1); PG8_BAR;
.LBB0_1093:
	v_mov_b64_e32 v[4:5], 0x900
	s_ashr_i32 s5, s4, 31
	v_cmp_lt_i64_e32 vcc, s[6:7], v[4:5]
	s_lshl_b64 s[6:7], s[4:5], 20
	s_add_u32 s6, s88, s6
	s_addc_u32 s7, s89, s7
	s_and_b64 s[14:15], vcc, exec
	s_cselect_b32 s5, s7, s19
	s_cselect_b32 s49, s6, s18
	s_ashr_i32 s1, s0, 31
	s_lshl_b64 s[14:15], s[0:1], 20
	s_add_u32 s14, s28, s14
	s_addc_u32 s15, s29, s15
	s_and_b64 s[24:25], vcc, exec
	s_cselect_b32 s1, s15, s21
	s_cselect_b32 s50, s14, s20
	s_add_u32 s18, s18, 0x80080
	s_addc_u32 s19, s19, 0
	s_add_u32 s51, s20, 0x100
	s_addc_u32 s52, s21, 0
	s_mov_b32 s53, -2
	s_setprio 0
	s_add_u32 s20, s18, 0xfff80080
	s_addc_u32 s21, s19, -1
	s_add_i32 s54, 0, 0x10000
	v_add_u32_e32 v146, s54, v1
	ds_read_b128 v[142:145], v146
	ds_read_b128 v[150:153], v146 offset:1024
	ds_read_b128 v[154:157], v146 offset:2048
	ds_read_b128 v[158:161], v146 offset:3072
	s_cmp_eq_u32 s53, 28
	s_cselect_b32 s25, s5, s21
	s_cselect_b32 s24, s49, s20
	s_cselect_b32 s21, s1, s52
	s_cselect_b32 s20, s50, s51
	ds_read_b128 v[162:165], v148
	ds_read_b128 v[166:169], v148 offset:1024
	ds_read_b128 v[170:173], v148 offset:2048
	ds_read_b128 v[174:177], v148 offset:3072
	ds_read_b128 v[178:181], v148 offset:4096
	ds_read_b128 v[182:185], v148 offset:5120
	ds_read_b128 v[186:189], v148 offset:6144
	ds_read_b128 v[190:193], v148 offset:7168
	s_add_i32 s56, 0, 0x14000
	v_add_u32_e32 v146, s56, v1
	ds_read_b128 v[194:197], v146
	ds_read_b128 v[198:201], v146 offset:1024
	ds_read_b128 v[202:205], v146 offset:2048
	ds_read_b128 v[206:209], v146 offset:3072
	s_add_i32 m0, s31, 0xc000
	s_nop 0
	global_load_lds_dwordx4 v138, s[18:19]
	s_add_i32 m0, s31, 0xe000
	s_nop 0
	global_load_lds_dwordx4 v140, s[18:19]
	s_waitcnt lgkmcnt(0)
	s_waitcnt vmcnt(8)
	s_setprio 1
	s_barrier
	v_mfma_f32_16x16x32_bf16 v[128:131], v[142:145], v[162:165], 0
	v_mfma_f32_16x16x32_bf16 v[124:127], v[154:157], v[162:165], 0
	v_mfma_f32_16x16x32_bf16 v[120:123], v[142:145], v[170:173], 0
	v_mfma_f32_16x16x32_bf16 v[112:115], v[154:157], v[170:173], 0
	v_mfma_f32_16x16x32_bf16 v[104:107], v[142:145], v[178:181], 0
	v_mfma_f32_16x16x32_bf16 v[96:99], v[154:157], v[178:181], 0
	v_mfma_f32_16x16x32_bf16 v[88:91], v[142:145], v[186:189], 0
	v_mfma_f32_16x16x32_bf16 v[80:83], v[154:157], v[186:189], 0
	v_mfma_f32_16x16x32_bf16 v[128:131], v[150:153], v[166:169], v[128:131]
	v_mfma_f32_16x16x32_bf16 v[124:127], v[158:161], v[166:169], v[124:127]
	v_mfma_f32_16x16x32_bf16 v[120:123], v[150:153], v[174:177], v[120:123]
	v_mfma_f32_16x16x32_bf16 v[112:115], v[158:161], v[174:177], v[112:115]
	v_mfma_f32_16x16x32_bf16 v[104:107], v[150:153], v[182:185], v[104:107]
	v_mfma_f32_16x16x32_bf16 v[96:99], v[158:161], v[182:185], v[96:99]
	v_mfma_f32_16x16x32_bf16 v[88:91], v[150:153], v[190:193], v[88:91]
	v_mfma_f32_16x16x32_bf16 v[80:83], v[158:161], v[190:193], v[80:83]
	v_mfma_f32_16x16x32_bf16 v[116:119], v[194:197], v[162:165], 0
	v_mfma_f32_16x16x32_bf16 v[108:111], v[202:205], v[162:165], 0
	v_mfma_f32_16x16x32_bf16 v[100:103], v[194:197], v[170:173], 0
	v_mfma_f32_16x16x32_bf16 v[92:95], v[202:205], v[170:173], 0
	v_mfma_f32_16x16x32_bf16 v[84:87], v[194:197], v[178:181], 0
	v_mfma_f32_16x16x32_bf16 v[76:79], v[202:205], v[178:181], 0
	v_mfma_f32_16x16x32_bf16 v[72:75], v[194:197], v[186:189], 0
	v_mfma_f32_16x16x32_bf16 v[68:71], v[202:205], v[186:189], 0
	v_mfma_f32_16x16x32_bf16 v[116:119], v[198:201], v[166:169], v[116:119]
	v_mfma_f32_16x16x32_bf16 v[108:111], v[206:209], v[166:169], v[108:111]
	v_mfma_f32_16x16x32_bf16 v[100:103], v[198:201], v[174:177], v[100:103]
	v_mfma_f32_16x16x32_bf16 v[92:95], v[206:209], v[174:177], v[92:95]
	v_mfma_f32_16x16x32_bf16 v[84:87], v[198:201], v[182:185], v[84:87]
	v_mfma_f32_16x16x32_bf16 v[76:79], v[206:209], v[182:185], v[76:79]
	v_mfma_f32_16x16x32_bf16 v[72:75], v[198:201], v[190:193], v[72:75]
	v_mfma_f32_16x16x32_bf16 v[68:71], v[206:209], v[190:193], v[68:71]
	s_barrier
	s_setprio 0
	ds_read_b128 v[162:165], v148 offset:16384
	ds_read_b128 v[166:169], v148 offset:17408
	ds_read_b128 v[170:173], v148 offset:18432
	ds_read_b128 v[174:177], v148 offset:19456
	ds_read_b128 v[178:181], v148 offset:20480
	ds_read_b128 v[182:185], v148 offset:21504
	ds_read_b128 v[186:189], v148 offset:22528
	ds_read_b128 v[190:193], v148 offset:23552
	s_add_i32 s54, s54, s30
	v_lshl_add_u64 v[146:147], s[20:21], 0, v[2:3]
	s_mov_b32 m0, s54
	v_lshl_add_u64 v[210:211], s[20:21], 0, v[132:133]
	global_load_lds_dwordx4 v[146:147], off
	s_add_i32 m0, s54, 0x2000
	s_nop 0
	global_load_lds_dwordx4 v[210:211], off
	s_mov_b32 m0, s31
	v_lshl_add_u64 v[212:213], s[24:25], 0, v[136:137]
	global_load_lds_dwordx4 v[212:213], off
	v_lshl_add_u64 v[216:217], s[24:25], 0, v[134:135]
	s_mov_b32 m0, s35
	s_nop 0
	global_load_lds_dwordx4 v[216:217], off
	s_add_u32 s54, s20, 0x80000
	s_addc_u32 s55, s21, 0
	s_add_i32 s56, s56, s30
	s_mov_b32 m0, s56
	s_nop 0
	global_load_lds_dwordx4 v2, s[54:55]
	s_add_i32 m0, s56, 0x2000
	s_nop 0
	global_load_lds_dwordx4 v132, s[54:55]
	s_waitcnt lgkmcnt(0)
	s_waitcnt vmcnt(8)
	s_setprio 1
	s_barrier
; #define PG8_STAGE(bufoff, gbase, voff) do { _Pragma("unroll") for (int _i = 0; _i < 2; ++_i) \
;         __builtin_amdgcn_global_load_lds((const unsigned*)((const char*)(gbase) + (voff)[_i]), (LAS unsigned*)(lds + (bufoff) + ldsw + _i * 8192), 16, 0, 0); } while (0)
; #define PG8_LDA(dst, b, h) do { _Pragma("unroll") for (int m = 0; m < 4; ++m) _Pragma("unroll") for (int k = 0; k < 2; ++k) dst[m][k] = *(const LAS bf16x8*)(lds + PG8_SA(b, h) + aoff + m * 2048 + k * 1024); } while (0)
; #define PG8_LDB(dst, b, h) do { _Pragma("unroll") for (int n = 0; n < 2; ++n) _Pragma("unroll") for (int k = 0; k < 2; ++k) dst[n][k] = *(const LAS bf16x8*)(lds + PG8_SB(b, h) + boff + n * 2048 + k * 1024); } while (0)
; #define PG8_MMA(ai, bj, At, Bt) do { __builtin_amdgcn_s_setprio(1); _Pragma("unroll") for (int m = 0; m < 4; ++m) _Pragma("unroll") for (int n = 0; n < 2; ++n) _Pragma("unroll") for (int k = 0; k < 2; ++k) \
;         acc[ai][bj][m][n] = __builtin_amdgcn_mfma_f32_16x16x32_bf16(Bt[n][k], At[m][k], acc[ai][bj][m][n], 0, 0, 0); __builtin_amdgcn_s_setprio(0); } while (0)
; #define PG8_WAIT_V(n) asm volatile("s_waitcnt vmcnt(" #n ")" ::: "memory")
; #define PG8_WAIT_L(n) asm volatile("s_waitcnt lgkmcnt(" #n ")" ::: "memory")
; #define PG8_BAR __builtin_amdgcn_s_barrier()
; #define PG8_SCHED __builtin_amdgcn_sched_barrier(0)
; template <class Epi, class Sched>
; __device__ __forceinline__ void gemm_phase(LAS unsigned char* lds, const Gemm g, const Sched& S, const Epi& E) {
;     ...
;             PG8_WAIT_V(6); PG8_BAR; PG8_MMA(1, 1, At, B1); PG8_BAR;
;             PG8_LDB(B0, 1, 0); PG8_SCHED; PG8_LDA(At, 1, 0); PG8_STAGE(PG8_SA(0, 1), a2 + hstepA, voffA);
;             PG8_WAIT_L(8); PG8_BAR; PG8_WAIT_L(0); PG8_MMA(0, 0, At, B0); PG8_BAR; PG8_SCHED;
;             PG8_LDB(B1, 1, 1); PG8_STAGE(PG8_SB(1, 0), b3, voffB);
;             PG8_BAR; PG8_WAIT_L(0); PG8_MMA(0, 1, At, B1); PG8_BAR;
;             PG8_LDA(At, 1, 1); PG8_STAGE(PG8_SA(1, 0), a3, voffA);
;             PG8_BAR; PG8_WAIT_L(0); PG8_MMA(1, 0, At, B0); PG8_BAR; PG8_SCHED;
	v_mfma_f32_16x16x32_bf16 v[64:67], v[142:145], v[162:165], 0
	v_mfma_f32_16x16x32_bf16 v[60:63], v[154:157], v[162:165], 0
	v_mfma_f32_16x16x32_bf16 v[56:59], v[142:145], v[170:173], 0
	v_mfma_f32_16x16x32_bf16 v[48:51], v[154:157], v[170:173], 0
	v_mfma_f32_16x16x32_bf16 v[40:43], v[142:145], v[178:181], 0
	v_mfma_f32_16x16x32_bf16 v[32:35], v[154:157], v[178:181], 0
	v_mfma_f32_16x16x32_bf16 v[24:27], v[142:145], v[186:189], 0
	v_mfma_f32_16x16x32_bf16 v[16:19], v[154:157], v[186:189], 0
	v_mfma_f32_16x16x32_bf16 v[64:67], v[150:153], v[166:169], v[64:67]
	v_mfma_f32_16x16x32_bf16 v[60:63], v[158:161], v[166:169], v[60:63]
	v_mfma_f32_16x16x32_bf16 v[56:59], v[150:153], v[174:177], v[56:59]
	v_mfma_f32_16x16x32_bf16 v[48:51], v[158:161], v[174:177], v[48:51]
	v_mfma_f32_16x16x32_bf16 v[40:43], v[150:153], v[182:185], v[40:43]
	v_mfma_f32_16x16x32_bf16 v[32:35], v[158:161], v[182:185], v[32:35]
	v_mfma_f32_16x16x32_bf16 v[24:27], v[150:153], v[190:193], v[24:27]
	v_mfma_f32_16x16x32_bf16 v[16:19], v[158:161], v[190:193], v[16:19]
	v_mfma_f32_16x16x32_bf16 v[52:55], v[194:197], v[162:165], 0
	v_mfma_f32_16x16x32_bf16 v[44:47], v[202:205], v[162:165], 0
	v_mfma_f32_16x16x32_bf16 v[36:39], v[194:197], v[170:173], 0
	v_mfma_f32_16x16x32_bf16 v[28:31], v[202:205], v[170:173], 0
	v_mfma_f32_16x16x32_bf16 v[20:23], v[194:197], v[178:181], 0
	v_mfma_f32_16x16x32_bf16 v[12:15], v[202:205], v[178:181], 0
	v_mfma_f32_16x16x32_bf16 v[8:11], v[194:197], v[186:189], 0
	v_mfma_f32_16x16x32_bf16 v[4:7], v[202:205], v[186:189], 0
	v_mfma_f32_16x16x32_bf16 v[52:55], v[198:201], v[166:169], v[52:55]
	v_mfma_f32_16x16x32_bf16 v[44:47], v[206:209], v[166:169], v[44:47]
	v_mfma_f32_16x16x32_bf16 v[36:39], v[198:201], v[174:177], v[36:39]
	v_mfma_f32_16x16x32_bf16 v[28:31], v[206:209], v[174:177], v[28:31]
	v_mfma_f32_16x16x32_bf16 v[20:23], v[198:201], v[182:185], v[20:23]
	v_mfma_f32_16x16x32_bf16 v[12:15], v[206:209], v[182:185], v[12:15]
	v_mfma_f32_16x16x32_bf16 v[8:11], v[198:201], v[190:193], v[8:11]
	v_mfma_f32_16x16x32_bf16 v[4:7], v[206:209], v[190:193], v[4:7]
	s_barrier
	s_setprio 0
	s_add_i32 s54, 0, 0x18000
	v_add_u32_e32 v149, s54, v1
	ds_read_b128 v[142:145], v149
	ds_read_b128 v[150:153], v149 offset:1024
	ds_read_b128 v[154:157], v149 offset:2048
	ds_read_b128 v[158:161], v149 offset:3072
	s_add_u32 s24, s24, 0x80000
	s_addc_u32 s25, s25, 0
	ds_read_b128 v[162:165], v148 offset:32768
	ds_read_b128 v[166:169], v148 offset:33792
	ds_read_b128 v[170:173], v148 offset:34816
	ds_read_b128 v[174:177], v148 offset:35840
	ds_read_b128 v[178:181], v148 offset:36864
	ds_read_b128 v[182:185], v148 offset:37888
	ds_read_b128 v[186:189], v148 offset:38912
	ds_read_b128 v[190:193], v148 offset:39936
	s_mov_b32 m0, s36
	s_nop 0
	global_load_lds_dwordx4 v136, s[24:25]
	s_mov_b32 m0, s37
	s_nop 0
	global_load_lds_dwordx4 v134, s[24:25]
	s_add_i32 s24, 0, 0x1c000
	v_add_u32_e32 v149, s24, v1
	ds_read_b128 v[194:197], v149
	ds_read_b128 v[198:201], v149 offset:1024
	ds_read_b128 v[202:205], v149 offset:2048
	ds_read_b128 v[206:209], v149 offset:3072
	s_waitcnt lgkmcnt(0)
	s_waitcnt vmcnt(8)
	s_setprio 1
	s_barrier
	v_mfma_f32_16x16x32_bf16 v[128:131], v[142:145], v[162:165], v[128:131]
	v_mfma_f32_16x16x32_bf16 v[124:127], v[154:157], v[162:165], v[124:127]
	v_mfma_f32_16x16x32_bf16 v[120:123], v[142:145], v[170:173], v[120:123]
	v_mfma_f32_16x16x32_bf16 v[112:115], v[154:157], v[170:173], v[112:115]
	v_mfma_f32_16x16x32_bf16 v[104:107], v[142:145], v[178:181], v[104:107]
	v_mfma_f32_16x16x32_bf16 v[96:99], v[154:157], v[178:181], v[96:99]
	v_mfma_f32_16x16x32_bf16 v[88:91], v[142:145], v[186:189], v[88:91]
	v_mfma_f32_16x16x32_bf16 v[80:83], v[154:157], v[186:189], v[80:83]
	v_mfma_f32_16x16x32_bf16 v[128:131], v[150:153], v[166:169], v[128:131]
	v_mfma_f32_16x16x32_bf16 v[124:127], v[158:161], v[166:169], v[124:127]
	v_mfma_f32_16x16x32_bf16 v[120:123], v[150:153], v[174:177], v[120:123]
	v_mfma_f32_16x16x32_bf16 v[112:115], v[158:161], v[174:177], v[112:115]
	v_mfma_f32_16x16x32_bf16 v[104:107], v[150:153], v[182:185], v[104:107]
	v_mfma_f32_16x16x32_bf16 v[96:99], v[158:161], v[182:185], v[96:99]
	v_mfma_f32_16x16x32_bf16 v[88:91], v[150:153], v[190:193], v[88:91]
	v_mfma_f32_16x16x32_bf16 v[80:83], v[158:161], v[190:193], v[80:83]
	v_mfma_f32_16x16x32_bf16 v[116:119], v[194:197], v[162:165], v[116:119]
	v_mfma_f32_16x16x32_bf16 v[108:111], v[202:205], v[162:165], v[108:111]
	v_mfma_f32_16x16x32_bf16 v[100:103], v[194:197], v[170:173], v[100:103]
	v_mfma_f32_16x16x32_bf16 v[92:95], v[202:205], v[170:173], v[92:95]
	v_mfma_f32_16x16x32_bf16 v[84:87], v[194:197], v[178:181], v[84:87]
	v_mfma_f32_16x16x32_bf16 v[76:79], v[202:205], v[178:181], v[76:79]
	v_mfma_f32_16x16x32_bf16 v[72:75], v[194:197], v[186:189], v[72:75]
	v_mfma_f32_16x16x32_bf16 v[68:71], v[202:205], v[186:189], v[68:71]
	v_mfma_f32_16x16x32_bf16 v[116:119], v[198:201], v[166:169], v[116:119]
	v_mfma_f32_16x16x32_bf16 v[108:111], v[206:209], v[166:169], v[108:111]
	v_mfma_f32_16x16x32_bf16 v[100:103], v[198:201], v[174:177], v[100:103]
	v_mfma_f32_16x16x32_bf16 v[92:95], v[206:209], v[174:177], v[92:95]
	v_mfma_f32_16x16x32_bf16 v[84:87], v[198:201], v[182:185], v[84:87]
	v_mfma_f32_16x16x32_bf16 v[76:79], v[206:209], v[182:185], v[76:79]
	v_mfma_f32_16x16x32_bf16 v[72:75], v[198:201], v[190:193], v[72:75]
	v_mfma_f32_16x16x32_bf16 v[68:71], v[206:209], v[190:193], v[68:71]
	s_barrier
; #define PG8_STAGE(bufoff, gbase, voff) do { _Pragma("unroll") for (int _i = 0; _i < 2; ++_i) \
;         __builtin_amdgcn_global_load_lds((const unsigned*)((const char*)(gbase) + (voff)[_i]), (LAS unsigned*)(lds + (bufoff) + ldsw + _i * 8192), 16, 0, 0); } while (0)
; #define PG8_LDA(dst, b, h) do { _Pragma("unroll") for (int m = 0; m < 4; ++m) _Pragma("unroll") for (int k = 0; k < 2; ++k) dst[m][k] = *(const LAS bf16x8*)(lds + PG8_SA(b, h) + aoff + m * 2048 + k * 1024); } while (0)
; #define PG8_LDB(dst, b, h) do { _Pragma("unroll") for (int n = 0; n < 2; ++n) _Pragma("unroll") for (int k = 0; k < 2; ++k) dst[n][k] = *(const LAS bf16x8*)(lds + PG8_SB(b, h) + boff + n * 2048 + k * 1024); } while (0)
; #define PG8_MMA(ai, bj, At, Bt) do { __builtin_amdgcn_s_setprio(1); _Pragma("unroll") for (int m = 0; m < 4; ++m) _Pragma("unroll") for (int n = 0; n < 2; ++n) _Pragma("unroll") for (int k = 0; k < 2; ++k) \
;         acc[ai][bj][m][n] = __builtin_amdgcn_mfma_f32_16x16x32_bf16(Bt[n][k], At[m][k], acc[ai][bj][m][n], 0, 0, 0); __builtin_amdgcn_s_setprio(0); } while (0)
; #define PG8_WAIT_V(n) asm volatile("s_waitcnt vmcnt(" #n ")" ::: "memory")
; #define PG8_WAIT_L(n) asm volatile("s_waitcnt lgkmcnt(" #n ")" ::: "memory")
; #define PG8_BAR __builtin_amdgcn_s_barrier()
; #define PG8_SCHED __builtin_amdgcn_sched_barrier(0)
; template <class Epi, class Sched>
; __device__ __forceinline__ void gemm_phase(LAS unsigned char* lds, const Gemm g, const Sched& S, const Epi& E) {
;     ...
;             PG8_LDB(B0, 0, 0); PG8_SCHED; PG8_LDA(At, 0, 0); PG8_STAGE(PG8_SA(1, 1), a1 + hstepA, voffA);
;             PG8_WAIT_L(8); PG8_BAR; PG8_WAIT_L(0); PG8_MMA(0, 0, At, B0); PG8_BAR; PG8_SCHED;
;     ...
;             PG8_LDA(At, 1, 1); PG8_STAGE(PG8_SA(1, 0), a3, voffA);
;             PG8_BAR; PG8_WAIT_L(0); PG8_MMA(1, 0, At, B0); PG8_BAR; PG8_SCHED;
;             PG8_STAGE(PG8_SB(1, 1), b3 + hstepB, voffB);
;             PG8_WAIT_V(6); PG8_BAR; PG8_MMA(1, 1, At, B1); PG8_BAR;
	s_setprio 0
	ds_read_b128 v[162:165], v148 offset:49152
	ds_read_b128 v[166:169], v148 offset:50176
	ds_read_b128 v[170:173], v148 offset:51200
	ds_read_b128 v[174:177], v148 offset:52224
	ds_read_b128 v[178:181], v148 offset:53248
	ds_read_b128 v[182:185], v148 offset:54272
	ds_read_b128 v[186:189], v148 offset:55296
	ds_read_b128 v[190:193], v148 offset:56320
	s_add_i32 s25, s54, s30
	v_lshl_add_u64 v[146:147], v[146:147], 0, s[8:9]
	s_mov_b32 m0, s25
	s_nop 0
	global_load_lds_dwordx4 v[146:147], off
	v_lshl_add_u64 v[146:147], v[210:211], 0, s[8:9]
	s_add_i32 m0, s25, 0x2000
	s_nop 0
	global_load_lds_dwordx4 v[146:147], off
	s_mov_b32 m0, s42
	v_lshl_add_u64 v[146:147], v[212:213], 0, s[8:9]
	global_load_lds_dwordx4 v[146:147], off
	v_lshl_add_u64 v[146:147], v[216:217], 0, s[8:9]
	s_mov_b32 m0, s43
	s_nop 0
	global_load_lds_dwordx4 v[146:147], off
	s_add_u32 s20, s20, 0x80080
	s_addc_u32 s21, s21, 0
	s_add_i32 s24, s24, s30
	s_mov_b32 m0, s24
	s_nop 0
	global_load_lds_dwordx4 v2, s[20:21]
	s_add_i32 m0, s24, 0x2000
	s_nop 0
	global_load_lds_dwordx4 v132, s[20:21]
	s_add_i32 s53, s53, 2
	s_add_u32 s18, s18, 0x100
	s_addc_u32 s19, s19, 0
	s_add_u32 s51, s51, 0x100
	s_addc_u32 s52, s52, 0
	s_cmp_gt_u32 s53, 29
	s_waitcnt lgkmcnt(0)
	s_waitcnt vmcnt(8)
	s_setprio 1
	s_barrier
	v_mfma_f32_16x16x32_bf16 v[64:67], v[142:145], v[162:165], v[64:67]
	v_mfma_f32_16x16x32_bf16 v[60:63], v[154:157], v[162:165], v[60:63]
	v_mfma_f32_16x16x32_bf16 v[56:59], v[142:145], v[170:173], v[56:59]
	v_mfma_f32_16x16x32_bf16 v[48:51], v[154:157], v[170:173], v[48:51]
	v_mfma_f32_16x16x32_bf16 v[40:43], v[142:145], v[178:181], v[40:43]
	v_mfma_f32_16x16x32_bf16 v[32:35], v[154:157], v[178:181], v[32:35]
	v_mfma_f32_16x16x32_bf16 v[24:27], v[142:145], v[186:189], v[24:27]
	v_mfma_f32_16x16x32_bf16 v[16:19], v[154:157], v[186:189], v[16:19]
	v_mfma_f32_16x16x32_bf16 v[64:67], v[150:153], v[166:169], v[64:67]
	v_mfma_f32_16x16x32_bf16 v[60:63], v[158:161], v[166:169], v[60:63]
	v_mfma_f32_16x16x32_bf16 v[56:59], v[150:153], v[174:177], v[56:59]
	v_mfma_f32_16x16x32_bf16 v[48:51], v[158:161], v[174:177], v[48:51]
	v_mfma_f32_16x16x32_bf16 v[40:43], v[150:153], v[182:185], v[40:43]
	v_mfma_f32_16x16x32_bf16 v[32:35], v[158:161], v[182:185], v[32:35]
	v_mfma_f32_16x16x32_bf16 v[24:27], v[150:153], v[190:193], v[24:27]
	v_mfma_f32_16x16x32_bf16 v[16:19], v[158:161], v[190:193], v[16:19]
	v_mfma_f32_16x16x32_bf16 v[52:55], v[194:197], v[162:165], v[52:55]
	v_mfma_f32_16x16x32_bf16 v[44:47], v[202:205], v[162:165], v[44:47]
	v_mfma_f32_16x16x32_bf16 v[36:39], v[194:197], v[170:173], v[36:39]
	v_mfma_f32_16x16x32_bf16 v[28:31], v[202:205], v[170:173], v[28:31]
	v_mfma_f32_16x16x32_bf16 v[20:23], v[194:197], v[178:181], v[20:23]
	v_mfma_f32_16x16x32_bf16 v[12:15], v[202:205], v[178:181], v[12:15]
	v_mfma_f32_16x16x32_bf16 v[8:11], v[194:197], v[186:189], v[8:11]
	v_mfma_f32_16x16x32_bf16 v[4:7], v[202:205], v[186:189], v[4:7]
	v_mfma_f32_16x16x32_bf16 v[52:55], v[198:201], v[166:169], v[52:55]
	v_mfma_f32_16x16x32_bf16 v[44:47], v[206:209], v[166:169], v[44:47]
	v_mfma_f32_16x16x32_bf16 v[36:39], v[198:201], v[174:177], v[36:39]
	v_mfma_f32_16x16x32_bf16 v[28:31], v[206:209], v[174:177], v[28:31]
	v_mfma_f32_16x16x32_bf16 v[20:23], v[198:201], v[182:185], v[20:23]
	v_mfma_f32_16x16x32_bf16 v[12:15], v[206:209], v[182:185], v[12:15]
	v_mfma_f32_16x16x32_bf16 v[8:11], v[198:201], v[190:193], v[8:11]
	v_mfma_f32_16x16x32_bf16 v[4:7], v[206:209], v[190:193], v[4:7]
	s_barrier
	s_setprio 0
.LBB0_1094:
	s_setprio 0
	s_add_u32 s20, s18, 0xfff80080
	s_addc_u32 s21, s19, -1
	s_add_i32 s54, 0, 0x10000
	v_add_u32_e32 v146, s54, v1
	ds_read_b128 v[142:145], v146
	ds_read_b128 v[150:153], v146 offset:1024
	ds_read_b128 v[154:157], v146 offset:2048
	ds_read_b128 v[158:161], v146 offset:3072
	s_cmp_eq_u32 s53, 28
	s_cselect_b32 s25, s5, s21
	s_cselect_b32 s24, s49, s20
	s_cselect_b32 s21, s1, s52
	s_cselect_b32 s20, s50, s51
	ds_read_b128 v[162:165], v148
	ds_read_b128 v[166:169], v148 offset:1024
	ds_read_b128 v[170:173], v148 offset:2048
	ds_read_b128 v[174:177], v148 offset:3072
	ds_read_b128 v[178:181], v148 offset:4096
	ds_read_b128 v[182:185], v148 offset:5120
	ds_read_b128 v[186:189], v148 offset:6144
	ds_read_b128 v[190:193], v148 offset:7168
	s_add_i32 s56, 0, 0x14000
	v_add_u32_e32 v146, s56, v1
	ds_read_b128 v[194:197], v146
	ds_read_b128 v[198:201], v146 offset:1024
	ds_read_b128 v[202:205], v146 offset:2048
	ds_read_b128 v[206:209], v146 offset:3072
	s_add_i32 m0, s31, 0xc000
	s_nop 0
	global_load_lds_dwordx4 v138, s[18:19]
	s_add_i32 m0, s31, 0xe000
	s_nop 0
	global_load_lds_dwordx4 v140, s[18:19]
	s_waitcnt lgkmcnt(0)
	s_waitcnt vmcnt(8)
	s_setprio 1
	s_barrier
; #define PG8_STAGE(bufoff, gbase, voff) do { _Pragma("unroll") for (int _i = 0; _i < 2; ++_i) \
;         __builtin_amdgcn_global_load_lds((const unsigned*)((const char*)(gbase) + (voff)[_i]), (LAS unsigned*)(lds + (bufoff) + ldsw + _i * 8192), 16, 0, 0); } while (0)
; #define PG8_LDA(dst, b, h) do { _Pragma("unroll") for (int m = 0; m < 4; ++m) _Pragma("unroll") for (int k = 0; k < 2; ++k) dst[m][k] = *(const LAS bf16x8*)(lds + PG8_SA(b, h) + aoff + m * 2048 + k * 1024); } while (0)
; #define PG8_LDB(dst, b, h) do { _Pragma("unroll") for (int n = 0; n < 2; ++n) _Pragma("unroll") for (int k = 0; k < 2; ++k) dst[n][k] = *(const LAS bf16x8*)(lds + PG8_SB(b, h) + boff + n * 2048 + k * 1024); } while (0)
; #define PG8_MMA(ai, bj, At, Bt) do { __builtin_amdgcn_s_setprio(1); _Pragma("unroll") for (int m = 0; m < 4; ++m) _Pragma("unroll") for (int n = 0; n < 2; ++n) _Pragma("unroll") for (int k = 0; k < 2; ++k) \
;         acc[ai][bj][m][n] = __builtin_amdgcn_mfma_f32_16x16x32_bf16(Bt[n][k], At[m][k], acc[ai][bj][m][n], 0, 0, 0); __builtin_amdgcn_s_setprio(0); } while (0)
; #define PG8_WAIT_V(n) asm volatile("s_waitcnt vmcnt(" #n ")" ::: "memory")
; #define PG8_WAIT_L(n) asm volatile("s_waitcnt lgkmcnt(" #n ")" ::: "memory")
; #define PG8_BAR __builtin_amdgcn_s_barrier()
; #define PG8_SCHED __builtin_amdgcn_sched_barrier(0)
; template <class Epi, class Sched>
; __device__ __forceinline__ void gemm_phase(LAS unsigned char* lds, const Gemm g, const Sched& S, const Epi& E) {
;     ...
;             PG8_WAIT_L(8); PG8_BAR; PG8_WAIT_L(0); PG8_MMA(0, 0, At, B0); PG8_BAR; PG8_SCHED;
;             PG8_LDB(B1, 0, 1); PG8_STAGE(PG8_SB(0, 0), b2, voffB);
;             PG8_BAR; PG8_WAIT_L(0); PG8_MMA(0, 1, At, B1); PG8_BAR;
;             PG8_LDA(At, 0, 1); PG8_STAGE(PG8_SA(0, 0), a2, voffA);
;             PG8_BAR; PG8_WAIT_L(0); PG8_MMA(1, 0, At, B0); PG8_BAR; PG8_SCHED;
;             PG8_STAGE(PG8_SB(0, 1), b2 + hstepB, voffB);
;             PG8_WAIT_V(6); PG8_BAR; PG8_MMA(1, 1, At, B1); PG8_BAR;
	v_mfma_f32_16x16x32_bf16 v[128:131], v[142:145], v[162:165], v[128:131]
	v_mfma_f32_16x16x32_bf16 v[124:127], v[154:157], v[162:165], v[124:127]
	v_mfma_f32_16x16x32_bf16 v[120:123], v[142:145], v[170:173], v[120:123]
	v_mfma_f32_16x16x32_bf16 v[112:115], v[154:157], v[170:173], v[112:115]
	v_mfma_f32_16x16x32_bf16 v[104:107], v[142:145], v[178:181], v[104:107]
	v_mfma_f32_16x16x32_bf16 v[96:99], v[154:157], v[178:181], v[96:99]
	v_mfma_f32_16x16x32_bf16 v[88:91], v[142:145], v[186:189], v[88:91]
	v_mfma_f32_16x16x32_bf16 v[80:83], v[154:157], v[186:189], v[80:83]
	v_mfma_f32_16x16x32_bf16 v[128:131], v[150:153], v[166:169], v[128:131]
	v_mfma_f32_16x16x32_bf16 v[124:127], v[158:161], v[166:169], v[124:127]
	v_mfma_f32_16x16x32_bf16 v[120:123], v[150:153], v[174:177], v[120:123]
	v_mfma_f32_16x16x32_bf16 v[112:115], v[158:161], v[174:177], v[112:115]
	v_mfma_f32_16x16x32_bf16 v[104:107], v[150:153], v[182:185], v[104:107]
	v_mfma_f32_16x16x32_bf16 v[96:99], v[158:161], v[182:185], v[96:99]
	v_mfma_f32_16x16x32_bf16 v[88:91], v[150:153], v[190:193], v[88:91]
	v_mfma_f32_16x16x32_bf16 v[80:83], v[158:161], v[190:193], v[80:83]
	v_mfma_f32_16x16x32_bf16 v[116:119], v[194:197], v[162:165], v[116:119]
	v_mfma_f32_16x16x32_bf16 v[108:111], v[202:205], v[162:165], v[108:111]
	v_mfma_f32_16x16x32_bf16 v[100:103], v[194:197], v[170:173], v[100:103]
	v_mfma_f32_16x16x32_bf16 v[92:95], v[202:205], v[170:173], v[92:95]
	v_mfma_f32_16x16x32_bf16 v[84:87], v[194:197], v[178:181], v[84:87]
	v_mfma_f32_16x16x32_bf16 v[76:79], v[202:205], v[178:181], v[76:79]
	v_mfma_f32_16x16x32_bf16 v[72:75], v[194:197], v[186:189], v[72:75]
	v_mfma_f32_16x16x32_bf16 v[68:71], v[202:205], v[186:189], v[68:71]
	v_mfma_f32_16x16x32_bf16 v[116:119], v[198:201], v[166:169], v[116:119]
	v_mfma_f32_16x16x32_bf16 v[108:111], v[206:209], v[166:169], v[108:111]
	v_mfma_f32_16x16x32_bf16 v[100:103], v[198:201], v[174:177], v[100:103]
	v_mfma_f32_16x16x32_bf16 v[92:95], v[206:209], v[174:177], v[92:95]
	v_mfma_f32_16x16x32_bf16 v[84:87], v[198:201], v[182:185], v[84:87]
	v_mfma_f32_16x16x32_bf16 v[76:79], v[206:209], v[182:185], v[76:79]
	v_mfma_f32_16x16x32_bf16 v[72:75], v[198:201], v[190:193], v[72:75]
	v_mfma_f32_16x16x32_bf16 v[68:71], v[206:209], v[190:193], v[68:71]
	s_barrier
	s_setprio 0
	ds_read_b128 v[162:165], v148 offset:16384
	ds_read_b128 v[166:169], v148 offset:17408
	ds_read_b128 v[170:173], v148 offset:18432
	ds_read_b128 v[174:177], v148 offset:19456
	ds_read_b128 v[178:181], v148 offset:20480
	ds_read_b128 v[182:185], v148 offset:21504
	ds_read_b128 v[186:189], v148 offset:22528
	ds_read_b128 v[190:193], v148 offset:23552
	s_add_i32 s54, s54, s30
	v_lshl_add_u64 v[146:147], s[20:21], 0, v[2:3]
	s_mov_b32 m0, s54
	v_lshl_add_u64 v[210:211], s[20:21], 0, v[132:133]
	global_load_lds_dwordx4 v[146:147], off
	s_add_i32 m0, s54, 0x2000
	s_nop 0
	global_load_lds_dwordx4 v[210:211], off
	s_mov_b32 m0, s31
	v_lshl_add_u64 v[212:213], s[24:25], 0, v[136:137]
	global_load_lds_dwordx4 v[212:213], off
	v_lshl_add_u64 v[216:217], s[24:25], 0, v[134:135]
	s_mov_b32 m0, s35
	s_nop 0
	global_load_lds_dwordx4 v[216:217], off
	s_add_u32 s54, s20, 0x80000
	s_addc_u32 s55, s21, 0
	s_add_i32 s56, s56, s30
	s_mov_b32 m0, s56
	s_nop 0
	global_load_lds_dwordx4 v2, s[54:55]
	s_add_i32 m0, s56, 0x2000
	s_nop 0
	global_load_lds_dwordx4 v132, s[54:55]
	s_waitcnt lgkmcnt(0)
	s_waitcnt vmcnt(8)
	s_setprio 1
	s_barrier
	v_mfma_f32_16x16x32_bf16 v[64:67], v[142:145], v[162:165], v[64:67]
	v_mfma_f32_16x16x32_bf16 v[60:63], v[154:157], v[162:165], v[60:63]
	v_mfma_f32_16x16x32_bf16 v[56:59], v[142:145], v[170:173], v[56:59]
	v_mfma_f32_16x16x32_bf16 v[48:51], v[154:157], v[170:173], v[48:51]
	v_mfma_f32_16x16x32_bf16 v[40:43], v[142:145], v[178:181], v[40:43]
	v_mfma_f32_16x16x32_bf16 v[32:35], v[154:157], v[178:181], v[32:35]
	v_mfma_f32_16x16x32_bf16 v[24:27], v[142:145], v[186:189], v[24:27]
	v_mfma_f32_16x16x32_bf16 v[16:19], v[154:157], v[186:189], v[16:19]
	v_mfma_f32_16x16x32_bf16 v[64:67], v[150:153], v[166:169], v[64:67]
	v_mfma_f32_16x16x32_bf16 v[60:63], v[158:161], v[166:169], v[60:63]
	v_mfma_f32_16x16x32_bf16 v[56:59], v[150:153], v[174:177], v[56:59]
	v_mfma_f32_16x16x32_bf16 v[48:51], v[158:161], v[174:177], v[48:51]
	v_mfma_f32_16x16x32_bf16 v[40:43], v[150:153], v[182:185], v[40:43]
	v_mfma_f32_16x16x32_bf16 v[32:35], v[158:161], v[182:185], v[32:35]
	v_mfma_f32_16x16x32_bf16 v[24:27], v[150:153], v[190:193], v[24:27]
	v_mfma_f32_16x16x32_bf16 v[16:19], v[158:161], v[190:193], v[16:19]
	v_mfma_f32_16x16x32_bf16 v[52:55], v[194:197], v[162:165], v[52:55]
	v_mfma_f32_16x16x32_bf16 v[44:47], v[202:205], v[162:165], v[44:47]
	v_mfma_f32_16x16x32_bf16 v[36:39], v[194:197], v[170:173], v[36:39]
	v_mfma_f32_16x16x32_bf16 v[28:31], v[202:205], v[170:173], v[28:31]
	v_mfma_f32_16x16x32_bf16 v[20:23], v[194:197], v[178:181], v[20:23]
	v_mfma_f32_16x16x32_bf16 v[12:15], v[202:205], v[178:181], v[12:15]
	v_mfma_f32_16x16x32_bf16 v[8:11], v[194:197], v[186:189], v[8:11]
	v_mfma_f32_16x16x32_bf16 v[4:7], v[202:205], v[186:189], v[4:7]
	v_mfma_f32_16x16x32_bf16 v[52:55], v[198:201], v[166:169], v[52:55]
	v_mfma_f32_16x16x32_bf16 v[44:47], v[206:209], v[166:169], v[44:47]
	v_mfma_f32_16x16x32_bf16 v[36:39], v[198:201], v[174:177], v[36:39]
	v_mfma_f32_16x16x32_bf16 v[28:31], v[206:209], v[174:177], v[28:31]
	v_mfma_f32_16x16x32_bf16 v[20:23], v[198:201], v[182:185], v[20:23]
	v_mfma_f32_16x16x32_bf16 v[12:15], v[206:209], v[182:185], v[12:15]
	v_mfma_f32_16x16x32_bf16 v[8:11], v[198:201], v[190:193], v[8:11]
	v_mfma_f32_16x16x32_bf16 v[4:7], v[206:209], v[190:193], v[4:7]
	s_barrier
; #define PG8_STAGE(bufoff, gbase, voff) do { _Pragma("unroll") for (int _i = 0; _i < 2; ++_i) \
;         __builtin_amdgcn_global_load_lds((const unsigned*)((const char*)(gbase) + (voff)[_i]), (LAS unsigned*)(lds + (bufoff) + ldsw + _i * 8192), 16, 0, 0); } while (0)
; #define PG8_LDA(dst, b, h) do { _Pragma("unroll") for (int m = 0; m < 4; ++m) _Pragma("unroll") for (int k = 0; k < 2; ++k) dst[m][k] = *(const LAS bf16x8*)(lds + PG8_SA(b, h) + aoff + m * 2048 + k * 1024); } while (0)
; #define PG8_LDB(dst, b, h) do { _Pragma("unroll") for (int n = 0; n < 2; ++n) _Pragma("unroll") for (int k = 0; k < 2; ++k) dst[n][k] = *(const LAS bf16x8*)(lds + PG8_SB(b, h) + boff + n * 2048 + k * 1024); } while (0)
; #define PG8_MMA(ai, bj, At, Bt) do { __builtin_amdgcn_s_setprio(1); _Pragma("unroll") for (int m = 0; m < 4; ++m) _Pragma("unroll") for (int n = 0; n < 2; ++n) _Pragma("unroll") for (int k = 0; k < 2; ++k) \
;         acc[ai][bj][m][n] = __builtin_amdgcn_mfma_f32_16x16x32_bf16(Bt[n][k], At[m][k], acc[ai][bj][m][n], 0, 0, 0); __builtin_amdgcn_s_setprio(0); } while (0)
; #define PG8_WAIT_L(n) asm volatile("s_waitcnt lgkmcnt(" #n ")" ::: "memory")
; #define PG8_BAR __builtin_amdgcn_s_barrier()
; #define PG8_SCHED __builtin_amdgcn_sched_barrier(0)
; template <class Epi, class Sched>
; __device__ __forceinline__ void gemm_phase(LAS unsigned char* lds, const Gemm g, const Sched& S, const Epi& E) {
;     ...
;             PG8_LDB(B0, 1, 0); PG8_SCHED; PG8_LDA(At, 1, 0); PG8_STAGE(PG8_SA(0, 1), a2 + hstepA, voffA);
;             PG8_WAIT_L(8); PG8_BAR; PG8_WAIT_L(0); PG8_MMA(0, 0, At, B0); PG8_BAR; PG8_SCHED;
;             PG8_LDB(B1, 1, 1); PG8_STAGE(PG8_SB(1, 0), b3, voffB);
;             PG8_BAR; PG8_WAIT_L(0); PG8_MMA(0, 1, At, B1); PG8_BAR;
;             PG8_LDA(At, 1, 1); PG8_STAGE(PG8_SA(1, 0), a3, voffA);
;             PG8_BAR; PG8_WAIT_L(0); PG8_MMA(1, 0, At, B0); PG8_BAR; PG8_SCHED;
;             PG8_STAGE(PG8_SB(1, 1), b3 + hstepB, voffB);
	s_setprio 0
	s_add_i32 s54, 0, 0x18000
	v_add_u32_e32 v149, s54, v1
	ds_read_b128 v[142:145], v149
	ds_read_b128 v[150:153], v149 offset:1024
	ds_read_b128 v[154:157], v149 offset:2048
	ds_read_b128 v[158:161], v149 offset:3072
	s_add_u32 s24, s24, 0x80000
	s_addc_u32 s25, s25, 0
	ds_read_b128 v[162:165], v148 offset:32768
	ds_read_b128 v[166:169], v148 offset:33792
	ds_read_b128 v[170:173], v148 offset:34816
	ds_read_b128 v[174:177], v148 offset:35840
	ds_read_b128 v[178:181], v148 offset:36864
	ds_read_b128 v[182:185], v148 offset:37888
	ds_read_b128 v[186:189], v148 offset:38912
	ds_read_b128 v[190:193], v148 offset:39936
	s_mov_b32 m0, s36
	s_nop 0
	global_load_lds_dwordx4 v136, s[24:25]
	s_mov_b32 m0, s37
	s_nop 0
	global_load_lds_dwordx4 v134, s[24:25]
	s_add_i32 s24, 0, 0x1c000
	v_add_u32_e32 v149, s24, v1
	ds_read_b128 v[194:197], v149
	ds_read_b128 v[198:201], v149 offset:1024
	ds_read_b128 v[202:205], v149 offset:2048
	ds_read_b128 v[206:209], v149 offset:3072
	s_waitcnt lgkmcnt(0)
	s_waitcnt vmcnt(8)
	s_setprio 1
	s_barrier
	v_mfma_f32_16x16x32_bf16 v[128:131], v[142:145], v[162:165], v[128:131]
	v_mfma_f32_16x16x32_bf16 v[124:127], v[154:157], v[162:165], v[124:127]
	v_mfma_f32_16x16x32_bf16 v[120:123], v[142:145], v[170:173], v[120:123]
	v_mfma_f32_16x16x32_bf16 v[112:115], v[154:157], v[170:173], v[112:115]
	v_mfma_f32_16x16x32_bf16 v[104:107], v[142:145], v[178:181], v[104:107]
	v_mfma_f32_16x16x32_bf16 v[96:99], v[154:157], v[178:181], v[96:99]
	v_mfma_f32_16x16x32_bf16 v[88:91], v[142:145], v[186:189], v[88:91]
	v_mfma_f32_16x16x32_bf16 v[80:83], v[154:157], v[186:189], v[80:83]
	v_mfma_f32_16x16x32_bf16 v[128:131], v[150:153], v[166:169], v[128:131]
	v_mfma_f32_16x16x32_bf16 v[124:127], v[158:161], v[166:169], v[124:127]
	v_mfma_f32_16x16x32_bf16 v[120:123], v[150:153], v[174:177], v[120:123]
	v_mfma_f32_16x16x32_bf16 v[112:115], v[158:161], v[174:177], v[112:115]
	v_mfma_f32_16x16x32_bf16 v[104:107], v[150:153], v[182:185], v[104:107]
	v_mfma_f32_16x16x32_bf16 v[96:99], v[158:161], v[182:185], v[96:99]
	v_mfma_f32_16x16x32_bf16 v[88:91], v[150:153], v[190:193], v[88:91]
	v_mfma_f32_16x16x32_bf16 v[80:83], v[158:161], v[190:193], v[80:83]
	v_mfma_f32_16x16x32_bf16 v[116:119], v[194:197], v[162:165], v[116:119]
	v_mfma_f32_16x16x32_bf16 v[108:111], v[202:205], v[162:165], v[108:111]
	v_mfma_f32_16x16x32_bf16 v[100:103], v[194:197], v[170:173], v[100:103]
	v_mfma_f32_16x16x32_bf16 v[92:95], v[202:205], v[170:173], v[92:95]
	v_mfma_f32_16x16x32_bf16 v[84:87], v[194:197], v[178:181], v[84:87]
	v_mfma_f32_16x16x32_bf16 v[76:79], v[202:205], v[178:181], v[76:79]
	v_mfma_f32_16x16x32_bf16 v[72:75], v[194:197], v[186:189], v[72:75]
	v_mfma_f32_16x16x32_bf16 v[68:71], v[202:205], v[186:189], v[68:71]
	v_mfma_f32_16x16x32_bf16 v[116:119], v[198:201], v[166:169], v[116:119]
	v_mfma_f32_16x16x32_bf16 v[108:111], v[206:209], v[166:169], v[108:111]
	v_mfma_f32_16x16x32_bf16 v[100:103], v[198:201], v[174:177], v[100:103]
	v_mfma_f32_16x16x32_bf16 v[92:95], v[206:209], v[174:177], v[92:95]
	v_mfma_f32_16x16x32_bf16 v[84:87], v[198:201], v[182:185], v[84:87]
	v_mfma_f32_16x16x32_bf16 v[76:79], v[206:209], v[182:185], v[76:79]
	v_mfma_f32_16x16x32_bf16 v[72:75], v[198:201], v[190:193], v[72:75]
	v_mfma_f32_16x16x32_bf16 v[68:71], v[206:209], v[190:193], v[68:71]
	s_barrier
	s_setprio 0
	ds_read_b128 v[162:165], v148 offset:49152
	ds_read_b128 v[166:169], v148 offset:50176
	ds_read_b128 v[170:173], v148 offset:51200
	ds_read_b128 v[174:177], v148 offset:52224
	ds_read_b128 v[178:181], v148 offset:53248
	ds_read_b128 v[182:185], v148 offset:54272
	ds_read_b128 v[186:189], v148 offset:55296
	ds_read_b128 v[190:193], v148 offset:56320
	s_add_i32 s25, s54, s30
	v_lshl_add_u64 v[146:147], v[146:147], 0, s[8:9]
	s_mov_b32 m0, s25
	s_nop 0
	global_load_lds_dwordx4 v[146:147], off
	v_lshl_add_u64 v[146:147], v[210:211], 0, s[8:9]
	s_add_i32 m0, s25, 0x2000
	s_nop 0
	global_load_lds_dwordx4 v[146:147], off
	s_mov_b32 m0, s42
	v_lshl_add_u64 v[146:147], v[212:213], 0, s[8:9]
	global_load_lds_dwordx4 v[146:147], off
	v_lshl_add_u64 v[146:147], v[216:217], 0, s[8:9]
	s_mov_b32 m0, s43
	s_nop 0
	global_load_lds_dwordx4 v[146:147], off
	s_add_u32 s20, s20, 0x80080
	s_addc_u32 s21, s21, 0
	s_add_i32 s24, s24, s30
	s_mov_b32 m0, s24
	s_nop 0
	global_load_lds_dwordx4 v2, s[20:21]
	s_add_i32 m0, s24, 0x2000
	s_nop 0
	global_load_lds_dwordx4 v132, s[20:21]
	s_add_i32 s53, s53, 2
	s_add_u32 s18, s18, 0x100
	s_addc_u32 s19, s19, 0
	s_add_u32 s51, s51, 0x100
	s_addc_u32 s52, s52, 0
	s_cmp_gt_u32 s53, 29
	s_waitcnt lgkmcnt(0)
	s_waitcnt vmcnt(8)
	s_setprio 1
	s_barrier
; __device__ __forceinline__ unsigned cvt_pk_bf16(float lo, float hi) { const f32x2 v = {lo, hi}; const bf16v2_ r = __builtin_convertvector(v, bf16v2_); return __builtin_bit_cast(unsigned, r); }
; __device__ __forceinline__ int opaque_tid() { int t = threadIdx.x; asm volatile("" : "+v"(t)); return t; }
; #define PG8_MMA(ai, bj, At, Bt) do { __builtin_amdgcn_s_setprio(1); _Pragma("unroll") for (int m = 0; m < 4; ++m) _Pragma("unroll") for (int n = 0; n < 2; ++n) _Pragma("unroll") for (int k = 0; k < 2; ++k) \
;         acc[ai][bj][m][n] = __builtin_amdgcn_mfma_f32_16x16x32_bf16(Bt[n][k], At[m][k], acc[ai][bj][m][n], 0, 0, 0); __builtin_amdgcn_s_setprio(0); } while (0)
; #define PG8_WAIT_V(n) asm volatile("s_waitcnt vmcnt(" #n ")" ::: "memory")
; #define PG8_BAR __builtin_amdgcn_s_barrier()
;     __device__ __forceinline__ void operator()(const f32x4 (&acc)[2][2][4][2], const Unit& u, int wr, int wc, int ui, int) const {
;         const int ol_ = opaque_tid() & 63, fr = ol_ & 15, fq = ol_ >> 4;
;         const int row0 = u.pm * BM + wr * 64 + fr, col0 = u.pn * BM + wc * 32 + 8 * fq;
;         float r_[2][4];
;         if (rs) rs_read(r_, ui, wr, fr);
;         else {
; #pragma unroll
;             for (int ai = 0; ai < 2; ++ai)
; #pragma unroll
;                 for (int m = 0; m < 4; ++m) r_[ai][m] = 1.f;
;         }
; #pragma unroll
;         for (int ai = 0; ai < 2; ++ai)
; #pragma unroll
;             for (int m = 0; m < 4; ++m) { bf16_t* rowp = O + (size_t)(row0 + ai * HALF + m * 16) * ldc + col0; const float r = r_[ai][m];
; #pragma unroll
;                 for (int bj = 0; bj < 2; ++bj) { const f32x4 v0 = acc[ai][bj][m][0] * r, v1 = acc[ai][bj][m][1] * r;
;                     u32x4 w; w.x = cvt_pk_bf16(v0[0], v0[1]); w.y = cvt_pk_bf16(v0[2], v0[3]); w.z = cvt_pk_bf16(v1[0], v1[1]); w.w = cvt_pk_bf16(v1[2], v1[3]);
;                     *(u32x4*)(rowp + bj * HALF) = w; } }
; template <class Epi, class Sched>
; __device__ __forceinline__ void gemm_phase(LAS unsigned char* lds, const Gemm g, const Sched& S, const Epi& E) {
;     ...
;             PG8_WAIT_V(6); PG8_BAR; PG8_MMA(1, 1, At, B1); PG8_BAR;
	v_mfma_f32_16x16x32_bf16 v[64:67], v[142:145], v[162:165], v[64:67]
	v_mfma_f32_16x16x32_bf16 v[60:63], v[154:157], v[162:165], v[60:63]
	v_mfma_f32_16x16x32_bf16 v[56:59], v[142:145], v[170:173], v[56:59]
	v_mfma_f32_16x16x32_bf16 v[48:51], v[154:157], v[170:173], v[48:51]
	v_mfma_f32_16x16x32_bf16 v[40:43], v[142:145], v[178:181], v[40:43]
	v_mfma_f32_16x16x32_bf16 v[32:35], v[154:157], v[178:181], v[32:35]
	v_mfma_f32_16x16x32_bf16 v[24:27], v[142:145], v[186:189], v[24:27]
	v_mfma_f32_16x16x32_bf16 v[16:19], v[154:157], v[186:189], v[16:19]
	v_mfma_f32_16x16x32_bf16 v[64:67], v[150:153], v[166:169], v[64:67]
	v_mfma_f32_16x16x32_bf16 v[60:63], v[158:161], v[166:169], v[60:63]
	v_mfma_f32_16x16x32_bf16 v[56:59], v[150:153], v[174:177], v[56:59]
	v_mfma_f32_16x16x32_bf16 v[48:51], v[158:161], v[174:177], v[48:51]
	v_mfma_f32_16x16x32_bf16 v[40:43], v[150:153], v[182:185], v[40:43]
	v_mfma_f32_16x16x32_bf16 v[32:35], v[158:161], v[182:185], v[32:35]
	v_mfma_f32_16x16x32_bf16 v[24:27], v[150:153], v[190:193], v[24:27]
	v_mfma_f32_16x16x32_bf16 v[16:19], v[158:161], v[190:193], v[16:19]
	v_mfma_f32_16x16x32_bf16 v[52:55], v[194:197], v[162:165], v[52:55]
	v_mfma_f32_16x16x32_bf16 v[44:47], v[202:205], v[162:165], v[44:47]
	v_mfma_f32_16x16x32_bf16 v[36:39], v[194:197], v[170:173], v[36:39]
	v_mfma_f32_16x16x32_bf16 v[28:31], v[202:205], v[170:173], v[28:31]
	v_mfma_f32_16x16x32_bf16 v[20:23], v[194:197], v[178:181], v[20:23]
	v_mfma_f32_16x16x32_bf16 v[12:15], v[202:205], v[178:181], v[12:15]
	v_mfma_f32_16x16x32_bf16 v[8:11], v[194:197], v[186:189], v[8:11]
	v_mfma_f32_16x16x32_bf16 v[4:7], v[202:205], v[186:189], v[4:7]
	v_mfma_f32_16x16x32_bf16 v[52:55], v[198:201], v[166:169], v[52:55]
	v_mfma_f32_16x16x32_bf16 v[44:47], v[206:209], v[166:169], v[44:47]
	v_mfma_f32_16x16x32_bf16 v[36:39], v[198:201], v[174:177], v[36:39]
	v_mfma_f32_16x16x32_bf16 v[28:31], v[206:209], v[174:177], v[28:31]
	v_mfma_f32_16x16x32_bf16 v[20:23], v[198:201], v[182:185], v[20:23]
	v_mfma_f32_16x16x32_bf16 v[12:15], v[206:209], v[182:185], v[12:15]
	v_mfma_f32_16x16x32_bf16 v[8:11], v[198:201], v[190:193], v[8:11]
	v_mfma_f32_16x16x32_bf16 v[4:7], v[206:209], v[190:193], v[4:7]
	s_barrier
	s_cbranch_scc0 .LBB0_1094
	s_setprio 0
	s_lshl_b32 s1, s48, 10
	v_mov_b32_e32 v144, v0
	s_and_b32 s1, s1, 0x400
	s_add_i32 s1, s44, s1
	v_and_b32_e32 v145, 15, v144
	v_lshl_add_u32 v142, v145, 2, s1
	s_lshl_b32 s1, s47, 8
	v_lshrrev_b32_e32 v144, 1, v144
	v_and_or_b32 v144, v144, 24, s1
	ds_read2_b32 v[150:151], v142 offset1:16
	ds_read2_b32 v[152:153], v142 offset0:32 offset1:48
	ds_read2_b32 v[154:155], v142 offset0:128 offset1:144
	ds_read2_b32 v[142:143], v142 offset0:160 offset1:176
	v_or_b32_e32 v146, s39, v144
	v_or_b32_e32 v144, s38, v145
	v_lshl_add_u32 v149, s46, 8, v144
	v_ashrrev_i32_e32 v147, 31, v146
	v_mov_b64_e32 v[144:145], s[92:93]
	v_mad_i64_i32 v[156:157], s[18:19], v149, s11, v[144:145]
	v_lshlrev_b64 v[146:147], 1, v[146:147]
	s_waitcnt lgkmcnt(0)
	v_pk_mul_f32 v[130:131], v[130:131], v[150:151] op_sel_hi:[1,0]
	v_pk_mul_f32 v[128:129], v[128:129], v[150:151] op_sel_hi:[1,0]
	v_pk_mul_f32 v[158:159], v[126:127], v[150:151] op_sel_hi:[1,0]
	v_pk_mul_f32 v[126:127], v[124:125], v[150:151] op_sel_hi:[1,0]
	v_lshl_add_u64 v[156:157], v[156:157], 0, v[146:147]
	v_cvt_pk_bf16_f32 v124, v128, v129
	v_cvt_pk_bf16_f32 v125, v130, v131
	v_cvt_pk_bf16_f32 v126, v126, v127
	v_cvt_pk_bf16_f32 v127, v158, v159
	global_store_dwordx4 v[156:157], v[124:127], off
	v_pk_mul_f32 v[118:119], v[118:119], v[150:151] op_sel_hi:[1,0]
	v_pk_mul_f32 v[116:117], v[116:117], v[150:151] op_sel_hi:[1,0]
	v_pk_mul_f32 v[124:125], v[110:111], v[150:151] op_sel_hi:[1,0]
	v_pk_mul_f32 v[110:111], v[108:109], v[150:151] op_sel_hi:[1,0]
	v_cvt_pk_bf16_f32 v108, v116, v117
	v_cvt_pk_bf16_f32 v109, v118, v119
	v_cvt_pk_bf16_f32 v110, v110, v111
	v_cvt_pk_bf16_f32 v111, v124, v125
	global_store_dwordx4 v[156:157], v[108:111], off offset:256
	v_mov_b32_e32 v118, v151
	v_pk_mul_f32 v[114:115], v[114:115], v[118:119] op_sel_hi:[1,0]
	v_or_b32_e32 v108, 16, v149
	v_mad_i64_i32 v[108:109], s[18:19], v108, s11, v[144:145]
	v_lshl_add_u64 v[116:117], v[108:109], 0, v[146:147]
	v_pk_mul_f32 v[110:111], v[122:123], v[118:119] op_sel_hi:[1,0]
	v_pk_mul_f32 v[108:109], v[120:121], v[118:119] op_sel_hi:[1,0]
	v_pk_mul_f32 v[112:113], v[112:113], v[118:119] op_sel_hi:[1,0]
	v_cvt_pk_bf16_f32 v108, v108, v109
	v_cvt_pk_bf16_f32 v109, v110, v111
	v_cvt_pk_bf16_f32 v110, v112, v113
	v_cvt_pk_bf16_f32 v111, v114, v115
	global_store_dwordx4 v[116:117], v[108:111], off
	v_pk_mul_f32 v[102:103], v[102:103], v[118:119] op_sel_hi:[1,0]
	v_pk_mul_f32 v[100:101], v[100:101], v[118:119] op_sel_hi:[1,0]
	v_pk_mul_f32 v[108:109], v[94:95], v[118:119] op_sel_hi:[1,0]
	v_pk_mul_f32 v[94:95], v[92:93], v[118:119] op_sel_hi:[1,0]
	v_cvt_pk_bf16_f32 v92, v100, v101
	v_cvt_pk_bf16_f32 v93, v102, v103
	v_cvt_pk_bf16_f32 v94, v94, v95
	v_cvt_pk_bf16_f32 v95, v108, v109
	global_store_dwordx4 v[116:117], v[92:95], off offset:256
	v_pk_mul_f32 v[98:99], v[98:99], v[152:153] op_sel_hi:[1,0]
	v_pk_mul_f32 v[96:97], v[96:97], v[152:153] op_sel_hi:[1,0]
	v_or_b32_e32 v92, 32, v149
	v_mad_i64_i32 v[92:93], s[18:19], v92, s11, v[144:145]
	v_lshl_add_u64 v[100:101], v[92:93], 0, v[146:147]
	v_pk_mul_f32 v[94:95], v[106:107], v[152:153] op_sel_hi:[1,0]
	v_pk_mul_f32 v[92:93], v[104:105], v[152:153] op_sel_hi:[1,0]
	v_pk_mul_f32 v[86:87], v[86:87], v[152:153] op_sel_hi:[1,0]
	v_cvt_pk_bf16_f32 v92, v92, v93
	v_cvt_pk_bf16_f32 v93, v94, v95
	v_cvt_pk_bf16_f32 v94, v96, v97
	v_cvt_pk_bf16_f32 v95, v98, v99
; __device__ __forceinline__ unsigned cvt_pk_bf16(float lo, float hi) { const f32x2 v = {lo, hi}; const bf16v2_ r = __builtin_convertvector(v, bf16v2_); return __builtin_bit_cast(unsigned, r); }
; #define PG8_WAIT_V(n) asm volatile("s_waitcnt vmcnt(" #n ")" ::: "memory")
; #define PG8_BAR __builtin_amdgcn_s_barrier()
;     __device__ __forceinline__ void operator()(const f32x4 (&acc)[2][2][4][2], const Unit& u, int wr, int wc, int ui, int) const {
;     ...
; #pragma unroll
;         for (int ai = 0; ai < 2; ++ai)
; #pragma unroll
;             for (int m = 0; m < 4; ++m) { bf16_t* rowp = O + (size_t)(row0 + ai * HALF + m * 16) * ldc + col0; const float r = r_[ai][m];
; #pragma unroll
;                 for (int bj = 0; bj < 2; ++bj) { const f32x4 v0 = acc[ai][bj][m][0] * r, v1 = acc[ai][bj][m][1] * r;
;                     u32x4 w; w.x = cvt_pk_bf16(v0[0], v0[1]); w.y = cvt_pk_bf16(v0[2], v0[3]); w.z = cvt_pk_bf16(v1[0], v1[1]); w.w = cvt_pk_bf16(v1[2], v1[3]);
;                     *(u32x4*)(rowp + bj * HALF) = w; } }
; template <class Epi, class Sched>
; __device__ __forceinline__ void gemm_phase(LAS unsigned char* lds, const Gemm g, const Sched& S, const Epi& E) {
;     ...
;     PG8_WAIT_V(0);
;     if (wr == 0) PG8_BAR;
;     PG8_BAR;
	global_store_dwordx4 v[100:101], v[92:95], off
	v_pk_mul_f32 v[84:85], v[84:85], v[152:153] op_sel_hi:[1,0]
	v_pk_mul_f32 v[66:67], v[66:67], v[154:155] op_sel_hi:[1,0]
	v_pk_mul_f32 v[92:93], v[78:79], v[152:153] op_sel_hi:[1,0]
	v_pk_mul_f32 v[78:79], v[76:77], v[152:153] op_sel_hi:[1,0]
	v_cvt_pk_bf16_f32 v76, v84, v85
	v_cvt_pk_bf16_f32 v77, v86, v87
	v_cvt_pk_bf16_f32 v78, v78, v79
	v_cvt_pk_bf16_f32 v79, v92, v93
	global_store_dwordx4 v[100:101], v[76:79], off offset:256
	v_mov_b32_e32 v86, v153
	v_pk_mul_f32 v[82:83], v[82:83], v[86:87] op_sel_hi:[1,0]
	v_or_b32_e32 v76, 48, v149
	v_mad_i64_i32 v[76:77], s[18:19], v76, s11, v[144:145]
	v_lshl_add_u64 v[84:85], v[76:77], 0, v[146:147]
	v_pk_mul_f32 v[78:79], v[90:91], v[86:87] op_sel_hi:[1,0]
	v_pk_mul_f32 v[76:77], v[88:89], v[86:87] op_sel_hi:[1,0]
	v_pk_mul_f32 v[80:81], v[80:81], v[86:87] op_sel_hi:[1,0]
	v_cvt_pk_bf16_f32 v76, v76, v77
	v_cvt_pk_bf16_f32 v77, v78, v79
	v_cvt_pk_bf16_f32 v78, v80, v81
	v_cvt_pk_bf16_f32 v79, v82, v83
	global_store_dwordx4 v[84:85], v[76:79], off
	v_pk_mul_f32 v[74:75], v[74:75], v[86:87] op_sel_hi:[1,0]
	v_pk_mul_f32 v[72:73], v[72:73], v[86:87] op_sel_hi:[1,0]
	v_pk_mul_f32 v[76:77], v[70:71], v[86:87] op_sel_hi:[1,0]
	v_pk_mul_f32 v[70:71], v[68:69], v[86:87] op_sel_hi:[1,0]
	v_cvt_pk_bf16_f32 v68, v72, v73
	v_cvt_pk_bf16_f32 v69, v74, v75
	v_cvt_pk_bf16_f32 v70, v70, v71
	v_cvt_pk_bf16_f32 v71, v76, v77
	global_store_dwordx4 v[84:85], v[68:71], off offset:256
	v_pk_mul_f32 v[64:65], v[64:65], v[154:155] op_sel_hi:[1,0]
	v_pk_mul_f32 v[54:55], v[54:55], v[154:155] op_sel_hi:[1,0]
	v_add_u32_e32 v68, 0x80, v149
	v_mad_i64_i32 v[68:69], s[18:19], v68, s11, v[144:145]
	v_pk_mul_f32 v[70:71], v[62:63], v[154:155] op_sel_hi:[1,0]
	v_pk_mul_f32 v[62:63], v[60:61], v[154:155] op_sel_hi:[1,0]
	v_lshl_add_u64 v[68:69], v[68:69], 0, v[146:147]
	v_cvt_pk_bf16_f32 v60, v64, v65
	v_cvt_pk_bf16_f32 v61, v66, v67
	v_cvt_pk_bf16_f32 v62, v62, v63
	v_cvt_pk_bf16_f32 v63, v70, v71
	global_store_dwordx4 v[68:69], v[60:63], off
	v_pk_mul_f32 v[52:53], v[52:53], v[154:155] op_sel_hi:[1,0]
	v_pk_mul_f32 v[34:35], v[34:35], v[142:143] op_sel_hi:[1,0]
	v_pk_mul_f32 v[60:61], v[46:47], v[154:155] op_sel_hi:[1,0]
	v_pk_mul_f32 v[46:47], v[44:45], v[154:155] op_sel_hi:[1,0]
	v_cvt_pk_bf16_f32 v44, v52, v53
	v_cvt_pk_bf16_f32 v45, v54, v55
	v_cvt_pk_bf16_f32 v46, v46, v47
	v_cvt_pk_bf16_f32 v47, v60, v61
	global_store_dwordx4 v[68:69], v[44:47], off offset:256
	v_mov_b32_e32 v54, v155
	v_pk_mul_f32 v[50:51], v[50:51], v[54:55] op_sel_hi:[1,0]
	v_add_u32_e32 v44, 0x90, v149
	v_mad_i64_i32 v[44:45], s[18:19], v44, s11, v[144:145]
	v_lshl_add_u64 v[52:53], v[44:45], 0, v[146:147]
	v_pk_mul_f32 v[46:47], v[58:59], v[54:55] op_sel_hi:[1,0]
	v_pk_mul_f32 v[44:45], v[56:57], v[54:55] op_sel_hi:[1,0]
	v_pk_mul_f32 v[48:49], v[48:49], v[54:55] op_sel_hi:[1,0]
	v_cvt_pk_bf16_f32 v44, v44, v45
	v_cvt_pk_bf16_f32 v45, v46, v47
	v_cvt_pk_bf16_f32 v46, v48, v49
	v_cvt_pk_bf16_f32 v47, v50, v51
	global_store_dwordx4 v[52:53], v[44:47], off
	v_pk_mul_f32 v[38:39], v[38:39], v[54:55] op_sel_hi:[1,0]
	v_pk_mul_f32 v[36:37], v[36:37], v[54:55] op_sel_hi:[1,0]
	v_pk_mul_f32 v[44:45], v[30:31], v[54:55] op_sel_hi:[1,0]
	v_pk_mul_f32 v[30:31], v[28:29], v[54:55] op_sel_hi:[1,0]
	v_cvt_pk_bf16_f32 v28, v36, v37
	v_cvt_pk_bf16_f32 v29, v38, v39
	v_cvt_pk_bf16_f32 v30, v30, v31
	v_cvt_pk_bf16_f32 v31, v44, v45
	global_store_dwordx4 v[52:53], v[28:31], off offset:256
	v_pk_mul_f32 v[32:33], v[32:33], v[142:143] op_sel_hi:[1,0]
	v_pk_mul_f32 v[22:23], v[22:23], v[142:143] op_sel_hi:[1,0]
	v_add_u32_e32 v28, 0xa0, v149
	v_mad_i64_i32 v[28:29], s[18:19], v28, s11, v[144:145]
	v_lshl_add_u64 v[36:37], v[28:29], 0, v[146:147]
	v_pk_mul_f32 v[30:31], v[42:43], v[142:143] op_sel_hi:[1,0]
	v_pk_mul_f32 v[28:29], v[40:41], v[142:143] op_sel_hi:[1,0]
	v_pk_mul_f32 v[20:21], v[20:21], v[142:143] op_sel_hi:[1,0]
	v_cvt_pk_bf16_f32 v28, v28, v29
	v_cvt_pk_bf16_f32 v29, v30, v31
	v_cvt_pk_bf16_f32 v30, v32, v33
	v_cvt_pk_bf16_f32 v31, v34, v35
	global_store_dwordx4 v[36:37], v[28:31], off
	s_and_b64 vcc, exec, s[40:41]
	s_mov_b32 s47, s0
	v_pk_mul_f32 v[28:29], v[14:15], v[142:143] op_sel_hi:[1,0]
	v_pk_mul_f32 v[14:15], v[12:13], v[142:143] op_sel_hi:[1,0]
	v_cvt_pk_bf16_f32 v12, v20, v21
	v_cvt_pk_bf16_f32 v13, v22, v23
	v_cvt_pk_bf16_f32 v14, v14, v15
	v_cvt_pk_bf16_f32 v15, v28, v29
	global_store_dwordx4 v[36:37], v[12:15], off offset:256
	v_mov_b32_e32 v22, v143
	v_pk_mul_f32 v[18:19], v[18:19], v[22:23] op_sel_hi:[1,0]
	v_add_u32_e32 v12, 0xb0, v149
	v_mad_i64_i32 v[12:13], s[18:19], v12, s11, v[144:145]
	v_lshl_add_u64 v[20:21], v[12:13], 0, v[146:147]
	v_pk_mul_f32 v[14:15], v[26:27], v[22:23] op_sel_hi:[1,0]
	v_pk_mul_f32 v[12:13], v[24:25], v[22:23] op_sel_hi:[1,0]
	v_pk_mul_f32 v[16:17], v[16:17], v[22:23] op_sel_hi:[1,0]
	v_cvt_pk_bf16_f32 v12, v12, v13
	v_cvt_pk_bf16_f32 v13, v14, v15
	v_cvt_pk_bf16_f32 v14, v16, v17
	v_cvt_pk_bf16_f32 v15, v18, v19
	global_store_dwordx4 v[20:21], v[12:15], off
	v_pk_mul_f32 v[10:11], v[10:11], v[22:23] op_sel_hi:[1,0]
	v_pk_mul_f32 v[8:9], v[8:9], v[22:23] op_sel_hi:[1,0]
	v_pk_mul_f32 v[12:13], v[6:7], v[22:23] op_sel_hi:[1,0]
	v_pk_mul_f32 v[6:7], v[4:5], v[22:23] op_sel_hi:[1,0]
	v_cvt_pk_bf16_f32 v4, v8, v9
	v_cvt_pk_bf16_f32 v5, v10, v11
	v_cvt_pk_bf16_f32 v6, v6, v7
	v_cvt_pk_bf16_f32 v7, v12, v13
	s_mov_b32 s46, s4
	s_mov_b64 s[20:21], s[14:15]
	s_mov_b64 s[18:19], s[6:7]
	s_mov_b32 s48, s45
	global_store_dwordx4 v[20:21], v[4:7], off offset:256
	s_cbranch_vccz .LBB0_1089
	s_waitcnt vmcnt(0)
	s_cmpk_gt_u32 s2, 0xff
	s_cbranch_scc1 .LBB0_1098
	s_barrier

; #define PG8_STAGE(bufoff, gbase, voff) do { _Pragma("unroll") for (int _i = 0; _i < 2; ++_i) \
;         __builtin_amdgcn_global_load_lds((const unsigned*)((const char*)(gbase) + (voff)[_i]), (LAS unsigned*)(lds + (bufoff) + ldsw + _i * 8192), 16, 0, 0); } while (0)
; #define PG8_LDA(dst, b, h) do { _Pragma("unroll") for (int m = 0; m < 4; ++m) _Pragma("unroll") for (int k = 0; k < 2; ++k) dst[m][k] = *(const LAS bf16x8*)(lds + PG8_SA(b, h) + aoff + m * 2048 + k * 1024); } while (0)
; #define PG8_LDB(dst, b, h) do { _Pragma("unroll") for (int n = 0; n < 2; ++n) _Pragma("unroll") for (int k = 0; k < 2; ++k) dst[n][k] = *(const LAS bf16x8*)(lds + PG8_SB(b, h) + boff + n * 2048 + k * 1024); } while (0)
; #define PG8_WAIT_V(n) asm volatile("s_waitcnt vmcnt(" #n ")" ::: "memory")
; #define PG8_WAIT_L(n) asm volatile("s_waitcnt lgkmcnt(" #n ")" ::: "memory")
; #define PG8_BAR __builtin_amdgcn_s_barrier()
; #define PG8_SCHED __builtin_amdgcn_sched_barrier(0)
; template <class Epi, class Sched>
; __device__ __forceinline__ void gemm_phase(LAS unsigned char* lds, const Gemm g, const Sched& S, const Epi& E) {
;     ...
;         const bool has_next = S.next(ui + 1, nxt);
;         const char* nA = has_next ? (const char*)g.A + (size_t)nxt.pm * tstepA : cA; const char* nB = has_next ? (const char*)g.Bt + (size_t)nxt.pn * tstepB : cB;
;         for (int t = 0; t < nt; t += 2) {
;             const bool last = (t == nt - 2);
;             const char* a1 = cA + (size_t)(t + 1) * kstep;
;             const char* a2 = last ? nA : cA + (size_t)(t + 2) * kstep; const char* b2 = last ? nB : cB + (size_t)(t + 2) * kstep;
;             const char* a3 = a2 + kstep; const char* b3 = b2 + kstep;
;             if (last && has_next) S.a_ready(nxt);
;             PG8_LDB(B0, 0, 0); PG8_SCHED; PG8_LDA(At, 0, 0); PG8_STAGE(PG8_SA(1, 1), a1 + hstepA, voffA);
;             PG8_WAIT_L(8); PG8_BAR; PG8_WAIT_L(0); PG8_MMA(0, 0, At, B0); PG8_BAR; PG8_SCHED;
;             PG8_LDB(B1, 0, 1); PG8_STAGE(PG8_SB(0, 0), b2, voffB);
;             PG8_BAR; PG8_WAIT_L(0); PG8_MMA(0, 1, At, B1); PG8_BAR;
;             PG8_LDA(At, 0, 1); PG8_STAGE(PG8_SA(0, 0), a2, voffA);
;             PG8_BAR; PG8_WAIT_L(0); PG8_MMA(1, 0, At, B0); PG8_BAR; PG8_SCHED;
;             PG8_STAGE(PG8_SB(0, 1), b2 + hstepB, voffB);
;             PG8_WAIT_V(6); PG8_BAR; PG8_MMA(1, 1, At, B1); PG8_BAR;
.LBB0_1395:
	v_mov_b64_e32 v[4:5], 0x400
	s_ashr_i32 s15, s14, 31
	v_cmp_lt_i64_e32 vcc, s[4:5], v[4:5]
	s_lshl_b64 s[4:5], s[14:15], 20
	v_readlane_b32 s48, v252, 0
	v_readlane_b32 s49, v252, 1
	s_add_u32 s4, s48, s4
	s_addc_u32 s5, s49, s5
	s_and_b64 s[18:19], vcc, exec
	s_cselect_b32 s15, s5, s7
	s_cselect_b32 s47, s4, s6
	s_ashr_i32 s1, s0, 31
	s_lshl_b64 s[18:19], s[0:1], 20
	s_add_u32 s18, s28, s18
	s_addc_u32 s19, s29, s19
	s_and_b64 s[24:25], vcc, exec
	s_cselect_b32 s1, s19, s21
	s_cselect_b32 s48, s18, s20
	s_add_u32 s6, s6, 0x80080
	s_addc_u32 s7, s7, 0
	v_readlane_b32 s50, v252, 2
	v_readlane_b32 s51, v252, 3
	s_add_u32 s49, s20, 0x100
	s_addc_u32 s50, s21, 0
	s_mov_b32 s51, -2
	s_setprio 0
	s_add_u32 s20, s6, 0xfff80080
	s_addc_u32 s21, s7, -1
	s_add_i32 s52, 0, 0x10000
	v_add_u32_e32 v144, s52, v1
	ds_read_b128 v[132:135], v144
	ds_read_b128 v[136:139], v144 offset:1024
	ds_read_b128 v[140:143], v144 offset:2048
	ds_read_b128 v[144:147], v144 offset:3072
	s_cmp_eq_u32 s51, 28
	s_cselect_b32 s25, s15, s21
	s_cselect_b32 s24, s47, s20
	s_cselect_b32 s21, s1, s50
	s_cselect_b32 s20, s48, s49
	ds_read_b128 v[148:151], v224
	ds_read_b128 v[152:155], v224 offset:1024
	ds_read_b128 v[156:159], v224 offset:2048
	ds_read_b128 v[160:163], v224 offset:3072
	ds_read_b128 v[164:167], v224 offset:4096
	ds_read_b128 v[168:171], v224 offset:5120
	ds_read_b128 v[172:175], v224 offset:6144
	ds_read_b128 v[176:179], v224 offset:7168
	s_add_i32 s54, 0, 0x14000
	v_add_u32_e32 v202, s54, v1
	ds_read_b128 v[180:183], v202
	ds_read_b128 v[184:187], v202 offset:1024
	ds_read_b128 v[188:191], v202 offset:2048
	ds_read_b128 v[202:205], v202 offset:3072
	s_add_i32 m0, s31, 0xc000
	s_nop 0
	global_load_lds_dwordx4 v198, s[6:7]
	s_add_i32 m0, s31, 0xe000
	s_nop 0
	global_load_lds_dwordx4 v200, s[6:7]
	s_waitcnt lgkmcnt(0)
	s_waitcnt vmcnt(8)
	s_setprio 1
	s_barrier
	v_mfma_f32_16x16x32_bf16 v[128:131], v[132:135], v[148:151], 0
	v_mfma_f32_16x16x32_bf16 v[124:127], v[140:143], v[148:151], 0
	v_mfma_f32_16x16x32_bf16 v[112:115], v[132:135], v[156:159], 0
	v_mfma_f32_16x16x32_bf16 v[108:111], v[140:143], v[156:159], 0
	v_mfma_f32_16x16x32_bf16 v[100:103], v[132:135], v[164:167], 0
	v_mfma_f32_16x16x32_bf16 v[92:95], v[140:143], v[164:167], 0
	v_mfma_f32_16x16x32_bf16 v[84:87], v[132:135], v[172:175], 0
	v_mfma_f32_16x16x32_bf16 v[76:79], v[140:143], v[172:175], 0
	v_mfma_f32_16x16x32_bf16 v[128:131], v[136:139], v[152:155], v[128:131]
	v_mfma_f32_16x16x32_bf16 v[124:127], v[144:147], v[152:155], v[124:127]
	v_mfma_f32_16x16x32_bf16 v[112:115], v[136:139], v[160:163], v[112:115]
	v_mfma_f32_16x16x32_bf16 v[108:111], v[144:147], v[160:163], v[108:111]
	v_mfma_f32_16x16x32_bf16 v[100:103], v[136:139], v[168:171], v[100:103]
	v_mfma_f32_16x16x32_bf16 v[92:95], v[144:147], v[168:171], v[92:95]
	v_mfma_f32_16x16x32_bf16 v[84:87], v[136:139], v[176:179], v[84:87]
	v_mfma_f32_16x16x32_bf16 v[76:79], v[144:147], v[176:179], v[76:79]
	v_mfma_f32_16x16x32_bf16 v[120:123], v[180:183], v[148:151], 0
	v_mfma_f32_16x16x32_bf16 v[116:119], v[188:191], v[148:151], 0
	v_mfma_f32_16x16x32_bf16 v[104:107], v[180:183], v[156:159], 0
	v_mfma_f32_16x16x32_bf16 v[96:99], v[188:191], v[156:159], 0
	v_mfma_f32_16x16x32_bf16 v[88:91], v[180:183], v[164:167], 0
	v_mfma_f32_16x16x32_bf16 v[80:83], v[188:191], v[164:167], 0
	v_mfma_f32_16x16x32_bf16 v[72:75], v[180:183], v[172:175], 0
	v_mfma_f32_16x16x32_bf16 v[68:71], v[188:191], v[172:175], 0
	v_mfma_f32_16x16x32_bf16 v[120:123], v[184:187], v[152:155], v[120:123]
	v_mfma_f32_16x16x32_bf16 v[116:119], v[202:205], v[152:155], v[116:119]
	v_mfma_f32_16x16x32_bf16 v[104:107], v[184:187], v[160:163], v[104:107]
	v_mfma_f32_16x16x32_bf16 v[96:99], v[202:205], v[160:163], v[96:99]
	v_mfma_f32_16x16x32_bf16 v[88:91], v[184:187], v[168:171], v[88:91]
	v_mfma_f32_16x16x32_bf16 v[80:83], v[202:205], v[168:171], v[80:83]
	v_mfma_f32_16x16x32_bf16 v[72:75], v[184:187], v[176:179], v[72:75]
	v_mfma_f32_16x16x32_bf16 v[68:71], v[202:205], v[176:179], v[68:71]
	s_barrier
	s_setprio 0
	ds_read_b128 v[148:151], v224 offset:16384
	ds_read_b128 v[152:155], v224 offset:17408
	ds_read_b128 v[156:159], v224 offset:18432
	ds_read_b128 v[160:163], v224 offset:19456
	ds_read_b128 v[164:167], v224 offset:20480
	ds_read_b128 v[168:171], v224 offset:21504
	ds_read_b128 v[172:175], v224 offset:22528
	ds_read_b128 v[176:179], v224 offset:23552
	s_add_i32 s52, s52, s30
	v_lshl_add_u64 v[206:207], s[20:21], 0, v[2:3]
	s_mov_b32 m0, s52
	s_nop 0
	global_load_lds_dwordx4 v[206:207], off
	v_lshl_add_u64 v[208:209], s[20:21], 0, v[192:193]
	s_add_i32 m0, s52, 0x2000
	s_nop 0
	global_load_lds_dwordx4 v[208:209], off
	s_mov_b32 m0, s31
	v_lshl_add_u64 v[210:211], s[24:25], 0, v[196:197]
	global_load_lds_dwordx4 v[210:211], off
	v_lshl_add_u64 v[212:213], s[24:25], 0, v[194:195]
	s_mov_b32 m0, s35
	s_nop 0
	global_load_lds_dwordx4 v[212:213], off
	s_add_u32 s52, s20, 0x80000
	s_addc_u32 s53, s21, 0
	s_add_i32 s54, s54, s30
	s_mov_b32 m0, s54
	s_nop 0
	global_load_lds_dwordx4 v2, s[52:53]
	s_add_i32 m0, s54, 0x2000
	s_nop 0
	global_load_lds_dwordx4 v192, s[52:53]
	s_waitcnt lgkmcnt(0)
	s_waitcnt vmcnt(8)
	s_setprio 1
	s_barrier
; #define PG8_STAGE(bufoff, gbase, voff) do { _Pragma("unroll") for (int _i = 0; _i < 2; ++_i) \
;         __builtin_amdgcn_global_load_lds((const unsigned*)((const char*)(gbase) + (voff)[_i]), (LAS unsigned*)(lds + (bufoff) + ldsw + _i * 8192), 16, 0, 0); } while (0)
; #define PG8_LDA(dst, b, h) do { _Pragma("unroll") for (int m = 0; m < 4; ++m) _Pragma("unroll") for (int k = 0; k < 2; ++k) dst[m][k] = *(const LAS bf16x8*)(lds + PG8_SA(b, h) + aoff + m * 2048 + k * 1024); } while (0)
; #define PG8_LDB(dst, b, h) do { _Pragma("unroll") for (int n = 0; n < 2; ++n) _Pragma("unroll") for (int k = 0; k < 2; ++k) dst[n][k] = *(const LAS bf16x8*)(lds + PG8_SB(b, h) + boff + n * 2048 + k * 1024); } while (0)
; #define PG8_MMA(ai, bj, At, Bt) do { __builtin_amdgcn_s_setprio(1); _Pragma("unroll") for (int m = 0; m < 4; ++m) _Pragma("unroll") for (int n = 0; n < 2; ++n) _Pragma("unroll") for (int k = 0; k < 2; ++k) \
;         acc[ai][bj][m][n] = __builtin_amdgcn_mfma_f32_16x16x32_bf16(Bt[n][k], At[m][k], acc[ai][bj][m][n], 0, 0, 0); __builtin_amdgcn_s_setprio(0); } while (0)
; #define PG8_WAIT_V(n) asm volatile("s_waitcnt vmcnt(" #n ")" ::: "memory")
; #define PG8_WAIT_L(n) asm volatile("s_waitcnt lgkmcnt(" #n ")" ::: "memory")
; #define PG8_BAR __builtin_amdgcn_s_barrier()
; #define PG8_SCHED __builtin_amdgcn_sched_barrier(0)
; template <class Epi, class Sched>
; __device__ __forceinline__ void gemm_phase(LAS unsigned char* lds, const Gemm g, const Sched& S, const Epi& E) {
;     ...
;             PG8_WAIT_V(6); PG8_BAR; PG8_MMA(1, 1, At, B1); PG8_BAR;
;             PG8_LDB(B0, 1, 0); PG8_SCHED; PG8_LDA(At, 1, 0); PG8_STAGE(PG8_SA(0, 1), a2 + hstepA, voffA);
;             PG8_WAIT_L(8); PG8_BAR; PG8_WAIT_L(0); PG8_MMA(0, 0, At, B0); PG8_BAR; PG8_SCHED;
;             PG8_LDB(B1, 1, 1); PG8_STAGE(PG8_SB(1, 0), b3, voffB);
;             PG8_BAR; PG8_WAIT_L(0); PG8_MMA(0, 1, At, B1); PG8_BAR;
;             PG8_LDA(At, 1, 1); PG8_STAGE(PG8_SA(1, 0), a3, voffA);
;             PG8_BAR; PG8_WAIT_L(0); PG8_MMA(1, 0, At, B0); PG8_BAR; PG8_SCHED;
	v_mfma_f32_16x16x32_bf16 v[64:67], v[132:135], v[148:151], 0
	v_mfma_f32_16x16x32_bf16 v[60:63], v[140:143], v[148:151], 0
	v_mfma_f32_16x16x32_bf16 v[52:55], v[132:135], v[156:159], 0
	v_mfma_f32_16x16x32_bf16 v[44:47], v[140:143], v[156:159], 0
	v_mfma_f32_16x16x32_bf16 v[36:39], v[132:135], v[164:167], 0
	v_mfma_f32_16x16x32_bf16 v[28:31], v[140:143], v[164:167], 0
	v_mfma_f32_16x16x32_bf16 v[20:23], v[132:135], v[172:175], 0
	v_mfma_f32_16x16x32_bf16 v[12:15], v[140:143], v[172:175], 0
	v_mfma_f32_16x16x32_bf16 v[64:67], v[136:139], v[152:155], v[64:67]
	v_mfma_f32_16x16x32_bf16 v[60:63], v[144:147], v[152:155], v[60:63]
	v_mfma_f32_16x16x32_bf16 v[52:55], v[136:139], v[160:163], v[52:55]
	v_mfma_f32_16x16x32_bf16 v[44:47], v[144:147], v[160:163], v[44:47]
	v_mfma_f32_16x16x32_bf16 v[36:39], v[136:139], v[168:171], v[36:39]
	v_mfma_f32_16x16x32_bf16 v[28:31], v[144:147], v[168:171], v[28:31]
	v_mfma_f32_16x16x32_bf16 v[20:23], v[136:139], v[176:179], v[20:23]
	v_mfma_f32_16x16x32_bf16 v[12:15], v[144:147], v[176:179], v[12:15]
	v_mfma_f32_16x16x32_bf16 v[56:59], v[180:183], v[148:151], 0
	v_mfma_f32_16x16x32_bf16 v[48:51], v[188:191], v[148:151], 0
	v_mfma_f32_16x16x32_bf16 v[40:43], v[180:183], v[156:159], 0
	v_mfma_f32_16x16x32_bf16 v[32:35], v[188:191], v[156:159], 0
	v_mfma_f32_16x16x32_bf16 v[24:27], v[180:183], v[164:167], 0
	v_mfma_f32_16x16x32_bf16 v[16:19], v[188:191], v[164:167], 0
	v_mfma_f32_16x16x32_bf16 v[8:11], v[180:183], v[172:175], 0
	v_mfma_f32_16x16x32_bf16 v[4:7], v[188:191], v[172:175], 0
	v_mfma_f32_16x16x32_bf16 v[56:59], v[184:187], v[152:155], v[56:59]
	v_mfma_f32_16x16x32_bf16 v[48:51], v[202:205], v[152:155], v[48:51]
	v_mfma_f32_16x16x32_bf16 v[40:43], v[184:187], v[160:163], v[40:43]
	v_mfma_f32_16x16x32_bf16 v[32:35], v[202:205], v[160:163], v[32:35]
	v_mfma_f32_16x16x32_bf16 v[24:27], v[184:187], v[168:171], v[24:27]
	v_mfma_f32_16x16x32_bf16 v[16:19], v[202:205], v[168:171], v[16:19]
	v_mfma_f32_16x16x32_bf16 v[8:11], v[184:187], v[176:179], v[8:11]
	v_mfma_f32_16x16x32_bf16 v[4:7], v[202:205], v[176:179], v[4:7]
	s_barrier
	s_setprio 0
	s_add_i32 s52, 0, 0x18000
	v_add_u32_e32 v144, s52, v1
	ds_read_b128 v[132:135], v144
	ds_read_b128 v[136:139], v144 offset:1024
	ds_read_b128 v[140:143], v144 offset:2048
	ds_read_b128 v[144:147], v144 offset:3072
	s_add_u32 s24, s24, 0x80000
	s_addc_u32 s25, s25, 0
	ds_read_b128 v[148:151], v224 offset:32768
	ds_read_b128 v[152:155], v224 offset:33792
	ds_read_b128 v[156:159], v224 offset:34816
	ds_read_b128 v[160:163], v224 offset:35840
	ds_read_b128 v[164:167], v224 offset:36864
	ds_read_b128 v[168:171], v224 offset:37888
	ds_read_b128 v[172:175], v224 offset:38912
	ds_read_b128 v[176:179], v224 offset:39936
	s_mov_b32 m0, s36
	s_nop 0
	global_load_lds_dwordx4 v196, s[24:25]
	s_mov_b32 m0, s37
	s_nop 0
	global_load_lds_dwordx4 v194, s[24:25]
	s_add_i32 s24, 0, 0x1c000
	v_add_u32_e32 v202, s24, v1
	ds_read_b128 v[180:183], v202
	ds_read_b128 v[184:187], v202 offset:1024
	ds_read_b128 v[188:191], v202 offset:2048
	ds_read_b128 v[202:205], v202 offset:3072
	s_waitcnt lgkmcnt(0)
	s_waitcnt vmcnt(8)
	s_setprio 1
	s_barrier
	v_mfma_f32_16x16x32_bf16 v[128:131], v[132:135], v[148:151], v[128:131]
	v_mfma_f32_16x16x32_bf16 v[124:127], v[140:143], v[148:151], v[124:127]
	v_mfma_f32_16x16x32_bf16 v[112:115], v[132:135], v[156:159], v[112:115]
	v_mfma_f32_16x16x32_bf16 v[108:111], v[140:143], v[156:159], v[108:111]
	v_mfma_f32_16x16x32_bf16 v[100:103], v[132:135], v[164:167], v[100:103]
	v_mfma_f32_16x16x32_bf16 v[92:95], v[140:143], v[164:167], v[92:95]
	v_mfma_f32_16x16x32_bf16 v[84:87], v[132:135], v[172:175], v[84:87]
	v_mfma_f32_16x16x32_bf16 v[76:79], v[140:143], v[172:175], v[76:79]
	v_mfma_f32_16x16x32_bf16 v[128:131], v[136:139], v[152:155], v[128:131]
	v_mfma_f32_16x16x32_bf16 v[124:127], v[144:147], v[152:155], v[124:127]
	v_mfma_f32_16x16x32_bf16 v[112:115], v[136:139], v[160:163], v[112:115]
	v_mfma_f32_16x16x32_bf16 v[108:111], v[144:147], v[160:163], v[108:111]
	v_mfma_f32_16x16x32_bf16 v[100:103], v[136:139], v[168:171], v[100:103]
	v_mfma_f32_16x16x32_bf16 v[92:95], v[144:147], v[168:171], v[92:95]
	v_mfma_f32_16x16x32_bf16 v[84:87], v[136:139], v[176:179], v[84:87]
	v_mfma_f32_16x16x32_bf16 v[76:79], v[144:147], v[176:179], v[76:79]
	v_mfma_f32_16x16x32_bf16 v[120:123], v[180:183], v[148:151], v[120:123]
	v_mfma_f32_16x16x32_bf16 v[116:119], v[188:191], v[148:151], v[116:119]
	v_mfma_f32_16x16x32_bf16 v[104:107], v[180:183], v[156:159], v[104:107]
	v_mfma_f32_16x16x32_bf16 v[96:99], v[188:191], v[156:159], v[96:99]
	v_mfma_f32_16x16x32_bf16 v[88:91], v[180:183], v[164:167], v[88:91]
	v_mfma_f32_16x16x32_bf16 v[80:83], v[188:191], v[164:167], v[80:83]
	v_mfma_f32_16x16x32_bf16 v[72:75], v[180:183], v[172:175], v[72:75]
	v_mfma_f32_16x16x32_bf16 v[68:71], v[188:191], v[172:175], v[68:71]
	v_mfma_f32_16x16x32_bf16 v[120:123], v[184:187], v[152:155], v[120:123]
	v_mfma_f32_16x16x32_bf16 v[116:119], v[202:205], v[152:155], v[116:119]
	v_mfma_f32_16x16x32_bf16 v[104:107], v[184:187], v[160:163], v[104:107]
	v_mfma_f32_16x16x32_bf16 v[96:99], v[202:205], v[160:163], v[96:99]
	v_mfma_f32_16x16x32_bf16 v[88:91], v[184:187], v[168:171], v[88:91]
	v_mfma_f32_16x16x32_bf16 v[80:83], v[202:205], v[168:171], v[80:83]
	v_mfma_f32_16x16x32_bf16 v[72:75], v[184:187], v[176:179], v[72:75]
	v_mfma_f32_16x16x32_bf16 v[68:71], v[202:205], v[176:179], v[68:71]
	s_barrier
; #define PG8_STAGE(bufoff, gbase, voff) do { _Pragma("unroll") for (int _i = 0; _i < 2; ++_i) \
;         __builtin_amdgcn_global_load_lds((const unsigned*)((const char*)(gbase) + (voff)[_i]), (LAS unsigned*)(lds + (bufoff) + ldsw + _i * 8192), 16, 0, 0); } while (0)
; #define PG8_LDA(dst, b, h) do { _Pragma("unroll") for (int m = 0; m < 4; ++m) _Pragma("unroll") for (int k = 0; k < 2; ++k) dst[m][k] = *(const LAS bf16x8*)(lds + PG8_SA(b, h) + aoff + m * 2048 + k * 1024); } while (0)
; #define PG8_LDB(dst, b, h) do { _Pragma("unroll") for (int n = 0; n < 2; ++n) _Pragma("unroll") for (int k = 0; k < 2; ++k) dst[n][k] = *(const LAS bf16x8*)(lds + PG8_SB(b, h) + boff + n * 2048 + k * 1024); } while (0)
; #define PG8_WAIT_V(n) asm volatile("s_waitcnt vmcnt(" #n ")" ::: "memory")
; #define PG8_WAIT_L(n) asm volatile("s_waitcnt lgkmcnt(" #n ")" ::: "memory")
; #define PG8_BAR __builtin_amdgcn_s_barrier()
; #define PG8_SCHED __builtin_amdgcn_sched_barrier(0)
; template <class Epi, class Sched>
; __device__ __forceinline__ void gemm_phase(LAS unsigned char* lds, const Gemm g, const Sched& S, const Epi& E) {
;     ...
;             PG8_LDB(B0, 0, 0); PG8_SCHED; PG8_LDA(At, 0, 0); PG8_STAGE(PG8_SA(1, 1), a1 + hstepA, voffA);
;             PG8_WAIT_L(8); PG8_BAR; PG8_WAIT_L(0); PG8_MMA(0, 0, At, B0); PG8_BAR; PG8_SCHED;
;             PG8_LDB(B1, 0, 1); PG8_STAGE(PG8_SB(0, 0), b2, voffB);
;             PG8_BAR; PG8_WAIT_L(0); PG8_MMA(0, 1, At, B1); PG8_BAR;
;             PG8_LDA(At, 0, 1); PG8_STAGE(PG8_SA(0, 0), a2, voffA);
;             PG8_BAR; PG8_WAIT_L(0); PG8_MMA(1, 0, At, B0); PG8_BAR; PG8_SCHED;
;             PG8_STAGE(PG8_SB(0, 1), b2 + hstepB, voffB);
;             PG8_WAIT_V(6); PG8_BAR; PG8_MMA(1, 1, At, B1); PG8_BAR;
;             PG8_LDB(B0, 1, 0); PG8_SCHED; PG8_LDA(At, 1, 0); PG8_STAGE(PG8_SA(0, 1), a2 + hstepA, voffA);
;             PG8_WAIT_L(8); PG8_BAR; PG8_WAIT_L(0); PG8_MMA(0, 0, At, B0); PG8_BAR; PG8_SCHED;
;             PG8_LDB(B1, 1, 1); PG8_STAGE(PG8_SB(1, 0), b3, voffB);
;             PG8_BAR; PG8_WAIT_L(0); PG8_MMA(0, 1, At, B1); PG8_BAR;
;             PG8_LDA(At, 1, 1); PG8_STAGE(PG8_SA(1, 0), a3, voffA);
;             PG8_BAR; PG8_WAIT_L(0); PG8_MMA(1, 0, At, B0); PG8_BAR; PG8_SCHED;
;             PG8_STAGE(PG8_SB(1, 1), b3 + hstepB, voffB);
;             PG8_WAIT_V(6); PG8_BAR; PG8_MMA(1, 1, At, B1); PG8_BAR;
	s_setprio 0
	ds_read_b128 v[148:151], v224 offset:49152
	ds_read_b128 v[152:155], v224 offset:50176
	ds_read_b128 v[156:159], v224 offset:51200
	ds_read_b128 v[160:163], v224 offset:52224
	ds_read_b128 v[164:167], v224 offset:53248
	ds_read_b128 v[168:171], v224 offset:54272
	ds_read_b128 v[172:175], v224 offset:55296
	ds_read_b128 v[176:179], v224 offset:56320
	s_add_i32 s25, s52, s30
	v_lshl_add_u64 v[206:207], v[206:207], 0, s[8:9]
	s_mov_b32 m0, s25
	s_nop 0
	global_load_lds_dwordx4 v[206:207], off
	v_lshl_add_u64 v[206:207], v[208:209], 0, s[8:9]
	s_add_i32 m0, s25, 0x2000
	s_nop 0
	global_load_lds_dwordx4 v[206:207], off
	s_mov_b32 m0, s42
	v_lshl_add_u64 v[206:207], v[210:211], 0, s[8:9]
	global_load_lds_dwordx4 v[206:207], off
	v_lshl_add_u64 v[206:207], v[212:213], 0, s[8:9]
	s_mov_b32 m0, s43
	s_nop 0
	global_load_lds_dwordx4 v[206:207], off
	s_add_u32 s20, s20, 0x80080
	s_addc_u32 s21, s21, 0
	s_add_i32 s24, s24, s30
	s_mov_b32 m0, s24
	s_nop 0
	global_load_lds_dwordx4 v2, s[20:21]
	s_add_i32 m0, s24, 0x2000
	s_nop 0
	global_load_lds_dwordx4 v192, s[20:21]
	s_add_i32 s51, s51, 2
	s_add_u32 s6, s6, 0x100
	s_addc_u32 s7, s7, 0
	s_add_u32 s49, s49, 0x100
	s_addc_u32 s50, s50, 0
	s_cmp_gt_u32 s51, 29
	s_waitcnt lgkmcnt(0)
	s_waitcnt vmcnt(8)
	s_setprio 1
	s_barrier
	v_mfma_f32_16x16x32_bf16 v[64:67], v[132:135], v[148:151], v[64:67]
	v_mfma_f32_16x16x32_bf16 v[60:63], v[140:143], v[148:151], v[60:63]
	v_mfma_f32_16x16x32_bf16 v[52:55], v[132:135], v[156:159], v[52:55]
	v_mfma_f32_16x16x32_bf16 v[44:47], v[140:143], v[156:159], v[44:47]
	v_mfma_f32_16x16x32_bf16 v[36:39], v[132:135], v[164:167], v[36:39]
	v_mfma_f32_16x16x32_bf16 v[28:31], v[140:143], v[164:167], v[28:31]
	v_mfma_f32_16x16x32_bf16 v[20:23], v[132:135], v[172:175], v[20:23]
	v_mfma_f32_16x16x32_bf16 v[12:15], v[140:143], v[172:175], v[12:15]
	v_mfma_f32_16x16x32_bf16 v[64:67], v[136:139], v[152:155], v[64:67]
	v_mfma_f32_16x16x32_bf16 v[60:63], v[144:147], v[152:155], v[60:63]
	v_mfma_f32_16x16x32_bf16 v[52:55], v[136:139], v[160:163], v[52:55]
	v_mfma_f32_16x16x32_bf16 v[44:47], v[144:147], v[160:163], v[44:47]
	v_mfma_f32_16x16x32_bf16 v[36:39], v[136:139], v[168:171], v[36:39]
	v_mfma_f32_16x16x32_bf16 v[28:31], v[144:147], v[168:171], v[28:31]
	v_mfma_f32_16x16x32_bf16 v[20:23], v[136:139], v[176:179], v[20:23]
	v_mfma_f32_16x16x32_bf16 v[12:15], v[144:147], v[176:179], v[12:15]
	v_mfma_f32_16x16x32_bf16 v[56:59], v[180:183], v[148:151], v[56:59]
	v_mfma_f32_16x16x32_bf16 v[48:51], v[188:191], v[148:151], v[48:51]
	v_mfma_f32_16x16x32_bf16 v[40:43], v[180:183], v[156:159], v[40:43]
	v_mfma_f32_16x16x32_bf16 v[32:35], v[188:191], v[156:159], v[32:35]
	v_mfma_f32_16x16x32_bf16 v[24:27], v[180:183], v[164:167], v[24:27]
	v_mfma_f32_16x16x32_bf16 v[16:19], v[188:191], v[164:167], v[16:19]
	v_mfma_f32_16x16x32_bf16 v[8:11], v[180:183], v[172:175], v[8:11]
	v_mfma_f32_16x16x32_bf16 v[4:7], v[188:191], v[172:175], v[4:7]
	v_mfma_f32_16x16x32_bf16 v[56:59], v[184:187], v[152:155], v[56:59]
	v_mfma_f32_16x16x32_bf16 v[48:51], v[202:205], v[152:155], v[48:51]
	v_mfma_f32_16x16x32_bf16 v[40:43], v[184:187], v[160:163], v[40:43]
	v_mfma_f32_16x16x32_bf16 v[32:35], v[202:205], v[160:163], v[32:35]
	v_mfma_f32_16x16x32_bf16 v[24:27], v[184:187], v[168:171], v[24:27]
	v_mfma_f32_16x16x32_bf16 v[16:19], v[202:205], v[168:171], v[16:19]
	v_mfma_f32_16x16x32_bf16 v[8:11], v[184:187], v[176:179], v[8:11]
	v_mfma_f32_16x16x32_bf16 v[4:7], v[202:205], v[176:179], v[4:7]
	s_barrier
	s_setprio 0
.LBB0_1396:
	s_setprio 0
	s_add_u32 s20, s6, 0xfff80080
	s_addc_u32 s21, s7, -1
	s_add_i32 s52, 0, 0x10000
	v_add_u32_e32 v144, s52, v1
	ds_read_b128 v[132:135], v144
	ds_read_b128 v[136:139], v144 offset:1024
	ds_read_b128 v[140:143], v144 offset:2048
	ds_read_b128 v[144:147], v144 offset:3072
	s_cmp_eq_u32 s51, 28
	s_cselect_b32 s25, s15, s21
	s_cselect_b32 s24, s47, s20
	s_cselect_b32 s21, s1, s50
	s_cselect_b32 s20, s48, s49
	ds_read_b128 v[148:151], v224
	ds_read_b128 v[152:155], v224 offset:1024
	ds_read_b128 v[156:159], v224 offset:2048
	ds_read_b128 v[160:163], v224 offset:3072
	ds_read_b128 v[164:167], v224 offset:4096
	ds_read_b128 v[168:171], v224 offset:5120
	ds_read_b128 v[172:175], v224 offset:6144
	ds_read_b128 v[176:179], v224 offset:7168
	s_add_i32 s54, 0, 0x14000
	v_add_u32_e32 v202, s54, v1
	ds_read_b128 v[180:183], v202
	ds_read_b128 v[184:187], v202 offset:1024
	ds_read_b128 v[188:191], v202 offset:2048
	ds_read_b128 v[202:205], v202 offset:3072
	s_add_i32 m0, s31, 0xc000
	s_nop 0
	global_load_lds_dwordx4 v198, s[6:7]
	s_add_i32 m0, s31, 0xe000
	s_nop 0
	global_load_lds_dwordx4 v200, s[6:7]
	s_waitcnt lgkmcnt(0)
	s_waitcnt vmcnt(8)
	s_setprio 1
	s_barrier
; #define PG8_STAGE(bufoff, gbase, voff) do { _Pragma("unroll") for (int _i = 0; _i < 2; ++_i) \
;         __builtin_amdgcn_global_load_lds((const unsigned*)((const char*)(gbase) + (voff)[_i]), (LAS unsigned*)(lds + (bufoff) + ldsw + _i * 8192), 16, 0, 0); } while (0)
; #define PG8_LDA(dst, b, h) do { _Pragma("unroll") for (int m = 0; m < 4; ++m) _Pragma("unroll") for (int k = 0; k < 2; ++k) dst[m][k] = *(const LAS bf16x8*)(lds + PG8_SA(b, h) + aoff + m * 2048 + k * 1024); } while (0)
; #define PG8_LDB(dst, b, h) do { _Pragma("unroll") for (int n = 0; n < 2; ++n) _Pragma("unroll") for (int k = 0; k < 2; ++k) dst[n][k] = *(const LAS bf16x8*)(lds + PG8_SB(b, h) + boff + n * 2048 + k * 1024); } while (0)
; #define PG8_MMA(ai, bj, At, Bt) do { __builtin_amdgcn_s_setprio(1); _Pragma("unroll") for (int m = 0; m < 4; ++m) _Pragma("unroll") for (int n = 0; n < 2; ++n) _Pragma("unroll") for (int k = 0; k < 2; ++k) \
;         acc[ai][bj][m][n] = __builtin_amdgcn_mfma_f32_16x16x32_bf16(Bt[n][k], At[m][k], acc[ai][bj][m][n], 0, 0, 0); __builtin_amdgcn_s_setprio(0); } while (0)
; #define PG8_WAIT_V(n) asm volatile("s_waitcnt vmcnt(" #n ")" ::: "memory")
; #define PG8_WAIT_L(n) asm volatile("s_waitcnt lgkmcnt(" #n ")" ::: "memory")
; #define PG8_BAR __builtin_amdgcn_s_barrier()
; #define PG8_SCHED __builtin_amdgcn_sched_barrier(0)
; template <class Epi, class Sched>
; __device__ __forceinline__ void gemm_phase(LAS unsigned char* lds, const Gemm g, const Sched& S, const Epi& E) {
;     ...
;             PG8_LDB(B0, 0, 0); PG8_SCHED; PG8_LDA(At, 0, 0); PG8_STAGE(PG8_SA(1, 1), a1 + hstepA, voffA);
;             PG8_WAIT_L(8); PG8_BAR; PG8_WAIT_L(0); PG8_MMA(0, 0, At, B0); PG8_BAR; PG8_SCHED;
;             PG8_LDB(B1, 0, 1); PG8_STAGE(PG8_SB(0, 0), b2, voffB);
;             PG8_BAR; PG8_WAIT_L(0); PG8_MMA(0, 1, At, B1); PG8_BAR;
;             PG8_LDA(At, 0, 1); PG8_STAGE(PG8_SA(0, 0), a2, voffA);
;             PG8_BAR; PG8_WAIT_L(0); PG8_MMA(1, 0, At, B0); PG8_BAR; PG8_SCHED;
;             PG8_STAGE(PG8_SB(0, 1), b2 + hstepB, voffB);
;             PG8_WAIT_V(6); PG8_BAR; PG8_MMA(1, 1, At, B1); PG8_BAR;
	v_mfma_f32_16x16x32_bf16 v[128:131], v[132:135], v[148:151], v[128:131]
	v_mfma_f32_16x16x32_bf16 v[124:127], v[140:143], v[148:151], v[124:127]
	v_mfma_f32_16x16x32_bf16 v[112:115], v[132:135], v[156:159], v[112:115]
	v_mfma_f32_16x16x32_bf16 v[108:111], v[140:143], v[156:159], v[108:111]
	v_mfma_f32_16x16x32_bf16 v[100:103], v[132:135], v[164:167], v[100:103]
	v_mfma_f32_16x16x32_bf16 v[92:95], v[140:143], v[164:167], v[92:95]
	v_mfma_f32_16x16x32_bf16 v[84:87], v[132:135], v[172:175], v[84:87]
	v_mfma_f32_16x16x32_bf16 v[76:79], v[140:143], v[172:175], v[76:79]
	v_mfma_f32_16x16x32_bf16 v[128:131], v[136:139], v[152:155], v[128:131]
	v_mfma_f32_16x16x32_bf16 v[124:127], v[144:147], v[152:155], v[124:127]
	v_mfma_f32_16x16x32_bf16 v[112:115], v[136:139], v[160:163], v[112:115]
	v_mfma_f32_16x16x32_bf16 v[108:111], v[144:147], v[160:163], v[108:111]
	v_mfma_f32_16x16x32_bf16 v[100:103], v[136:139], v[168:171], v[100:103]
	v_mfma_f32_16x16x32_bf16 v[92:95], v[144:147], v[168:171], v[92:95]
	v_mfma_f32_16x16x32_bf16 v[84:87], v[136:139], v[176:179], v[84:87]
	v_mfma_f32_16x16x32_bf16 v[76:79], v[144:147], v[176:179], v[76:79]
	v_mfma_f32_16x16x32_bf16 v[120:123], v[180:183], v[148:151], v[120:123]
	v_mfma_f32_16x16x32_bf16 v[116:119], v[188:191], v[148:151], v[116:119]
	v_mfma_f32_16x16x32_bf16 v[104:107], v[180:183], v[156:159], v[104:107]
	v_mfma_f32_16x16x32_bf16 v[96:99], v[188:191], v[156:159], v[96:99]
	v_mfma_f32_16x16x32_bf16 v[88:91], v[180:183], v[164:167], v[88:91]
	v_mfma_f32_16x16x32_bf16 v[80:83], v[188:191], v[164:167], v[80:83]
	v_mfma_f32_16x16x32_bf16 v[72:75], v[180:183], v[172:175], v[72:75]
	v_mfma_f32_16x16x32_bf16 v[68:71], v[188:191], v[172:175], v[68:71]
	v_mfma_f32_16x16x32_bf16 v[120:123], v[184:187], v[152:155], v[120:123]
	v_mfma_f32_16x16x32_bf16 v[116:119], v[202:205], v[152:155], v[116:119]
	v_mfma_f32_16x16x32_bf16 v[104:107], v[184:187], v[160:163], v[104:107]
	v_mfma_f32_16x16x32_bf16 v[96:99], v[202:205], v[160:163], v[96:99]
	v_mfma_f32_16x16x32_bf16 v[88:91], v[184:187], v[168:171], v[88:91]
	v_mfma_f32_16x16x32_bf16 v[80:83], v[202:205], v[168:171], v[80:83]
	v_mfma_f32_16x16x32_bf16 v[72:75], v[184:187], v[176:179], v[72:75]
	v_mfma_f32_16x16x32_bf16 v[68:71], v[202:205], v[176:179], v[68:71]
	s_barrier
	s_setprio 0
	ds_read_b128 v[148:151], v224 offset:16384
	ds_read_b128 v[152:155], v224 offset:17408
	ds_read_b128 v[156:159], v224 offset:18432
	ds_read_b128 v[160:163], v224 offset:19456
	ds_read_b128 v[164:167], v224 offset:20480
	ds_read_b128 v[168:171], v224 offset:21504
	ds_read_b128 v[172:175], v224 offset:22528
	ds_read_b128 v[176:179], v224 offset:23552
	s_add_i32 s52, s52, s30
	v_lshl_add_u64 v[206:207], s[20:21], 0, v[2:3]
	s_mov_b32 m0, s52
	s_nop 0
	global_load_lds_dwordx4 v[206:207], off
	v_lshl_add_u64 v[208:209], s[20:21], 0, v[192:193]
	s_add_i32 m0, s52, 0x2000
	s_nop 0
	global_load_lds_dwordx4 v[208:209], off
	s_mov_b32 m0, s31
	v_lshl_add_u64 v[210:211], s[24:25], 0, v[196:197]
	global_load_lds_dwordx4 v[210:211], off
	v_lshl_add_u64 v[212:213], s[24:25], 0, v[194:195]
	s_mov_b32 m0, s35
	s_nop 0
	global_load_lds_dwordx4 v[212:213], off
	s_add_u32 s52, s20, 0x80000
	s_addc_u32 s53, s21, 0
	s_add_i32 s54, s54, s30
	s_mov_b32 m0, s54
	s_nop 0
	global_load_lds_dwordx4 v2, s[52:53]
	s_add_i32 m0, s54, 0x2000
	s_nop 0
	global_load_lds_dwordx4 v192, s[52:53]
	s_waitcnt lgkmcnt(0)
	s_waitcnt vmcnt(8)
	s_setprio 1
	s_barrier
	v_mfma_f32_16x16x32_bf16 v[64:67], v[132:135], v[148:151], v[64:67]
	v_mfma_f32_16x16x32_bf16 v[60:63], v[140:143], v[148:151], v[60:63]
	v_mfma_f32_16x16x32_bf16 v[52:55], v[132:135], v[156:159], v[52:55]
	v_mfma_f32_16x16x32_bf16 v[44:47], v[140:143], v[156:159], v[44:47]
	v_mfma_f32_16x16x32_bf16 v[36:39], v[132:135], v[164:167], v[36:39]
	v_mfma_f32_16x16x32_bf16 v[28:31], v[140:143], v[164:167], v[28:31]
	v_mfma_f32_16x16x32_bf16 v[20:23], v[132:135], v[172:175], v[20:23]
	v_mfma_f32_16x16x32_bf16 v[12:15], v[140:143], v[172:175], v[12:15]
	v_mfma_f32_16x16x32_bf16 v[64:67], v[136:139], v[152:155], v[64:67]
	v_mfma_f32_16x16x32_bf16 v[60:63], v[144:147], v[152:155], v[60:63]
	v_mfma_f32_16x16x32_bf16 v[52:55], v[136:139], v[160:163], v[52:55]
	v_mfma_f32_16x16x32_bf16 v[44:47], v[144:147], v[160:163], v[44:47]
	v_mfma_f32_16x16x32_bf16 v[36:39], v[136:139], v[168:171], v[36:39]
	v_mfma_f32_16x16x32_bf16 v[28:31], v[144:147], v[168:171], v[28:31]
	v_mfma_f32_16x16x32_bf16 v[20:23], v[136:139], v[176:179], v[20:23]
	v_mfma_f32_16x16x32_bf16 v[12:15], v[144:147], v[176:179], v[12:15]
	v_mfma_f32_16x16x32_bf16 v[56:59], v[180:183], v[148:151], v[56:59]
	v_mfma_f32_16x16x32_bf16 v[48:51], v[188:191], v[148:151], v[48:51]
	v_mfma_f32_16x16x32_bf16 v[40:43], v[180:183], v[156:159], v[40:43]
	v_mfma_f32_16x16x32_bf16 v[32:35], v[188:191], v[156:159], v[32:35]
	v_mfma_f32_16x16x32_bf16 v[24:27], v[180:183], v[164:167], v[24:27]
	v_mfma_f32_16x16x32_bf16 v[16:19], v[188:191], v[164:167], v[16:19]
	v_mfma_f32_16x16x32_bf16 v[8:11], v[180:183], v[172:175], v[8:11]
	v_mfma_f32_16x16x32_bf16 v[4:7], v[188:191], v[172:175], v[4:7]
	v_mfma_f32_16x16x32_bf16 v[56:59], v[184:187], v[152:155], v[56:59]
	v_mfma_f32_16x16x32_bf16 v[48:51], v[202:205], v[152:155], v[48:51]
	v_mfma_f32_16x16x32_bf16 v[40:43], v[184:187], v[160:163], v[40:43]
	v_mfma_f32_16x16x32_bf16 v[32:35], v[202:205], v[160:163], v[32:35]
	v_mfma_f32_16x16x32_bf16 v[24:27], v[184:187], v[168:171], v[24:27]
	v_mfma_f32_16x16x32_bf16 v[16:19], v[202:205], v[168:171], v[16:19]
	v_mfma_f32_16x16x32_bf16 v[8:11], v[184:187], v[176:179], v[8:11]
	v_mfma_f32_16x16x32_bf16 v[4:7], v[202:205], v[176:179], v[4:7]
	s_barrier
; #define PG8_STAGE(bufoff, gbase, voff) do { _Pragma("unroll") for (int _i = 0; _i < 2; ++_i) \
;         __builtin_amdgcn_global_load_lds((const unsigned*)((const char*)(gbase) + (voff)[_i]), (LAS unsigned*)(lds + (bufoff) + ldsw + _i * 8192), 16, 0, 0); } while (0)
; #define PG8_LDA(dst, b, h) do { _Pragma("unroll") for (int m = 0; m < 4; ++m) _Pragma("unroll") for (int k = 0; k < 2; ++k) dst[m][k] = *(const LAS bf16x8*)(lds + PG8_SA(b, h) + aoff + m * 2048 + k * 1024); } while (0)
; #define PG8_LDB(dst, b, h) do { _Pragma("unroll") for (int n = 0; n < 2; ++n) _Pragma("unroll") for (int k = 0; k < 2; ++k) dst[n][k] = *(const LAS bf16x8*)(lds + PG8_SB(b, h) + boff + n * 2048 + k * 1024); } while (0)
; #define PG8_MMA(ai, bj, At, Bt) do { __builtin_amdgcn_s_setprio(1); _Pragma("unroll") for (int m = 0; m < 4; ++m) _Pragma("unroll") for (int n = 0; n < 2; ++n) _Pragma("unroll") for (int k = 0; k < 2; ++k) \
;         acc[ai][bj][m][n] = __builtin_amdgcn_mfma_f32_16x16x32_bf16(Bt[n][k], At[m][k], acc[ai][bj][m][n], 0, 0, 0); __builtin_amdgcn_s_setprio(0); } while (0)
; #define PG8_WAIT_V(n) asm volatile("s_waitcnt vmcnt(" #n ")" ::: "memory")
; #define PG8_WAIT_L(n) asm volatile("s_waitcnt lgkmcnt(" #n ")" ::: "memory")
; #define PG8_BAR __builtin_amdgcn_s_barrier()
; #define PG8_SCHED __builtin_amdgcn_sched_barrier(0)
; template <class Epi, class Sched>
; __device__ __forceinline__ void gemm_phase(LAS unsigned char* lds, const Gemm g, const Sched& S, const Epi& E) {
;     ...
;             PG8_LDB(B0, 1, 0); PG8_SCHED; PG8_LDA(At, 1, 0); PG8_STAGE(PG8_SA(0, 1), a2 + hstepA, voffA);
;             PG8_WAIT_L(8); PG8_BAR; PG8_WAIT_L(0); PG8_MMA(0, 0, At, B0); PG8_BAR; PG8_SCHED;
;             PG8_LDB(B1, 1, 1); PG8_STAGE(PG8_SB(1, 0), b3, voffB);
;             PG8_BAR; PG8_WAIT_L(0); PG8_MMA(0, 1, At, B1); PG8_BAR;
;             PG8_LDA(At, 1, 1); PG8_STAGE(PG8_SA(1, 0), a3, voffA);
;             PG8_BAR; PG8_WAIT_L(0); PG8_MMA(1, 0, At, B0); PG8_BAR; PG8_SCHED;
;             PG8_STAGE(PG8_SB(1, 1), b3 + hstepB, voffB);
;             PG8_WAIT_V(6); PG8_BAR; PG8_MMA(1, 1, At, B1); PG8_BAR;
	s_setprio 0
	s_add_i32 s52, 0, 0x18000
	v_add_u32_e32 v144, s52, v1
	ds_read_b128 v[132:135], v144
	ds_read_b128 v[136:139], v144 offset:1024
	ds_read_b128 v[140:143], v144 offset:2048
	ds_read_b128 v[144:147], v144 offset:3072
	s_add_u32 s24, s24, 0x80000
	s_addc_u32 s25, s25, 0
	ds_read_b128 v[148:151], v224 offset:32768
	ds_read_b128 v[152:155], v224 offset:33792
	ds_read_b128 v[156:159], v224 offset:34816
	ds_read_b128 v[160:163], v224 offset:35840
	ds_read_b128 v[164:167], v224 offset:36864
	ds_read_b128 v[168:171], v224 offset:37888
	ds_read_b128 v[172:175], v224 offset:38912
	ds_read_b128 v[176:179], v224 offset:39936
	s_mov_b32 m0, s36
	s_nop 0
	global_load_lds_dwordx4 v196, s[24:25]
	s_mov_b32 m0, s37
	s_nop 0
	global_load_lds_dwordx4 v194, s[24:25]
	s_add_i32 s24, 0, 0x1c000
	v_add_u32_e32 v202, s24, v1
	ds_read_b128 v[180:183], v202
	ds_read_b128 v[184:187], v202 offset:1024
	ds_read_b128 v[188:191], v202 offset:2048
	ds_read_b128 v[202:205], v202 offset:3072
	s_waitcnt lgkmcnt(0)
	s_waitcnt vmcnt(8)
	s_setprio 1
	s_barrier
	v_mfma_f32_16x16x32_bf16 v[128:131], v[132:135], v[148:151], v[128:131]
	v_mfma_f32_16x16x32_bf16 v[124:127], v[140:143], v[148:151], v[124:127]
	v_mfma_f32_16x16x32_bf16 v[112:115], v[132:135], v[156:159], v[112:115]
	v_mfma_f32_16x16x32_bf16 v[108:111], v[140:143], v[156:159], v[108:111]
	v_mfma_f32_16x16x32_bf16 v[100:103], v[132:135], v[164:167], v[100:103]
	v_mfma_f32_16x16x32_bf16 v[92:95], v[140:143], v[164:167], v[92:95]
	v_mfma_f32_16x16x32_bf16 v[84:87], v[132:135], v[172:175], v[84:87]
	v_mfma_f32_16x16x32_bf16 v[76:79], v[140:143], v[172:175], v[76:79]
	v_mfma_f32_16x16x32_bf16 v[128:131], v[136:139], v[152:155], v[128:131]
	v_mfma_f32_16x16x32_bf16 v[124:127], v[144:147], v[152:155], v[124:127]
	v_mfma_f32_16x16x32_bf16 v[112:115], v[136:139], v[160:163], v[112:115]
	v_mfma_f32_16x16x32_bf16 v[108:111], v[144:147], v[160:163], v[108:111]
	v_mfma_f32_16x16x32_bf16 v[100:103], v[136:139], v[168:171], v[100:103]
	v_mfma_f32_16x16x32_bf16 v[92:95], v[144:147], v[168:171], v[92:95]
	v_mfma_f32_16x16x32_bf16 v[84:87], v[136:139], v[176:179], v[84:87]
	v_mfma_f32_16x16x32_bf16 v[76:79], v[144:147], v[176:179], v[76:79]
	v_mfma_f32_16x16x32_bf16 v[120:123], v[180:183], v[148:151], v[120:123]
	v_mfma_f32_16x16x32_bf16 v[116:119], v[188:191], v[148:151], v[116:119]
	v_mfma_f32_16x16x32_bf16 v[104:107], v[180:183], v[156:159], v[104:107]
	v_mfma_f32_16x16x32_bf16 v[96:99], v[188:191], v[156:159], v[96:99]
	v_mfma_f32_16x16x32_bf16 v[88:91], v[180:183], v[164:167], v[88:91]
	v_mfma_f32_16x16x32_bf16 v[80:83], v[188:191], v[164:167], v[80:83]
	v_mfma_f32_16x16x32_bf16 v[72:75], v[180:183], v[172:175], v[72:75]
	v_mfma_f32_16x16x32_bf16 v[68:71], v[188:191], v[172:175], v[68:71]
	v_mfma_f32_16x16x32_bf16 v[120:123], v[184:187], v[152:155], v[120:123]
	v_mfma_f32_16x16x32_bf16 v[116:119], v[202:205], v[152:155], v[116:119]
	v_mfma_f32_16x16x32_bf16 v[104:107], v[184:187], v[160:163], v[104:107]
	v_mfma_f32_16x16x32_bf16 v[96:99], v[202:205], v[160:163], v[96:99]
	v_mfma_f32_16x16x32_bf16 v[88:91], v[184:187], v[168:171], v[88:91]
	v_mfma_f32_16x16x32_bf16 v[80:83], v[202:205], v[168:171], v[80:83]
	v_mfma_f32_16x16x32_bf16 v[72:75], v[184:187], v[176:179], v[72:75]
	v_mfma_f32_16x16x32_bf16 v[68:71], v[202:205], v[176:179], v[68:71]
	s_barrier
	s_setprio 0
	ds_read_b128 v[148:151], v224 offset:49152
	ds_read_b128 v[152:155], v224 offset:50176
	ds_read_b128 v[156:159], v224 offset:51200
	ds_read_b128 v[160:163], v224 offset:52224
	ds_read_b128 v[164:167], v224 offset:53248
	ds_read_b128 v[168:171], v224 offset:54272
	ds_read_b128 v[172:175], v224 offset:55296
	ds_read_b128 v[176:179], v224 offset:56320
	s_add_i32 s25, s52, s30
	v_lshl_add_u64 v[206:207], v[206:207], 0, s[8:9]
	s_mov_b32 m0, s25
	s_nop 0
	global_load_lds_dwordx4 v[206:207], off
	v_lshl_add_u64 v[206:207], v[208:209], 0, s[8:9]
	s_add_i32 m0, s25, 0x2000
	s_nop 0
	global_load_lds_dwordx4 v[206:207], off
	s_mov_b32 m0, s42
	v_lshl_add_u64 v[206:207], v[210:211], 0, s[8:9]
	global_load_lds_dwordx4 v[206:207], off
	v_lshl_add_u64 v[206:207], v[212:213], 0, s[8:9]
	s_mov_b32 m0, s43
	s_nop 0
	global_load_lds_dwordx4 v[206:207], off
	s_add_u32 s20, s20, 0x80080
	s_addc_u32 s21, s21, 0
	s_add_i32 s24, s24, s30
	s_mov_b32 m0, s24
	s_nop 0
	global_load_lds_dwordx4 v2, s[20:21]
	s_add_i32 m0, s24, 0x2000
	s_nop 0
	global_load_lds_dwordx4 v192, s[20:21]
	s_add_i32 s51, s51, 2
	s_add_u32 s6, s6, 0x100
	s_addc_u32 s7, s7, 0
	s_add_u32 s49, s49, 0x100
	s_addc_u32 s50, s50, 0
	s_cmp_gt_u32 s51, 29
	s_waitcnt lgkmcnt(0)
	s_waitcnt vmcnt(8)
	s_setprio 1
	s_barrier
; __device__ __forceinline__ int opaque_tid() { int t = threadIdx.x; asm volatile("" : "+v"(t)); return t; }
; #define PG8_MMA(ai, bj, At, Bt) do { __builtin_amdgcn_s_setprio(1); _Pragma("unroll") for (int m = 0; m < 4; ++m) _Pragma("unroll") for (int n = 0; n < 2; ++n) _Pragma("unroll") for (int k = 0; k < 2; ++k) \
;         acc[ai][bj][m][n] = __builtin_amdgcn_mfma_f32_16x16x32_bf16(Bt[n][k], At[m][k], acc[ai][bj][m][n], 0, 0, 0); __builtin_amdgcn_s_setprio(0); } while (0)
; #define PG8_WAIT_V(n) asm volatile("s_waitcnt vmcnt(" #n ")" ::: "memory")
; #define PG8_BAR __builtin_amdgcn_s_barrier()
;     __device__ __forceinline__ void operator()(const f32x4 (&acc)[2][2][4][2], const Unit& u, int wr, int wc, int, int) const {
;         const int ol_ = opaque_tid() & 63, fr = ol_ & 15, fq = ol_ >> 4;
;         const int row0 = u.pm * BM + wr * 64 + fr, col0 = u.pn * BM + wc * 32 + 8 * fq;
;         u32x4 cin[2][4][2];
; #pragma unroll
;         for (int ai = 0; ai < 2; ++ai)
; #pragma unroll
;             for (int m = 0; m < 4; ++m)
; #pragma unroll
;                 for (int bj = 0; bj < 2; ++bj) cin[ai][m][bj] = *(const u32x4*)(C + (size_t)(row0 + ai * HALF + m * 16) * ldc + col0 + bj * HALF);
; template <class Epi, class Sched>
; __device__ __forceinline__ void gemm_phase(LAS unsigned char* lds, const Gemm g, const Sched& S, const Epi& E) {
;     ...
;             PG8_WAIT_V(6); PG8_BAR; PG8_MMA(1, 1, At, B1); PG8_BAR;
;         }
	v_mfma_f32_16x16x32_bf16 v[64:67], v[132:135], v[148:151], v[64:67]
	v_mfma_f32_16x16x32_bf16 v[60:63], v[140:143], v[148:151], v[60:63]
	v_mfma_f32_16x16x32_bf16 v[52:55], v[132:135], v[156:159], v[52:55]
	v_mfma_f32_16x16x32_bf16 v[44:47], v[140:143], v[156:159], v[44:47]
	v_mfma_f32_16x16x32_bf16 v[36:39], v[132:135], v[164:167], v[36:39]
	v_mfma_f32_16x16x32_bf16 v[28:31], v[140:143], v[164:167], v[28:31]
	v_mfma_f32_16x16x32_bf16 v[20:23], v[132:135], v[172:175], v[20:23]
	v_mfma_f32_16x16x32_bf16 v[12:15], v[140:143], v[172:175], v[12:15]
	v_mfma_f32_16x16x32_bf16 v[64:67], v[136:139], v[152:155], v[64:67]
	v_mfma_f32_16x16x32_bf16 v[60:63], v[144:147], v[152:155], v[60:63]
	v_mfma_f32_16x16x32_bf16 v[52:55], v[136:139], v[160:163], v[52:55]
	v_mfma_f32_16x16x32_bf16 v[44:47], v[144:147], v[160:163], v[44:47]
	v_mfma_f32_16x16x32_bf16 v[36:39], v[136:139], v[168:171], v[36:39]
	v_mfma_f32_16x16x32_bf16 v[28:31], v[144:147], v[168:171], v[28:31]
	v_mfma_f32_16x16x32_bf16 v[20:23], v[136:139], v[176:179], v[20:23]
	v_mfma_f32_16x16x32_bf16 v[12:15], v[144:147], v[176:179], v[12:15]
	v_mfma_f32_16x16x32_bf16 v[56:59], v[180:183], v[148:151], v[56:59]
	v_mfma_f32_16x16x32_bf16 v[48:51], v[188:191], v[148:151], v[48:51]
	v_mfma_f32_16x16x32_bf16 v[40:43], v[180:183], v[156:159], v[40:43]
	v_mfma_f32_16x16x32_bf16 v[32:35], v[188:191], v[156:159], v[32:35]
	v_mfma_f32_16x16x32_bf16 v[24:27], v[180:183], v[164:167], v[24:27]
	v_mfma_f32_16x16x32_bf16 v[16:19], v[188:191], v[164:167], v[16:19]
	v_mfma_f32_16x16x32_bf16 v[8:11], v[180:183], v[172:175], v[8:11]
	v_mfma_f32_16x16x32_bf16 v[4:7], v[188:191], v[172:175], v[4:7]
	v_mfma_f32_16x16x32_bf16 v[56:59], v[184:187], v[152:155], v[56:59]
	v_mfma_f32_16x16x32_bf16 v[48:51], v[202:205], v[152:155], v[48:51]
	v_mfma_f32_16x16x32_bf16 v[40:43], v[184:187], v[160:163], v[40:43]
	v_mfma_f32_16x16x32_bf16 v[32:35], v[202:205], v[160:163], v[32:35]
	v_mfma_f32_16x16x32_bf16 v[24:27], v[184:187], v[168:171], v[24:27]
	v_mfma_f32_16x16x32_bf16 v[16:19], v[202:205], v[168:171], v[16:19]
	v_mfma_f32_16x16x32_bf16 v[8:11], v[184:187], v[176:179], v[8:11]
	v_mfma_f32_16x16x32_bf16 v[4:7], v[202:205], v[176:179], v[4:7]
	s_barrier
	s_cbranch_scc0 .LBB0_1396
	s_setprio 0
	v_mov_b32_e32 v133, v0
	s_lshl_b32 s1, s46, 8
	s_add_i32 s1, s1, s38
	v_and_or_b32 v132, v133, 15, s1
	s_lshl_b32 s1, s45, 8
	v_lshrrev_b32_e32 v133, 1, v133
	v_and_or_b32 v133, v133, 24, s1
	v_or_b32_e32 v134, s39, v133
	v_ashrrev_i32_e32 v135, 31, v134
	v_lshlrev_b64 v[202:203], 1, v[134:135]
	v_ashrrev_i32_e32 v133, 31, v132
	v_lshl_add_u64 v[134:135], s[88:89], 0, v[202:203]
	v_lshlrev_b64 v[216:217], 12, v[132:133]
	v_lshl_add_u64 v[136:137], v[134:135], 0, v[216:217]
	global_load_dwordx4 v[226:229], v[136:137], off
	global_load_dwordx4 v[188:191], v[136:137], off offset:256
	v_or_b32_e32 v136, 16, v132
	v_ashrrev_i32_e32 v137, 31, v136
	v_lshlrev_b64 v[222:223], 12, v[136:137]
	v_lshl_add_u64 v[136:137], v[134:135], 0, v[222:223]
	global_load_dwordx4 v[184:187], v[136:137], off
	global_load_dwordx4 v[180:183], v[136:137], off offset:256
	v_or_b32_e32 v136, 32, v132
	v_ashrrev_i32_e32 v137, 31, v136
	v_lshlrev_b64 v[220:221], 12, v[136:137]
	v_lshl_add_u64 v[136:137], v[134:135], 0, v[220:221]
	global_load_dwordx4 v[176:179], v[136:137], off
	global_load_dwordx4 v[168:171], v[136:137], off offset:256
	v_or_b32_e32 v132, 48, v132
	v_ashrrev_i32_e32 v133, 31, v132
	v_lshlrev_b64 v[212:213], 12, v[132:133]
	v_lshl_add_u64 v[132:133], v[134:135], 0, v[212:213]
	global_load_dwordx4 v[172:175], v[132:133], off
	global_load_dwordx4 v[164:167], v[132:133], off offset:256
	s_mov_b64 s[6:7], 0x80000
	v_lshl_add_u64 v[210:211], v[216:217], 0, s[6:7]
	v_lshl_add_u64 v[132:133], v[134:135], 0, v[210:211]
	global_load_dwordx4 v[160:163], v[132:133], off
	global_load_dwordx4 v[156:159], v[132:133], off offset:256
	s_mov_b64 s[6:7], 0x90000
	v_lshl_add_u64 v[208:209], v[216:217], 0, s[6:7]
	v_lshl_add_u64 v[132:133], v[134:135], 0, v[208:209]
	global_load_dwordx4 v[152:155], v[132:133], off
	global_load_dwordx4 v[148:151], v[132:133], off offset:256
	s_mov_b64 s[6:7], 0xa0000
	v_lshl_add_u64 v[206:207], v[216:217], 0, s[6:7]
	v_lshl_add_u64 v[132:133], v[134:135], 0, v[206:207]
	global_load_dwordx4 v[144:147], v[132:133], off
	global_load_dwordx4 v[140:143], v[132:133], off offset:256
	s_mov_b64 s[6:7], 0xb0000
	v_lshl_add_u64 v[204:205], v[216:217], 0, s[6:7]
	v_lshl_add_u64 v[132:133], v[134:135], 0, v[204:205]
	global_load_dwordx4 v[136:139], v[132:133], off
	s_nop 0
	global_load_dwordx4 v[132:135], v[132:133], off offset:256
	s_and_b64 vcc, exec, s[40:41]
	s_mov_b32 s45, s0
	s_mov_b32 s46, s14
	s_mov_b64 s[20:21], s[18:19]
	s_mov_b64 s[6:7], s[4:5]
	s_waitcnt vmcnt(15)
	v_lshlrev_b32_e32 v218, 16, v226
	v_and_b32_e32 v219, 0xffff0000, v226
	v_pk_add_f32 v[128:129], v[128:129], v[218:219]
	v_lshlrev_b32_e32 v218, 16, v227
	v_and_b32_e32 v219, 0xffff0000, v227
	v_pk_add_f32 v[130:131], v[130:131], v[218:219]
	v_cvt_pk_bf16_f32 v128, v128, v129
	v_cvt_pk_bf16_f32 v129, v130, v131
	v_lshlrev_b32_e32 v130, 16, v228
	v_and_b32_e32 v131, 0xffff0000, v228
	v_pk_add_f32 v[124:125], v[124:125], v[130:131]
	s_nop 0
	v_cvt_pk_bf16_f32 v130, v124, v125
	v_lshlrev_b32_e32 v124, 16, v229
	v_and_b32_e32 v125, 0xffff0000, v229
	v_pk_add_f32 v[124:125], v[126:127], v[124:125]
	s_waitcnt vmcnt(14)
; __device__ __forceinline__ unsigned cvt_pk_bf16(float lo, float hi) { const f32x2 v = {lo, hi}; const bf16v2_ r = __builtin_convertvector(v, bf16v2_); return __builtin_bit_cast(unsigned, r); }
; __device__ __forceinline__ float bflo(unsigned w) { return __uint_as_float(w << 16); }
; __device__ __forceinline__ float bfhi(unsigned w) { return __uint_as_float(w & 0xffff0000u); }
;     __device__ __forceinline__ void operator()(const f32x4 (&acc)[2][2][4][2], const Unit& u, int wr, int wc, int, int) const {
;     ...
;                 for (int bj = 0; bj < 2; ++bj) { const u32x4 c = cin[ai][m][bj]; const f32x4 v0 = acc[ai][bj][m][0], v1 = acc[ai][bj][m][1];
;                     u32x4 w; w.x = cvt_pk_bf16(bflo(c.x) + v0[0], bfhi(c.x) + v0[1]); w.y = cvt_pk_bf16(bflo(c.y) + v0[2], bfhi(c.y) + v0[3]);
;                     w.z = cvt_pk_bf16(bflo(c.z) + v1[0], bfhi(c.z) + v1[1]); w.w = cvt_pk_bf16(bflo(c.w) + v1[2], bfhi(c.w) + v1[3]);
;                     *(u32x4*)(C + (size_t)(row0 + ai * HALF + m * 16) * ldc + col0 + bj * HALF) = w; }
	v_lshlrev_b32_e32 v126, 16, v188
	v_and_b32_e32 v127, 0xffff0000, v188
	v_pk_add_f32 v[120:121], v[120:121], v[126:127]
	v_lshlrev_b32_e32 v126, 16, v189
	v_and_b32_e32 v127, 0xffff0000, v189
	v_pk_add_f32 v[122:123], v[122:123], v[126:127]
	v_cvt_pk_bf16_f32 v120, v120, v121
	v_cvt_pk_bf16_f32 v121, v122, v123
	v_lshlrev_b32_e32 v122, 16, v190
	v_and_b32_e32 v123, 0xffff0000, v190
	v_pk_add_f32 v[116:117], v[116:117], v[122:123]
	v_cvt_pk_bf16_f32 v131, v124, v125
	v_cvt_pk_bf16_f32 v122, v116, v117
	v_lshlrev_b32_e32 v116, 16, v191
	v_and_b32_e32 v117, 0xffff0000, v191
	v_pk_add_f32 v[116:117], v[118:119], v[116:117]
	v_lshl_add_u64 v[124:125], s[88:89], 0, v[216:217]
	v_cvt_pk_bf16_f32 v123, v116, v117
	s_waitcnt vmcnt(13)
	v_lshlrev_b32_e32 v116, 16, v184
	v_and_b32_e32 v117, 0xffff0000, v184
	v_pk_add_f32 v[112:113], v[112:113], v[116:117]
	v_lshlrev_b32_e32 v116, 16, v185
	v_and_b32_e32 v117, 0xffff0000, v185
	v_pk_add_f32 v[114:115], v[114:115], v[116:117]
	v_cvt_pk_bf16_f32 v112, v112, v113
	v_cvt_pk_bf16_f32 v113, v114, v115
	v_lshlrev_b32_e32 v114, 16, v186
	v_and_b32_e32 v115, 0xffff0000, v186
	v_pk_add_f32 v[108:109], v[108:109], v[114:115]
	v_lshl_add_u64 v[124:125], v[124:125], 0, v[202:203]
	v_cvt_pk_bf16_f32 v114, v108, v109
	v_lshlrev_b32_e32 v108, 16, v187
	v_and_b32_e32 v109, 0xffff0000, v187
	v_pk_add_f32 v[108:109], v[110:111], v[108:109]
	s_waitcnt vmcnt(12)
	v_lshlrev_b32_e32 v110, 16, v180
	v_and_b32_e32 v111, 0xffff0000, v180
	v_pk_add_f32 v[104:105], v[104:105], v[110:111]
	v_lshlrev_b32_e32 v110, 16, v181
	v_and_b32_e32 v111, 0xffff0000, v181
	v_pk_add_f32 v[106:107], v[106:107], v[110:111]
	v_cvt_pk_bf16_f32 v104, v104, v105
	v_cvt_pk_bf16_f32 v105, v106, v107
	v_lshlrev_b32_e32 v106, 16, v182
	v_and_b32_e32 v107, 0xffff0000, v182
	v_pk_add_f32 v[96:97], v[96:97], v[106:107]
	v_cvt_pk_bf16_f32 v115, v108, v109
	v_cvt_pk_bf16_f32 v106, v96, v97
	v_lshlrev_b32_e32 v96, 16, v183
	v_and_b32_e32 v97, 0xffff0000, v183
	v_pk_add_f32 v[96:97], v[98:99], v[96:97]
	s_waitcnt vmcnt(11)
	v_lshlrev_b32_e32 v98, 16, v177
	v_cvt_pk_bf16_f32 v107, v96, v97
	v_lshlrev_b32_e32 v96, 16, v176
	v_and_b32_e32 v97, 0xffff0000, v176
	v_and_b32_e32 v99, 0xffff0000, v177
	v_pk_add_f32 v[96:97], v[100:101], v[96:97]
	v_pk_add_f32 v[98:99], v[102:103], v[98:99]
	v_cvt_pk_bf16_f32 v96, v96, v97
	v_cvt_pk_bf16_f32 v97, v98, v99
	v_lshlrev_b32_e32 v98, 16, v178
	v_and_b32_e32 v99, 0xffff0000, v178
	v_pk_add_f32 v[92:93], v[92:93], v[98:99]
	v_lshl_add_u64 v[108:109], s[88:89], 0, v[222:223]
	v_cvt_pk_bf16_f32 v98, v92, v93
	v_lshlrev_b32_e32 v92, 16, v179
	v_and_b32_e32 v93, 0xffff0000, v179
	v_pk_add_f32 v[92:93], v[94:95], v[92:93]
	s_waitcnt vmcnt(10)
	v_lshlrev_b32_e32 v94, 16, v168
	v_and_b32_e32 v95, 0xffff0000, v168
	v_pk_add_f32 v[88:89], v[88:89], v[94:95]
	v_lshlrev_b32_e32 v94, 16, v169
	v_and_b32_e32 v95, 0xffff0000, v169
	v_pk_add_f32 v[90:91], v[90:91], v[94:95]
	v_cvt_pk_bf16_f32 v88, v88, v89
	v_cvt_pk_bf16_f32 v89, v90, v91
	v_lshlrev_b32_e32 v90, 16, v170
	v_and_b32_e32 v91, 0xffff0000, v170
	v_pk_add_f32 v[80:81], v[80:81], v[90:91]
	v_cvt_pk_bf16_f32 v99, v92, v93
	v_cvt_pk_bf16_f32 v90, v80, v81
	v_lshlrev_b32_e32 v80, 16, v171
	v_and_b32_e32 v81, 0xffff0000, v171
	v_pk_add_f32 v[80:81], v[82:83], v[80:81]
	s_waitcnt vmcnt(9)
	v_lshlrev_b32_e32 v82, 16, v173
	v_cvt_pk_bf16_f32 v91, v80, v81
	v_lshlrev_b32_e32 v80, 16, v172
	v_and_b32_e32 v81, 0xffff0000, v172
	v_and_b32_e32 v83, 0xffff0000, v173
	v_pk_add_f32 v[80:81], v[84:85], v[80:81]
	v_pk_add_f32 v[82:83], v[86:87], v[82:83]
	v_cvt_pk_bf16_f32 v80, v80, v81
	v_cvt_pk_bf16_f32 v81, v82, v83
	v_lshlrev_b32_e32 v82, 16, v174
	v_and_b32_e32 v83, 0xffff0000, v174
	v_pk_add_f32 v[76:77], v[76:77], v[82:83]
	v_lshl_add_u64 v[92:93], s[88:89], 0, v[220:221]
	v_cvt_pk_bf16_f32 v82, v76, v77
	v_lshlrev_b32_e32 v76, 16, v175
	v_and_b32_e32 v77, 0xffff0000, v175
	v_pk_add_f32 v[76:77], v[78:79], v[76:77]
	s_waitcnt vmcnt(8)
	v_lshlrev_b32_e32 v78, 16, v164
	v_and_b32_e32 v79, 0xffff0000, v164
	v_pk_add_f32 v[72:73], v[72:73], v[78:79]
	v_lshlrev_b32_e32 v78, 16, v165
	v_and_b32_e32 v79, 0xffff0000, v165
	v_pk_add_f32 v[74:75], v[74:75], v[78:79]
	v_cvt_pk_bf16_f32 v72, v72, v73
	v_cvt_pk_bf16_f32 v73, v74, v75
	v_lshlrev_b32_e32 v74, 16, v166
	v_and_b32_e32 v75, 0xffff0000, v166
	v_pk_add_f32 v[68:69], v[68:69], v[74:75]
	v_cvt_pk_bf16_f32 v83, v76, v77
	v_cvt_pk_bf16_f32 v74, v68, v69
	v_lshlrev_b32_e32 v68, 16, v167
	v_and_b32_e32 v69, 0xffff0000, v167
	v_pk_add_f32 v[68:69], v[70:71], v[68:69]
	v_lshl_add_u64 v[76:77], s[88:89], 0, v[212:213]
	v_cvt_pk_bf16_f32 v75, v68, v69
	s_waitcnt vmcnt(7)
	v_lshlrev_b32_e32 v68, 16, v160
	v_and_b32_e32 v69, 0xffff0000, v160
	v_pk_add_f32 v[64:65], v[64:65], v[68:69]
	v_lshlrev_b32_e32 v68, 16, v161
	v_and_b32_e32 v69, 0xffff0000, v161
	v_pk_add_f32 v[66:67], v[66:67], v[68:69]
	v_cvt_pk_bf16_f32 v64, v64, v65
	v_cvt_pk_bf16_f32 v65, v66, v67
	v_lshlrev_b32_e32 v66, 16, v162
	v_and_b32_e32 v67, 0xffff0000, v162
	v_pk_add_f32 v[60:61], v[60:61], v[66:67]
	v_lshl_add_u64 v[108:109], v[108:109], 0, v[202:203]
	v_cvt_pk_bf16_f32 v66, v60, v61
	v_lshlrev_b32_e32 v60, 16, v163
	v_and_b32_e32 v61, 0xffff0000, v163
	v_pk_add_f32 v[60:61], v[62:63], v[60:61]
	s_waitcnt vmcnt(6)
; __device__ __forceinline__ unsigned cvt_pk_bf16(float lo, float hi) { const f32x2 v = {lo, hi}; const bf16v2_ r = __builtin_convertvector(v, bf16v2_); return __builtin_bit_cast(unsigned, r); }
; __device__ __forceinline__ float bflo(unsigned w) { return __uint_as_float(w << 16); }
; __device__ __forceinline__ float bfhi(unsigned w) { return __uint_as_float(w & 0xffff0000u); }
; #define PG8_WAIT_V(n) asm volatile("s_waitcnt vmcnt(" #n ")" ::: "memory")
; #define PG8_BAR __builtin_amdgcn_s_barrier()
;     __device__ __forceinline__ void operator()(const f32x4 (&acc)[2][2][4][2], const Unit& u, int wr, int wc, int, int) const {
;     ...
;                 for (int bj = 0; bj < 2; ++bj) { const u32x4 c = cin[ai][m][bj]; const f32x4 v0 = acc[ai][bj][m][0], v1 = acc[ai][bj][m][1];
;                     u32x4 w; w.x = cvt_pk_bf16(bflo(c.x) + v0[0], bfhi(c.x) + v0[1]); w.y = cvt_pk_bf16(bflo(c.y) + v0[2], bfhi(c.y) + v0[3]);
;                     w.z = cvt_pk_bf16(bflo(c.z) + v1[0], bfhi(c.z) + v1[1]); w.w = cvt_pk_bf16(bflo(c.w) + v1[2], bfhi(c.w) + v1[3]);
;                     *(u32x4*)(C + (size_t)(row0 + ai * HALF + m * 16) * ldc + col0 + bj * HALF) = w; }
; template <class Epi, class Sched>
; __device__ __forceinline__ void gemm_phase(LAS unsigned char* lds, const Gemm g, const Sched& S, const Epi& E) {
;     ...
;         if (!has_next) break;
; #pragma unroll
;         for (int a = 0; a < 2; ++a)
; #pragma unroll
;             for (int b = 0; b < 2; ++b)
; #pragma unroll
;                 for (int m = 0; m < 4; ++m)
; #pragma unroll
;                     for (int n = 0; n < 2; ++n) acc[a][b][m][n] = (f32x4){0.f, 0.f, 0.f, 0.f};
;         cur = nxt; cA = nA; cB = nB; ++ui;
;     }
;     PG8_WAIT_V(0);
;     if (wr == 0) PG8_BAR;
;     PG8_BAR;
	v_lshlrev_b32_e32 v62, 16, v156
	v_and_b32_e32 v63, 0xffff0000, v156
	v_pk_add_f32 v[56:57], v[56:57], v[62:63]
	v_lshlrev_b32_e32 v62, 16, v157
	v_and_b32_e32 v63, 0xffff0000, v157
	v_pk_add_f32 v[58:59], v[58:59], v[62:63]
	v_cvt_pk_bf16_f32 v56, v56, v57
	v_cvt_pk_bf16_f32 v57, v58, v59
	v_lshlrev_b32_e32 v58, 16, v158
	v_and_b32_e32 v59, 0xffff0000, v158
	v_pk_add_f32 v[48:49], v[48:49], v[58:59]
	v_cvt_pk_bf16_f32 v67, v60, v61
	v_cvt_pk_bf16_f32 v58, v48, v49
	v_lshlrev_b32_e32 v48, 16, v159
	v_and_b32_e32 v49, 0xffff0000, v159
	v_pk_add_f32 v[48:49], v[50:51], v[48:49]
	s_waitcnt vmcnt(5)
	v_lshlrev_b32_e32 v50, 16, v153
	v_cvt_pk_bf16_f32 v59, v48, v49
	v_lshlrev_b32_e32 v48, 16, v152
	v_and_b32_e32 v49, 0xffff0000, v152
	v_and_b32_e32 v51, 0xffff0000, v153
	v_pk_add_f32 v[48:49], v[52:53], v[48:49]
	v_pk_add_f32 v[50:51], v[54:55], v[50:51]
	v_cvt_pk_bf16_f32 v48, v48, v49
	v_cvt_pk_bf16_f32 v49, v50, v51
	v_lshlrev_b32_e32 v50, 16, v154
	v_and_b32_e32 v51, 0xffff0000, v154
	v_pk_add_f32 v[44:45], v[44:45], v[50:51]
	v_lshl_add_u64 v[60:61], s[88:89], 0, v[210:211]
	v_cvt_pk_bf16_f32 v50, v44, v45
	v_lshlrev_b32_e32 v44, 16, v155
	v_and_b32_e32 v45, 0xffff0000, v155
	v_pk_add_f32 v[44:45], v[46:47], v[44:45]
	s_waitcnt vmcnt(4)
	v_lshlrev_b32_e32 v46, 16, v148
	v_and_b32_e32 v47, 0xffff0000, v148
	v_pk_add_f32 v[40:41], v[40:41], v[46:47]
	v_lshlrev_b32_e32 v46, 16, v149
	v_and_b32_e32 v47, 0xffff0000, v149
	v_pk_add_f32 v[42:43], v[42:43], v[46:47]
	v_cvt_pk_bf16_f32 v40, v40, v41
	v_cvt_pk_bf16_f32 v41, v42, v43
	v_lshlrev_b32_e32 v42, 16, v150
	v_and_b32_e32 v43, 0xffff0000, v150
	v_pk_add_f32 v[32:33], v[32:33], v[42:43]
	v_cvt_pk_bf16_f32 v51, v44, v45
	v_cvt_pk_bf16_f32 v42, v32, v33
	v_lshlrev_b32_e32 v32, 16, v151
	v_and_b32_e32 v33, 0xffff0000, v151
	v_pk_add_f32 v[32:33], v[34:35], v[32:33]
	s_waitcnt vmcnt(3)
	v_lshlrev_b32_e32 v34, 16, v145
	v_cvt_pk_bf16_f32 v43, v32, v33
	v_lshlrev_b32_e32 v32, 16, v144
	v_and_b32_e32 v33, 0xffff0000, v144
	v_and_b32_e32 v35, 0xffff0000, v145
	v_pk_add_f32 v[32:33], v[36:37], v[32:33]
	v_pk_add_f32 v[34:35], v[38:39], v[34:35]
	v_cvt_pk_bf16_f32 v32, v32, v33
	v_cvt_pk_bf16_f32 v33, v34, v35
	v_lshlrev_b32_e32 v34, 16, v146
	v_and_b32_e32 v35, 0xffff0000, v146
	v_pk_add_f32 v[28:29], v[28:29], v[34:35]
	v_lshl_add_u64 v[44:45], s[88:89], 0, v[208:209]
	v_cvt_pk_bf16_f32 v34, v28, v29
	v_lshlrev_b32_e32 v28, 16, v147
	v_and_b32_e32 v29, 0xffff0000, v147
	v_pk_add_f32 v[28:29], v[30:31], v[28:29]
	s_waitcnt vmcnt(2)
	v_lshlrev_b32_e32 v30, 16, v140
	v_and_b32_e32 v31, 0xffff0000, v140
	v_pk_add_f32 v[24:25], v[24:25], v[30:31]
	v_lshlrev_b32_e32 v30, 16, v141
	v_and_b32_e32 v31, 0xffff0000, v141
	v_pk_add_f32 v[26:27], v[26:27], v[30:31]
	v_cvt_pk_bf16_f32 v24, v24, v25
	v_cvt_pk_bf16_f32 v25, v26, v27
	v_lshlrev_b32_e32 v26, 16, v142
	v_and_b32_e32 v27, 0xffff0000, v142
	v_pk_add_f32 v[16:17], v[16:17], v[26:27]
	v_cvt_pk_bf16_f32 v35, v28, v29
	v_cvt_pk_bf16_f32 v26, v16, v17
	v_lshlrev_b32_e32 v16, 16, v143
	v_and_b32_e32 v17, 0xffff0000, v143
	v_pk_add_f32 v[16:17], v[18:19], v[16:17]
	s_waitcnt vmcnt(1)
	v_lshlrev_b32_e32 v18, 16, v137
	v_cvt_pk_bf16_f32 v27, v16, v17
	v_lshlrev_b32_e32 v16, 16, v136
	v_and_b32_e32 v17, 0xffff0000, v136
	v_and_b32_e32 v19, 0xffff0000, v137
	v_pk_add_f32 v[16:17], v[20:21], v[16:17]
	v_pk_add_f32 v[18:19], v[22:23], v[18:19]
	v_cvt_pk_bf16_f32 v16, v16, v17
	v_cvt_pk_bf16_f32 v17, v18, v19
	v_lshlrev_b32_e32 v18, 16, v138
	v_and_b32_e32 v19, 0xffff0000, v138
	v_pk_add_f32 v[12:13], v[12:13], v[18:19]
	v_lshl_add_u64 v[28:29], s[88:89], 0, v[206:207]
	v_cvt_pk_bf16_f32 v18, v12, v13
	v_lshlrev_b32_e32 v12, 16, v139
	v_and_b32_e32 v13, 0xffff0000, v139
	v_pk_add_f32 v[12:13], v[14:15], v[12:13]
	s_waitcnt vmcnt(0)
	v_lshlrev_b32_e32 v14, 16, v132
	v_and_b32_e32 v15, 0xffff0000, v132
	v_pk_add_f32 v[8:9], v[8:9], v[14:15]
	v_lshlrev_b32_e32 v14, 16, v133
	v_and_b32_e32 v15, 0xffff0000, v133
	v_pk_add_f32 v[10:11], v[10:11], v[14:15]
	v_cvt_pk_bf16_f32 v8, v8, v9
	v_cvt_pk_bf16_f32 v9, v10, v11
	v_lshlrev_b32_e32 v10, 16, v134
	v_and_b32_e32 v11, 0xffff0000, v134
	v_pk_add_f32 v[4:5], v[4:5], v[10:11]
	v_cvt_pk_bf16_f32 v19, v12, v13
	v_cvt_pk_bf16_f32 v10, v4, v5
	v_lshlrev_b32_e32 v4, 16, v135
	v_and_b32_e32 v5, 0xffff0000, v135
	v_lshl_add_u64 v[12:13], s[88:89], 0, v[204:205]
	v_pk_add_f32 v[4:5], v[6:7], v[4:5]
	v_lshl_add_u64 v[92:93], v[92:93], 0, v[202:203]
	v_lshl_add_u64 v[76:77], v[76:77], 0, v[202:203]
	v_lshl_add_u64 v[60:61], v[60:61], 0, v[202:203]
	v_lshl_add_u64 v[44:45], v[44:45], 0, v[202:203]
	v_lshl_add_u64 v[28:29], v[28:29], 0, v[202:203]
	v_lshl_add_u64 v[12:13], v[12:13], 0, v[202:203]
	v_cvt_pk_bf16_f32 v11, v4, v5
	global_store_dwordx4 v[124:125], v[128:131], off
	global_store_dwordx4 v[124:125], v[120:123], off offset:256
	global_store_dwordx4 v[108:109], v[112:115], off
	global_store_dwordx4 v[108:109], v[104:107], off offset:256
	global_store_dwordx4 v[92:93], v[96:99], off
	global_store_dwordx4 v[92:93], v[88:91], off offset:256
	global_store_dwordx4 v[76:77], v[80:83], off
	global_store_dwordx4 v[76:77], v[72:75], off offset:256
	global_store_dwordx4 v[60:61], v[64:67], off
	global_store_dwordx4 v[60:61], v[56:59], off offset:256
	global_store_dwordx4 v[44:45], v[48:51], off
	global_store_dwordx4 v[44:45], v[40:43], off offset:256
	global_store_dwordx4 v[28:29], v[32:35], off
	global_store_dwordx4 v[28:29], v[24:27], off offset:256
	global_store_dwordx4 v[12:13], v[16:19], off
	global_store_dwordx4 v[12:13], v[8:11], off offset:256
	s_cbranch_vccz .LBB0_1389
	s_waitcnt vmcnt(0)
	s_cmpk_gt_u32 s2, 0xff
	s_cbranch_scc1 .LBB0_1400
	s_barrier

; #define PG8_STAGE(bufoff, gbase, voff) do { _Pragma("unroll") for (int _i = 0; _i < 2; ++_i) \
;         __builtin_amdgcn_global_load_lds((const unsigned*)((const char*)(gbase) + (voff)[_i]), (LAS unsigned*)(lds + (bufoff) + ldsw + _i * 8192), 16, 0, 0); } while (0)
; #define PG8_LDA(dst, b, h) do { _Pragma("unroll") for (int m = 0; m < 4; ++m) _Pragma("unroll") for (int k = 0; k < 2; ++k) dst[m][k] = *(const LAS bf16x8*)(lds + PG8_SA(b, h) + aoff + m * 2048 + k * 1024); } while (0)
; #define PG8_LDB(dst, b, h) do { _Pragma("unroll") for (int n = 0; n < 2; ++n) _Pragma("unroll") for (int k = 0; k < 2; ++k) dst[n][k] = *(const LAS bf16x8*)(lds + PG8_SB(b, h) + boff + n * 2048 + k * 1024); } while (0)
; #define PG8_MMA(ai, bj, At, Bt) do { __builtin_amdgcn_s_setprio(1); _Pragma("unroll") for (int m = 0; m < 4; ++m) _Pragma("unroll") for (int n = 0; n < 2; ++n) _Pragma("unroll") for (int k = 0; k < 2; ++k) \
;         acc[ai][bj][m][n] = __builtin_amdgcn_mfma_f32_16x16x32_bf16(Bt[n][k], At[m][k], acc[ai][bj][m][n], 0, 0, 0); __builtin_amdgcn_s_setprio(0); } while (0)
; #define PG8_WAIT_V(n) asm volatile("s_waitcnt vmcnt(" #n ")" ::: "memory")
; #define PG8_WAIT_L(n) asm volatile("s_waitcnt lgkmcnt(" #n ")" ::: "memory")
; #define PG8_BAR __builtin_amdgcn_s_barrier()
; #define PG8_SCHED __builtin_amdgcn_sched_barrier(0)
; template <class Epi, class Sched>
; __device__ __forceinline__ void gemm_phase(LAS unsigned char* lds, const Gemm g, const Sched& S, const Epi& E) {
;     ...
;             PG8_LDB(B0, 0, 0); PG8_SCHED; PG8_LDA(At, 0, 0); PG8_STAGE(PG8_SA(1, 1), a1 + hstepA, voffA);
;             PG8_WAIT_L(8); PG8_BAR; PG8_WAIT_L(0); PG8_MMA(0, 0, At, B0); PG8_BAR; PG8_SCHED;
;             PG8_LDB(B1, 0, 1); PG8_STAGE(PG8_SB(0, 0), b2, voffB);
;             PG8_BAR; PG8_WAIT_L(0); PG8_MMA(0, 1, At, B1); PG8_BAR;
;             PG8_LDA(At, 0, 1); PG8_STAGE(PG8_SA(0, 0), a2, voffA);
;             PG8_BAR; PG8_WAIT_L(0); PG8_MMA(1, 0, At, B0); PG8_BAR; PG8_SCHED;
;             PG8_STAGE(PG8_SB(0, 1), b2 + hstepB, voffB);
;             PG8_WAIT_V(6); PG8_BAR; PG8_MMA(1, 1, At, B1); PG8_BAR;
.LBB0_1525:
	v_mov_b64_e32 v[4:5], 0x1600
	s_ashr_i32 s57, s56, 31
	v_cmp_lt_i64_e32 vcc, s[14:15], v[4:5]
	s_lshl_b64 s[14:15], s[56:57], 20
	s_add_u32 s58, s88, s14
	s_addc_u32 s59, s89, s15
	s_and_b64 s[14:15], vcc, exec
	s_cselect_b32 s57, s59, s5
	s_cselect_b32 s67, s58, s4
	s_ashr_i32 s55, s54, 31
	s_lshl_b64 s[14:15], s[54:55], 20
	s_add_u32 s60, s2, s14
	s_addc_u32 s61, s18, s15
	s_and_b64 s[14:15], vcc, exec
	s_cselect_b32 s55, s61, s7
	s_cselect_b32 s68, s60, s6
	s_add_u32 s4, s4, 0x80080
	s_addc_u32 s5, s5, 0
	s_add_u32 s69, s6, 0x100
	s_addc_u32 s70, s7, 0
	s_mov_b32 s71, -2
	s_setprio 0
	s_add_u32 s6, s4, 0xfff80080
	s_addc_u32 s7, s5, -1
	s_add_i32 s72, 0, 0x10000
	v_add_u32_e32 v2, s72, v1
	ds_read_b128 v[132:135], v2
	ds_read_b128 v[136:139], v2 offset:1024
	ds_read_b128 v[140:143], v2 offset:2048
	ds_read_b128 v[144:147], v2 offset:3072
	s_cmp_eq_u32 s71, 28
	s_cselect_b32 s15, s57, s7
	s_cselect_b32 s14, s67, s6
	s_cselect_b32 s7, s55, s70
	s_cselect_b32 s6, s68, s69
	ds_read_b128 v[148:151], v207
	ds_read_b128 v[152:155], v207 offset:1024
	ds_read_b128 v[156:159], v207 offset:2048
	ds_read_b128 v[160:163], v207 offset:3072
	ds_read_b128 v[164:167], v207 offset:4096
	ds_read_b128 v[168:171], v207 offset:5120
	ds_read_b128 v[186:189], v207 offset:6144
	ds_read_b128 v[190:193], v207 offset:7168
	s_add_i32 s74, 0, 0x14000
	v_add_u32_e32 v2, s74, v1
	ds_read_b128 v[194:197], v2
	ds_read_b128 v[198:201], v2 offset:1024
	ds_read_b128 v[202:205], v2 offset:2048
	ds_read_b128 v[208:211], v2 offset:3072
	s_add_i32 m0, s20, 0xc000
	s_nop 0
	global_load_lds_dwordx4 v182, s[4:5]
	s_add_i32 m0, s20, 0xe000
	s_nop 0
	global_load_lds_dwordx4 v184, s[4:5]
	s_waitcnt lgkmcnt(0)
	s_waitcnt vmcnt(8)
	s_setprio 1
	s_barrier
	v_mfma_f32_16x16x32_bf16 v[68:71], v[132:135], v[148:151], 0
	v_mfma_f32_16x16x32_bf16 v[72:75], v[140:143], v[148:151], 0
	v_mfma_f32_16x16x32_bf16 v[120:123], v[132:135], v[156:159], 0
	v_mfma_f32_16x16x32_bf16 v[116:119], v[140:143], v[156:159], 0
	v_mfma_f32_16x16x32_bf16 v[112:115], v[132:135], v[164:167], 0
	v_mfma_f32_16x16x32_bf16 v[108:111], v[140:143], v[164:167], 0
	v_mfma_f32_16x16x32_bf16 v[104:107], v[132:135], v[186:189], 0
	v_mfma_f32_16x16x32_bf16 v[100:103], v[140:143], v[186:189], 0
	v_mfma_f32_16x16x32_bf16 v[68:71], v[136:139], v[152:155], v[68:71]
	v_mfma_f32_16x16x32_bf16 v[72:75], v[144:147], v[152:155], v[72:75]
	v_mfma_f32_16x16x32_bf16 v[120:123], v[136:139], v[160:163], v[120:123]
	v_mfma_f32_16x16x32_bf16 v[116:119], v[144:147], v[160:163], v[116:119]
	v_mfma_f32_16x16x32_bf16 v[112:115], v[136:139], v[168:171], v[112:115]
	v_mfma_f32_16x16x32_bf16 v[108:111], v[144:147], v[168:171], v[108:111]
	v_mfma_f32_16x16x32_bf16 v[104:107], v[136:139], v[190:193], v[104:107]
	v_mfma_f32_16x16x32_bf16 v[100:103], v[144:147], v[190:193], v[100:103]
	v_mfma_f32_16x16x32_bf16 v[76:79], v[194:197], v[148:151], 0
	v_mfma_f32_16x16x32_bf16 v[80:83], v[202:205], v[148:151], 0
	v_mfma_f32_16x16x32_bf16 v[96:99], v[194:197], v[156:159], 0
	v_mfma_f32_16x16x32_bf16 v[92:95], v[202:205], v[156:159], 0
	v_mfma_f32_16x16x32_bf16 v[88:91], v[194:197], v[164:167], 0
	v_mfma_f32_16x16x32_bf16 v[84:87], v[202:205], v[164:167], 0
	v_mfma_f32_16x16x32_bf16 v[128:131], v[194:197], v[186:189], 0
	v_mfma_f32_16x16x32_bf16 v[124:127], v[202:205], v[186:189], 0
	v_mfma_f32_16x16x32_bf16 v[76:79], v[198:201], v[152:155], v[76:79]
	v_mfma_f32_16x16x32_bf16 v[80:83], v[208:211], v[152:155], v[80:83]
	v_mfma_f32_16x16x32_bf16 v[96:99], v[198:201], v[160:163], v[96:99]
	v_mfma_f32_16x16x32_bf16 v[92:95], v[208:211], v[160:163], v[92:95]
	v_mfma_f32_16x16x32_bf16 v[88:91], v[198:201], v[168:171], v[88:91]
	v_mfma_f32_16x16x32_bf16 v[84:87], v[208:211], v[168:171], v[84:87]
	v_mfma_f32_16x16x32_bf16 v[128:131], v[198:201], v[190:193], v[128:131]
	v_mfma_f32_16x16x32_bf16 v[124:127], v[208:211], v[190:193], v[124:127]
	s_barrier
	s_setprio 0
	ds_read_b128 v[148:151], v207 offset:16384
	ds_read_b128 v[152:155], v207 offset:17408
	ds_read_b128 v[156:159], v207 offset:18432
	ds_read_b128 v[160:163], v207 offset:19456
	ds_read_b128 v[164:167], v207 offset:20480
	ds_read_b128 v[168:171], v207 offset:21504
	ds_read_b128 v[186:189], v207 offset:22528
	ds_read_b128 v[190:193], v207 offset:23552
	s_add_i32 s72, s72, s19
	v_lshl_add_u64 v[172:173], s[6:7], 0, v[178:179]
	s_mov_b32 m0, s72
	s_nop 0
	global_load_lds_dwordx4 v[172:173], off
	v_lshl_add_u64 v[212:213], s[6:7], 0, v[174:175]
	s_add_i32 m0, s72, 0x2000
	s_nop 0
	global_load_lds_dwordx4 v[212:213], off
	s_mov_b32 m0, s20
	v_lshl_add_u64 v[216:217], s[14:15], 0, v[180:181]
	global_load_lds_dwordx4 v[216:217], off
	v_lshl_add_u64 v[218:219], s[14:15], 0, v[176:177]
	s_mov_b32 m0, s21
	s_nop 0
	global_load_lds_dwordx4 v[218:219], off
	s_add_u32 s72, s6, 0x80000
	s_addc_u32 s73, s7, 0
	s_add_i32 s74, s74, s19
	s_mov_b32 m0, s74
	s_nop 0
	global_load_lds_dwordx4 v178, s[72:73]
	s_add_i32 m0, s74, 0x2000
	s_nop 0
	global_load_lds_dwordx4 v174, s[72:73]
	s_waitcnt lgkmcnt(0)
	s_waitcnt vmcnt(8)
	s_setprio 1
	s_barrier
; #define PG8_STAGE(bufoff, gbase, voff) do { _Pragma("unroll") for (int _i = 0; _i < 2; ++_i) \
;         __builtin_amdgcn_global_load_lds((const unsigned*)((const char*)(gbase) + (voff)[_i]), (LAS unsigned*)(lds + (bufoff) + ldsw + _i * 8192), 16, 0, 0); } while (0)
; #define PG8_LDA(dst, b, h) do { _Pragma("unroll") for (int m = 0; m < 4; ++m) _Pragma("unroll") for (int k = 0; k < 2; ++k) dst[m][k] = *(const LAS bf16x8*)(lds + PG8_SA(b, h) + aoff + m * 2048 + k * 1024); } while (0)
; #define PG8_LDB(dst, b, h) do { _Pragma("unroll") for (int n = 0; n < 2; ++n) _Pragma("unroll") for (int k = 0; k < 2; ++k) dst[n][k] = *(const LAS bf16x8*)(lds + PG8_SB(b, h) + boff + n * 2048 + k * 1024); } while (0)
; #define PG8_MMA(ai, bj, At, Bt) do { __builtin_amdgcn_s_setprio(1); _Pragma("unroll") for (int m = 0; m < 4; ++m) _Pragma("unroll") for (int n = 0; n < 2; ++n) _Pragma("unroll") for (int k = 0; k < 2; ++k) \
;         acc[ai][bj][m][n] = __builtin_amdgcn_mfma_f32_16x16x32_bf16(Bt[n][k], At[m][k], acc[ai][bj][m][n], 0, 0, 0); __builtin_amdgcn_s_setprio(0); } while (0)
; #define PG8_WAIT_V(n) asm volatile("s_waitcnt vmcnt(" #n ")" ::: "memory")
; #define PG8_WAIT_L(n) asm volatile("s_waitcnt lgkmcnt(" #n ")" ::: "memory")
; #define PG8_BAR __builtin_amdgcn_s_barrier()
; #define PG8_SCHED __builtin_amdgcn_sched_barrier(0)
; template <class Epi, class Sched>
; __device__ __forceinline__ void gemm_phase(LAS unsigned char* lds, const Gemm g, const Sched& S, const Epi& E) {
;     ...
;             PG8_BAR; PG8_WAIT_L(0); PG8_MMA(1, 0, At, B0); PG8_BAR; PG8_SCHED;
;             PG8_STAGE(PG8_SB(0, 1), b2 + hstepB, voffB);
;             PG8_WAIT_V(6); PG8_BAR; PG8_MMA(1, 1, At, B1); PG8_BAR;
;             PG8_LDB(B0, 1, 0); PG8_SCHED; PG8_LDA(At, 1, 0); PG8_STAGE(PG8_SA(0, 1), a2 + hstepA, voffA);
;             PG8_WAIT_L(8); PG8_BAR; PG8_WAIT_L(0); PG8_MMA(0, 0, At, B0); PG8_BAR; PG8_SCHED;
;             PG8_LDB(B1, 1, 1); PG8_STAGE(PG8_SB(1, 0), b3, voffB);
;             PG8_BAR; PG8_WAIT_L(0); PG8_MMA(0, 1, At, B1); PG8_BAR;
;             PG8_LDA(At, 1, 1); PG8_STAGE(PG8_SA(1, 0), a3, voffA);
;             PG8_BAR; PG8_WAIT_L(0); PG8_MMA(1, 0, At, B0); PG8_BAR; PG8_SCHED;
	v_mfma_f32_16x16x32_bf16 v[56:59], v[132:135], v[148:151], 0
	v_mfma_f32_16x16x32_bf16 v[52:55], v[140:143], v[148:151], 0
	v_mfma_f32_16x16x32_bf16 v[48:51], v[132:135], v[156:159], 0
	v_mfma_f32_16x16x32_bf16 v[44:47], v[140:143], v[156:159], 0
	v_mfma_f32_16x16x32_bf16 v[40:43], v[132:135], v[164:167], 0
	v_mfma_f32_16x16x32_bf16 v[36:39], v[140:143], v[164:167], 0
	v_mfma_f32_16x16x32_bf16 v[32:35], v[132:135], v[186:189], 0
	v_mfma_f32_16x16x32_bf16 v[28:31], v[140:143], v[186:189], 0
	v_mfma_f32_16x16x32_bf16 v[56:59], v[136:139], v[152:155], v[56:59]
	v_mfma_f32_16x16x32_bf16 v[52:55], v[144:147], v[152:155], v[52:55]
	v_mfma_f32_16x16x32_bf16 v[48:51], v[136:139], v[160:163], v[48:51]
	v_mfma_f32_16x16x32_bf16 v[44:47], v[144:147], v[160:163], v[44:47]
	v_mfma_f32_16x16x32_bf16 v[40:43], v[136:139], v[168:171], v[40:43]
	v_mfma_f32_16x16x32_bf16 v[36:39], v[144:147], v[168:171], v[36:39]
	v_mfma_f32_16x16x32_bf16 v[32:35], v[136:139], v[190:193], v[32:35]
	v_mfma_f32_16x16x32_bf16 v[28:31], v[144:147], v[190:193], v[28:31]
	v_mfma_f32_16x16x32_bf16 v[24:27], v[194:197], v[148:151], 0
	v_mfma_f32_16x16x32_bf16 v[20:23], v[202:205], v[148:151], 0
	v_mfma_f32_16x16x32_bf16 v[16:19], v[194:197], v[156:159], 0
	v_mfma_f32_16x16x32_bf16 v[12:15], v[202:205], v[156:159], 0
	v_mfma_f32_16x16x32_bf16 v[8:11], v[194:197], v[164:167], 0
	v_mfma_f32_16x16x32_bf16 v[4:7], v[202:205], v[164:167], 0
	v_mfma_f32_16x16x32_bf16 v[60:63], v[194:197], v[186:189], 0
	v_mfma_f32_16x16x32_bf16 v[64:67], v[202:205], v[186:189], 0
	v_mfma_f32_16x16x32_bf16 v[24:27], v[198:201], v[152:155], v[24:27]
	v_mfma_f32_16x16x32_bf16 v[20:23], v[208:211], v[152:155], v[20:23]
	v_mfma_f32_16x16x32_bf16 v[16:19], v[198:201], v[160:163], v[16:19]
	v_mfma_f32_16x16x32_bf16 v[12:15], v[208:211], v[160:163], v[12:15]
	v_mfma_f32_16x16x32_bf16 v[8:11], v[198:201], v[168:171], v[8:11]
	v_mfma_f32_16x16x32_bf16 v[4:7], v[208:211], v[168:171], v[4:7]
	v_mfma_f32_16x16x32_bf16 v[60:63], v[198:201], v[190:193], v[60:63]
	v_mfma_f32_16x16x32_bf16 v[64:67], v[208:211], v[190:193], v[64:67]
	s_barrier
	s_setprio 0
	s_add_i32 s72, 0, 0x18000
	v_add_u32_e32 v2, s72, v1
	ds_read_b128 v[132:135], v2
	ds_read_b128 v[136:139], v2 offset:1024
	ds_read_b128 v[140:143], v2 offset:2048
	ds_read_b128 v[144:147], v2 offset:3072
	s_add_u32 s14, s14, 0x80000
	s_addc_u32 s15, s15, 0
	ds_read_b128 v[148:151], v207 offset:32768
	ds_read_b128 v[152:155], v207 offset:33792
	ds_read_b128 v[156:159], v207 offset:34816
	ds_read_b128 v[160:163], v207 offset:35840
	ds_read_b128 v[164:167], v207 offset:36864
	ds_read_b128 v[168:171], v207 offset:37888
	ds_read_b128 v[186:189], v207 offset:38912
	ds_read_b128 v[190:193], v207 offset:39936
	s_mov_b32 m0, s24
	s_nop 0
	global_load_lds_dwordx4 v180, s[14:15]
	s_mov_b32 m0, s25
	s_nop 0
	global_load_lds_dwordx4 v176, s[14:15]
	s_add_i32 s14, 0, 0x1c000
	v_add_u32_e32 v2, s14, v1
	ds_read_b128 v[194:197], v2
	ds_read_b128 v[198:201], v2 offset:1024
	ds_read_b128 v[202:205], v2 offset:2048
	ds_read_b128 v[208:211], v2 offset:3072
	s_waitcnt lgkmcnt(0)
	s_waitcnt vmcnt(8)
	s_setprio 1
	s_barrier
	v_mfma_f32_16x16x32_bf16 v[68:71], v[132:135], v[148:151], v[68:71]
	v_mfma_f32_16x16x32_bf16 v[72:75], v[140:143], v[148:151], v[72:75]
	v_mfma_f32_16x16x32_bf16 v[120:123], v[132:135], v[156:159], v[120:123]
	v_mfma_f32_16x16x32_bf16 v[116:119], v[140:143], v[156:159], v[116:119]
	v_mfma_f32_16x16x32_bf16 v[112:115], v[132:135], v[164:167], v[112:115]
	v_mfma_f32_16x16x32_bf16 v[108:111], v[140:143], v[164:167], v[108:111]
	v_mfma_f32_16x16x32_bf16 v[104:107], v[132:135], v[186:189], v[104:107]
	v_mfma_f32_16x16x32_bf16 v[100:103], v[140:143], v[186:189], v[100:103]
	v_mfma_f32_16x16x32_bf16 v[68:71], v[136:139], v[152:155], v[68:71]
	v_mfma_f32_16x16x32_bf16 v[72:75], v[144:147], v[152:155], v[72:75]
	v_mfma_f32_16x16x32_bf16 v[120:123], v[136:139], v[160:163], v[120:123]
	v_mfma_f32_16x16x32_bf16 v[116:119], v[144:147], v[160:163], v[116:119]
	v_mfma_f32_16x16x32_bf16 v[112:115], v[136:139], v[168:171], v[112:115]
	v_mfma_f32_16x16x32_bf16 v[108:111], v[144:147], v[168:171], v[108:111]
	v_mfma_f32_16x16x32_bf16 v[104:107], v[136:139], v[190:193], v[104:107]
	v_mfma_f32_16x16x32_bf16 v[100:103], v[144:147], v[190:193], v[100:103]
	v_mfma_f32_16x16x32_bf16 v[76:79], v[194:197], v[148:151], v[76:79]
	v_mfma_f32_16x16x32_bf16 v[80:83], v[202:205], v[148:151], v[80:83]
	v_mfma_f32_16x16x32_bf16 v[96:99], v[194:197], v[156:159], v[96:99]
	v_mfma_f32_16x16x32_bf16 v[92:95], v[202:205], v[156:159], v[92:95]
	v_mfma_f32_16x16x32_bf16 v[88:91], v[194:197], v[164:167], v[88:91]
	v_mfma_f32_16x16x32_bf16 v[84:87], v[202:205], v[164:167], v[84:87]
	v_mfma_f32_16x16x32_bf16 v[128:131], v[194:197], v[186:189], v[128:131]
	v_mfma_f32_16x16x32_bf16 v[124:127], v[202:205], v[186:189], v[124:127]
	v_mfma_f32_16x16x32_bf16 v[76:79], v[198:201], v[152:155], v[76:79]
	v_mfma_f32_16x16x32_bf16 v[80:83], v[208:211], v[152:155], v[80:83]
	v_mfma_f32_16x16x32_bf16 v[96:99], v[198:201], v[160:163], v[96:99]
	v_mfma_f32_16x16x32_bf16 v[92:95], v[208:211], v[160:163], v[92:95]
	v_mfma_f32_16x16x32_bf16 v[88:91], v[198:201], v[168:171], v[88:91]
	v_mfma_f32_16x16x32_bf16 v[84:87], v[208:211], v[168:171], v[84:87]
	v_mfma_f32_16x16x32_bf16 v[128:131], v[198:201], v[190:193], v[128:131]
	v_mfma_f32_16x16x32_bf16 v[124:127], v[208:211], v[190:193], v[124:127]
	s_barrier
; #define PG8_STAGE(bufoff, gbase, voff) do { _Pragma("unroll") for (int _i = 0; _i < 2; ++_i) \
;         __builtin_amdgcn_global_load_lds((const unsigned*)((const char*)(gbase) + (voff)[_i]), (LAS unsigned*)(lds + (bufoff) + ldsw + _i * 8192), 16, 0, 0); } while (0)
; #define PG8_LDA(dst, b, h) do { _Pragma("unroll") for (int m = 0; m < 4; ++m) _Pragma("unroll") for (int k = 0; k < 2; ++k) dst[m][k] = *(const LAS bf16x8*)(lds + PG8_SA(b, h) + aoff + m * 2048 + k * 1024); } while (0)
; #define PG8_LDB(dst, b, h) do { _Pragma("unroll") for (int n = 0; n < 2; ++n) _Pragma("unroll") for (int k = 0; k < 2; ++k) dst[n][k] = *(const LAS bf16x8*)(lds + PG8_SB(b, h) + boff + n * 2048 + k * 1024); } while (0)
; #define PG8_MMA(ai, bj, At, Bt) do { __builtin_amdgcn_s_setprio(1); _Pragma("unroll") for (int m = 0; m < 4; ++m) _Pragma("unroll") for (int n = 0; n < 2; ++n) _Pragma("unroll") for (int k = 0; k < 2; ++k) \
;         acc[ai][bj][m][n] = __builtin_amdgcn_mfma_f32_16x16x32_bf16(Bt[n][k], At[m][k], acc[ai][bj][m][n], 0, 0, 0); __builtin_amdgcn_s_setprio(0); } while (0)
; #define PG8_WAIT_V(n) asm volatile("s_waitcnt vmcnt(" #n ")" ::: "memory")
; #define PG8_WAIT_L(n) asm volatile("s_waitcnt lgkmcnt(" #n ")" ::: "memory")
; #define PG8_BAR __builtin_amdgcn_s_barrier()
; #define PG8_SCHED __builtin_amdgcn_sched_barrier(0)
; template <class Epi, class Sched>
; __device__ __forceinline__ void gemm_phase(LAS unsigned char* lds, const Gemm g, const Sched& S, const Epi& E) {
;     ...
;             PG8_LDB(B0, 0, 0); PG8_SCHED; PG8_LDA(At, 0, 0); PG8_STAGE(PG8_SA(1, 1), a1 + hstepA, voffA);
;             PG8_WAIT_L(8); PG8_BAR; PG8_WAIT_L(0); PG8_MMA(0, 0, At, B0); PG8_BAR; PG8_SCHED;
;     ...
;             PG8_LDA(At, 1, 1); PG8_STAGE(PG8_SA(1, 0), a3, voffA);
;             PG8_BAR; PG8_WAIT_L(0); PG8_MMA(1, 0, At, B0); PG8_BAR; PG8_SCHED;
;             PG8_STAGE(PG8_SB(1, 1), b3 + hstepB, voffB);
;             PG8_WAIT_V(6); PG8_BAR; PG8_MMA(1, 1, At, B1); PG8_BAR;
	s_setprio 0
	ds_read_b128 v[148:151], v207 offset:49152
	ds_read_b128 v[152:155], v207 offset:50176
	ds_read_b128 v[156:159], v207 offset:51200
	ds_read_b128 v[160:163], v207 offset:52224
	ds_read_b128 v[164:167], v207 offset:53248
	ds_read_b128 v[168:171], v207 offset:54272
	ds_read_b128 v[186:189], v207 offset:55296
	ds_read_b128 v[190:193], v207 offset:56320
	s_add_i32 s15, s72, s19
	v_lshl_add_u64 v[172:173], v[172:173], 0, s[8:9]
	s_mov_b32 m0, s15
	s_nop 0
	global_load_lds_dwordx4 v[172:173], off
	v_lshl_add_u64 v[172:173], v[212:213], 0, s[8:9]
	s_add_i32 m0, s15, 0x2000
	s_nop 0
	global_load_lds_dwordx4 v[172:173], off
	s_mov_b32 m0, s30
	v_lshl_add_u64 v[172:173], v[216:217], 0, s[8:9]
	global_load_lds_dwordx4 v[172:173], off
	v_lshl_add_u64 v[172:173], v[218:219], 0, s[8:9]
	s_mov_b32 m0, s31
	s_nop 0
	global_load_lds_dwordx4 v[172:173], off
	s_add_u32 s6, s6, 0x80080
	s_addc_u32 s7, s7, 0
	s_add_i32 s14, s14, s19
	s_mov_b32 m0, s14
	s_nop 0
	global_load_lds_dwordx4 v178, s[6:7]
	s_add_i32 m0, s14, 0x2000
	s_nop 0
	global_load_lds_dwordx4 v174, s[6:7]
	s_add_i32 s71, s71, 2
	s_add_u32 s4, s4, 0x100
	s_addc_u32 s5, s5, 0
	s_add_u32 s69, s69, 0x100
	s_addc_u32 s70, s70, 0
	s_cmp_gt_u32 s71, 29
	s_waitcnt lgkmcnt(0)
	s_waitcnt vmcnt(8)
	s_setprio 1
	s_barrier
	v_mfma_f32_16x16x32_bf16 v[56:59], v[132:135], v[148:151], v[56:59]
	v_mfma_f32_16x16x32_bf16 v[52:55], v[140:143], v[148:151], v[52:55]
	v_mfma_f32_16x16x32_bf16 v[48:51], v[132:135], v[156:159], v[48:51]
	v_mfma_f32_16x16x32_bf16 v[44:47], v[140:143], v[156:159], v[44:47]
	v_mfma_f32_16x16x32_bf16 v[40:43], v[132:135], v[164:167], v[40:43]
	v_mfma_f32_16x16x32_bf16 v[36:39], v[140:143], v[164:167], v[36:39]
	v_mfma_f32_16x16x32_bf16 v[32:35], v[132:135], v[186:189], v[32:35]
	v_mfma_f32_16x16x32_bf16 v[28:31], v[140:143], v[186:189], v[28:31]
	v_mfma_f32_16x16x32_bf16 v[56:59], v[136:139], v[152:155], v[56:59]
	v_mfma_f32_16x16x32_bf16 v[52:55], v[144:147], v[152:155], v[52:55]
	v_mfma_f32_16x16x32_bf16 v[48:51], v[136:139], v[160:163], v[48:51]
	v_mfma_f32_16x16x32_bf16 v[44:47], v[144:147], v[160:163], v[44:47]
	v_mfma_f32_16x16x32_bf16 v[40:43], v[136:139], v[168:171], v[40:43]
	v_mfma_f32_16x16x32_bf16 v[36:39], v[144:147], v[168:171], v[36:39]
	v_mfma_f32_16x16x32_bf16 v[32:35], v[136:139], v[190:193], v[32:35]
	v_mfma_f32_16x16x32_bf16 v[28:31], v[144:147], v[190:193], v[28:31]
	v_mfma_f32_16x16x32_bf16 v[24:27], v[194:197], v[148:151], v[24:27]
	v_mfma_f32_16x16x32_bf16 v[20:23], v[202:205], v[148:151], v[20:23]
	v_mfma_f32_16x16x32_bf16 v[16:19], v[194:197], v[156:159], v[16:19]
	v_mfma_f32_16x16x32_bf16 v[12:15], v[202:205], v[156:159], v[12:15]
	v_mfma_f32_16x16x32_bf16 v[8:11], v[194:197], v[164:167], v[8:11]
	v_mfma_f32_16x16x32_bf16 v[4:7], v[202:205], v[164:167], v[4:7]
	v_mfma_f32_16x16x32_bf16 v[60:63], v[194:197], v[186:189], v[60:63]
	v_mfma_f32_16x16x32_bf16 v[64:67], v[202:205], v[186:189], v[64:67]
	v_mfma_f32_16x16x32_bf16 v[24:27], v[198:201], v[152:155], v[24:27]
	v_mfma_f32_16x16x32_bf16 v[20:23], v[208:211], v[152:155], v[20:23]
	v_mfma_f32_16x16x32_bf16 v[16:19], v[198:201], v[160:163], v[16:19]
	v_mfma_f32_16x16x32_bf16 v[12:15], v[208:211], v[160:163], v[12:15]
	v_mfma_f32_16x16x32_bf16 v[8:11], v[198:201], v[168:171], v[8:11]
	v_mfma_f32_16x16x32_bf16 v[4:7], v[208:211], v[168:171], v[4:7]
	v_mfma_f32_16x16x32_bf16 v[60:63], v[198:201], v[190:193], v[60:63]
	v_mfma_f32_16x16x32_bf16 v[64:67], v[208:211], v[190:193], v[64:67]
	s_barrier
	s_setprio 0
.LBB0_1526:
	s_setprio 0
	s_add_u32 s6, s4, 0xfff80080
	s_addc_u32 s7, s5, -1
	s_add_i32 s72, 0, 0x10000
	v_add_u32_e32 v2, s72, v1
	ds_read_b128 v[132:135], v2
	ds_read_b128 v[136:139], v2 offset:1024
	ds_read_b128 v[140:143], v2 offset:2048
	ds_read_b128 v[144:147], v2 offset:3072
	s_cmp_eq_u32 s71, 28
	s_cselect_b32 s15, s57, s7
	s_cselect_b32 s14, s67, s6
	s_cselect_b32 s7, s55, s70
	s_cselect_b32 s6, s68, s69
	ds_read_b128 v[148:151], v207
	ds_read_b128 v[152:155], v207 offset:1024
	ds_read_b128 v[156:159], v207 offset:2048
	ds_read_b128 v[160:163], v207 offset:3072
	ds_read_b128 v[164:167], v207 offset:4096
	ds_read_b128 v[168:171], v207 offset:5120
	ds_read_b128 v[186:189], v207 offset:6144
	ds_read_b128 v[190:193], v207 offset:7168
	s_add_i32 s74, 0, 0x14000
	v_add_u32_e32 v2, s74, v1
	ds_read_b128 v[194:197], v2
	ds_read_b128 v[198:201], v2 offset:1024
	ds_read_b128 v[202:205], v2 offset:2048
	ds_read_b128 v[208:211], v2 offset:3072
	s_add_i32 m0, s20, 0xc000
	s_nop 0
	global_load_lds_dwordx4 v182, s[4:5]
	s_add_i32 m0, s20, 0xe000
	s_nop 0
	global_load_lds_dwordx4 v184, s[4:5]
	s_waitcnt lgkmcnt(0)
	s_waitcnt vmcnt(8)
	s_setprio 1
	s_barrier
; #define PG8_STAGE(bufoff, gbase, voff) do { _Pragma("unroll") for (int _i = 0; _i < 2; ++_i) \
;         __builtin_amdgcn_global_load_lds((const unsigned*)((const char*)(gbase) + (voff)[_i]), (LAS unsigned*)(lds + (bufoff) + ldsw + _i * 8192), 16, 0, 0); } while (0)
; #define PG8_LDA(dst, b, h) do { _Pragma("unroll") for (int m = 0; m < 4; ++m) _Pragma("unroll") for (int k = 0; k < 2; ++k) dst[m][k] = *(const LAS bf16x8*)(lds + PG8_SA(b, h) + aoff + m * 2048 + k * 1024); } while (0)
; #define PG8_LDB(dst, b, h) do { _Pragma("unroll") for (int n = 0; n < 2; ++n) _Pragma("unroll") for (int k = 0; k < 2; ++k) dst[n][k] = *(const LAS bf16x8*)(lds + PG8_SB(b, h) + boff + n * 2048 + k * 1024); } while (0)
; #define PG8_MMA(ai, bj, At, Bt) do { __builtin_amdgcn_s_setprio(1); _Pragma("unroll") for (int m = 0; m < 4; ++m) _Pragma("unroll") for (int n = 0; n < 2; ++n) _Pragma("unroll") for (int k = 0; k < 2; ++k) \
;         acc[ai][bj][m][n] = __builtin_amdgcn_mfma_f32_16x16x32_bf16(Bt[n][k], At[m][k], acc[ai][bj][m][n], 0, 0, 0); __builtin_amdgcn_s_setprio(0); } while (0)
; #define PG8_WAIT_V(n) asm volatile("s_waitcnt vmcnt(" #n ")" ::: "memory")
; #define PG8_WAIT_L(n) asm volatile("s_waitcnt lgkmcnt(" #n ")" ::: "memory")
; #define PG8_BAR __builtin_amdgcn_s_barrier()
; #define PG8_SCHED __builtin_amdgcn_sched_barrier(0)
; template <class Epi, class Sched>
; __device__ __forceinline__ void gemm_phase(LAS unsigned char* lds, const Gemm g, const Sched& S, const Epi& E) {
;     ...
;             PG8_WAIT_L(8); PG8_BAR; PG8_WAIT_L(0); PG8_MMA(0, 0, At, B0); PG8_BAR; PG8_SCHED;
;             PG8_LDB(B1, 0, 1); PG8_STAGE(PG8_SB(0, 0), b2, voffB);
;             PG8_BAR; PG8_WAIT_L(0); PG8_MMA(0, 1, At, B1); PG8_BAR;
;             PG8_LDA(At, 0, 1); PG8_STAGE(PG8_SA(0, 0), a2, voffA);
;             PG8_BAR; PG8_WAIT_L(0); PG8_MMA(1, 0, At, B0); PG8_BAR; PG8_SCHED;
;             PG8_STAGE(PG8_SB(0, 1), b2 + hstepB, voffB);
;             PG8_WAIT_V(6); PG8_BAR; PG8_MMA(1, 1, At, B1); PG8_BAR;
	v_mfma_f32_16x16x32_bf16 v[68:71], v[132:135], v[148:151], v[68:71]
	v_mfma_f32_16x16x32_bf16 v[72:75], v[140:143], v[148:151], v[72:75]
	v_mfma_f32_16x16x32_bf16 v[120:123], v[132:135], v[156:159], v[120:123]
	v_mfma_f32_16x16x32_bf16 v[116:119], v[140:143], v[156:159], v[116:119]
	v_mfma_f32_16x16x32_bf16 v[112:115], v[132:135], v[164:167], v[112:115]
	v_mfma_f32_16x16x32_bf16 v[108:111], v[140:143], v[164:167], v[108:111]
	v_mfma_f32_16x16x32_bf16 v[104:107], v[132:135], v[186:189], v[104:107]
	v_mfma_f32_16x16x32_bf16 v[100:103], v[140:143], v[186:189], v[100:103]
	v_mfma_f32_16x16x32_bf16 v[68:71], v[136:139], v[152:155], v[68:71]
	v_mfma_f32_16x16x32_bf16 v[72:75], v[144:147], v[152:155], v[72:75]
	v_mfma_f32_16x16x32_bf16 v[120:123], v[136:139], v[160:163], v[120:123]
	v_mfma_f32_16x16x32_bf16 v[116:119], v[144:147], v[160:163], v[116:119]
	v_mfma_f32_16x16x32_bf16 v[112:115], v[136:139], v[168:171], v[112:115]
	v_mfma_f32_16x16x32_bf16 v[108:111], v[144:147], v[168:171], v[108:111]
	v_mfma_f32_16x16x32_bf16 v[104:107], v[136:139], v[190:193], v[104:107]
	v_mfma_f32_16x16x32_bf16 v[100:103], v[144:147], v[190:193], v[100:103]
	v_mfma_f32_16x16x32_bf16 v[76:79], v[194:197], v[148:151], v[76:79]
	v_mfma_f32_16x16x32_bf16 v[80:83], v[202:205], v[148:151], v[80:83]
	v_mfma_f32_16x16x32_bf16 v[96:99], v[194:197], v[156:159], v[96:99]
	v_mfma_f32_16x16x32_bf16 v[92:95], v[202:205], v[156:159], v[92:95]
	v_mfma_f32_16x16x32_bf16 v[88:91], v[194:197], v[164:167], v[88:91]
	v_mfma_f32_16x16x32_bf16 v[84:87], v[202:205], v[164:167], v[84:87]
	v_mfma_f32_16x16x32_bf16 v[128:131], v[194:197], v[186:189], v[128:131]
	v_mfma_f32_16x16x32_bf16 v[124:127], v[202:205], v[186:189], v[124:127]
	v_mfma_f32_16x16x32_bf16 v[76:79], v[198:201], v[152:155], v[76:79]
	v_mfma_f32_16x16x32_bf16 v[80:83], v[208:211], v[152:155], v[80:83]
	v_mfma_f32_16x16x32_bf16 v[96:99], v[198:201], v[160:163], v[96:99]
	v_mfma_f32_16x16x32_bf16 v[92:95], v[208:211], v[160:163], v[92:95]
	v_mfma_f32_16x16x32_bf16 v[88:91], v[198:201], v[168:171], v[88:91]
	v_mfma_f32_16x16x32_bf16 v[84:87], v[208:211], v[168:171], v[84:87]
	v_mfma_f32_16x16x32_bf16 v[128:131], v[198:201], v[190:193], v[128:131]
	v_mfma_f32_16x16x32_bf16 v[124:127], v[208:211], v[190:193], v[124:127]
	s_barrier
	s_setprio 0
	ds_read_b128 v[148:151], v207 offset:16384
	ds_read_b128 v[152:155], v207 offset:17408
	ds_read_b128 v[156:159], v207 offset:18432
	ds_read_b128 v[160:163], v207 offset:19456
	ds_read_b128 v[164:167], v207 offset:20480
	ds_read_b128 v[168:171], v207 offset:21504
	ds_read_b128 v[186:189], v207 offset:22528
	ds_read_b128 v[190:193], v207 offset:23552
	s_add_i32 s72, s72, s19
	v_lshl_add_u64 v[172:173], s[6:7], 0, v[178:179]
	s_mov_b32 m0, s72
	s_nop 0
	global_load_lds_dwordx4 v[172:173], off
	v_lshl_add_u64 v[212:213], s[6:7], 0, v[174:175]
	s_add_i32 m0, s72, 0x2000
	s_nop 0
	global_load_lds_dwordx4 v[212:213], off
	s_mov_b32 m0, s20
	v_lshl_add_u64 v[216:217], s[14:15], 0, v[180:181]
	global_load_lds_dwordx4 v[216:217], off
	v_lshl_add_u64 v[218:219], s[14:15], 0, v[176:177]
	s_mov_b32 m0, s21
	s_nop 0
	global_load_lds_dwordx4 v[218:219], off
	s_add_u32 s72, s6, 0x80000
	s_addc_u32 s73, s7, 0
	s_add_i32 s74, s74, s19
	s_mov_b32 m0, s74
	s_nop 0
	global_load_lds_dwordx4 v178, s[72:73]
	s_add_i32 m0, s74, 0x2000
	s_nop 0
	global_load_lds_dwordx4 v174, s[72:73]
	s_waitcnt lgkmcnt(0)
	s_waitcnt vmcnt(8)
	s_setprio 1
	s_barrier
	v_mfma_f32_16x16x32_bf16 v[56:59], v[132:135], v[148:151], v[56:59]
	v_mfma_f32_16x16x32_bf16 v[52:55], v[140:143], v[148:151], v[52:55]
	v_mfma_f32_16x16x32_bf16 v[48:51], v[132:135], v[156:159], v[48:51]
	v_mfma_f32_16x16x32_bf16 v[44:47], v[140:143], v[156:159], v[44:47]
	v_mfma_f32_16x16x32_bf16 v[40:43], v[132:135], v[164:167], v[40:43]
	v_mfma_f32_16x16x32_bf16 v[36:39], v[140:143], v[164:167], v[36:39]
	v_mfma_f32_16x16x32_bf16 v[32:35], v[132:135], v[186:189], v[32:35]
	v_mfma_f32_16x16x32_bf16 v[28:31], v[140:143], v[186:189], v[28:31]
	v_mfma_f32_16x16x32_bf16 v[56:59], v[136:139], v[152:155], v[56:59]
	v_mfma_f32_16x16x32_bf16 v[52:55], v[144:147], v[152:155], v[52:55]
	v_mfma_f32_16x16x32_bf16 v[48:51], v[136:139], v[160:163], v[48:51]
	v_mfma_f32_16x16x32_bf16 v[44:47], v[144:147], v[160:163], v[44:47]
	v_mfma_f32_16x16x32_bf16 v[40:43], v[136:139], v[168:171], v[40:43]
	v_mfma_f32_16x16x32_bf16 v[36:39], v[144:147], v[168:171], v[36:39]
	v_mfma_f32_16x16x32_bf16 v[32:35], v[136:139], v[190:193], v[32:35]
	v_mfma_f32_16x16x32_bf16 v[28:31], v[144:147], v[190:193], v[28:31]
	v_mfma_f32_16x16x32_bf16 v[24:27], v[194:197], v[148:151], v[24:27]
	v_mfma_f32_16x16x32_bf16 v[20:23], v[202:205], v[148:151], v[20:23]
	v_mfma_f32_16x16x32_bf16 v[16:19], v[194:197], v[156:159], v[16:19]
	v_mfma_f32_16x16x32_bf16 v[12:15], v[202:205], v[156:159], v[12:15]
	v_mfma_f32_16x16x32_bf16 v[8:11], v[194:197], v[164:167], v[8:11]
	v_mfma_f32_16x16x32_bf16 v[4:7], v[202:205], v[164:167], v[4:7]
	v_mfma_f32_16x16x32_bf16 v[60:63], v[194:197], v[186:189], v[60:63]
	v_mfma_f32_16x16x32_bf16 v[64:67], v[202:205], v[186:189], v[64:67]
	v_mfma_f32_16x16x32_bf16 v[24:27], v[198:201], v[152:155], v[24:27]
	v_mfma_f32_16x16x32_bf16 v[20:23], v[208:211], v[152:155], v[20:23]
	v_mfma_f32_16x16x32_bf16 v[16:19], v[198:201], v[160:163], v[16:19]
	v_mfma_f32_16x16x32_bf16 v[12:15], v[208:211], v[160:163], v[12:15]
	v_mfma_f32_16x16x32_bf16 v[8:11], v[198:201], v[168:171], v[8:11]
	v_mfma_f32_16x16x32_bf16 v[4:7], v[208:211], v[168:171], v[4:7]
	v_mfma_f32_16x16x32_bf16 v[60:63], v[198:201], v[190:193], v[60:63]
	v_mfma_f32_16x16x32_bf16 v[64:67], v[208:211], v[190:193], v[64:67]
	s_barrier
; #define PG8_STAGE(bufoff, gbase, voff) do { _Pragma("unroll") for (int _i = 0; _i < 2; ++_i) \
;         __builtin_amdgcn_global_load_lds((const unsigned*)((const char*)(gbase) + (voff)[_i]), (LAS unsigned*)(lds + (bufoff) + ldsw + _i * 8192), 16, 0, 0); } while (0)
; #define PG8_LDA(dst, b, h) do { _Pragma("unroll") for (int m = 0; m < 4; ++m) _Pragma("unroll") for (int k = 0; k < 2; ++k) dst[m][k] = *(const LAS bf16x8*)(lds + PG8_SA(b, h) + aoff + m * 2048 + k * 1024); } while (0)
; #define PG8_LDB(dst, b, h) do { _Pragma("unroll") for (int n = 0; n < 2; ++n) _Pragma("unroll") for (int k = 0; k < 2; ++k) dst[n][k] = *(const LAS bf16x8*)(lds + PG8_SB(b, h) + boff + n * 2048 + k * 1024); } while (0)
; #define PG8_MMA(ai, bj, At, Bt) do { __builtin_amdgcn_s_setprio(1); _Pragma("unroll") for (int m = 0; m < 4; ++m) _Pragma("unroll") for (int n = 0; n < 2; ++n) _Pragma("unroll") for (int k = 0; k < 2; ++k) \
;         acc[ai][bj][m][n] = __builtin_amdgcn_mfma_f32_16x16x32_bf16(Bt[n][k], At[m][k], acc[ai][bj][m][n], 0, 0, 0); __builtin_amdgcn_s_setprio(0); } while (0)
; #define PG8_WAIT_V(n) asm volatile("s_waitcnt vmcnt(" #n ")" ::: "memory")
; #define PG8_WAIT_L(n) asm volatile("s_waitcnt lgkmcnt(" #n ")" ::: "memory")
; #define PG8_BAR __builtin_amdgcn_s_barrier()
; #define PG8_SCHED __builtin_amdgcn_sched_barrier(0)
; template <class Epi, class Sched>
; __device__ __forceinline__ void gemm_phase(LAS unsigned char* lds, const Gemm g, const Sched& S, const Epi& E) {
;     ...
;             PG8_LDB(B0, 1, 0); PG8_SCHED; PG8_LDA(At, 1, 0); PG8_STAGE(PG8_SA(0, 1), a2 + hstepA, voffA);
;             PG8_WAIT_L(8); PG8_BAR; PG8_WAIT_L(0); PG8_MMA(0, 0, At, B0); PG8_BAR; PG8_SCHED;
;             PG8_LDB(B1, 1, 1); PG8_STAGE(PG8_SB(1, 0), b3, voffB);
;             PG8_BAR; PG8_WAIT_L(0); PG8_MMA(0, 1, At, B1); PG8_BAR;
;             PG8_LDA(At, 1, 1); PG8_STAGE(PG8_SA(1, 0), a3, voffA);
;             PG8_BAR; PG8_WAIT_L(0); PG8_MMA(1, 0, At, B0); PG8_BAR; PG8_SCHED;
;             PG8_STAGE(PG8_SB(1, 1), b3 + hstepB, voffB);
;             PG8_WAIT_V(6); PG8_BAR; PG8_MMA(1, 1, At, B1); PG8_BAR;
	s_setprio 0
	s_add_i32 s72, 0, 0x18000
	v_add_u32_e32 v2, s72, v1
	ds_read_b128 v[132:135], v2
	ds_read_b128 v[136:139], v2 offset:1024
	ds_read_b128 v[140:143], v2 offset:2048
	ds_read_b128 v[144:147], v2 offset:3072
	s_add_u32 s14, s14, 0x80000
	s_addc_u32 s15, s15, 0
	ds_read_b128 v[148:151], v207 offset:32768
	ds_read_b128 v[152:155], v207 offset:33792
	ds_read_b128 v[156:159], v207 offset:34816
	ds_read_b128 v[160:163], v207 offset:35840
	ds_read_b128 v[164:167], v207 offset:36864
	ds_read_b128 v[168:171], v207 offset:37888
	ds_read_b128 v[186:189], v207 offset:38912
	ds_read_b128 v[190:193], v207 offset:39936
	s_mov_b32 m0, s24
	s_nop 0
	global_load_lds_dwordx4 v180, s[14:15]
	s_mov_b32 m0, s25
	s_nop 0
	global_load_lds_dwordx4 v176, s[14:15]
	s_add_i32 s14, 0, 0x1c000
	v_add_u32_e32 v2, s14, v1
	ds_read_b128 v[194:197], v2
	ds_read_b128 v[198:201], v2 offset:1024
	ds_read_b128 v[202:205], v2 offset:2048
	ds_read_b128 v[208:211], v2 offset:3072
	s_waitcnt lgkmcnt(0)
	s_waitcnt vmcnt(8)
	s_setprio 1
	s_barrier
	v_mfma_f32_16x16x32_bf16 v[68:71], v[132:135], v[148:151], v[68:71]
	v_mfma_f32_16x16x32_bf16 v[72:75], v[140:143], v[148:151], v[72:75]
	v_mfma_f32_16x16x32_bf16 v[120:123], v[132:135], v[156:159], v[120:123]
	v_mfma_f32_16x16x32_bf16 v[116:119], v[140:143], v[156:159], v[116:119]
	v_mfma_f32_16x16x32_bf16 v[112:115], v[132:135], v[164:167], v[112:115]
	v_mfma_f32_16x16x32_bf16 v[108:111], v[140:143], v[164:167], v[108:111]
	v_mfma_f32_16x16x32_bf16 v[104:107], v[132:135], v[186:189], v[104:107]
	v_mfma_f32_16x16x32_bf16 v[100:103], v[140:143], v[186:189], v[100:103]
	v_mfma_f32_16x16x32_bf16 v[68:71], v[136:139], v[152:155], v[68:71]
	v_mfma_f32_16x16x32_bf16 v[72:75], v[144:147], v[152:155], v[72:75]
	v_mfma_f32_16x16x32_bf16 v[120:123], v[136:139], v[160:163], v[120:123]
	v_mfma_f32_16x16x32_bf16 v[116:119], v[144:147], v[160:163], v[116:119]
	v_mfma_f32_16x16x32_bf16 v[112:115], v[136:139], v[168:171], v[112:115]
	v_mfma_f32_16x16x32_bf16 v[108:111], v[144:147], v[168:171], v[108:111]
	v_mfma_f32_16x16x32_bf16 v[104:107], v[136:139], v[190:193], v[104:107]
	v_mfma_f32_16x16x32_bf16 v[100:103], v[144:147], v[190:193], v[100:103]
	v_mfma_f32_16x16x32_bf16 v[76:79], v[194:197], v[148:151], v[76:79]
	v_mfma_f32_16x16x32_bf16 v[80:83], v[202:205], v[148:151], v[80:83]
	v_mfma_f32_16x16x32_bf16 v[96:99], v[194:197], v[156:159], v[96:99]
	v_mfma_f32_16x16x32_bf16 v[92:95], v[202:205], v[156:159], v[92:95]
	v_mfma_f32_16x16x32_bf16 v[88:91], v[194:197], v[164:167], v[88:91]
	v_mfma_f32_16x16x32_bf16 v[84:87], v[202:205], v[164:167], v[84:87]
	v_mfma_f32_16x16x32_bf16 v[128:131], v[194:197], v[186:189], v[128:131]
	v_mfma_f32_16x16x32_bf16 v[124:127], v[202:205], v[186:189], v[124:127]
	v_mfma_f32_16x16x32_bf16 v[76:79], v[198:201], v[152:155], v[76:79]
	v_mfma_f32_16x16x32_bf16 v[80:83], v[208:211], v[152:155], v[80:83]
	v_mfma_f32_16x16x32_bf16 v[96:99], v[198:201], v[160:163], v[96:99]
	v_mfma_f32_16x16x32_bf16 v[92:95], v[208:211], v[160:163], v[92:95]
	v_mfma_f32_16x16x32_bf16 v[88:91], v[198:201], v[168:171], v[88:91]
	v_mfma_f32_16x16x32_bf16 v[84:87], v[208:211], v[168:171], v[84:87]
	v_mfma_f32_16x16x32_bf16 v[128:131], v[198:201], v[190:193], v[128:131]
	v_mfma_f32_16x16x32_bf16 v[124:127], v[208:211], v[190:193], v[124:127]
	s_barrier
	s_setprio 0
	ds_read_b128 v[148:151], v207 offset:49152
	ds_read_b128 v[152:155], v207 offset:50176
	ds_read_b128 v[156:159], v207 offset:51200
	ds_read_b128 v[160:163], v207 offset:52224
	ds_read_b128 v[164:167], v207 offset:53248
	ds_read_b128 v[168:171], v207 offset:54272
	ds_read_b128 v[186:189], v207 offset:55296
	ds_read_b128 v[190:193], v207 offset:56320
	s_add_i32 s15, s72, s19
	v_lshl_add_u64 v[172:173], v[172:173], 0, s[8:9]
	s_mov_b32 m0, s15
	s_nop 0
	global_load_lds_dwordx4 v[172:173], off
	v_lshl_add_u64 v[172:173], v[212:213], 0, s[8:9]
	s_add_i32 m0, s15, 0x2000
	s_nop 0
	global_load_lds_dwordx4 v[172:173], off
	s_mov_b32 m0, s30
	v_lshl_add_u64 v[172:173], v[216:217], 0, s[8:9]
	global_load_lds_dwordx4 v[172:173], off
	v_lshl_add_u64 v[172:173], v[218:219], 0, s[8:9]
	s_mov_b32 m0, s31
	s_nop 0
	global_load_lds_dwordx4 v[172:173], off
	s_add_u32 s6, s6, 0x80080
	s_addc_u32 s7, s7, 0
	s_add_i32 s14, s14, s19
	s_mov_b32 m0, s14
	s_nop 0
	global_load_lds_dwordx4 v178, s[6:7]
	s_add_i32 m0, s14, 0x2000
	s_nop 0
	global_load_lds_dwordx4 v174, s[6:7]
	s_add_i32 s71, s71, 2
	s_add_u32 s4, s4, 0x100
	s_addc_u32 s5, s5, 0
	s_add_u32 s69, s69, 0x100
	s_addc_u32 s70, s70, 0
	s_cmp_gt_u32 s71, 29
	s_waitcnt lgkmcnt(0)
	s_waitcnt vmcnt(8)
	s_setprio 1
	s_barrier
; #define LAS __attribute__((address_space(3)))
; __device__ __forceinline__ int opaque_tid() { int t = threadIdx.x; asm volatile("" : "+v"(t)); return t; }
; #define PG8_MMA(ai, bj, At, Bt) do { __builtin_amdgcn_s_setprio(1); _Pragma("unroll") for (int m = 0; m < 4; ++m) _Pragma("unroll") for (int n = 0; n < 2; ++n) _Pragma("unroll") for (int k = 0; k < 2; ++k) \
;         acc[ai][bj][m][n] = __builtin_amdgcn_mfma_f32_16x16x32_bf16(Bt[n][k], At[m][k], acc[ai][bj][m][n], 0, 0, 0); __builtin_amdgcn_s_setprio(0); } while (0)
; #define PG8_WAIT_V(n) asm volatile("s_waitcnt vmcnt(" #n ")" ::: "memory")
; #define PG8_BAR __builtin_amdgcn_s_barrier()
;     __device__ __forceinline__ void operator()(f32x4 (&acc)[2][2][4][2], const Unit& u, int wr, int wc, int ui, int) const {
;         const int ol_ = opaque_tid() & 63, fr = ol_ & 15, fq = ol_ >> 4;
;         { float r_[2][4];
;           rs_read(r_, ui, wr, fr);
; #pragma unroll
;           for (int ai = 0; ai < 2; ++ai)
; #pragma unroll
;               for (int bj = 0; bj < 2; ++bj)
; #pragma unroll
;                   for (int m = 0; m < 4; ++m) { acc[ai][bj][m][0] *= r_[ai][m]; acc[ai][bj][m][1] *= r_[ai][m]; } }
;         const int col = u.pn * 128 + wc * 32 + 8 * fq;
;         if (fr >= 14) {
; #pragma unroll
;             for (int ai = 0; ai < 2; ++ai) { LAS f32x4* s = (LAS f32x4*)(hl + ((((ai * 2 + wr) * 4 + wc) * 8 + fq * 2 + (fr - 14)) * 32));
;                 s[0] = acc[ai][1][3][0]; s[1] = acc[ai][1][3][1]; }
; template <class Epi, class Sched>
; __device__ __forceinline__ void gemm_phase(LAS unsigned char* lds, const Gemm g, const Sched& S, const Epi& E) {
;     ...
;             PG8_WAIT_V(6); PG8_BAR; PG8_MMA(1, 1, At, B1); PG8_BAR;
;         }
	v_mfma_f32_16x16x32_bf16 v[56:59], v[132:135], v[148:151], v[56:59]
	v_mfma_f32_16x16x32_bf16 v[52:55], v[140:143], v[148:151], v[52:55]
	v_mfma_f32_16x16x32_bf16 v[48:51], v[132:135], v[156:159], v[48:51]
	v_mfma_f32_16x16x32_bf16 v[44:47], v[140:143], v[156:159], v[44:47]
	v_mfma_f32_16x16x32_bf16 v[40:43], v[132:135], v[164:167], v[40:43]
	v_mfma_f32_16x16x32_bf16 v[36:39], v[140:143], v[164:167], v[36:39]
	v_mfma_f32_16x16x32_bf16 v[32:35], v[132:135], v[186:189], v[32:35]
	v_mfma_f32_16x16x32_bf16 v[28:31], v[140:143], v[186:189], v[28:31]
	v_mfma_f32_16x16x32_bf16 v[56:59], v[136:139], v[152:155], v[56:59]
	v_mfma_f32_16x16x32_bf16 v[52:55], v[144:147], v[152:155], v[52:55]
	v_mfma_f32_16x16x32_bf16 v[48:51], v[136:139], v[160:163], v[48:51]
	v_mfma_f32_16x16x32_bf16 v[44:47], v[144:147], v[160:163], v[44:47]
	v_mfma_f32_16x16x32_bf16 v[40:43], v[136:139], v[168:171], v[40:43]
	v_mfma_f32_16x16x32_bf16 v[36:39], v[144:147], v[168:171], v[36:39]
	v_mfma_f32_16x16x32_bf16 v[32:35], v[136:139], v[190:193], v[32:35]
	v_mfma_f32_16x16x32_bf16 v[28:31], v[144:147], v[190:193], v[28:31]
	v_mfma_f32_16x16x32_bf16 v[24:27], v[194:197], v[148:151], v[24:27]
	v_mfma_f32_16x16x32_bf16 v[20:23], v[202:205], v[148:151], v[20:23]
	v_mfma_f32_16x16x32_bf16 v[16:19], v[194:197], v[156:159], v[16:19]
	v_mfma_f32_16x16x32_bf16 v[12:15], v[202:205], v[156:159], v[12:15]
	v_mfma_f32_16x16x32_bf16 v[8:11], v[194:197], v[164:167], v[8:11]
	v_mfma_f32_16x16x32_bf16 v[4:7], v[202:205], v[164:167], v[4:7]
	v_mfma_f32_16x16x32_bf16 v[60:63], v[194:197], v[186:189], v[60:63]
	v_mfma_f32_16x16x32_bf16 v[64:67], v[202:205], v[186:189], v[64:67]
	v_mfma_f32_16x16x32_bf16 v[24:27], v[198:201], v[152:155], v[24:27]
	v_mfma_f32_16x16x32_bf16 v[20:23], v[208:211], v[152:155], v[20:23]
	v_mfma_f32_16x16x32_bf16 v[16:19], v[198:201], v[160:163], v[16:19]
	v_mfma_f32_16x16x32_bf16 v[12:15], v[208:211], v[160:163], v[12:15]
	v_mfma_f32_16x16x32_bf16 v[8:11], v[198:201], v[168:171], v[8:11]
	v_mfma_f32_16x16x32_bf16 v[4:7], v[208:211], v[168:171], v[4:7]
	v_mfma_f32_16x16x32_bf16 v[60:63], v[198:201], v[190:193], v[60:63]
	v_mfma_f32_16x16x32_bf16 v[64:67], v[208:211], v[190:193], v[64:67]
	s_barrier
	s_cbranch_scc0 .LBB0_1526
	s_setprio 0
	v_bfe_u32 v186, v0, 4, 2
	s_lshl_b32 s4, s53, 7
	s_or_b32 s4, s4, s29
	v_lshl_or_b32 v186, v186, 3, s4
	v_lshlrev_b32_e32 v186, 2, v186
	global_load_dwordx4 v[162:165], v186, s[36:37] offset:16
	global_load_dwordx4 v[170:173], v186, s[36:37]
	global_load_dwordx4 v[154:157], v186, s[48:49] offset:16
	global_load_dwordx4 v[166:169], v186, s[48:49]
	global_load_dwordx4 v[146:149], v186, s[50:51] offset:16
	global_load_dwordx4 v[158:161], v186, s[50:51]
	global_load_dwordx4 v[142:145], v186, s[42:43] offset:16
	global_load_dwordx4 v[150:153], v186, s[42:43]
	s_lshl_b32 s4, s66, 10
	v_mov_b32_e32 v134, v0
	s_and_b32 s4, s4, 0x400
	s_add_i32 s4, s35, s4
	v_and_b32_e32 v210, 15, v134
	v_lshl_add_u32 v2, v210, 2, s4
	ds_read2_b32 v[204:205], v2 offset1:16
	ds_read2_b32 v[202:203], v2 offset0:32 offset1:48
	ds_read2_b32 v[198:199], v2 offset0:128 offset1:144
	ds_read2_b32 v[196:197], v2 offset0:160 offset1:176
	v_cmp_lt_u32_e32 vcc, 13, v210
	s_waitcnt lgkmcnt(0)
	v_mov_b32_e32 v206, v205
	v_mov_b32_e32 v208, v203
	v_mov_b32_e32 v2, v199
	v_mov_b32_e32 v200, v197
	v_pk_mul_f32 v[132:133], v[130:131], v[208:209] op_sel_hi:[1,0]
	v_pk_mul_f32 v[130:131], v[128:129], v[208:209] op_sel_hi:[1,0]
	v_pk_mul_f32 v[128:129], v[126:127], v[208:209] op_sel_hi:[1,0]
	v_pk_mul_f32 v[126:127], v[124:125], v[208:209] op_sel_hi:[1,0]
	v_pk_mul_f32 v[62:63], v[62:63], v[200:201] op_sel_hi:[1,0]
	v_pk_mul_f32 v[60:61], v[60:61], v[200:201] op_sel_hi:[1,0]
	v_pk_mul_f32 v[66:67], v[66:67], v[200:201] op_sel_hi:[1,0]
	v_pk_mul_f32 v[64:65], v[64:65], v[200:201] op_sel_hi:[1,0]
	v_bfe_u32 v125, v134, 4, 2
	s_and_saveexec_b64 s[4:5], vcc
	s_cbranch_execz .LBB0_1529
	v_lshlrev_b32_e32 v124, 1, v125
	v_add3_u32 v124, v210, v124, -14
	v_add_u32_e32 v134, s39, v124
	v_add_u32_e32 v124, s38, v124
	v_lshl_add_u32 v124, v124, 5, s62
	v_lshl_add_u32 v134, v134, 5, s62
	ds_write_b128 v124, v[130:133]
	ds_write_b128 v124, v[126:129] offset:16
	ds_write_b128 v134, v[60:63]
	ds_write_b128 v134, v[64:67] offset:16

; #define PG8_STAGE(bufoff, gbase, voff) do { _Pragma("unroll") for (int _i = 0; _i < 2; ++_i) \
;         __builtin_amdgcn_global_load_lds((const unsigned*)((const char*)(gbase) + (voff)[_i]), (LAS unsigned*)(lds + (bufoff) + ldsw + _i * 8192), 16, 0, 0); } while (0)
; #define PG8_LDA(dst, b, h) do { _Pragma("unroll") for (int m = 0; m < 4; ++m) _Pragma("unroll") for (int k = 0; k < 2; ++k) dst[m][k] = *(const LAS bf16x8*)(lds + PG8_SA(b, h) + aoff + m * 2048 + k * 1024); } while (0)
; #define PG8_LDB(dst, b, h) do { _Pragma("unroll") for (int n = 0; n < 2; ++n) _Pragma("unroll") for (int k = 0; k < 2; ++k) dst[n][k] = *(const LAS bf16x8*)(lds + PG8_SB(b, h) + boff + n * 2048 + k * 1024); } while (0)
; #define PG8_MMA(ai, bj, At, Bt) do { __builtin_amdgcn_s_setprio(1); _Pragma("unroll") for (int m = 0; m < 4; ++m) _Pragma("unroll") for (int n = 0; n < 2; ++n) _Pragma("unroll") for (int k = 0; k < 2; ++k) \
;         acc[ai][bj][m][n] = __builtin_amdgcn_mfma_f32_16x16x32_bf16(Bt[n][k], At[m][k], acc[ai][bj][m][n], 0, 0, 0); __builtin_amdgcn_s_setprio(0); } while (0)
; #define PG8_WAIT_V(n) asm volatile("s_waitcnt vmcnt(" #n ")" ::: "memory")
; #define PG8_WAIT_L(n) asm volatile("s_waitcnt lgkmcnt(" #n ")" ::: "memory")
; #define PG8_BAR __builtin_amdgcn_s_barrier()
; #define PG8_SCHED __builtin_amdgcn_sched_barrier(0)
; template <class Epi, class Sched>
; __device__ __forceinline__ void gemm_phase(LAS unsigned char* lds, const Gemm g, const Sched& S, const Epi& E) {
;     ...
;             PG8_LDB(B0, 0, 0); PG8_SCHED; PG8_LDA(At, 0, 0); PG8_STAGE(PG8_SA(1, 1), a1 + hstepA, voffA);
;             PG8_WAIT_L(8); PG8_BAR; PG8_WAIT_L(0); PG8_MMA(0, 0, At, B0); PG8_BAR; PG8_SCHED;
;             PG8_LDB(B1, 0, 1); PG8_STAGE(PG8_SB(0, 0), b2, voffB);
;             PG8_BAR; PG8_WAIT_L(0); PG8_MMA(0, 1, At, B1); PG8_BAR;
;             PG8_LDA(At, 0, 1); PG8_STAGE(PG8_SA(0, 0), a2, voffA);
;             PG8_BAR; PG8_WAIT_L(0); PG8_MMA(1, 0, At, B0); PG8_BAR; PG8_SCHED;
;             PG8_STAGE(PG8_SB(0, 1), b2 + hstepB, voffB);
;             PG8_WAIT_V(6); PG8_BAR; PG8_MMA(1, 1, At, B1); PG8_BAR;
.LBB0_1665:
	s_add_u32 s42, s14, 0x100
	s_addc_u32 s43, s15, 0
	s_mov_b32 s44, -2
	s_setprio 0
	s_add_u32 s14, s6, 0x100
	s_addc_u32 s15, s7, 0
	s_add_i32 s45, 0, 0x10000
	v_add_u32_e32 v144, s45, v1
	ds_read_b128 v[132:135], v144
	ds_read_b128 v[136:139], v144 offset:1024
	ds_read_b128 v[140:143], v144 offset:2048
	ds_read_b128 v[144:147], v144 offset:3072
	s_cmpk_eq_i32 s44, 0x54
	s_cselect_b32 s21, s1, s15
	s_cselect_b32 s20, s0, s14
	s_cselect_b32 s19, s5, s43
	s_cselect_b32 s18, s4, s42
	ds_read_b128 v[148:151], v224
	ds_read_b128 v[152:155], v224 offset:1024
	ds_read_b128 v[156:159], v224 offset:2048
	ds_read_b128 v[160:163], v224 offset:3072
	ds_read_b128 v[164:167], v224 offset:4096
	ds_read_b128 v[168:171], v224 offset:5120
	ds_read_b128 v[172:175], v224 offset:6144
	ds_read_b128 v[176:179], v224 offset:7168
	s_add_i32 s51, 0, 0x14000
	v_add_u32_e32 v202, s51, v1
	ds_read_b128 v[180:183], v202
	ds_read_b128 v[184:187], v202 offset:1024
	ds_read_b128 v[188:191], v202 offset:2048
	ds_read_b128 v[202:205], v202 offset:3072
	s_add_i32 m0, s29, 0xc000
	s_nop 0
	global_load_lds_dwordx4 v198, s[6:7]
	s_add_i32 m0, s29, 0xe000
	s_nop 0
	global_load_lds_dwordx4 v200, s[6:7]
	s_waitcnt lgkmcnt(0)
	s_waitcnt vmcnt(8)
	s_setprio 1
	s_barrier
	v_mfma_f32_16x16x32_bf16 v[128:131], v[132:135], v[148:151], 0
	v_mfma_f32_16x16x32_bf16 v[124:127], v[140:143], v[148:151], 0
	v_mfma_f32_16x16x32_bf16 v[112:115], v[132:135], v[156:159], 0
	v_mfma_f32_16x16x32_bf16 v[108:111], v[140:143], v[156:159], 0
	v_mfma_f32_16x16x32_bf16 v[100:103], v[132:135], v[164:167], 0
	v_mfma_f32_16x16x32_bf16 v[92:95], v[140:143], v[164:167], 0
	v_mfma_f32_16x16x32_bf16 v[84:87], v[132:135], v[172:175], 0
	v_mfma_f32_16x16x32_bf16 v[76:79], v[140:143], v[172:175], 0
	v_mfma_f32_16x16x32_bf16 v[128:131], v[136:139], v[152:155], v[128:131]
	v_mfma_f32_16x16x32_bf16 v[124:127], v[144:147], v[152:155], v[124:127]
	v_mfma_f32_16x16x32_bf16 v[112:115], v[136:139], v[160:163], v[112:115]
	v_mfma_f32_16x16x32_bf16 v[108:111], v[144:147], v[160:163], v[108:111]
	v_mfma_f32_16x16x32_bf16 v[100:103], v[136:139], v[168:171], v[100:103]
	v_mfma_f32_16x16x32_bf16 v[92:95], v[144:147], v[168:171], v[92:95]
	v_mfma_f32_16x16x32_bf16 v[84:87], v[136:139], v[176:179], v[84:87]
	v_mfma_f32_16x16x32_bf16 v[76:79], v[144:147], v[176:179], v[76:79]
	v_mfma_f32_16x16x32_bf16 v[120:123], v[180:183], v[148:151], 0
	v_mfma_f32_16x16x32_bf16 v[116:119], v[188:191], v[148:151], 0
	v_mfma_f32_16x16x32_bf16 v[104:107], v[180:183], v[156:159], 0
	v_mfma_f32_16x16x32_bf16 v[96:99], v[188:191], v[156:159], 0
	v_mfma_f32_16x16x32_bf16 v[88:91], v[180:183], v[164:167], 0
	v_mfma_f32_16x16x32_bf16 v[80:83], v[188:191], v[164:167], 0
	v_mfma_f32_16x16x32_bf16 v[72:75], v[180:183], v[172:175], 0
	v_mfma_f32_16x16x32_bf16 v[68:71], v[188:191], v[172:175], 0
	v_mfma_f32_16x16x32_bf16 v[120:123], v[184:187], v[152:155], v[120:123]
	v_mfma_f32_16x16x32_bf16 v[116:119], v[202:205], v[152:155], v[116:119]
	v_mfma_f32_16x16x32_bf16 v[104:107], v[184:187], v[160:163], v[104:107]
	v_mfma_f32_16x16x32_bf16 v[96:99], v[202:205], v[160:163], v[96:99]
	v_mfma_f32_16x16x32_bf16 v[88:91], v[184:187], v[168:171], v[88:91]
	v_mfma_f32_16x16x32_bf16 v[80:83], v[202:205], v[168:171], v[80:83]
	v_mfma_f32_16x16x32_bf16 v[72:75], v[184:187], v[176:179], v[72:75]
	v_mfma_f32_16x16x32_bf16 v[68:71], v[202:205], v[176:179], v[68:71]
	s_barrier
	s_setprio 0
	ds_read_b128 v[148:151], v224 offset:16384
	ds_read_b128 v[152:155], v224 offset:17408
	ds_read_b128 v[156:159], v224 offset:18432
	ds_read_b128 v[160:163], v224 offset:19456
	ds_read_b128 v[164:167], v224 offset:20480
	ds_read_b128 v[168:171], v224 offset:21504
	ds_read_b128 v[172:175], v224 offset:22528
	ds_read_b128 v[176:179], v224 offset:23552
	s_add_i32 s6, s45, s28
	v_lshl_add_u64 v[206:207], s[18:19], 0, v[2:3]
	s_mov_b32 m0, s6
	s_nop 0
	global_load_lds_dwordx4 v[206:207], off
	v_lshl_add_u64 v[208:209], s[18:19], 0, v[192:193]
	s_add_i32 m0, s6, 0x2000
	s_nop 0
	global_load_lds_dwordx4 v[208:209], off
	s_mov_b32 m0, s29
	v_lshl_add_u64 v[210:211], s[20:21], 0, v[196:197]
	global_load_lds_dwordx4 v[210:211], off
	v_lshl_add_u64 v[212:213], s[20:21], 0, v[194:195]
	s_mov_b32 m0, s30
	s_nop 0
	global_load_lds_dwordx4 v[212:213], off
	s_add_u32 s6, s18, 0x160000
	s_addc_u32 s7, s19, 0
	s_add_i32 s45, s51, s28
	s_mov_b32 m0, s45
	s_nop 0
	global_load_lds_dwordx4 v2, s[6:7]
	s_add_i32 m0, s45, 0x2000
	s_nop 0
	global_load_lds_dwordx4 v192, s[6:7]
	s_waitcnt lgkmcnt(0)
	s_waitcnt vmcnt(8)
	s_setprio 1
	s_barrier
	v_mfma_f32_16x16x32_bf16 v[64:67], v[132:135], v[148:151], 0
	v_mfma_f32_16x16x32_bf16 v[60:63], v[140:143], v[148:151], 0
	v_mfma_f32_16x16x32_bf16 v[52:55], v[132:135], v[156:159], 0
	v_mfma_f32_16x16x32_bf16 v[44:47], v[140:143], v[156:159], 0
	v_mfma_f32_16x16x32_bf16 v[36:39], v[132:135], v[164:167], 0
	v_mfma_f32_16x16x32_bf16 v[28:31], v[140:143], v[164:167], 0
	v_mfma_f32_16x16x32_bf16 v[20:23], v[132:135], v[172:175], 0
	v_mfma_f32_16x16x32_bf16 v[12:15], v[140:143], v[172:175], 0
	v_mfma_f32_16x16x32_bf16 v[64:67], v[136:139], v[152:155], v[64:67]
	v_mfma_f32_16x16x32_bf16 v[60:63], v[144:147], v[152:155], v[60:63]
	v_mfma_f32_16x16x32_bf16 v[52:55], v[136:139], v[160:163], v[52:55]
	v_mfma_f32_16x16x32_bf16 v[44:47], v[144:147], v[160:163], v[44:47]
	v_mfma_f32_16x16x32_bf16 v[36:39], v[136:139], v[168:171], v[36:39]
	v_mfma_f32_16x16x32_bf16 v[28:31], v[144:147], v[168:171], v[28:31]
	v_mfma_f32_16x16x32_bf16 v[20:23], v[136:139], v[176:179], v[20:23]
	v_mfma_f32_16x16x32_bf16 v[12:15], v[144:147], v[176:179], v[12:15]
	v_mfma_f32_16x16x32_bf16 v[56:59], v[180:183], v[148:151], 0
	v_mfma_f32_16x16x32_bf16 v[48:51], v[188:191], v[148:151], 0
	v_mfma_f32_16x16x32_bf16 v[40:43], v[180:183], v[156:159], 0
	v_mfma_f32_16x16x32_bf16 v[32:35], v[188:191], v[156:159], 0
	v_mfma_f32_16x16x32_bf16 v[24:27], v[180:183], v[164:167], 0
	v_mfma_f32_16x16x32_bf16 v[16:19], v[188:191], v[164:167], 0
	v_mfma_f32_16x16x32_bf16 v[8:11], v[180:183], v[172:175], 0
	v_mfma_f32_16x16x32_bf16 v[4:7], v[188:191], v[172:175], 0
	v_mfma_f32_16x16x32_bf16 v[56:59], v[184:187], v[152:155], v[56:59]
	v_mfma_f32_16x16x32_bf16 v[48:51], v[202:205], v[152:155], v[48:51]
	v_mfma_f32_16x16x32_bf16 v[40:43], v[184:187], v[160:163], v[40:43]
	v_mfma_f32_16x16x32_bf16 v[32:35], v[202:205], v[160:163], v[32:35]
	v_mfma_f32_16x16x32_bf16 v[24:27], v[184:187], v[168:171], v[24:27]
	v_mfma_f32_16x16x32_bf16 v[16:19], v[202:205], v[168:171], v[16:19]
	v_mfma_f32_16x16x32_bf16 v[8:11], v[184:187], v[176:179], v[8:11]
	v_mfma_f32_16x16x32_bf16 v[4:7], v[202:205], v[176:179], v[4:7]
	s_barrier
; #define PG8_STAGE(bufoff, gbase, voff) do { _Pragma("unroll") for (int _i = 0; _i < 2; ++_i) \
;         __builtin_amdgcn_global_load_lds((const unsigned*)((const char*)(gbase) + (voff)[_i]), (LAS unsigned*)(lds + (bufoff) + ldsw + _i * 8192), 16, 0, 0); } while (0)
; #define PG8_LDA(dst, b, h) do { _Pragma("unroll") for (int m = 0; m < 4; ++m) _Pragma("unroll") for (int k = 0; k < 2; ++k) dst[m][k] = *(const LAS bf16x8*)(lds + PG8_SA(b, h) + aoff + m * 2048 + k * 1024); } while (0)
; #define PG8_LDB(dst, b, h) do { _Pragma("unroll") for (int n = 0; n < 2; ++n) _Pragma("unroll") for (int k = 0; k < 2; ++k) dst[n][k] = *(const LAS bf16x8*)(lds + PG8_SB(b, h) + boff + n * 2048 + k * 1024); } while (0)
; #define PG8_MMA(ai, bj, At, Bt) do { __builtin_amdgcn_s_setprio(1); _Pragma("unroll") for (int m = 0; m < 4; ++m) _Pragma("unroll") for (int n = 0; n < 2; ++n) _Pragma("unroll") for (int k = 0; k < 2; ++k) \
;         acc[ai][bj][m][n] = __builtin_amdgcn_mfma_f32_16x16x32_bf16(Bt[n][k], At[m][k], acc[ai][bj][m][n], 0, 0, 0); __builtin_amdgcn_s_setprio(0); } while (0)
; #define PG8_WAIT_V(n) asm volatile("s_waitcnt vmcnt(" #n ")" ::: "memory")
; #define PG8_WAIT_L(n) asm volatile("s_waitcnt lgkmcnt(" #n ")" ::: "memory")
; #define PG8_BAR __builtin_amdgcn_s_barrier()
; #define PG8_SCHED __builtin_amdgcn_sched_barrier(0)
; template <class Epi, class Sched>
; __device__ __forceinline__ void gemm_phase(LAS unsigned char* lds, const Gemm g, const Sched& S, const Epi& E) {
;     ...
;             PG8_LDB(B0, 1, 0); PG8_SCHED; PG8_LDA(At, 1, 0); PG8_STAGE(PG8_SA(0, 1), a2 + hstepA, voffA);
;             PG8_WAIT_L(8); PG8_BAR; PG8_WAIT_L(0); PG8_MMA(0, 0, At, B0); PG8_BAR; PG8_SCHED;
;             PG8_LDB(B1, 1, 1); PG8_STAGE(PG8_SB(1, 0), b3, voffB);
;             PG8_BAR; PG8_WAIT_L(0); PG8_MMA(0, 1, At, B1); PG8_BAR;
;             PG8_LDA(At, 1, 1); PG8_STAGE(PG8_SA(1, 0), a3, voffA);
;             PG8_BAR; PG8_WAIT_L(0); PG8_MMA(1, 0, At, B0); PG8_BAR; PG8_SCHED;
;             PG8_STAGE(PG8_SB(1, 1), b3 + hstepB, voffB);
;             PG8_WAIT_V(6); PG8_BAR; PG8_MMA(1, 1, At, B1); PG8_BAR;
	s_setprio 0
	s_add_i32 s45, 0, 0x18000
	v_add_u32_e32 v144, s45, v1
	ds_read_b128 v[132:135], v144
	ds_read_b128 v[136:139], v144 offset:1024
	ds_read_b128 v[140:143], v144 offset:2048
	ds_read_b128 v[144:147], v144 offset:3072
	s_add_u32 s6, s20, 0x160000
	s_addc_u32 s7, s21, 0
	ds_read_b128 v[148:151], v224 offset:32768
	ds_read_b128 v[152:155], v224 offset:33792
	ds_read_b128 v[156:159], v224 offset:34816
	ds_read_b128 v[160:163], v224 offset:35840
	ds_read_b128 v[164:167], v224 offset:36864
	ds_read_b128 v[168:171], v224 offset:37888
	ds_read_b128 v[172:175], v224 offset:38912
	ds_read_b128 v[176:179], v224 offset:39936
	s_mov_b32 m0, s31
	s_nop 0
	global_load_lds_dwordx4 v196, s[6:7]
	s_mov_b32 m0, s35
	s_nop 0
	global_load_lds_dwordx4 v194, s[6:7]
	s_add_i32 s20, 0, 0x1c000
	v_add_u32_e32 v202, s20, v1
	ds_read_b128 v[180:183], v202
	ds_read_b128 v[184:187], v202 offset:1024
	ds_read_b128 v[188:191], v202 offset:2048
	ds_read_b128 v[202:205], v202 offset:3072
	s_waitcnt lgkmcnt(0)
	s_waitcnt vmcnt(8)
	s_setprio 1
	s_barrier
	v_mfma_f32_16x16x32_bf16 v[128:131], v[132:135], v[148:151], v[128:131]
	v_mfma_f32_16x16x32_bf16 v[124:127], v[140:143], v[148:151], v[124:127]
	v_mfma_f32_16x16x32_bf16 v[112:115], v[132:135], v[156:159], v[112:115]
	v_mfma_f32_16x16x32_bf16 v[108:111], v[140:143], v[156:159], v[108:111]
	v_mfma_f32_16x16x32_bf16 v[100:103], v[132:135], v[164:167], v[100:103]
	v_mfma_f32_16x16x32_bf16 v[92:95], v[140:143], v[164:167], v[92:95]
	v_mfma_f32_16x16x32_bf16 v[84:87], v[132:135], v[172:175], v[84:87]
	v_mfma_f32_16x16x32_bf16 v[76:79], v[140:143], v[172:175], v[76:79]
	v_mfma_f32_16x16x32_bf16 v[128:131], v[136:139], v[152:155], v[128:131]
	v_mfma_f32_16x16x32_bf16 v[124:127], v[144:147], v[152:155], v[124:127]
	v_mfma_f32_16x16x32_bf16 v[112:115], v[136:139], v[160:163], v[112:115]
	v_mfma_f32_16x16x32_bf16 v[108:111], v[144:147], v[160:163], v[108:111]
	v_mfma_f32_16x16x32_bf16 v[100:103], v[136:139], v[168:171], v[100:103]
	v_mfma_f32_16x16x32_bf16 v[92:95], v[144:147], v[168:171], v[92:95]
	v_mfma_f32_16x16x32_bf16 v[84:87], v[136:139], v[176:179], v[84:87]
	v_mfma_f32_16x16x32_bf16 v[76:79], v[144:147], v[176:179], v[76:79]
	v_mfma_f32_16x16x32_bf16 v[120:123], v[180:183], v[148:151], v[120:123]
	v_mfma_f32_16x16x32_bf16 v[116:119], v[188:191], v[148:151], v[116:119]
	v_mfma_f32_16x16x32_bf16 v[104:107], v[180:183], v[156:159], v[104:107]
	v_mfma_f32_16x16x32_bf16 v[96:99], v[188:191], v[156:159], v[96:99]
	v_mfma_f32_16x16x32_bf16 v[88:91], v[180:183], v[164:167], v[88:91]
	v_mfma_f32_16x16x32_bf16 v[80:83], v[188:191], v[164:167], v[80:83]
	v_mfma_f32_16x16x32_bf16 v[72:75], v[180:183], v[172:175], v[72:75]
	v_mfma_f32_16x16x32_bf16 v[68:71], v[188:191], v[172:175], v[68:71]
	v_mfma_f32_16x16x32_bf16 v[120:123], v[184:187], v[152:155], v[120:123]
	v_mfma_f32_16x16x32_bf16 v[116:119], v[202:205], v[152:155], v[116:119]
	v_mfma_f32_16x16x32_bf16 v[104:107], v[184:187], v[160:163], v[104:107]
	v_mfma_f32_16x16x32_bf16 v[96:99], v[202:205], v[160:163], v[96:99]
	v_mfma_f32_16x16x32_bf16 v[88:91], v[184:187], v[168:171], v[88:91]
	v_mfma_f32_16x16x32_bf16 v[80:83], v[202:205], v[168:171], v[80:83]
	v_mfma_f32_16x16x32_bf16 v[72:75], v[184:187], v[176:179], v[72:75]
	v_mfma_f32_16x16x32_bf16 v[68:71], v[202:205], v[176:179], v[68:71]
	s_barrier
	s_setprio 0
	ds_read_b128 v[148:151], v224 offset:49152
	ds_read_b128 v[152:155], v224 offset:50176
	ds_read_b128 v[156:159], v224 offset:51200
	ds_read_b128 v[160:163], v224 offset:52224
	ds_read_b128 v[164:167], v224 offset:53248
	ds_read_b128 v[168:171], v224 offset:54272
	ds_read_b128 v[172:175], v224 offset:55296
	ds_read_b128 v[176:179], v224 offset:56320
	s_add_i32 s6, s45, s28
	v_lshl_add_u64 v[206:207], v[206:207], 0, s[8:9]
	s_mov_b32 m0, s6
	s_nop 0
	global_load_lds_dwordx4 v[206:207], off
	v_lshl_add_u64 v[206:207], v[208:209], 0, s[8:9]
	s_add_i32 m0, s6, 0x2000
	s_nop 0
	global_load_lds_dwordx4 v[206:207], off
	s_mov_b32 m0, s38
	v_lshl_add_u64 v[206:207], v[210:211], 0, s[8:9]
	global_load_lds_dwordx4 v[206:207], off
	v_lshl_add_u64 v[206:207], v[212:213], 0, s[8:9]
	s_mov_b32 m0, s39
	s_nop 0
	global_load_lds_dwordx4 v[206:207], off
	s_add_u32 s6, s18, 0x160080
	s_addc_u32 s7, s19, 0
	s_add_i32 s18, s20, s28
	s_mov_b32 m0, s18
	s_nop 0
	global_load_lds_dwordx4 v2, s[6:7]
	s_add_i32 m0, s18, 0x2000
	s_nop 0
	global_load_lds_dwordx4 v192, s[6:7]
	s_add_i32 s44, s44, 2
	s_add_u32 s42, s42, 0x100
	s_addc_u32 s43, s43, 0
	s_cmpk_gt_u32 s44, 0x55
	s_mov_b64 s[6:7], s[14:15]
	s_waitcnt lgkmcnt(0)
	s_waitcnt vmcnt(8)
	s_setprio 1
	s_barrier
	v_mfma_f32_16x16x32_bf16 v[64:67], v[132:135], v[148:151], v[64:67]
	v_mfma_f32_16x16x32_bf16 v[60:63], v[140:143], v[148:151], v[60:63]
	v_mfma_f32_16x16x32_bf16 v[52:55], v[132:135], v[156:159], v[52:55]
	v_mfma_f32_16x16x32_bf16 v[44:47], v[140:143], v[156:159], v[44:47]
	v_mfma_f32_16x16x32_bf16 v[36:39], v[132:135], v[164:167], v[36:39]
	v_mfma_f32_16x16x32_bf16 v[28:31], v[140:143], v[164:167], v[28:31]
	v_mfma_f32_16x16x32_bf16 v[20:23], v[132:135], v[172:175], v[20:23]
	v_mfma_f32_16x16x32_bf16 v[12:15], v[140:143], v[172:175], v[12:15]
	v_mfma_f32_16x16x32_bf16 v[64:67], v[136:139], v[152:155], v[64:67]
	v_mfma_f32_16x16x32_bf16 v[60:63], v[144:147], v[152:155], v[60:63]
	v_mfma_f32_16x16x32_bf16 v[52:55], v[136:139], v[160:163], v[52:55]
	v_mfma_f32_16x16x32_bf16 v[44:47], v[144:147], v[160:163], v[44:47]
	v_mfma_f32_16x16x32_bf16 v[36:39], v[136:139], v[168:171], v[36:39]
	v_mfma_f32_16x16x32_bf16 v[28:31], v[144:147], v[168:171], v[28:31]
	v_mfma_f32_16x16x32_bf16 v[20:23], v[136:139], v[176:179], v[20:23]
	v_mfma_f32_16x16x32_bf16 v[12:15], v[144:147], v[176:179], v[12:15]
	v_mfma_f32_16x16x32_bf16 v[56:59], v[180:183], v[148:151], v[56:59]
	v_mfma_f32_16x16x32_bf16 v[48:51], v[188:191], v[148:151], v[48:51]
	v_mfma_f32_16x16x32_bf16 v[40:43], v[180:183], v[156:159], v[40:43]
	v_mfma_f32_16x16x32_bf16 v[32:35], v[188:191], v[156:159], v[32:35]
	v_mfma_f32_16x16x32_bf16 v[24:27], v[180:183], v[164:167], v[24:27]
	v_mfma_f32_16x16x32_bf16 v[16:19], v[188:191], v[164:167], v[16:19]
	v_mfma_f32_16x16x32_bf16 v[8:11], v[180:183], v[172:175], v[8:11]
	v_mfma_f32_16x16x32_bf16 v[4:7], v[188:191], v[172:175], v[4:7]
	v_mfma_f32_16x16x32_bf16 v[56:59], v[184:187], v[152:155], v[56:59]
	v_mfma_f32_16x16x32_bf16 v[48:51], v[202:205], v[152:155], v[48:51]
	v_mfma_f32_16x16x32_bf16 v[40:43], v[184:187], v[160:163], v[40:43]
	v_mfma_f32_16x16x32_bf16 v[32:35], v[202:205], v[160:163], v[32:35]
	v_mfma_f32_16x16x32_bf16 v[24:27], v[184:187], v[168:171], v[24:27]
	v_mfma_f32_16x16x32_bf16 v[16:19], v[202:205], v[168:171], v[16:19]
	v_mfma_f32_16x16x32_bf16 v[8:11], v[184:187], v[176:179], v[8:11]
	v_mfma_f32_16x16x32_bf16 v[4:7], v[202:205], v[176:179], v[4:7]
	s_barrier
	s_setprio 0
; #define PG8_STAGE(bufoff, gbase, voff) do { _Pragma("unroll") for (int _i = 0; _i < 2; ++_i) \
;         __builtin_amdgcn_global_load_lds((const unsigned*)((const char*)(gbase) + (voff)[_i]), (LAS unsigned*)(lds + (bufoff) + ldsw + _i * 8192), 16, 0, 0); } while (0)
; #define PG8_LDA(dst, b, h) do { _Pragma("unroll") for (int m = 0; m < 4; ++m) _Pragma("unroll") for (int k = 0; k < 2; ++k) dst[m][k] = *(const LAS bf16x8*)(lds + PG8_SA(b, h) + aoff + m * 2048 + k * 1024); } while (0)
; #define PG8_LDB(dst, b, h) do { _Pragma("unroll") for (int n = 0; n < 2; ++n) _Pragma("unroll") for (int k = 0; k < 2; ++k) dst[n][k] = *(const LAS bf16x8*)(lds + PG8_SB(b, h) + boff + n * 2048 + k * 1024); } while (0)
; #define PG8_MMA(ai, bj, At, Bt) do { __builtin_amdgcn_s_setprio(1); _Pragma("unroll") for (int m = 0; m < 4; ++m) _Pragma("unroll") for (int n = 0; n < 2; ++n) _Pragma("unroll") for (int k = 0; k < 2; ++k) \
;         acc[ai][bj][m][n] = __builtin_amdgcn_mfma_f32_16x16x32_bf16(Bt[n][k], At[m][k], acc[ai][bj][m][n], 0, 0, 0); __builtin_amdgcn_s_setprio(0); } while (0)
; #define PG8_WAIT_V(n) asm volatile("s_waitcnt vmcnt(" #n ")" ::: "memory")
; #define PG8_WAIT_L(n) asm volatile("s_waitcnt lgkmcnt(" #n ")" ::: "memory")
; #define PG8_BAR __builtin_amdgcn_s_barrier()
; #define PG8_SCHED __builtin_amdgcn_sched_barrier(0)
; template <class Epi, class Sched>
; __device__ __forceinline__ void gemm_phase(LAS unsigned char* lds, const Gemm g, const Sched& S, const Epi& E) {
;     ...
;             PG8_LDB(B0, 0, 0); PG8_SCHED; PG8_LDA(At, 0, 0); PG8_STAGE(PG8_SA(1, 1), a1 + hstepA, voffA);
;             PG8_WAIT_L(8); PG8_BAR; PG8_WAIT_L(0); PG8_MMA(0, 0, At, B0); PG8_BAR; PG8_SCHED;
;             PG8_LDB(B1, 0, 1); PG8_STAGE(PG8_SB(0, 0), b2, voffB);
;             PG8_BAR; PG8_WAIT_L(0); PG8_MMA(0, 1, At, B1); PG8_BAR;
;             PG8_LDA(At, 0, 1); PG8_STAGE(PG8_SA(0, 0), a2, voffA);
;             PG8_BAR; PG8_WAIT_L(0); PG8_MMA(1, 0, At, B0); PG8_BAR; PG8_SCHED;
;             PG8_STAGE(PG8_SB(0, 1), b2 + hstepB, voffB);
;             PG8_WAIT_V(6); PG8_BAR; PG8_MMA(1, 1, At, B1); PG8_BAR;
.LBB0_1666:
	s_setprio 0
	s_add_u32 s14, s6, 0x100
	s_addc_u32 s15, s7, 0
	s_add_i32 s45, 0, 0x10000
	v_add_u32_e32 v144, s45, v1
	ds_read_b128 v[132:135], v144
	ds_read_b128 v[136:139], v144 offset:1024
	ds_read_b128 v[140:143], v144 offset:2048
	ds_read_b128 v[144:147], v144 offset:3072
	s_cmpk_eq_i32 s44, 0x54
	s_cselect_b32 s21, s1, s15
	s_cselect_b32 s20, s0, s14
	s_cselect_b32 s19, s5, s43
	s_cselect_b32 s18, s4, s42
	ds_read_b128 v[148:151], v224
	ds_read_b128 v[152:155], v224 offset:1024
	ds_read_b128 v[156:159], v224 offset:2048
	ds_read_b128 v[160:163], v224 offset:3072
	ds_read_b128 v[164:167], v224 offset:4096
	ds_read_b128 v[168:171], v224 offset:5120
	ds_read_b128 v[172:175], v224 offset:6144
	ds_read_b128 v[176:179], v224 offset:7168
	s_add_i32 s51, 0, 0x14000
	v_add_u32_e32 v202, s51, v1
	ds_read_b128 v[180:183], v202
	ds_read_b128 v[184:187], v202 offset:1024
	ds_read_b128 v[188:191], v202 offset:2048
	ds_read_b128 v[202:205], v202 offset:3072
	s_add_i32 m0, s29, 0xc000
	s_nop 0
	global_load_lds_dwordx4 v198, s[6:7]
	s_add_i32 m0, s29, 0xe000
	s_nop 0
	global_load_lds_dwordx4 v200, s[6:7]
	s_waitcnt lgkmcnt(0)
	s_waitcnt vmcnt(8)
	s_setprio 1
	s_barrier
	v_mfma_f32_16x16x32_bf16 v[128:131], v[132:135], v[148:151], v[128:131]
	v_mfma_f32_16x16x32_bf16 v[124:127], v[140:143], v[148:151], v[124:127]
	v_mfma_f32_16x16x32_bf16 v[112:115], v[132:135], v[156:159], v[112:115]
	v_mfma_f32_16x16x32_bf16 v[108:111], v[140:143], v[156:159], v[108:111]
	v_mfma_f32_16x16x32_bf16 v[100:103], v[132:135], v[164:167], v[100:103]
	v_mfma_f32_16x16x32_bf16 v[92:95], v[140:143], v[164:167], v[92:95]
	v_mfma_f32_16x16x32_bf16 v[84:87], v[132:135], v[172:175], v[84:87]
	v_mfma_f32_16x16x32_bf16 v[76:79], v[140:143], v[172:175], v[76:79]
	v_mfma_f32_16x16x32_bf16 v[128:131], v[136:139], v[152:155], v[128:131]
	v_mfma_f32_16x16x32_bf16 v[124:127], v[144:147], v[152:155], v[124:127]
	v_mfma_f32_16x16x32_bf16 v[112:115], v[136:139], v[160:163], v[112:115]
	v_mfma_f32_16x16x32_bf16 v[108:111], v[144:147], v[160:163], v[108:111]
	v_mfma_f32_16x16x32_bf16 v[100:103], v[136:139], v[168:171], v[100:103]
	v_mfma_f32_16x16x32_bf16 v[92:95], v[144:147], v[168:171], v[92:95]
	v_mfma_f32_16x16x32_bf16 v[84:87], v[136:139], v[176:179], v[84:87]
	v_mfma_f32_16x16x32_bf16 v[76:79], v[144:147], v[176:179], v[76:79]
	v_mfma_f32_16x16x32_bf16 v[120:123], v[180:183], v[148:151], v[120:123]
	v_mfma_f32_16x16x32_bf16 v[116:119], v[188:191], v[148:151], v[116:119]
	v_mfma_f32_16x16x32_bf16 v[104:107], v[180:183], v[156:159], v[104:107]
	v_mfma_f32_16x16x32_bf16 v[96:99], v[188:191], v[156:159], v[96:99]
	v_mfma_f32_16x16x32_bf16 v[88:91], v[180:183], v[164:167], v[88:91]
	v_mfma_f32_16x16x32_bf16 v[80:83], v[188:191], v[164:167], v[80:83]
	v_mfma_f32_16x16x32_bf16 v[72:75], v[180:183], v[172:175], v[72:75]
	v_mfma_f32_16x16x32_bf16 v[68:71], v[188:191], v[172:175], v[68:71]
	v_mfma_f32_16x16x32_bf16 v[120:123], v[184:187], v[152:155], v[120:123]
	v_mfma_f32_16x16x32_bf16 v[116:119], v[202:205], v[152:155], v[116:119]
	v_mfma_f32_16x16x32_bf16 v[104:107], v[184:187], v[160:163], v[104:107]
	v_mfma_f32_16x16x32_bf16 v[96:99], v[202:205], v[160:163], v[96:99]
	v_mfma_f32_16x16x32_bf16 v[88:91], v[184:187], v[168:171], v[88:91]
	v_mfma_f32_16x16x32_bf16 v[80:83], v[202:205], v[168:171], v[80:83]
	v_mfma_f32_16x16x32_bf16 v[72:75], v[184:187], v[176:179], v[72:75]
	v_mfma_f32_16x16x32_bf16 v[68:71], v[202:205], v[176:179], v[68:71]
	s_barrier
	s_setprio 0
	ds_read_b128 v[148:151], v224 offset:16384
	ds_read_b128 v[152:155], v224 offset:17408
	ds_read_b128 v[156:159], v224 offset:18432
	ds_read_b128 v[160:163], v224 offset:19456
	ds_read_b128 v[164:167], v224 offset:20480
	ds_read_b128 v[168:171], v224 offset:21504
	ds_read_b128 v[172:175], v224 offset:22528
	ds_read_b128 v[176:179], v224 offset:23552
	s_add_i32 s6, s45, s28
	v_lshl_add_u64 v[206:207], s[18:19], 0, v[2:3]
	s_mov_b32 m0, s6
	s_nop 0
	global_load_lds_dwordx4 v[206:207], off
	v_lshl_add_u64 v[208:209], s[18:19], 0, v[192:193]
	s_add_i32 m0, s6, 0x2000
	s_nop 0
	global_load_lds_dwordx4 v[208:209], off
	s_mov_b32 m0, s29
	v_lshl_add_u64 v[210:211], s[20:21], 0, v[196:197]
	global_load_lds_dwordx4 v[210:211], off
	v_lshl_add_u64 v[212:213], s[20:21], 0, v[194:195]
	s_mov_b32 m0, s30
	s_nop 0
	global_load_lds_dwordx4 v[212:213], off
	s_add_u32 s6, s18, 0x160000
	s_addc_u32 s7, s19, 0
	s_add_i32 s45, s51, s28
	s_mov_b32 m0, s45
	s_nop 0
	global_load_lds_dwordx4 v2, s[6:7]
	s_add_i32 m0, s45, 0x2000
	s_nop 0
	global_load_lds_dwordx4 v192, s[6:7]
	s_waitcnt lgkmcnt(0)
	s_waitcnt vmcnt(8)
	s_setprio 1
	s_barrier
; #define PG8_STAGE(bufoff, gbase, voff) do { _Pragma("unroll") for (int _i = 0; _i < 2; ++_i) \
;         __builtin_amdgcn_global_load_lds((const unsigned*)((const char*)(gbase) + (voff)[_i]), (LAS unsigned*)(lds + (bufoff) + ldsw + _i * 8192), 16, 0, 0); } while (0)
; #define PG8_LDA(dst, b, h) do { _Pragma("unroll") for (int m = 0; m < 4; ++m) _Pragma("unroll") for (int k = 0; k < 2; ++k) dst[m][k] = *(const LAS bf16x8*)(lds + PG8_SA(b, h) + aoff + m * 2048 + k * 1024); } while (0)
; #define PG8_LDB(dst, b, h) do { _Pragma("unroll") for (int n = 0; n < 2; ++n) _Pragma("unroll") for (int k = 0; k < 2; ++k) dst[n][k] = *(const LAS bf16x8*)(lds + PG8_SB(b, h) + boff + n * 2048 + k * 1024); } while (0)
; #define PG8_MMA(ai, bj, At, Bt) do { __builtin_amdgcn_s_setprio(1); _Pragma("unroll") for (int m = 0; m < 4; ++m) _Pragma("unroll") for (int n = 0; n < 2; ++n) _Pragma("unroll") for (int k = 0; k < 2; ++k) \
;         acc[ai][bj][m][n] = __builtin_amdgcn_mfma_f32_16x16x32_bf16(Bt[n][k], At[m][k], acc[ai][bj][m][n], 0, 0, 0); __builtin_amdgcn_s_setprio(0); } while (0)
; #define PG8_WAIT_V(n) asm volatile("s_waitcnt vmcnt(" #n ")" ::: "memory")
; #define PG8_WAIT_L(n) asm volatile("s_waitcnt lgkmcnt(" #n ")" ::: "memory")
; #define PG8_BAR __builtin_amdgcn_s_barrier()
; #define PG8_SCHED __builtin_amdgcn_sched_barrier(0)
; template <class Epi, class Sched>
; __device__ __forceinline__ void gemm_phase(LAS unsigned char* lds, const Gemm g, const Sched& S, const Epi& E) {
;     ...
;             PG8_WAIT_V(6); PG8_BAR; PG8_MMA(1, 1, At, B1); PG8_BAR;
;             PG8_LDB(B0, 1, 0); PG8_SCHED; PG8_LDA(At, 1, 0); PG8_STAGE(PG8_SA(0, 1), a2 + hstepA, voffA);
;             PG8_WAIT_L(8); PG8_BAR; PG8_WAIT_L(0); PG8_MMA(0, 0, At, B0); PG8_BAR; PG8_SCHED;
;             PG8_LDB(B1, 1, 1); PG8_STAGE(PG8_SB(1, 0), b3, voffB);
;             PG8_BAR; PG8_WAIT_L(0); PG8_MMA(0, 1, At, B1); PG8_BAR;
;             PG8_LDA(At, 1, 1); PG8_STAGE(PG8_SA(1, 0), a3, voffA);
;             PG8_BAR; PG8_WAIT_L(0); PG8_MMA(1, 0, At, B0); PG8_BAR; PG8_SCHED;
	v_mfma_f32_16x16x32_bf16 v[64:67], v[132:135], v[148:151], v[64:67]
	v_mfma_f32_16x16x32_bf16 v[60:63], v[140:143], v[148:151], v[60:63]
	v_mfma_f32_16x16x32_bf16 v[52:55], v[132:135], v[156:159], v[52:55]
	v_mfma_f32_16x16x32_bf16 v[44:47], v[140:143], v[156:159], v[44:47]
	v_mfma_f32_16x16x32_bf16 v[36:39], v[132:135], v[164:167], v[36:39]
	v_mfma_f32_16x16x32_bf16 v[28:31], v[140:143], v[164:167], v[28:31]
	v_mfma_f32_16x16x32_bf16 v[20:23], v[132:135], v[172:175], v[20:23]
	v_mfma_f32_16x16x32_bf16 v[12:15], v[140:143], v[172:175], v[12:15]
	v_mfma_f32_16x16x32_bf16 v[64:67], v[136:139], v[152:155], v[64:67]
	v_mfma_f32_16x16x32_bf16 v[60:63], v[144:147], v[152:155], v[60:63]
	v_mfma_f32_16x16x32_bf16 v[52:55], v[136:139], v[160:163], v[52:55]
	v_mfma_f32_16x16x32_bf16 v[44:47], v[144:147], v[160:163], v[44:47]
	v_mfma_f32_16x16x32_bf16 v[36:39], v[136:139], v[168:171], v[36:39]
	v_mfma_f32_16x16x32_bf16 v[28:31], v[144:147], v[168:171], v[28:31]
	v_mfma_f32_16x16x32_bf16 v[20:23], v[136:139], v[176:179], v[20:23]
	v_mfma_f32_16x16x32_bf16 v[12:15], v[144:147], v[176:179], v[12:15]
	v_mfma_f32_16x16x32_bf16 v[56:59], v[180:183], v[148:151], v[56:59]
	v_mfma_f32_16x16x32_bf16 v[48:51], v[188:191], v[148:151], v[48:51]
	v_mfma_f32_16x16x32_bf16 v[40:43], v[180:183], v[156:159], v[40:43]
	v_mfma_f32_16x16x32_bf16 v[32:35], v[188:191], v[156:159], v[32:35]
	v_mfma_f32_16x16x32_bf16 v[24:27], v[180:183], v[164:167], v[24:27]
	v_mfma_f32_16x16x32_bf16 v[16:19], v[188:191], v[164:167], v[16:19]
	v_mfma_f32_16x16x32_bf16 v[8:11], v[180:183], v[172:175], v[8:11]
	v_mfma_f32_16x16x32_bf16 v[4:7], v[188:191], v[172:175], v[4:7]
	v_mfma_f32_16x16x32_bf16 v[56:59], v[184:187], v[152:155], v[56:59]
	v_mfma_f32_16x16x32_bf16 v[48:51], v[202:205], v[152:155], v[48:51]
	v_mfma_f32_16x16x32_bf16 v[40:43], v[184:187], v[160:163], v[40:43]
	v_mfma_f32_16x16x32_bf16 v[32:35], v[202:205], v[160:163], v[32:35]
	v_mfma_f32_16x16x32_bf16 v[24:27], v[184:187], v[168:171], v[24:27]
	v_mfma_f32_16x16x32_bf16 v[16:19], v[202:205], v[168:171], v[16:19]
	v_mfma_f32_16x16x32_bf16 v[8:11], v[184:187], v[176:179], v[8:11]
	v_mfma_f32_16x16x32_bf16 v[4:7], v[202:205], v[176:179], v[4:7]
	s_barrier
	s_setprio 0
	s_add_i32 s45, 0, 0x18000
	v_add_u32_e32 v144, s45, v1
	ds_read_b128 v[132:135], v144
	ds_read_b128 v[136:139], v144 offset:1024
	ds_read_b128 v[140:143], v144 offset:2048
	ds_read_b128 v[144:147], v144 offset:3072
	s_add_u32 s6, s20, 0x160000
	s_addc_u32 s7, s21, 0
	ds_read_b128 v[148:151], v224 offset:32768
	ds_read_b128 v[152:155], v224 offset:33792
	ds_read_b128 v[156:159], v224 offset:34816
	ds_read_b128 v[160:163], v224 offset:35840
	ds_read_b128 v[164:167], v224 offset:36864
	ds_read_b128 v[168:171], v224 offset:37888
	ds_read_b128 v[172:175], v224 offset:38912
	ds_read_b128 v[176:179], v224 offset:39936
	s_mov_b32 m0, s31
	s_nop 0
	global_load_lds_dwordx4 v196, s[6:7]
	s_mov_b32 m0, s35
	s_nop 0
	global_load_lds_dwordx4 v194, s[6:7]
	s_add_i32 s20, 0, 0x1c000
	v_add_u32_e32 v202, s20, v1
	ds_read_b128 v[180:183], v202
	ds_read_b128 v[184:187], v202 offset:1024
	ds_read_b128 v[188:191], v202 offset:2048
	ds_read_b128 v[202:205], v202 offset:3072
	s_waitcnt lgkmcnt(0)
	s_waitcnt vmcnt(8)
	s_setprio 1
	s_barrier
	v_mfma_f32_16x16x32_bf16 v[128:131], v[132:135], v[148:151], v[128:131]
	v_mfma_f32_16x16x32_bf16 v[124:127], v[140:143], v[148:151], v[124:127]
	v_mfma_f32_16x16x32_bf16 v[112:115], v[132:135], v[156:159], v[112:115]
	v_mfma_f32_16x16x32_bf16 v[108:111], v[140:143], v[156:159], v[108:111]
	v_mfma_f32_16x16x32_bf16 v[100:103], v[132:135], v[164:167], v[100:103]
	v_mfma_f32_16x16x32_bf16 v[92:95], v[140:143], v[164:167], v[92:95]
	v_mfma_f32_16x16x32_bf16 v[84:87], v[132:135], v[172:175], v[84:87]
	v_mfma_f32_16x16x32_bf16 v[76:79], v[140:143], v[172:175], v[76:79]
	v_mfma_f32_16x16x32_bf16 v[128:131], v[136:139], v[152:155], v[128:131]
	v_mfma_f32_16x16x32_bf16 v[124:127], v[144:147], v[152:155], v[124:127]
	v_mfma_f32_16x16x32_bf16 v[112:115], v[136:139], v[160:163], v[112:115]
	v_mfma_f32_16x16x32_bf16 v[108:111], v[144:147], v[160:163], v[108:111]
	v_mfma_f32_16x16x32_bf16 v[100:103], v[136:139], v[168:171], v[100:103]
	v_mfma_f32_16x16x32_bf16 v[92:95], v[144:147], v[168:171], v[92:95]
	v_mfma_f32_16x16x32_bf16 v[84:87], v[136:139], v[176:179], v[84:87]
	v_mfma_f32_16x16x32_bf16 v[76:79], v[144:147], v[176:179], v[76:79]
	v_mfma_f32_16x16x32_bf16 v[120:123], v[180:183], v[148:151], v[120:123]
	v_mfma_f32_16x16x32_bf16 v[116:119], v[188:191], v[148:151], v[116:119]
	v_mfma_f32_16x16x32_bf16 v[104:107], v[180:183], v[156:159], v[104:107]
	v_mfma_f32_16x16x32_bf16 v[96:99], v[188:191], v[156:159], v[96:99]
	v_mfma_f32_16x16x32_bf16 v[88:91], v[180:183], v[164:167], v[88:91]
	v_mfma_f32_16x16x32_bf16 v[80:83], v[188:191], v[164:167], v[80:83]
	v_mfma_f32_16x16x32_bf16 v[72:75], v[180:183], v[172:175], v[72:75]
	v_mfma_f32_16x16x32_bf16 v[68:71], v[188:191], v[172:175], v[68:71]
	v_mfma_f32_16x16x32_bf16 v[120:123], v[184:187], v[152:155], v[120:123]
	v_mfma_f32_16x16x32_bf16 v[116:119], v[202:205], v[152:155], v[116:119]
	v_mfma_f32_16x16x32_bf16 v[104:107], v[184:187], v[160:163], v[104:107]
	v_mfma_f32_16x16x32_bf16 v[96:99], v[202:205], v[160:163], v[96:99]
	v_mfma_f32_16x16x32_bf16 v[88:91], v[184:187], v[168:171], v[88:91]
	v_mfma_f32_16x16x32_bf16 v[80:83], v[202:205], v[168:171], v[80:83]
	v_mfma_f32_16x16x32_bf16 v[72:75], v[184:187], v[176:179], v[72:75]
	v_mfma_f32_16x16x32_bf16 v[68:71], v[202:205], v[176:179], v[68:71]
	s_barrier
; __device__ __forceinline__ int opaque_tid() { int t = threadIdx.x; asm volatile("" : "+v"(t)); return t; }
; #define PG8_STAGE(bufoff, gbase, voff) do { _Pragma("unroll") for (int _i = 0; _i < 2; ++_i) \
;         __builtin_amdgcn_global_load_lds((const unsigned*)((const char*)(gbase) + (voff)[_i]), (LAS unsigned*)(lds + (bufoff) + ldsw + _i * 8192), 16, 0, 0); } while (0)
; #define PG8_LDA(dst, b, h) do { _Pragma("unroll") for (int m = 0; m < 4; ++m) _Pragma("unroll") for (int k = 0; k < 2; ++k) dst[m][k] = *(const LAS bf16x8*)(lds + PG8_SA(b, h) + aoff + m * 2048 + k * 1024); } while (0)
; #define PG8_MMA(ai, bj, At, Bt) do { __builtin_amdgcn_s_setprio(1); _Pragma("unroll") for (int m = 0; m < 4; ++m) _Pragma("unroll") for (int n = 0; n < 2; ++n) _Pragma("unroll") for (int k = 0; k < 2; ++k) \
;         acc[ai][bj][m][n] = __builtin_amdgcn_mfma_f32_16x16x32_bf16(Bt[n][k], At[m][k], acc[ai][bj][m][n], 0, 0, 0); __builtin_amdgcn_s_setprio(0); } while (0)
; #define PG8_WAIT_V(n) asm volatile("s_waitcnt vmcnt(" #n ")" ::: "memory")
; #define PG8_WAIT_L(n) asm volatile("s_waitcnt lgkmcnt(" #n ")" ::: "memory")
; #define PG8_BAR __builtin_amdgcn_s_barrier()
; #define PG8_SCHED __builtin_amdgcn_sched_barrier(0)
;     __device__ __forceinline__ void operator()(const f32x4 (&acc)[2][2][4][2], const Unit& u, int wr, int wc, int, int) const {
;         const int ol_ = opaque_tid() & 63, fr = ol_ & 15, fq = ol_ >> 4;
;         const int row0 = u.pm * BM + wr * 64 + fr, col0 = u.pn * BM + wc * 32 + 8 * fq;
;         u32x4 cin[2][4][2];
; #pragma unroll
;         for (int ai = 0; ai < 2; ++ai)
; #pragma unroll
;             for (int m = 0; m < 4; ++m)
; #pragma unroll
;                 for (int bj = 0; bj < 2; ++bj) cin[ai][m][bj] = *(const u32x4*)(C + (size_t)(row0 + ai * HALF + m * 16) * ldc + col0 + bj * HALF);
; template <class Epi, class Sched>
; __device__ __forceinline__ void gemm_phase(LAS unsigned char* lds, const Gemm g, const Sched& S, const Epi& E) {
;     ...
;             PG8_LDA(At, 1, 1); PG8_STAGE(PG8_SA(1, 0), a3, voffA);
;             PG8_BAR; PG8_WAIT_L(0); PG8_MMA(1, 0, At, B0); PG8_BAR; PG8_SCHED;
;             PG8_STAGE(PG8_SB(1, 1), b3 + hstepB, voffB);
;             PG8_WAIT_V(6); PG8_BAR; PG8_MMA(1, 1, At, B1); PG8_BAR;
;         }
	s_setprio 0
	ds_read_b128 v[148:151], v224 offset:49152
	ds_read_b128 v[152:155], v224 offset:50176
	ds_read_b128 v[156:159], v224 offset:51200
	ds_read_b128 v[160:163], v224 offset:52224
	ds_read_b128 v[164:167], v224 offset:53248
	ds_read_b128 v[168:171], v224 offset:54272
	ds_read_b128 v[172:175], v224 offset:55296
	ds_read_b128 v[176:179], v224 offset:56320
	s_add_i32 s6, s45, s28
	v_lshl_add_u64 v[206:207], v[206:207], 0, s[8:9]
	s_mov_b32 m0, s6
	s_nop 0
	global_load_lds_dwordx4 v[206:207], off
	v_lshl_add_u64 v[206:207], v[208:209], 0, s[8:9]
	s_add_i32 m0, s6, 0x2000
	s_nop 0
	global_load_lds_dwordx4 v[206:207], off
	s_mov_b32 m0, s38
	v_lshl_add_u64 v[206:207], v[210:211], 0, s[8:9]
	global_load_lds_dwordx4 v[206:207], off
	v_lshl_add_u64 v[206:207], v[212:213], 0, s[8:9]
	s_mov_b32 m0, s39
	s_nop 0
	global_load_lds_dwordx4 v[206:207], off
	s_add_u32 s6, s18, 0x160080
	s_addc_u32 s7, s19, 0
	s_add_i32 s18, s20, s28
	s_mov_b32 m0, s18
	s_nop 0
	global_load_lds_dwordx4 v2, s[6:7]
	s_add_i32 m0, s18, 0x2000
	s_nop 0
	global_load_lds_dwordx4 v192, s[6:7]
	s_add_i32 s44, s44, 2
	s_add_u32 s42, s42, 0x100
	s_addc_u32 s43, s43, 0
	s_cmpk_gt_u32 s44, 0x55
	s_mov_b64 s[6:7], s[14:15]
	s_waitcnt lgkmcnt(0)
	s_waitcnt vmcnt(8)
	s_setprio 1
	s_barrier
	v_mfma_f32_16x16x32_bf16 v[64:67], v[132:135], v[148:151], v[64:67]
	v_mfma_f32_16x16x32_bf16 v[60:63], v[140:143], v[148:151], v[60:63]
	v_mfma_f32_16x16x32_bf16 v[52:55], v[132:135], v[156:159], v[52:55]
	v_mfma_f32_16x16x32_bf16 v[44:47], v[140:143], v[156:159], v[44:47]
	v_mfma_f32_16x16x32_bf16 v[36:39], v[132:135], v[164:167], v[36:39]
	v_mfma_f32_16x16x32_bf16 v[28:31], v[140:143], v[164:167], v[28:31]
	v_mfma_f32_16x16x32_bf16 v[20:23], v[132:135], v[172:175], v[20:23]
	v_mfma_f32_16x16x32_bf16 v[12:15], v[140:143], v[172:175], v[12:15]
	v_mfma_f32_16x16x32_bf16 v[64:67], v[136:139], v[152:155], v[64:67]
	v_mfma_f32_16x16x32_bf16 v[60:63], v[144:147], v[152:155], v[60:63]
	v_mfma_f32_16x16x32_bf16 v[52:55], v[136:139], v[160:163], v[52:55]
	v_mfma_f32_16x16x32_bf16 v[44:47], v[144:147], v[160:163], v[44:47]
	v_mfma_f32_16x16x32_bf16 v[36:39], v[136:139], v[168:171], v[36:39]
	v_mfma_f32_16x16x32_bf16 v[28:31], v[144:147], v[168:171], v[28:31]
	v_mfma_f32_16x16x32_bf16 v[20:23], v[136:139], v[176:179], v[20:23]
	v_mfma_f32_16x16x32_bf16 v[12:15], v[144:147], v[176:179], v[12:15]
	v_mfma_f32_16x16x32_bf16 v[56:59], v[180:183], v[148:151], v[56:59]
	v_mfma_f32_16x16x32_bf16 v[48:51], v[188:191], v[148:151], v[48:51]
	v_mfma_f32_16x16x32_bf16 v[40:43], v[180:183], v[156:159], v[40:43]
	v_mfma_f32_16x16x32_bf16 v[32:35], v[188:191], v[156:159], v[32:35]
	v_mfma_f32_16x16x32_bf16 v[24:27], v[180:183], v[164:167], v[24:27]
	v_mfma_f32_16x16x32_bf16 v[16:19], v[188:191], v[164:167], v[16:19]
	v_mfma_f32_16x16x32_bf16 v[8:11], v[180:183], v[172:175], v[8:11]
	v_mfma_f32_16x16x32_bf16 v[4:7], v[188:191], v[172:175], v[4:7]
	v_mfma_f32_16x16x32_bf16 v[56:59], v[184:187], v[152:155], v[56:59]
	v_mfma_f32_16x16x32_bf16 v[48:51], v[202:205], v[152:155], v[48:51]
	v_mfma_f32_16x16x32_bf16 v[40:43], v[184:187], v[160:163], v[40:43]
	v_mfma_f32_16x16x32_bf16 v[32:35], v[202:205], v[160:163], v[32:35]
	v_mfma_f32_16x16x32_bf16 v[24:27], v[184:187], v[168:171], v[24:27]
	v_mfma_f32_16x16x32_bf16 v[16:19], v[202:205], v[168:171], v[16:19]
	v_mfma_f32_16x16x32_bf16 v[8:11], v[184:187], v[176:179], v[8:11]
	v_mfma_f32_16x16x32_bf16 v[4:7], v[202:205], v[176:179], v[4:7]
	s_barrier
	s_cbranch_scc0 .LBB0_1666
	s_setprio 0
	v_mov_b32_e32 v133, v0
	s_lshl_b32 s6, s50, 8
	s_add_i32 s6, s6, s36
	v_and_or_b32 v132, v133, 15, s6
	s_lshl_b32 s6, s49, 8
	v_lshrrev_b32_e32 v133, 1, v133
	v_and_or_b32 v133, v133, 24, s6
	v_or_b32_e32 v134, s37, v133
	v_ashrrev_i32_e32 v135, 31, v134
	v_lshlrev_b64 v[202:203], 1, v[134:135]
	v_ashrrev_i32_e32 v133, 31, v132
	v_lshl_add_u64 v[134:135], s[88:89], 0, v[202:203]
	v_lshlrev_b64 v[226:227], 12, v[132:133]
	v_lshl_add_u64 v[136:137], v[134:135], 0, v[226:227]
	global_load_dwordx4 v[216:219], v[136:137], off
	global_load_dwordx4 v[188:191], v[136:137], off offset:256
	v_or_b32_e32 v136, 16, v132
	v_ashrrev_i32_e32 v137, 31, v136
	v_lshlrev_b64 v[222:223], 12, v[136:137]
	v_lshl_add_u64 v[136:137], v[134:135], 0, v[222:223]
	global_load_dwordx4 v[184:187], v[136:137], off
	global_load_dwordx4 v[180:183], v[136:137], off offset:256
	v_or_b32_e32 v136, 32, v132
	v_ashrrev_i32_e32 v137, 31, v136
	v_lshlrev_b64 v[220:221], 12, v[136:137]
	v_lshl_add_u64 v[136:137], v[134:135], 0, v[220:221]
	global_load_dwordx4 v[176:179], v[136:137], off
	global_load_dwordx4 v[168:171], v[136:137], off offset:256
	v_or_b32_e32 v132, 48, v132
	v_ashrrev_i32_e32 v133, 31, v132
	v_lshlrev_b64 v[212:213], 12, v[132:133]
	v_lshl_add_u64 v[132:133], v[134:135], 0, v[212:213]
	global_load_dwordx4 v[172:175], v[132:133], off
	global_load_dwordx4 v[164:167], v[132:133], off offset:256
	s_mov_b64 s[6:7], 0x80000
	v_lshl_add_u64 v[210:211], v[226:227], 0, s[6:7]
	v_lshl_add_u64 v[132:133], v[134:135], 0, v[210:211]
	global_load_dwordx4 v[160:163], v[132:133], off
	global_load_dwordx4 v[156:159], v[132:133], off offset:256
	s_mov_b64 s[6:7], 0x90000
	v_lshl_add_u64 v[208:209], v[226:227], 0, s[6:7]
	v_lshl_add_u64 v[132:133], v[134:135], 0, v[208:209]
	global_load_dwordx4 v[152:155], v[132:133], off
	global_load_dwordx4 v[148:151], v[132:133], off offset:256
	s_mov_b64 s[6:7], 0xa0000
	v_lshl_add_u64 v[206:207], v[226:227], 0, s[6:7]
	v_lshl_add_u64 v[132:133], v[134:135], 0, v[206:207]
	global_load_dwordx4 v[144:147], v[132:133], off
	global_load_dwordx4 v[140:143], v[132:133], off offset:256
	s_mov_b64 s[6:7], 0xb0000
	v_lshl_add_u64 v[204:205], v[226:227], 0, s[6:7]
	v_lshl_add_u64 v[132:133], v[134:135], 0, v[204:205]
	global_load_dwordx4 v[136:139], v[132:133], off
	s_nop 0
	global_load_dwordx4 v[132:135], v[132:133], off offset:256
	s_and_b64 vcc, exec, s[40:41]
	s_mov_b32 s49, s47
	s_mov_b32 s50, s48
	s_mov_b64 s[14:15], s[4:5]
	s_mov_b64 s[6:7], s[0:1]
	s_waitcnt vmcnt(15)
; __device__ __forceinline__ unsigned cvt_pk_bf16(float lo, float hi) { const f32x2 v = {lo, hi}; const bf16v2_ r = __builtin_convertvector(v, bf16v2_); return __builtin_bit_cast(unsigned, r); }
; __device__ __forceinline__ float bflo(unsigned w) { return __uint_as_float(w << 16); }
; __device__ __forceinline__ float bfhi(unsigned w) { return __uint_as_float(w & 0xffff0000u); }
;     __device__ __forceinline__ void operator()(const f32x4 (&acc)[2][2][4][2], const Unit& u, int wr, int wc, int, int) const {
;     ...
;                 for (int bj = 0; bj < 2; ++bj) { const u32x4 c = cin[ai][m][bj]; const f32x4 v0 = acc[ai][bj][m][0], v1 = acc[ai][bj][m][1];
;                     u32x4 w; w.x = cvt_pk_bf16(bflo(c.x) + v0[0], bfhi(c.x) + v0[1]); w.y = cvt_pk_bf16(bflo(c.y) + v0[2], bfhi(c.y) + v0[3]);
;                     w.z = cvt_pk_bf16(bflo(c.z) + v1[0], bfhi(c.z) + v1[1]); w.w = cvt_pk_bf16(bflo(c.w) + v1[2], bfhi(c.w) + v1[3]);
;                     *(u32x4*)(C + (size_t)(row0 + ai * HALF + m * 16) * ldc + col0 + bj * HALF) = w; }
	v_lshlrev_b32_e32 v228, 16, v216
	v_and_b32_e32 v229, 0xffff0000, v216
	v_lshlrev_b32_e32 v216, 16, v217
	v_and_b32_e32 v217, 0xffff0000, v217
	v_pk_add_f32 v[128:129], v[128:129], v[228:229]
	v_pk_add_f32 v[130:131], v[130:131], v[216:217]
	v_cvt_pk_bf16_f32 v128, v128, v129
	v_cvt_pk_bf16_f32 v129, v130, v131
	v_lshlrev_b32_e32 v130, 16, v218
	v_and_b32_e32 v131, 0xffff0000, v218
	v_pk_add_f32 v[124:125], v[124:125], v[130:131]
	s_nop 0
	v_cvt_pk_bf16_f32 v130, v124, v125
	v_lshlrev_b32_e32 v124, 16, v219
	v_and_b32_e32 v125, 0xffff0000, v219
	v_pk_add_f32 v[124:125], v[126:127], v[124:125]
	s_waitcnt vmcnt(14)
	v_lshlrev_b32_e32 v126, 16, v188
	v_and_b32_e32 v127, 0xffff0000, v188
	v_pk_add_f32 v[120:121], v[120:121], v[126:127]
	v_lshlrev_b32_e32 v126, 16, v189
	v_and_b32_e32 v127, 0xffff0000, v189
	v_pk_add_f32 v[122:123], v[122:123], v[126:127]
	v_cvt_pk_bf16_f32 v120, v120, v121
	v_cvt_pk_bf16_f32 v121, v122, v123
	v_lshlrev_b32_e32 v122, 16, v190
	v_and_b32_e32 v123, 0xffff0000, v190
	v_pk_add_f32 v[116:117], v[116:117], v[122:123]
	v_cvt_pk_bf16_f32 v131, v124, v125
	v_cvt_pk_bf16_f32 v122, v116, v117
	v_lshlrev_b32_e32 v116, 16, v191
	v_and_b32_e32 v117, 0xffff0000, v191
	v_pk_add_f32 v[116:117], v[118:119], v[116:117]
	v_lshl_add_u64 v[124:125], s[88:89], 0, v[226:227]
	v_cvt_pk_bf16_f32 v123, v116, v117
	s_waitcnt vmcnt(13)
	v_lshlrev_b32_e32 v116, 16, v184
	v_and_b32_e32 v117, 0xffff0000, v184
	v_pk_add_f32 v[112:113], v[112:113], v[116:117]
	v_lshlrev_b32_e32 v116, 16, v185
	v_and_b32_e32 v117, 0xffff0000, v185
	v_pk_add_f32 v[114:115], v[114:115], v[116:117]
	v_cvt_pk_bf16_f32 v112, v112, v113
	v_cvt_pk_bf16_f32 v113, v114, v115
	v_lshlrev_b32_e32 v114, 16, v186
	v_and_b32_e32 v115, 0xffff0000, v186
	v_pk_add_f32 v[108:109], v[108:109], v[114:115]
	v_lshl_add_u64 v[124:125], v[124:125], 0, v[202:203]
	v_cvt_pk_bf16_f32 v114, v108, v109
	v_lshlrev_b32_e32 v108, 16, v187
	v_and_b32_e32 v109, 0xffff0000, v187
	v_pk_add_f32 v[108:109], v[110:111], v[108:109]
	s_waitcnt vmcnt(12)
	v_lshlrev_b32_e32 v110, 16, v180
	v_and_b32_e32 v111, 0xffff0000, v180
	v_pk_add_f32 v[104:105], v[104:105], v[110:111]
	v_lshlrev_b32_e32 v110, 16, v181
	v_and_b32_e32 v111, 0xffff0000, v181
	v_pk_add_f32 v[106:107], v[106:107], v[110:111]
	v_cvt_pk_bf16_f32 v104, v104, v105
	v_cvt_pk_bf16_f32 v105, v106, v107
	v_lshlrev_b32_e32 v106, 16, v182
	v_and_b32_e32 v107, 0xffff0000, v182
	v_pk_add_f32 v[96:97], v[96:97], v[106:107]
	v_cvt_pk_bf16_f32 v115, v108, v109
	v_cvt_pk_bf16_f32 v106, v96, v97
	v_lshlrev_b32_e32 v96, 16, v183
	v_and_b32_e32 v97, 0xffff0000, v183
	v_pk_add_f32 v[96:97], v[98:99], v[96:97]
	s_waitcnt vmcnt(11)
	v_lshlrev_b32_e32 v98, 16, v177
	v_cvt_pk_bf16_f32 v107, v96, v97
	v_lshlrev_b32_e32 v96, 16, v176
	v_and_b32_e32 v97, 0xffff0000, v176
	v_and_b32_e32 v99, 0xffff0000, v177
	v_pk_add_f32 v[96:97], v[100:101], v[96:97]
	v_pk_add_f32 v[98:99], v[102:103], v[98:99]
	v_cvt_pk_bf16_f32 v96, v96, v97
	v_cvt_pk_bf16_f32 v97, v98, v99
	v_lshlrev_b32_e32 v98, 16, v178
	v_and_b32_e32 v99, 0xffff0000, v178
	v_pk_add_f32 v[92:93], v[92:93], v[98:99]
	v_lshl_add_u64 v[108:109], s[88:89], 0, v[222:223]
	v_cvt_pk_bf16_f32 v98, v92, v93
	v_lshlrev_b32_e32 v92, 16, v179
	v_and_b32_e32 v93, 0xffff0000, v179
	v_pk_add_f32 v[92:93], v[94:95], v[92:93]
	s_waitcnt vmcnt(10)
	v_lshlrev_b32_e32 v94, 16, v168
	v_and_b32_e32 v95, 0xffff0000, v168
	v_pk_add_f32 v[88:89], v[88:89], v[94:95]
	v_lshlrev_b32_e32 v94, 16, v169
	v_and_b32_e32 v95, 0xffff0000, v169
	v_pk_add_f32 v[90:91], v[90:91], v[94:95]
	v_cvt_pk_bf16_f32 v88, v88, v89
	v_cvt_pk_bf16_f32 v89, v90, v91
	v_lshlrev_b32_e32 v90, 16, v170
	v_and_b32_e32 v91, 0xffff0000, v170
	v_pk_add_f32 v[80:81], v[80:81], v[90:91]
	v_cvt_pk_bf16_f32 v99, v92, v93
	v_cvt_pk_bf16_f32 v90, v80, v81
	v_lshlrev_b32_e32 v80, 16, v171
	v_and_b32_e32 v81, 0xffff0000, v171
	v_pk_add_f32 v[80:81], v[82:83], v[80:81]
	s_waitcnt vmcnt(9)
	v_lshlrev_b32_e32 v82, 16, v173
	v_cvt_pk_bf16_f32 v91, v80, v81
	v_lshlrev_b32_e32 v80, 16, v172
	v_and_b32_e32 v81, 0xffff0000, v172
	v_and_b32_e32 v83, 0xffff0000, v173
	v_pk_add_f32 v[80:81], v[84:85], v[80:81]
	v_pk_add_f32 v[82:83], v[86:87], v[82:83]
	v_cvt_pk_bf16_f32 v80, v80, v81
	v_cvt_pk_bf16_f32 v81, v82, v83
	v_lshlrev_b32_e32 v82, 16, v174
	v_and_b32_e32 v83, 0xffff0000, v174
	v_pk_add_f32 v[76:77], v[76:77], v[82:83]
	v_lshl_add_u64 v[92:93], s[88:89], 0, v[220:221]
	v_cvt_pk_bf16_f32 v82, v76, v77
	v_lshlrev_b32_e32 v76, 16, v175
	v_and_b32_e32 v77, 0xffff0000, v175
	v_pk_add_f32 v[76:77], v[78:79], v[76:77]
	s_waitcnt vmcnt(8)
	v_lshlrev_b32_e32 v78, 16, v164
	v_and_b32_e32 v79, 0xffff0000, v164
	v_pk_add_f32 v[72:73], v[72:73], v[78:79]
	v_lshlrev_b32_e32 v78, 16, v165
	v_and_b32_e32 v79, 0xffff0000, v165
	v_pk_add_f32 v[74:75], v[74:75], v[78:79]
	v_cvt_pk_bf16_f32 v72, v72, v73
	v_cvt_pk_bf16_f32 v73, v74, v75
	v_lshlrev_b32_e32 v74, 16, v166
	v_and_b32_e32 v75, 0xffff0000, v166
	v_pk_add_f32 v[68:69], v[68:69], v[74:75]
	v_cvt_pk_bf16_f32 v83, v76, v77
	v_cvt_pk_bf16_f32 v74, v68, v69
	v_lshlrev_b32_e32 v68, 16, v167
	v_and_b32_e32 v69, 0xffff0000, v167
	v_pk_add_f32 v[68:69], v[70:71], v[68:69]
	v_lshl_add_u64 v[76:77], s[88:89], 0, v[212:213]
	v_cvt_pk_bf16_f32 v75, v68, v69
	s_waitcnt vmcnt(7)
	v_lshlrev_b32_e32 v68, 16, v160
	v_and_b32_e32 v69, 0xffff0000, v160
	v_pk_add_f32 v[64:65], v[64:65], v[68:69]
	v_lshlrev_b32_e32 v68, 16, v161
	v_and_b32_e32 v69, 0xffff0000, v161
	v_pk_add_f32 v[66:67], v[66:67], v[68:69]
	v_cvt_pk_bf16_f32 v64, v64, v65
	v_cvt_pk_bf16_f32 v65, v66, v67
	v_lshlrev_b32_e32 v66, 16, v162
	v_and_b32_e32 v67, 0xffff0000, v162
	v_pk_add_f32 v[60:61], v[60:61], v[66:67]
	v_lshl_add_u64 v[108:109], v[108:109], 0, v[202:203]
	v_cvt_pk_bf16_f32 v66, v60, v61
	v_lshlrev_b32_e32 v60, 16, v163
	v_and_b32_e32 v61, 0xffff0000, v163
	v_pk_add_f32 v[60:61], v[62:63], v[60:61]
	s_waitcnt vmcnt(6)
; __device__ __forceinline__ unsigned cvt_pk_bf16(float lo, float hi) { const f32x2 v = {lo, hi}; const bf16v2_ r = __builtin_convertvector(v, bf16v2_); return __builtin_bit_cast(unsigned, r); }
; __device__ __forceinline__ float bflo(unsigned w) { return __uint_as_float(w << 16); }
; __device__ __forceinline__ float bfhi(unsigned w) { return __uint_as_float(w & 0xffff0000u); }
; #define PG8_WAIT_V(n) asm volatile("s_waitcnt vmcnt(" #n ")" ::: "memory")
; #define PG8_BAR __builtin_amdgcn_s_barrier()
;     __device__ __forceinline__ void operator()(const f32x4 (&acc)[2][2][4][2], const Unit& u, int wr, int wc, int, int) const {
;     ...
;                 for (int bj = 0; bj < 2; ++bj) { const u32x4 c = cin[ai][m][bj]; const f32x4 v0 = acc[ai][bj][m][0], v1 = acc[ai][bj][m][1];
;                     u32x4 w; w.x = cvt_pk_bf16(bflo(c.x) + v0[0], bfhi(c.x) + v0[1]); w.y = cvt_pk_bf16(bflo(c.y) + v0[2], bfhi(c.y) + v0[3]);
;                     w.z = cvt_pk_bf16(bflo(c.z) + v1[0], bfhi(c.z) + v1[1]); w.w = cvt_pk_bf16(bflo(c.w) + v1[2], bfhi(c.w) + v1[3]);
;                     *(u32x4*)(C + (size_t)(row0 + ai * HALF + m * 16) * ldc + col0 + bj * HALF) = w; }
; template <class Epi, class Sched>
; __device__ __forceinline__ void gemm_phase(LAS unsigned char* lds, const Gemm g, const Sched& S, const Epi& E) {
;     ...
;         if (!has_next) break;
; #pragma unroll
;         for (int a = 0; a < 2; ++a)
; #pragma unroll
;             for (int b = 0; b < 2; ++b)
; #pragma unroll
;                 for (int m = 0; m < 4; ++m)
; #pragma unroll
;                     for (int n = 0; n < 2; ++n) acc[a][b][m][n] = (f32x4){0.f, 0.f, 0.f, 0.f};
;         cur = nxt; cA = nA; cB = nB; ++ui;
;     }
;     PG8_WAIT_V(0);
;     if (wr == 0) PG8_BAR;
;     PG8_BAR;
	v_lshlrev_b32_e32 v62, 16, v156
	v_and_b32_e32 v63, 0xffff0000, v156
	v_pk_add_f32 v[56:57], v[56:57], v[62:63]
	v_lshlrev_b32_e32 v62, 16, v157
	v_and_b32_e32 v63, 0xffff0000, v157
	v_pk_add_f32 v[58:59], v[58:59], v[62:63]
	v_cvt_pk_bf16_f32 v56, v56, v57
	v_cvt_pk_bf16_f32 v57, v58, v59
	v_lshlrev_b32_e32 v58, 16, v158
	v_and_b32_e32 v59, 0xffff0000, v158
	v_pk_add_f32 v[48:49], v[48:49], v[58:59]
	v_cvt_pk_bf16_f32 v67, v60, v61
	v_cvt_pk_bf16_f32 v58, v48, v49
	v_lshlrev_b32_e32 v48, 16, v159
	v_and_b32_e32 v49, 0xffff0000, v159
	v_pk_add_f32 v[48:49], v[50:51], v[48:49]
	s_waitcnt vmcnt(5)
	v_lshlrev_b32_e32 v50, 16, v153
	v_cvt_pk_bf16_f32 v59, v48, v49
	v_lshlrev_b32_e32 v48, 16, v152
	v_and_b32_e32 v49, 0xffff0000, v152
	v_and_b32_e32 v51, 0xffff0000, v153
	v_pk_add_f32 v[48:49], v[52:53], v[48:49]
	v_pk_add_f32 v[50:51], v[54:55], v[50:51]
	v_cvt_pk_bf16_f32 v48, v48, v49
	v_cvt_pk_bf16_f32 v49, v50, v51
	v_lshlrev_b32_e32 v50, 16, v154
	v_and_b32_e32 v51, 0xffff0000, v154
	v_pk_add_f32 v[44:45], v[44:45], v[50:51]
	v_lshl_add_u64 v[60:61], s[88:89], 0, v[210:211]
	v_cvt_pk_bf16_f32 v50, v44, v45
	v_lshlrev_b32_e32 v44, 16, v155
	v_and_b32_e32 v45, 0xffff0000, v155
	v_pk_add_f32 v[44:45], v[46:47], v[44:45]
	s_waitcnt vmcnt(4)
	v_lshlrev_b32_e32 v46, 16, v148
	v_and_b32_e32 v47, 0xffff0000, v148
	v_pk_add_f32 v[40:41], v[40:41], v[46:47]
	v_lshlrev_b32_e32 v46, 16, v149
	v_and_b32_e32 v47, 0xffff0000, v149
	v_pk_add_f32 v[42:43], v[42:43], v[46:47]
	v_cvt_pk_bf16_f32 v40, v40, v41
	v_cvt_pk_bf16_f32 v41, v42, v43
	v_lshlrev_b32_e32 v42, 16, v150
	v_and_b32_e32 v43, 0xffff0000, v150
	v_pk_add_f32 v[32:33], v[32:33], v[42:43]
	v_cvt_pk_bf16_f32 v51, v44, v45
	v_cvt_pk_bf16_f32 v42, v32, v33
	v_lshlrev_b32_e32 v32, 16, v151
	v_and_b32_e32 v33, 0xffff0000, v151
	v_pk_add_f32 v[32:33], v[34:35], v[32:33]
	s_waitcnt vmcnt(3)
	v_lshlrev_b32_e32 v34, 16, v145
	v_cvt_pk_bf16_f32 v43, v32, v33
	v_lshlrev_b32_e32 v32, 16, v144
	v_and_b32_e32 v33, 0xffff0000, v144
	v_and_b32_e32 v35, 0xffff0000, v145
	v_pk_add_f32 v[32:33], v[36:37], v[32:33]
	v_pk_add_f32 v[34:35], v[38:39], v[34:35]
	v_cvt_pk_bf16_f32 v32, v32, v33
	v_cvt_pk_bf16_f32 v33, v34, v35
	v_lshlrev_b32_e32 v34, 16, v146
	v_and_b32_e32 v35, 0xffff0000, v146
	v_pk_add_f32 v[28:29], v[28:29], v[34:35]
	v_lshl_add_u64 v[44:45], s[88:89], 0, v[208:209]
	v_cvt_pk_bf16_f32 v34, v28, v29
	v_lshlrev_b32_e32 v28, 16, v147
	v_and_b32_e32 v29, 0xffff0000, v147
	v_pk_add_f32 v[28:29], v[30:31], v[28:29]
	s_waitcnt vmcnt(2)
	v_lshlrev_b32_e32 v30, 16, v140
	v_and_b32_e32 v31, 0xffff0000, v140
	v_pk_add_f32 v[24:25], v[24:25], v[30:31]
	v_lshlrev_b32_e32 v30, 16, v141
	v_and_b32_e32 v31, 0xffff0000, v141
	v_pk_add_f32 v[26:27], v[26:27], v[30:31]
	v_cvt_pk_bf16_f32 v24, v24, v25
	v_cvt_pk_bf16_f32 v25, v26, v27
	v_lshlrev_b32_e32 v26, 16, v142
	v_and_b32_e32 v27, 0xffff0000, v142
	v_pk_add_f32 v[16:17], v[16:17], v[26:27]
	v_cvt_pk_bf16_f32 v35, v28, v29
	v_cvt_pk_bf16_f32 v26, v16, v17
	v_lshlrev_b32_e32 v16, 16, v143
	v_and_b32_e32 v17, 0xffff0000, v143
	v_pk_add_f32 v[16:17], v[18:19], v[16:17]
	s_waitcnt vmcnt(1)
	v_lshlrev_b32_e32 v18, 16, v137
	v_cvt_pk_bf16_f32 v27, v16, v17
	v_lshlrev_b32_e32 v16, 16, v136
	v_and_b32_e32 v17, 0xffff0000, v136
	v_and_b32_e32 v19, 0xffff0000, v137
	v_pk_add_f32 v[16:17], v[20:21], v[16:17]
	v_pk_add_f32 v[18:19], v[22:23], v[18:19]
	v_cvt_pk_bf16_f32 v16, v16, v17
	v_cvt_pk_bf16_f32 v17, v18, v19
	v_lshlrev_b32_e32 v18, 16, v138
	v_and_b32_e32 v19, 0xffff0000, v138
	v_pk_add_f32 v[12:13], v[12:13], v[18:19]
	v_lshl_add_u64 v[28:29], s[88:89], 0, v[206:207]
	v_cvt_pk_bf16_f32 v18, v12, v13
	v_lshlrev_b32_e32 v12, 16, v139
	v_and_b32_e32 v13, 0xffff0000, v139
	v_pk_add_f32 v[12:13], v[14:15], v[12:13]
	s_waitcnt vmcnt(0)
	v_lshlrev_b32_e32 v14, 16, v132
	v_and_b32_e32 v15, 0xffff0000, v132
	v_pk_add_f32 v[8:9], v[8:9], v[14:15]
	v_lshlrev_b32_e32 v14, 16, v133
	v_and_b32_e32 v15, 0xffff0000, v133
	v_pk_add_f32 v[10:11], v[10:11], v[14:15]
	v_cvt_pk_bf16_f32 v8, v8, v9
	v_cvt_pk_bf16_f32 v9, v10, v11
	v_lshlrev_b32_e32 v10, 16, v134
	v_and_b32_e32 v11, 0xffff0000, v134
	v_pk_add_f32 v[4:5], v[4:5], v[10:11]
	v_cvt_pk_bf16_f32 v19, v12, v13
	v_cvt_pk_bf16_f32 v10, v4, v5
	v_lshlrev_b32_e32 v4, 16, v135
	v_and_b32_e32 v5, 0xffff0000, v135
	v_lshl_add_u64 v[12:13], s[88:89], 0, v[204:205]
	v_pk_add_f32 v[4:5], v[6:7], v[4:5]
	v_lshl_add_u64 v[92:93], v[92:93], 0, v[202:203]
	v_lshl_add_u64 v[76:77], v[76:77], 0, v[202:203]
	v_lshl_add_u64 v[60:61], v[60:61], 0, v[202:203]
	v_lshl_add_u64 v[44:45], v[44:45], 0, v[202:203]
	v_lshl_add_u64 v[28:29], v[28:29], 0, v[202:203]
	v_lshl_add_u64 v[12:13], v[12:13], 0, v[202:203]
	v_cvt_pk_bf16_f32 v11, v4, v5
	global_store_dwordx4 v[124:125], v[128:131], off
	global_store_dwordx4 v[124:125], v[120:123], off offset:256
	global_store_dwordx4 v[108:109], v[112:115], off
	global_store_dwordx4 v[108:109], v[104:107], off offset:256
	global_store_dwordx4 v[92:93], v[96:99], off
	global_store_dwordx4 v[92:93], v[88:91], off offset:256
	global_store_dwordx4 v[76:77], v[80:83], off
	global_store_dwordx4 v[76:77], v[72:75], off offset:256
	global_store_dwordx4 v[60:61], v[64:67], off
	global_store_dwordx4 v[60:61], v[56:59], off offset:256
	global_store_dwordx4 v[44:45], v[48:51], off
	global_store_dwordx4 v[44:45], v[40:43], off offset:256
	global_store_dwordx4 v[28:29], v[32:35], off
	global_store_dwordx4 v[28:29], v[24:27], off offset:256
	global_store_dwordx4 v[12:13], v[16:19], off
	global_store_dwordx4 v[12:13], v[8:11], off offset:256
	s_cbranch_vccz .LBB0_1655
	s_waitcnt vmcnt(0)
	s_cmpk_gt_u32 s2, 0xff
	s_cbranch_scc1 .LBB0_1670
	s_barrier
